# K-loops: closing waits merged into one s_waitcnt vmcnt(N) lgkmcnt(0); redundant lgkmcnt(0) after the phase barrier removed (on the saddr-form balanced loops)
# baseline (speedup 1.0000x reference)
; #define PG8_STAGE(bufoff, gbase, voff) do { _Pragma("unroll") for (int _i = 0; _i < 2; ++_i) \
;         __builtin_amdgcn_global_load_lds((const unsigned*)((const char*)(gbase) + (voff)[_i]), (PG8_LAS unsigned*)(lds + (bufoff) + ldsw + _i * 8192), 16, 0, 0); } while (0)
; #define PG8_LDA(dst, b, h) do { _Pragma("unroll") for (int m = 0; m < 4; ++m) _Pragma("unroll") for (int k = 0; k < 2; ++k) dst[m][k] = *(const PG8_LAS bf16x8*)(lds + PG8_SA(b, h) + aoff + m * 2048 + k * 1024); } while (0)
; #define PG8_LDB(dst, b, h) do { _Pragma("unroll") for (int n = 0; n < 2; ++n) _Pragma("unroll") for (int k = 0; k < 2; ++k) dst[n][k] = *(const PG8_LAS bf16x8*)(lds + PG8_SB(b, h) + boff + n * 2048 + k * 1024); } while (0)
; #define PG8_WAIT_V(n) asm volatile("s_waitcnt vmcnt(" #n ")" ::: "memory")
; #define PG8_WAIT_L(n) asm volatile("s_waitcnt lgkmcnt(" #n ")" ::: "memory")
; #define PG8_BAR __builtin_amdgcn_s_barrier()
; #define PG8_SCHED __builtin_amdgcn_sched_barrier(0)
; template <class Epi, class Sched, bool ALIGN_EPI = false, bool SP2 = false, bool I8 = false>
; __device__ __forceinline__ void gemm_phase(PG8_LAS unsigned char* lds, const Gemm g, const Sched& S, const Epi& E) {
;     ...
;         const bool has_next = S.next(ui + 1, nxt);
;         const char* nA = has_next ? (const char*)g.A + (size_t)nxt.pm * tstep : cA; const char* nB = has_next ? (const char*)g.Bt + (size_t)nxt.pn * tstep : cB;
;         for (int t = 0; t < nt; t += 2) {
;             const bool last = (t == nt - 2);
;             const char* a1 = cA + (size_t)(t + 1) * kstep;
;             const char* a2 = last ? nA : cA + (size_t)(t + 2) * kstep; const char* b2 = last ? nB : cB + (size_t)(t + 2) * kstep;
;             const char* a3 = a2 + kstep; const char* b3 = b2 + kstep;
;             if (last && has_next) S.a_ready(nxt);
;             if constexpr (SP2) {
;             PG8_LDB(B0, 0, 0); PG8_LDB(B1, 0, 1); PG8_SCHED; PG8_LDA(At, 0, 0); PG8_STAGE(PG8_SA(1, 1), a1 + hstep, voffA);
;             PG8_WAIT_V(8); PG8_WAIT_L(0); PG8_BAR; PG8_MMA(0, 0, At, B0); PG8_MMA(0, 1, At, B1); PG8_BAR; PG8_SCHED;
;             PG8_LDA(At, 0, 1); PG8_STAGE(PG8_SB(0, 0), b2, voffB); PG8_STAGE(PG8_SB(0, 1), b2 + hstep, voffB); PG8_STAGE(PG8_SA(0, 0), a2, voffA);
;             PG8_WAIT_V(8); PG8_WAIT_L(0); PG8_BAR; PG8_MMA(1, 0, At, B0); PG8_MMA(1, 1, At, B1); PG8_BAR; PG8_SCHED;
.LBB0_207:
	s_ashr_i32 s19, s18, 31
	s_lshl_b64 s[22:23], s[18:19], 20
	s_add_u32 s22, s28, s22
	s_addc_u32 s23, s34, s23
	s_and_b64 s[24:25], s[6:7], exec
	s_cselect_b32 s19, s23, s27
	s_cselect_b32 s64, s22, s26
	s_ashr_i32 s17, s16, 31
	s_lshl_b64 s[24:25], s[16:17], 20
	s_add_u32 s24, s35, s24
	s_addc_u32 s25, s42, s25
	s_and_b64 s[40:41], s[6:7], exec
	s_cselect_b32 s17, s25, s37
	s_cselect_b32 s65, s24, s36
	s_add_u32 s26, s26, 0x80080
	s_addc_u32 s27, s27, 0
	s_add_u32 s72, s36, 0x100
	s_addc_u32 s73, s37, 0
	s_mov_b32 s76, -2
	s_add_u32 s36, s26, 0xfff80080
	s_addc_u32 s37, s27, -1
	s_add_i32 s50, 0, 0x10000
	s_cmp_eq_u32 s76, 28
	s_cselect_b32 s41, s19, s37
	s_cselect_b32 s40, s64, s36
	s_cselect_b32 s37, s17, s73
	s_cselect_b32 s36, s65, s72
	s_add_i32 s56, 0, 0x14000
	v_add_u32_e32 v136, s50, v175
	v_add_u32_e32 v172, s56, v175
	ds_read_b128 v[116:119], v136
	ds_read_b128 v[124:127], v136 offset:1024
	ds_read_b128 v[132:135], v136 offset:2048
	ds_read_b128 v[136:139], v136 offset:3072
	ds_read_b128 v[160:163], v172
	ds_read_b128 v[164:167], v172 offset:1024
	ds_read_b128 v[168:171], v172 offset:2048
	ds_read_b128 v[178:181], v172 offset:3072
	s_add_i32 m0, s44, 0xc000
	ds_read_b128 v[182:185], v177
	ds_read_b128 v[186:189], v177 offset:1024
	ds_read_b128 v[204:207], v177 offset:2048
	ds_read_b128 v[208:211], v177 offset:3072
	ds_read_b128 v[212:215], v177 offset:4096
	ds_read_b128 v[216:219], v177 offset:5120
	ds_read_b128 v[220:223], v177 offset:6144
	ds_read_b128 v[224:227], v177 offset:7168
	global_load_lds_dwordx4 v156, s[26:27]
	s_add_i32 m0, s44, 0xe000
	s_nop 0
	global_load_lds_dwordx4 v158, s[26:27]
	s_waitcnt vmcnt(8) lgkmcnt(0)
	s_barrier
	s_setprio 1
	v_mfma_i32_16x16x64_i8 v[144:147], v[116:119], v[182:185], 0
	v_mfma_i32_16x16x64_i8 v[144:147], v[124:127], v[186:189], v[144:147]
	v_mfma_i32_16x16x64_i8 v[112:115], v[124:127], v[208:211], 0
	v_mfma_i32_16x16x64_i8 v[112:115], v[116:119], v[204:207], v[112:115]
	v_mfma_i32_16x16x64_i8 v[96:99], v[116:119], v[212:215], 0
	v_mfma_i32_16x16x64_i8 v[96:99], v[124:127], v[216:219], v[96:99]
	v_mfma_i32_16x16x64_i8 v[80:83], v[124:127], v[224:227], 0
	v_mfma_i32_16x16x64_i8 v[80:83], v[116:119], v[220:223], v[80:83]
	v_mfma_i32_16x16x64_i8 v[76:79], v[132:135], v[220:223], 0
	v_mfma_i32_16x16x64_i8 v[76:79], v[136:139], v[224:227], v[76:79]
	v_mfma_i32_16x16x64_i8 v[92:95], v[136:139], v[216:219], 0
	v_mfma_i32_16x16x64_i8 v[92:95], v[132:135], v[212:215], v[92:95]
	v_mfma_i32_16x16x64_i8 v[108:111], v[132:135], v[204:207], 0
	v_mfma_i32_16x16x64_i8 v[108:111], v[136:139], v[208:211], v[108:111]
	v_mfma_i32_16x16x64_i8 v[140:143], v[136:139], v[186:189], 0
	v_mfma_i32_16x16x64_i8 v[140:143], v[132:135], v[182:185], v[140:143]
	v_mfma_i32_16x16x64_i8 v[128:131], v[160:163], v[182:185], 0
	v_mfma_i32_16x16x64_i8 v[128:131], v[164:167], v[186:189], v[128:131]
	v_mfma_i32_16x16x64_i8 v[104:107], v[164:167], v[208:211], 0
	v_mfma_i32_16x16x64_i8 v[104:107], v[160:163], v[204:207], v[104:107]
	v_mfma_i32_16x16x64_i8 v[88:91], v[160:163], v[212:215], 0
	v_mfma_i32_16x16x64_i8 v[88:91], v[164:167], v[216:219], v[88:91]
	v_mfma_i32_16x16x64_i8 v[72:75], v[164:167], v[224:227], 0
	v_mfma_i32_16x16x64_i8 v[72:75], v[160:163], v[220:223], v[72:75]
	v_mfma_i32_16x16x64_i8 v[68:71], v[168:171], v[220:223], 0
	v_mfma_i32_16x16x64_i8 v[68:71], v[178:181], v[224:227], v[68:71]
	v_mfma_i32_16x16x64_i8 v[84:87], v[178:181], v[216:219], 0
	v_mfma_i32_16x16x64_i8 v[84:87], v[168:171], v[212:215], v[84:87]
	v_mfma_i32_16x16x64_i8 v[100:103], v[168:171], v[204:207], 0
	v_mfma_i32_16x16x64_i8 v[100:103], v[178:181], v[208:211], v[100:103]
	v_mfma_i32_16x16x64_i8 v[120:123], v[178:181], v[186:189], 0
	v_mfma_i32_16x16x64_i8 v[120:123], v[168:171], v[182:185], v[120:123]
	s_setprio 0
	s_barrier
	s_add_i32 s50, s50, s43
	v_lshl_add_u64 v[172:173], s[36:37], 0, v[2:3]
	s_mov_b32 m0, s50
	ds_read_b128 v[182:185], v177 offset:16384
	ds_read_b128 v[186:189], v177 offset:17408
	ds_read_b128 v[204:207], v177 offset:18432
	ds_read_b128 v[208:211], v177 offset:19456
	ds_read_b128 v[212:215], v177 offset:20480
	ds_read_b128 v[216:219], v177 offset:21504
	ds_read_b128 v[220:223], v177 offset:22528
	ds_read_b128 v[224:227], v177 offset:23552
	global_load_lds_dwordx4 v[172:173], off
	s_add_i32 m0, s50, 0x2000
	s_add_u32 s50, s36, 0x80000
	v_lshl_add_u64 v[190:191], s[36:37], 0, v[148:149]
	s_addc_u32 s51, s37, 0
	s_add_i32 s56, s56, s43
	global_load_lds_dwordx4 v[190:191], off
	s_mov_b32 m0, s56
	v_lshl_add_u64 v[240:241], s[40:41], 0, v[150:151]
	global_load_lds_dwordx4 v2, s[50:51]
	s_add_i32 m0, s56, 0x2000
	s_nop 0
	global_load_lds_dwordx4 v148, s[50:51]
	v_lshl_add_u64 v[228:229], s[40:41], 0, v[152:153]
	s_waitcnt vmcnt(6) lgkmcnt(0)
	s_barrier
; #define PG8_STAGE(bufoff, gbase, voff) do { _Pragma("unroll") for (int _i = 0; _i < 2; ++_i) \
;         __builtin_amdgcn_global_load_lds((const unsigned*)((const char*)(gbase) + (voff)[_i]), (PG8_LAS unsigned*)(lds + (bufoff) + ldsw + _i * 8192), 16, 0, 0); } while (0)
; #define PG8_LDA(dst, b, h) do { _Pragma("unroll") for (int m = 0; m < 4; ++m) _Pragma("unroll") for (int k = 0; k < 2; ++k) dst[m][k] = *(const PG8_LAS bf16x8*)(lds + PG8_SA(b, h) + aoff + m * 2048 + k * 1024); } while (0)
; #define PG8_LDB(dst, b, h) do { _Pragma("unroll") for (int n = 0; n < 2; ++n) _Pragma("unroll") for (int k = 0; k < 2; ++k) dst[n][k] = *(const PG8_LAS bf16x8*)(lds + PG8_SB(b, h) + boff + n * 2048 + k * 1024); } while (0)
; #define PG8_WAIT_V(n) asm volatile("s_waitcnt vmcnt(" #n ")" ::: "memory")
; #define PG8_WAIT_L(n) asm volatile("s_waitcnt lgkmcnt(" #n ")" ::: "memory")
; #define PG8_BAR __builtin_amdgcn_s_barrier()
; #define PG8_SCHED __builtin_amdgcn_sched_barrier(0)
; template <class Epi, class Sched, bool ALIGN_EPI = false, bool SP2 = false, bool I8 = false>
; __device__ __forceinline__ void gemm_phase(PG8_LAS unsigned char* lds, const Gemm g, const Sched& S, const Epi& E) {
;     ...
;             PG8_WAIT_V(8); PG8_WAIT_L(0); PG8_BAR; PG8_MMA(0, 0, At, B0); PG8_MMA(0, 1, At, B1); PG8_BAR; PG8_SCHED;
;             PG8_LDA(At, 0, 1); PG8_STAGE(PG8_SB(0, 0), b2, voffB); PG8_STAGE(PG8_SB(0, 1), b2 + hstep, voffB); PG8_STAGE(PG8_SA(0, 0), a2, voffA);
;             PG8_WAIT_V(8); PG8_WAIT_L(0); PG8_BAR; PG8_MMA(1, 0, At, B0); PG8_MMA(1, 1, At, B1); PG8_BAR; PG8_SCHED;
;             PG8_LDB(B0, 1, 0); PG8_LDB(B1, 1, 1); PG8_SCHED; PG8_LDA(At, 1, 0); PG8_STAGE(PG8_SA(0, 1), a2 + hstep, voffA);
;             PG8_WAIT_V(8); PG8_WAIT_L(0); PG8_BAR; PG8_MMA(0, 0, At, B0); PG8_MMA(0, 1, At, B1); PG8_BAR; PG8_SCHED;
;             PG8_LDA(At, 1, 1); PG8_STAGE(PG8_SB(1, 0), b3, voffB); PG8_STAGE(PG8_SB(1, 1), b3 + hstep, voffB); PG8_STAGE(PG8_SA(1, 0), a3, voffA);
;             PG8_WAIT_V(8); PG8_WAIT_L(0); PG8_BAR; PG8_MMA(1, 0, At, B0); PG8_MMA(1, 1, At, B1); PG8_BAR; PG8_SCHED;
	s_setprio 1
	v_mfma_i32_16x16x64_i8 v[64:67], v[116:119], v[182:185], 0
	v_mfma_i32_16x16x64_i8 v[64:67], v[124:127], v[186:189], v[64:67]
	v_mfma_i32_16x16x64_i8 v[48:51], v[124:127], v[208:211], 0
	v_mfma_i32_16x16x64_i8 v[48:51], v[116:119], v[204:207], v[48:51]
	v_mfma_i32_16x16x64_i8 v[32:35], v[116:119], v[212:215], 0
	v_mfma_i32_16x16x64_i8 v[32:35], v[124:127], v[216:219], v[32:35]
	v_mfma_i32_16x16x64_i8 v[16:19], v[124:127], v[224:227], 0
	v_mfma_i32_16x16x64_i8 v[16:19], v[116:119], v[220:223], v[16:19]
	v_mfma_i32_16x16x64_i8 v[12:15], v[132:135], v[220:223], 0
	v_mfma_i32_16x16x64_i8 v[12:15], v[136:139], v[224:227], v[12:15]
	v_mfma_i32_16x16x64_i8 v[28:31], v[136:139], v[216:219], 0
	v_mfma_i32_16x16x64_i8 v[28:31], v[132:135], v[212:215], v[28:31]
	v_mfma_i32_16x16x64_i8 v[44:47], v[132:135], v[204:207], 0
	v_mfma_i32_16x16x64_i8 v[44:47], v[136:139], v[208:211], v[44:47]
	v_mfma_i32_16x16x64_i8 v[60:63], v[136:139], v[186:189], 0
	v_mfma_i32_16x16x64_i8 v[60:63], v[132:135], v[182:185], v[60:63]
	v_mfma_i32_16x16x64_i8 v[56:59], v[160:163], v[182:185], 0
	v_mfma_i32_16x16x64_i8 v[56:59], v[164:167], v[186:189], v[56:59]
	v_mfma_i32_16x16x64_i8 v[40:43], v[164:167], v[208:211], 0
	v_mfma_i32_16x16x64_i8 v[40:43], v[160:163], v[204:207], v[40:43]
	v_mfma_i32_16x16x64_i8 v[24:27], v[160:163], v[212:215], 0
	v_mfma_i32_16x16x64_i8 v[24:27], v[164:167], v[216:219], v[24:27]
	v_mfma_i32_16x16x64_i8 v[8:11], v[164:167], v[224:227], 0
	v_mfma_i32_16x16x64_i8 v[8:11], v[160:163], v[220:223], v[8:11]
	v_mfma_i32_16x16x64_i8 v[4:7], v[168:171], v[220:223], 0
	v_mfma_i32_16x16x64_i8 v[4:7], v[178:181], v[224:227], v[4:7]
	v_mfma_i32_16x16x64_i8 v[20:23], v[178:181], v[216:219], 0
	v_mfma_i32_16x16x64_i8 v[20:23], v[168:171], v[212:215], v[20:23]
	v_mfma_i32_16x16x64_i8 v[36:39], v[168:171], v[204:207], 0
	v_mfma_i32_16x16x64_i8 v[36:39], v[178:181], v[208:211], v[36:39]
	v_mfma_i32_16x16x64_i8 v[52:55], v[178:181], v[186:189], 0
	v_mfma_i32_16x16x64_i8 v[52:55], v[168:171], v[182:185], v[52:55]
	s_setprio 0
	s_barrier
	s_mov_b32 m0, s44
	s_nop 0
	global_load_lds_dwordx4 v[228:229], off
	s_mov_b32 m0, s45
	s_nop 0
	global_load_lds_dwordx4 v[240:241], off
	s_add_i32 s50, 0, 0x18000
	s_add_i32 s51, 0, 0x1c000
	v_add_u32_e32 v136, s50, v175
	v_add_u32_e32 v178, s51, v175
	ds_read_b128 v[116:119], v136
	ds_read_b128 v[124:127], v136 offset:1024
	ds_read_b128 v[132:135], v136 offset:2048
	ds_read_b128 v[136:139], v136 offset:3072
	ds_read_b128 v[160:163], v178
	ds_read_b128 v[164:167], v178 offset:1024
	ds_read_b128 v[168:171], v178 offset:2048
	ds_read_b128 v[178:181], v178 offset:3072
	s_add_u32 s40, s40, 0x80000
	s_addc_u32 s41, s41, 0
	s_mov_b32 m0, s46
	ds_read_b128 v[182:185], v177 offset:32768
	ds_read_b128 v[186:189], v177 offset:33792
	ds_read_b128 v[204:207], v177 offset:34816
	ds_read_b128 v[208:211], v177 offset:35840
	ds_read_b128 v[212:215], v177 offset:36864
	ds_read_b128 v[216:219], v177 offset:37888
	ds_read_b128 v[220:223], v177 offset:38912
	ds_read_b128 v[224:227], v177 offset:39936
	global_load_lds_dwordx4 v152, s[40:41]
	s_mov_b32 m0, s47
	s_nop 0
	global_load_lds_dwordx4 v150, s[40:41]
	s_waitcnt vmcnt(8) lgkmcnt(0)
	s_barrier
	s_setprio 1
	v_mfma_i32_16x16x64_i8 v[144:147], v[116:119], v[182:185], v[144:147]
	v_mfma_i32_16x16x64_i8 v[144:147], v[124:127], v[186:189], v[144:147]
	v_mfma_i32_16x16x64_i8 v[112:115], v[124:127], v[208:211], v[112:115]
	v_mfma_i32_16x16x64_i8 v[112:115], v[116:119], v[204:207], v[112:115]
	v_mfma_i32_16x16x64_i8 v[96:99], v[116:119], v[212:215], v[96:99]
	v_mfma_i32_16x16x64_i8 v[96:99], v[124:127], v[216:219], v[96:99]
	v_mfma_i32_16x16x64_i8 v[80:83], v[124:127], v[224:227], v[80:83]
	v_mfma_i32_16x16x64_i8 v[80:83], v[116:119], v[220:223], v[80:83]
	v_mfma_i32_16x16x64_i8 v[76:79], v[132:135], v[220:223], v[76:79]
	v_mfma_i32_16x16x64_i8 v[76:79], v[136:139], v[224:227], v[76:79]
	v_mfma_i32_16x16x64_i8 v[92:95], v[136:139], v[216:219], v[92:95]
	v_mfma_i32_16x16x64_i8 v[92:95], v[132:135], v[212:215], v[92:95]
	v_mfma_i32_16x16x64_i8 v[108:111], v[132:135], v[204:207], v[108:111]
	v_mfma_i32_16x16x64_i8 v[108:111], v[136:139], v[208:211], v[108:111]
	v_mfma_i32_16x16x64_i8 v[140:143], v[136:139], v[186:189], v[140:143]
	v_mfma_i32_16x16x64_i8 v[140:143], v[132:135], v[182:185], v[140:143]
	v_mfma_i32_16x16x64_i8 v[128:131], v[160:163], v[182:185], v[128:131]
	v_mfma_i32_16x16x64_i8 v[128:131], v[164:167], v[186:189], v[128:131]
	v_mfma_i32_16x16x64_i8 v[104:107], v[164:167], v[208:211], v[104:107]
	v_mfma_i32_16x16x64_i8 v[104:107], v[160:163], v[204:207], v[104:107]
	v_mfma_i32_16x16x64_i8 v[88:91], v[160:163], v[212:215], v[88:91]
	v_mfma_i32_16x16x64_i8 v[88:91], v[164:167], v[216:219], v[88:91]
	v_mfma_i32_16x16x64_i8 v[72:75], v[164:167], v[224:227], v[72:75]
	v_mfma_i32_16x16x64_i8 v[72:75], v[160:163], v[220:223], v[72:75]
	v_mfma_i32_16x16x64_i8 v[68:71], v[168:171], v[220:223], v[68:71]
	v_mfma_i32_16x16x64_i8 v[68:71], v[178:181], v[224:227], v[68:71]
	v_mfma_i32_16x16x64_i8 v[84:87], v[178:181], v[216:219], v[84:87]
	v_mfma_i32_16x16x64_i8 v[84:87], v[168:171], v[212:215], v[84:87]
	v_mfma_i32_16x16x64_i8 v[100:103], v[168:171], v[204:207], v[100:103]
	v_mfma_i32_16x16x64_i8 v[100:103], v[178:181], v[208:211], v[100:103]
	v_mfma_i32_16x16x64_i8 v[120:123], v[178:181], v[186:189], v[120:123]
	v_mfma_i32_16x16x64_i8 v[120:123], v[168:171], v[182:185], v[120:123]
	s_setprio 0
	s_barrier
	s_add_i32 s40, s50, s43
	v_lshl_add_u64 v[172:173], v[172:173], 0, s[84:85]
	s_mov_b32 m0, s40
	ds_read_b128 v[182:185], v177 offset:49152
	ds_read_b128 v[186:189], v177 offset:50176
	ds_read_b128 v[204:207], v177 offset:51200
	ds_read_b128 v[208:211], v177 offset:52224
	ds_read_b128 v[212:215], v177 offset:53248
	ds_read_b128 v[216:219], v177 offset:54272
	ds_read_b128 v[220:223], v177 offset:55296
	ds_read_b128 v[224:227], v177 offset:56320
	global_load_lds_dwordx4 v[172:173], off
	s_add_i32 m0, s40, 0x2000
	s_add_u32 s36, s36, 0x80080
	v_lshl_add_u64 v[172:173], v[190:191], 0, s[84:85]
	s_addc_u32 s37, s37, 0
	s_add_i32 s40, s51, s43
	global_load_lds_dwordx4 v[172:173], off
	s_mov_b32 m0, s40
	s_nop 0
	global_load_lds_dwordx4 v2, s[36:37]
	s_add_i32 m0, s40, 0x2000
	s_nop 0
	global_load_lds_dwordx4 v148, s[36:37]
	s_cmp_eq_u32 s76, 28
	s_cbranch_scc0 .Ldefer_208_peel
	v_lshl_add_u64 v[172:173], v[228:229], 0, s[84:85]
	s_mov_b32 m0, s52
	s_nop 0
	global_load_lds_dwordx4 v[172:173], off
	v_lshl_add_u64 v[172:173], v[240:241], 0, s[84:85]
	s_mov_b32 m0, s53
	s_nop 0
	global_load_lds_dwordx4 v[172:173], off
; #define PG8_STAGE(bufoff, gbase, voff) do { _Pragma("unroll") for (int _i = 0; _i < 2; ++_i) \
;         __builtin_amdgcn_global_load_lds((const unsigned*)((const char*)(gbase) + (voff)[_i]), (PG8_LAS unsigned*)(lds + (bufoff) + ldsw + _i * 8192), 16, 0, 0); } while (0)
; #define PG8_LDA(dst, b, h) do { _Pragma("unroll") for (int m = 0; m < 4; ++m) _Pragma("unroll") for (int k = 0; k < 2; ++k) dst[m][k] = *(const PG8_LAS bf16x8*)(lds + PG8_SA(b, h) + aoff + m * 2048 + k * 1024); } while (0)
; #define PG8_LDB(dst, b, h) do { _Pragma("unroll") for (int n = 0; n < 2; ++n) _Pragma("unroll") for (int k = 0; k < 2; ++k) dst[n][k] = *(const PG8_LAS bf16x8*)(lds + PG8_SB(b, h) + boff + n * 2048 + k * 1024); } while (0)
; #define PG8_WAIT_V(n) asm volatile("s_waitcnt vmcnt(" #n ")" ::: "memory")
; #define PG8_WAIT_L(n) asm volatile("s_waitcnt lgkmcnt(" #n ")" ::: "memory")
; #define PG8_BAR __builtin_amdgcn_s_barrier()
; #define PG8_SCHED __builtin_amdgcn_sched_barrier(0)
; template <class Epi, class Sched, bool ALIGN_EPI = false, bool SP2 = false, bool I8 = false>
; __device__ __forceinline__ void gemm_phase(PG8_LAS unsigned char* lds, const Gemm g, const Sched& S, const Epi& E) {
;     ...
;             const char* a2 = last ? nA : cA + (size_t)(t + 2) * kstep; const char* b2 = last ? nB : cB + (size_t)(t + 2) * kstep;
;             const char* a3 = a2 + kstep; const char* b3 = b2 + kstep;
;             if (last && has_next) S.a_ready(nxt);
;             if constexpr (SP2) {
;             PG8_LDB(B0, 0, 0); PG8_LDB(B1, 0, 1); PG8_SCHED; PG8_LDA(At, 0, 0); PG8_STAGE(PG8_SA(1, 1), a1 + hstep, voffA);
;             PG8_WAIT_V(8); PG8_WAIT_L(0); PG8_BAR; PG8_MMA(0, 0, At, B0); PG8_MMA(0, 1, At, B1); PG8_BAR; PG8_SCHED;
;             PG8_LDA(At, 0, 1); PG8_STAGE(PG8_SB(0, 0), b2, voffB); PG8_STAGE(PG8_SB(0, 1), b2 + hstep, voffB); PG8_STAGE(PG8_SA(0, 0), a2, voffA);
;             PG8_WAIT_V(8); PG8_WAIT_L(0); PG8_BAR; PG8_MMA(1, 0, At, B0); PG8_MMA(1, 1, At, B1); PG8_BAR; PG8_SCHED;
;     ...
;             PG8_WAIT_V(8); PG8_WAIT_L(0); PG8_BAR; PG8_MMA(1, 0, At, B0); PG8_MMA(1, 1, At, B1); PG8_BAR; PG8_SCHED;
.Ldefer_208_peel:
	s_waitcnt vmcnt(6) lgkmcnt(0)
	s_barrier
	s_setprio 1
	v_mfma_i32_16x16x64_i8 v[64:67], v[116:119], v[182:185], v[64:67]
	v_mfma_i32_16x16x64_i8 v[64:67], v[124:127], v[186:189], v[64:67]
	v_mfma_i32_16x16x64_i8 v[48:51], v[124:127], v[208:211], v[48:51]
	v_mfma_i32_16x16x64_i8 v[48:51], v[116:119], v[204:207], v[48:51]
	v_mfma_i32_16x16x64_i8 v[32:35], v[116:119], v[212:215], v[32:35]
	v_mfma_i32_16x16x64_i8 v[32:35], v[124:127], v[216:219], v[32:35]
	v_mfma_i32_16x16x64_i8 v[16:19], v[124:127], v[224:227], v[16:19]
	v_mfma_i32_16x16x64_i8 v[16:19], v[116:119], v[220:223], v[16:19]
	v_mfma_i32_16x16x64_i8 v[12:15], v[132:135], v[220:223], v[12:15]
	v_mfma_i32_16x16x64_i8 v[12:15], v[136:139], v[224:227], v[12:15]
	v_mfma_i32_16x16x64_i8 v[28:31], v[136:139], v[216:219], v[28:31]
	v_mfma_i32_16x16x64_i8 v[28:31], v[132:135], v[212:215], v[28:31]
	v_mfma_i32_16x16x64_i8 v[44:47], v[132:135], v[204:207], v[44:47]
	v_mfma_i32_16x16x64_i8 v[44:47], v[136:139], v[208:211], v[44:47]
	v_mfma_i32_16x16x64_i8 v[60:63], v[136:139], v[186:189], v[60:63]
	v_mfma_i32_16x16x64_i8 v[60:63], v[132:135], v[182:185], v[60:63]
	v_mfma_i32_16x16x64_i8 v[56:59], v[160:163], v[182:185], v[56:59]
	v_mfma_i32_16x16x64_i8 v[56:59], v[164:167], v[186:189], v[56:59]
	v_mfma_i32_16x16x64_i8 v[40:43], v[164:167], v[208:211], v[40:43]
	v_mfma_i32_16x16x64_i8 v[40:43], v[160:163], v[204:207], v[40:43]
	v_mfma_i32_16x16x64_i8 v[24:27], v[160:163], v[212:215], v[24:27]
	v_mfma_i32_16x16x64_i8 v[24:27], v[164:167], v[216:219], v[24:27]
	v_mfma_i32_16x16x64_i8 v[8:11], v[164:167], v[224:227], v[8:11]
	v_mfma_i32_16x16x64_i8 v[8:11], v[160:163], v[220:223], v[8:11]
	v_mfma_i32_16x16x64_i8 v[4:7], v[168:171], v[220:223], v[4:7]
	v_mfma_i32_16x16x64_i8 v[4:7], v[178:181], v[224:227], v[4:7]
	v_mfma_i32_16x16x64_i8 v[20:23], v[178:181], v[216:219], v[20:23]
	v_mfma_i32_16x16x64_i8 v[20:23], v[168:171], v[212:215], v[20:23]
	v_mfma_i32_16x16x64_i8 v[36:39], v[168:171], v[204:207], v[36:39]
	v_mfma_i32_16x16x64_i8 v[36:39], v[178:181], v[208:211], v[36:39]
	v_mfma_i32_16x16x64_i8 v[52:55], v[178:181], v[186:189], v[52:55]
	v_mfma_i32_16x16x64_i8 v[52:55], v[168:171], v[182:185], v[52:55]
	s_setprio 0
	s_barrier
	s_add_i32 s76, s76, 2
	s_add_u32 s26, s26, 0x100
	s_addc_u32 s27, s27, 0
	s_add_u32 s72, s72, 0x100
	s_addc_u32 s73, s73, 0
	s_cmp_gt_u32 s76, 29
	s_cbranch_scc1 .Lkloop_exit_0
.LBB0_208:
	s_add_u32 s36, s26, 0xfff80080
	s_addc_u32 s37, s27, -1
	s_add_i32 s50, 0, 0x10000
	s_cmp_eq_u32 s76, 28
	s_cselect_b32 s41, s19, s37
	s_cselect_b32 s40, s64, s36
	s_cselect_b32 s37, s17, s73
	s_cselect_b32 s36, s65, s72
	s_add_i32 s56, 0, 0x14000
	v_add_u32_e32 v136, s50, v175
	v_add_u32_e32 v172, s56, v175
	ds_read_b128 v[116:119], v136
	ds_read_b128 v[124:127], v136 offset:1024
	ds_read_b128 v[132:135], v136 offset:2048
	ds_read_b128 v[136:139], v136 offset:3072
	ds_read_b128 v[160:163], v172
	ds_read_b128 v[164:167], v172 offset:1024
	ds_read_b128 v[168:171], v172 offset:2048
	ds_read_b128 v[178:181], v172 offset:3072
	v_lshl_add_u64 v[172:173], v[228:229], 0, s[84:85]
	s_mov_b32 m0, s52
	s_nop 0
	global_load_lds_dwordx4 v[172:173], off
	v_lshl_add_u64 v[172:173], v[240:241], 0, s[84:85]
	s_mov_b32 m0, s53
	s_nop 0
	global_load_lds_dwordx4 v[172:173], off
	s_add_i32 m0, s44, 0xc000
	ds_read_b128 v[182:185], v177
	ds_read_b128 v[186:189], v177 offset:1024
	ds_read_b128 v[204:207], v177 offset:2048
	ds_read_b128 v[208:211], v177 offset:3072
	ds_read_b128 v[212:215], v177 offset:4096
	ds_read_b128 v[216:219], v177 offset:5120
	ds_read_b128 v[220:223], v177 offset:6144
	ds_read_b128 v[224:227], v177 offset:7168
	global_load_lds_dwordx4 v156, s[26:27]
	s_add_i32 m0, s44, 0xe000
	s_nop 0
	global_load_lds_dwordx4 v158, s[26:27]
	s_waitcnt vmcnt(8) lgkmcnt(0)
	s_barrier
	s_setprio 1
	v_mfma_i32_16x16x64_i8 v[144:147], v[116:119], v[182:185], v[144:147]
	v_mfma_i32_16x16x64_i8 v[144:147], v[124:127], v[186:189], v[144:147]
	v_mfma_i32_16x16x64_i8 v[112:115], v[124:127], v[208:211], v[112:115]
	v_mfma_i32_16x16x64_i8 v[112:115], v[116:119], v[204:207], v[112:115]
	v_mfma_i32_16x16x64_i8 v[96:99], v[116:119], v[212:215], v[96:99]
	v_mfma_i32_16x16x64_i8 v[96:99], v[124:127], v[216:219], v[96:99]
	v_mfma_i32_16x16x64_i8 v[80:83], v[124:127], v[224:227], v[80:83]
	v_mfma_i32_16x16x64_i8 v[80:83], v[116:119], v[220:223], v[80:83]
	v_mfma_i32_16x16x64_i8 v[76:79], v[132:135], v[220:223], v[76:79]
	v_mfma_i32_16x16x64_i8 v[76:79], v[136:139], v[224:227], v[76:79]
	v_mfma_i32_16x16x64_i8 v[92:95], v[136:139], v[216:219], v[92:95]
	v_mfma_i32_16x16x64_i8 v[92:95], v[132:135], v[212:215], v[92:95]
	v_mfma_i32_16x16x64_i8 v[108:111], v[132:135], v[204:207], v[108:111]
	v_mfma_i32_16x16x64_i8 v[108:111], v[136:139], v[208:211], v[108:111]
	v_mfma_i32_16x16x64_i8 v[140:143], v[136:139], v[186:189], v[140:143]
	v_mfma_i32_16x16x64_i8 v[140:143], v[132:135], v[182:185], v[140:143]
	v_mfma_i32_16x16x64_i8 v[128:131], v[160:163], v[182:185], v[128:131]
	v_mfma_i32_16x16x64_i8 v[128:131], v[164:167], v[186:189], v[128:131]
	v_mfma_i32_16x16x64_i8 v[104:107], v[164:167], v[208:211], v[104:107]
	v_mfma_i32_16x16x64_i8 v[104:107], v[160:163], v[204:207], v[104:107]
	v_mfma_i32_16x16x64_i8 v[88:91], v[160:163], v[212:215], v[88:91]
	v_mfma_i32_16x16x64_i8 v[88:91], v[164:167], v[216:219], v[88:91]
	v_mfma_i32_16x16x64_i8 v[72:75], v[164:167], v[224:227], v[72:75]
	v_mfma_i32_16x16x64_i8 v[72:75], v[160:163], v[220:223], v[72:75]
	v_mfma_i32_16x16x64_i8 v[68:71], v[168:171], v[220:223], v[68:71]
	v_mfma_i32_16x16x64_i8 v[68:71], v[178:181], v[224:227], v[68:71]
	v_mfma_i32_16x16x64_i8 v[84:87], v[178:181], v[216:219], v[84:87]
	v_mfma_i32_16x16x64_i8 v[84:87], v[168:171], v[212:215], v[84:87]
	v_mfma_i32_16x16x64_i8 v[100:103], v[168:171], v[204:207], v[100:103]
	v_mfma_i32_16x16x64_i8 v[100:103], v[178:181], v[208:211], v[100:103]
	v_mfma_i32_16x16x64_i8 v[120:123], v[178:181], v[186:189], v[120:123]
	v_mfma_i32_16x16x64_i8 v[120:123], v[168:171], v[182:185], v[120:123]
	s_setprio 0
	s_barrier
; #define PG8_STAGE(bufoff, gbase, voff) do { _Pragma("unroll") for (int _i = 0; _i < 2; ++_i) \
;         __builtin_amdgcn_global_load_lds((const unsigned*)((const char*)(gbase) + (voff)[_i]), (PG8_LAS unsigned*)(lds + (bufoff) + ldsw + _i * 8192), 16, 0, 0); } while (0)
; #define PG8_LDA(dst, b, h) do { _Pragma("unroll") for (int m = 0; m < 4; ++m) _Pragma("unroll") for (int k = 0; k < 2; ++k) dst[m][k] = *(const PG8_LAS bf16x8*)(lds + PG8_SA(b, h) + aoff + m * 2048 + k * 1024); } while (0)
; #define PG8_LDB(dst, b, h) do { _Pragma("unroll") for (int n = 0; n < 2; ++n) _Pragma("unroll") for (int k = 0; k < 2; ++k) dst[n][k] = *(const PG8_LAS bf16x8*)(lds + PG8_SB(b, h) + boff + n * 2048 + k * 1024); } while (0)
; #define PG8_WAIT_V(n) asm volatile("s_waitcnt vmcnt(" #n ")" ::: "memory")
; #define PG8_WAIT_L(n) asm volatile("s_waitcnt lgkmcnt(" #n ")" ::: "memory")
; #define PG8_BAR __builtin_amdgcn_s_barrier()
; #define PG8_SCHED __builtin_amdgcn_sched_barrier(0)
; template <class Epi, class Sched, bool ALIGN_EPI = false, bool SP2 = false, bool I8 = false>
; __device__ __forceinline__ void gemm_phase(PG8_LAS unsigned char* lds, const Gemm g, const Sched& S, const Epi& E) {
;     ...
;             PG8_WAIT_V(8); PG8_WAIT_L(0); PG8_BAR; PG8_MMA(0, 0, At, B0); PG8_MMA(0, 1, At, B1); PG8_BAR; PG8_SCHED;
;             PG8_LDA(At, 0, 1); PG8_STAGE(PG8_SB(0, 0), b2, voffB); PG8_STAGE(PG8_SB(0, 1), b2 + hstep, voffB); PG8_STAGE(PG8_SA(0, 0), a2, voffA);
;             PG8_WAIT_V(8); PG8_WAIT_L(0); PG8_BAR; PG8_MMA(1, 0, At, B0); PG8_MMA(1, 1, At, B1); PG8_BAR; PG8_SCHED;
;             PG8_LDB(B0, 1, 0); PG8_LDB(B1, 1, 1); PG8_SCHED; PG8_LDA(At, 1, 0); PG8_STAGE(PG8_SA(0, 1), a2 + hstep, voffA);
;             PG8_WAIT_V(8); PG8_WAIT_L(0); PG8_BAR; PG8_MMA(0, 0, At, B0); PG8_MMA(0, 1, At, B1); PG8_BAR; PG8_SCHED;
	s_add_i32 s50, s50, s43
	v_lshl_add_u64 v[172:173], s[36:37], 0, v[2:3]
	s_mov_b32 m0, s50
	ds_read_b128 v[182:185], v177 offset:16384
	ds_read_b128 v[186:189], v177 offset:17408
	ds_read_b128 v[204:207], v177 offset:18432
	ds_read_b128 v[208:211], v177 offset:19456
	ds_read_b128 v[212:215], v177 offset:20480
	ds_read_b128 v[216:219], v177 offset:21504
	ds_read_b128 v[220:223], v177 offset:22528
	ds_read_b128 v[224:227], v177 offset:23552
	global_load_lds_dwordx4 v[172:173], off
	s_add_i32 m0, s50, 0x2000
	s_add_u32 s50, s36, 0x80000
	v_lshl_add_u64 v[190:191], s[36:37], 0, v[148:149]
	s_addc_u32 s51, s37, 0
	s_add_i32 s56, s56, s43
	global_load_lds_dwordx4 v[190:191], off
	s_mov_b32 m0, s56
	v_lshl_add_u64 v[240:241], s[40:41], 0, v[150:151]
	global_load_lds_dwordx4 v2, s[50:51]
	s_add_i32 m0, s56, 0x2000
	s_nop 0
	global_load_lds_dwordx4 v148, s[50:51]
	v_lshl_add_u64 v[228:229], s[40:41], 0, v[152:153]
	s_waitcnt vmcnt(6) lgkmcnt(0)
	s_barrier
	s_setprio 1
	v_mfma_i32_16x16x64_i8 v[64:67], v[116:119], v[182:185], v[64:67]
	v_mfma_i32_16x16x64_i8 v[64:67], v[124:127], v[186:189], v[64:67]
	v_mfma_i32_16x16x64_i8 v[48:51], v[124:127], v[208:211], v[48:51]
	v_mfma_i32_16x16x64_i8 v[48:51], v[116:119], v[204:207], v[48:51]
	v_mfma_i32_16x16x64_i8 v[32:35], v[116:119], v[212:215], v[32:35]
	v_mfma_i32_16x16x64_i8 v[32:35], v[124:127], v[216:219], v[32:35]
	v_mfma_i32_16x16x64_i8 v[16:19], v[124:127], v[224:227], v[16:19]
	v_mfma_i32_16x16x64_i8 v[16:19], v[116:119], v[220:223], v[16:19]
	v_mfma_i32_16x16x64_i8 v[12:15], v[132:135], v[220:223], v[12:15]
	v_mfma_i32_16x16x64_i8 v[12:15], v[136:139], v[224:227], v[12:15]
	v_mfma_i32_16x16x64_i8 v[28:31], v[136:139], v[216:219], v[28:31]
	v_mfma_i32_16x16x64_i8 v[28:31], v[132:135], v[212:215], v[28:31]
	v_mfma_i32_16x16x64_i8 v[44:47], v[132:135], v[204:207], v[44:47]
	v_mfma_i32_16x16x64_i8 v[44:47], v[136:139], v[208:211], v[44:47]
	v_mfma_i32_16x16x64_i8 v[60:63], v[136:139], v[186:189], v[60:63]
	v_mfma_i32_16x16x64_i8 v[60:63], v[132:135], v[182:185], v[60:63]
	v_mfma_i32_16x16x64_i8 v[56:59], v[160:163], v[182:185], v[56:59]
	v_mfma_i32_16x16x64_i8 v[56:59], v[164:167], v[186:189], v[56:59]
	v_mfma_i32_16x16x64_i8 v[40:43], v[164:167], v[208:211], v[40:43]
	v_mfma_i32_16x16x64_i8 v[40:43], v[160:163], v[204:207], v[40:43]
	v_mfma_i32_16x16x64_i8 v[24:27], v[160:163], v[212:215], v[24:27]
	v_mfma_i32_16x16x64_i8 v[24:27], v[164:167], v[216:219], v[24:27]
	v_mfma_i32_16x16x64_i8 v[8:11], v[164:167], v[224:227], v[8:11]
	v_mfma_i32_16x16x64_i8 v[8:11], v[160:163], v[220:223], v[8:11]
	v_mfma_i32_16x16x64_i8 v[4:7], v[168:171], v[220:223], v[4:7]
	v_mfma_i32_16x16x64_i8 v[4:7], v[178:181], v[224:227], v[4:7]
	v_mfma_i32_16x16x64_i8 v[20:23], v[178:181], v[216:219], v[20:23]
	v_mfma_i32_16x16x64_i8 v[20:23], v[168:171], v[212:215], v[20:23]
	v_mfma_i32_16x16x64_i8 v[36:39], v[168:171], v[204:207], v[36:39]
	v_mfma_i32_16x16x64_i8 v[36:39], v[178:181], v[208:211], v[36:39]
	v_mfma_i32_16x16x64_i8 v[52:55], v[178:181], v[186:189], v[52:55]
	v_mfma_i32_16x16x64_i8 v[52:55], v[168:171], v[182:185], v[52:55]
	s_setprio 0
	s_barrier
	s_mov_b32 m0, s44
	s_nop 0
	global_load_lds_dwordx4 v[228:229], off
	s_mov_b32 m0, s45
	s_nop 0
	global_load_lds_dwordx4 v[240:241], off
	s_add_i32 s50, 0, 0x18000
	s_add_i32 s51, 0, 0x1c000
	v_add_u32_e32 v136, s50, v175
	v_add_u32_e32 v178, s51, v175
	ds_read_b128 v[116:119], v136
	ds_read_b128 v[124:127], v136 offset:1024
	ds_read_b128 v[132:135], v136 offset:2048
	ds_read_b128 v[136:139], v136 offset:3072
	ds_read_b128 v[160:163], v178
	ds_read_b128 v[164:167], v178 offset:1024
	ds_read_b128 v[168:171], v178 offset:2048
	ds_read_b128 v[178:181], v178 offset:3072
	s_add_u32 s40, s40, 0x80000
	s_addc_u32 s41, s41, 0
	s_mov_b32 m0, s46
	ds_read_b128 v[182:185], v177 offset:32768
	ds_read_b128 v[186:189], v177 offset:33792
	ds_read_b128 v[204:207], v177 offset:34816
	ds_read_b128 v[208:211], v177 offset:35840
	ds_read_b128 v[212:215], v177 offset:36864
	ds_read_b128 v[216:219], v177 offset:37888
	ds_read_b128 v[220:223], v177 offset:38912
	ds_read_b128 v[224:227], v177 offset:39936
	global_load_lds_dwordx4 v152, s[40:41]
	s_mov_b32 m0, s47
	s_nop 0
	global_load_lds_dwordx4 v150, s[40:41]
	s_waitcnt vmcnt(8) lgkmcnt(0)
	s_barrier
; #define PG8_STAGE(bufoff, gbase, voff) do { _Pragma("unroll") for (int _i = 0; _i < 2; ++_i) \
;         __builtin_amdgcn_global_load_lds((const unsigned*)((const char*)(gbase) + (voff)[_i]), (PG8_LAS unsigned*)(lds + (bufoff) + ldsw + _i * 8192), 16, 0, 0); } while (0)
; #define PG8_LDA(dst, b, h) do { _Pragma("unroll") for (int m = 0; m < 4; ++m) _Pragma("unroll") for (int k = 0; k < 2; ++k) dst[m][k] = *(const PG8_LAS bf16x8*)(lds + PG8_SA(b, h) + aoff + m * 2048 + k * 1024); } while (0)
; #define PG8_WAIT_V(n) asm volatile("s_waitcnt vmcnt(" #n ")" ::: "memory")
; #define PG8_WAIT_L(n) asm volatile("s_waitcnt lgkmcnt(" #n ")" ::: "memory")
; #define PG8_BAR __builtin_amdgcn_s_barrier()
; #define PG8_SCHED __builtin_amdgcn_sched_barrier(0)
; template <class Epi, class Sched, bool ALIGN_EPI = false, bool SP2 = false, bool I8 = false>
; __device__ __forceinline__ void gemm_phase(PG8_LAS unsigned char* lds, const Gemm g, const Sched& S, const Epi& E) {
;     ...
;             PG8_WAIT_V(8); PG8_WAIT_L(0); PG8_BAR; PG8_MMA(0, 0, At, B0); PG8_MMA(0, 1, At, B1); PG8_BAR; PG8_SCHED;
;             PG8_LDA(At, 1, 1); PG8_STAGE(PG8_SB(1, 0), b3, voffB); PG8_STAGE(PG8_SB(1, 1), b3 + hstep, voffB); PG8_STAGE(PG8_SA(1, 0), a3, voffA);
;             PG8_WAIT_V(8); PG8_WAIT_L(0); PG8_BAR; PG8_MMA(1, 0, At, B0); PG8_MMA(1, 1, At, B1); PG8_BAR; PG8_SCHED;
	s_setprio 1
	v_mfma_i32_16x16x64_i8 v[144:147], v[116:119], v[182:185], v[144:147]
	v_mfma_i32_16x16x64_i8 v[144:147], v[124:127], v[186:189], v[144:147]
	v_mfma_i32_16x16x64_i8 v[112:115], v[124:127], v[208:211], v[112:115]
	v_mfma_i32_16x16x64_i8 v[112:115], v[116:119], v[204:207], v[112:115]
	v_mfma_i32_16x16x64_i8 v[96:99], v[116:119], v[212:215], v[96:99]
	v_mfma_i32_16x16x64_i8 v[96:99], v[124:127], v[216:219], v[96:99]
	v_mfma_i32_16x16x64_i8 v[80:83], v[124:127], v[224:227], v[80:83]
	v_mfma_i32_16x16x64_i8 v[80:83], v[116:119], v[220:223], v[80:83]
	v_mfma_i32_16x16x64_i8 v[76:79], v[132:135], v[220:223], v[76:79]
	v_mfma_i32_16x16x64_i8 v[76:79], v[136:139], v[224:227], v[76:79]
	v_mfma_i32_16x16x64_i8 v[92:95], v[136:139], v[216:219], v[92:95]
	v_mfma_i32_16x16x64_i8 v[92:95], v[132:135], v[212:215], v[92:95]
	v_mfma_i32_16x16x64_i8 v[108:111], v[132:135], v[204:207], v[108:111]
	v_mfma_i32_16x16x64_i8 v[108:111], v[136:139], v[208:211], v[108:111]
	v_mfma_i32_16x16x64_i8 v[140:143], v[136:139], v[186:189], v[140:143]
	v_mfma_i32_16x16x64_i8 v[140:143], v[132:135], v[182:185], v[140:143]
	v_mfma_i32_16x16x64_i8 v[128:131], v[160:163], v[182:185], v[128:131]
	v_mfma_i32_16x16x64_i8 v[128:131], v[164:167], v[186:189], v[128:131]
	v_mfma_i32_16x16x64_i8 v[104:107], v[164:167], v[208:211], v[104:107]
	v_mfma_i32_16x16x64_i8 v[104:107], v[160:163], v[204:207], v[104:107]
	v_mfma_i32_16x16x64_i8 v[88:91], v[160:163], v[212:215], v[88:91]
	v_mfma_i32_16x16x64_i8 v[88:91], v[164:167], v[216:219], v[88:91]
	v_mfma_i32_16x16x64_i8 v[72:75], v[164:167], v[224:227], v[72:75]
	v_mfma_i32_16x16x64_i8 v[72:75], v[160:163], v[220:223], v[72:75]
	v_mfma_i32_16x16x64_i8 v[68:71], v[168:171], v[220:223], v[68:71]
	v_mfma_i32_16x16x64_i8 v[68:71], v[178:181], v[224:227], v[68:71]
	v_mfma_i32_16x16x64_i8 v[84:87], v[178:181], v[216:219], v[84:87]
	v_mfma_i32_16x16x64_i8 v[84:87], v[168:171], v[212:215], v[84:87]
	v_mfma_i32_16x16x64_i8 v[100:103], v[168:171], v[204:207], v[100:103]
	v_mfma_i32_16x16x64_i8 v[100:103], v[178:181], v[208:211], v[100:103]
	v_mfma_i32_16x16x64_i8 v[120:123], v[178:181], v[186:189], v[120:123]
	v_mfma_i32_16x16x64_i8 v[120:123], v[168:171], v[182:185], v[120:123]
	s_setprio 0
	s_barrier
	s_add_i32 s40, s50, s43
	v_lshl_add_u64 v[172:173], v[172:173], 0, s[84:85]
	s_mov_b32 m0, s40
	ds_read_b128 v[182:185], v177 offset:49152
	ds_read_b128 v[186:189], v177 offset:50176
	ds_read_b128 v[204:207], v177 offset:51200
	ds_read_b128 v[208:211], v177 offset:52224
	ds_read_b128 v[212:215], v177 offset:53248
	ds_read_b128 v[216:219], v177 offset:54272
	ds_read_b128 v[220:223], v177 offset:55296
	ds_read_b128 v[224:227], v177 offset:56320
	global_load_lds_dwordx4 v[172:173], off
	s_add_i32 m0, s40, 0x2000
	s_add_u32 s36, s36, 0x80080
	v_lshl_add_u64 v[172:173], v[190:191], 0, s[84:85]
	s_addc_u32 s37, s37, 0
	s_add_i32 s40, s51, s43
	global_load_lds_dwordx4 v[172:173], off
	s_mov_b32 m0, s40
	s_nop 0
	global_load_lds_dwordx4 v2, s[36:37]
	s_add_i32 m0, s40, 0x2000
	s_nop 0
	global_load_lds_dwordx4 v148, s[36:37]
	s_cmp_eq_u32 s76, 28
	s_cbranch_scc0 .Ldefer_208_body
	v_lshl_add_u64 v[172:173], v[228:229], 0, s[84:85]
	s_mov_b32 m0, s52
	s_nop 0
	global_load_lds_dwordx4 v[172:173], off
	v_lshl_add_u64 v[172:173], v[240:241], 0, s[84:85]
	s_mov_b32 m0, s53
	s_nop 0
	global_load_lds_dwordx4 v[172:173], off
.Ldefer_208_body:
	s_waitcnt vmcnt(6) lgkmcnt(0)
	s_barrier
	s_setprio 1
	v_mfma_i32_16x16x64_i8 v[64:67], v[116:119], v[182:185], v[64:67]
	v_mfma_i32_16x16x64_i8 v[64:67], v[124:127], v[186:189], v[64:67]
	v_mfma_i32_16x16x64_i8 v[48:51], v[124:127], v[208:211], v[48:51]
	v_mfma_i32_16x16x64_i8 v[48:51], v[116:119], v[204:207], v[48:51]
	v_mfma_i32_16x16x64_i8 v[32:35], v[116:119], v[212:215], v[32:35]
	v_mfma_i32_16x16x64_i8 v[32:35], v[124:127], v[216:219], v[32:35]
	v_mfma_i32_16x16x64_i8 v[16:19], v[124:127], v[224:227], v[16:19]
	v_mfma_i32_16x16x64_i8 v[16:19], v[116:119], v[220:223], v[16:19]
	v_mfma_i32_16x16x64_i8 v[12:15], v[132:135], v[220:223], v[12:15]
	v_mfma_i32_16x16x64_i8 v[12:15], v[136:139], v[224:227], v[12:15]
	v_mfma_i32_16x16x64_i8 v[28:31], v[136:139], v[216:219], v[28:31]
	v_mfma_i32_16x16x64_i8 v[28:31], v[132:135], v[212:215], v[28:31]
	v_mfma_i32_16x16x64_i8 v[44:47], v[132:135], v[204:207], v[44:47]
	v_mfma_i32_16x16x64_i8 v[44:47], v[136:139], v[208:211], v[44:47]
	v_mfma_i32_16x16x64_i8 v[60:63], v[136:139], v[186:189], v[60:63]
	v_mfma_i32_16x16x64_i8 v[60:63], v[132:135], v[182:185], v[60:63]
	v_mfma_i32_16x16x64_i8 v[56:59], v[160:163], v[182:185], v[56:59]
	v_mfma_i32_16x16x64_i8 v[56:59], v[164:167], v[186:189], v[56:59]
	v_mfma_i32_16x16x64_i8 v[40:43], v[164:167], v[208:211], v[40:43]
	v_mfma_i32_16x16x64_i8 v[40:43], v[160:163], v[204:207], v[40:43]
	v_mfma_i32_16x16x64_i8 v[24:27], v[160:163], v[212:215], v[24:27]
	v_mfma_i32_16x16x64_i8 v[24:27], v[164:167], v[216:219], v[24:27]
	v_mfma_i32_16x16x64_i8 v[8:11], v[164:167], v[224:227], v[8:11]
	v_mfma_i32_16x16x64_i8 v[8:11], v[160:163], v[220:223], v[8:11]
	v_mfma_i32_16x16x64_i8 v[4:7], v[168:171], v[220:223], v[4:7]
	v_mfma_i32_16x16x64_i8 v[4:7], v[178:181], v[224:227], v[4:7]
	v_mfma_i32_16x16x64_i8 v[20:23], v[178:181], v[216:219], v[20:23]
	v_mfma_i32_16x16x64_i8 v[20:23], v[168:171], v[212:215], v[20:23]
	v_mfma_i32_16x16x64_i8 v[36:39], v[168:171], v[204:207], v[36:39]
	v_mfma_i32_16x16x64_i8 v[36:39], v[178:181], v[208:211], v[36:39]
	v_mfma_i32_16x16x64_i8 v[52:55], v[178:181], v[186:189], v[52:55]
	v_mfma_i32_16x16x64_i8 v[52:55], v[168:171], v[182:185], v[52:55]
	s_setprio 0
	s_barrier
	s_add_i32 s76, s76, 2
	s_add_u32 s26, s26, 0x100
	s_addc_u32 s27, s27, 0
	s_add_u32 s72, s72, 0x100
	s_addc_u32 s73, s73, 0
	s_cmp_gt_u32 s76, 29
	s_cbranch_scc0 .LBB0_208

; #define PG8_STAGE(bufoff, gbase, voff) do { _Pragma("unroll") for (int _i = 0; _i < 2; ++_i) \
;         __builtin_amdgcn_global_load_lds((const unsigned*)((const char*)(gbase) + (voff)[_i]), (PG8_LAS unsigned*)(lds + (bufoff) + ldsw + _i * 8192), 16, 0, 0); } while (0)
; #define PG8_LDA(dst, b, h) do { _Pragma("unroll") for (int m = 0; m < 4; ++m) _Pragma("unroll") for (int k = 0; k < 2; ++k) dst[m][k] = *(const PG8_LAS bf16x8*)(lds + PG8_SA(b, h) + aoff + m * 2048 + k * 1024); } while (0)
; #define PG8_LDB(dst, b, h) do { _Pragma("unroll") for (int n = 0; n < 2; ++n) _Pragma("unroll") for (int k = 0; k < 2; ++k) dst[n][k] = *(const PG8_LAS bf16x8*)(lds + PG8_SB(b, h) + boff + n * 2048 + k * 1024); } while (0)
; #define PG8_WAIT_V(n) asm volatile("s_waitcnt vmcnt(" #n ")" ::: "memory")
; #define PG8_WAIT_L(n) asm volatile("s_waitcnt lgkmcnt(" #n ")" ::: "memory")
; #define PG8_BAR __builtin_amdgcn_s_barrier()
; #define PG8_SCHED __builtin_amdgcn_sched_barrier(0)
; template <class Epi, class Sched, bool ALIGN_EPI = false, bool SP2 = false, bool I8 = false>
; __device__ __forceinline__ void gemm_phase(PG8_LAS unsigned char* lds, const Gemm g, const Sched& S, const Epi& E) {
;     ...
;         const bool has_next = S.next(ui + 1, nxt);
;         const char* nA = has_next ? (const char*)g.A + (size_t)nxt.pm * tstep : cA; const char* nB = has_next ? (const char*)g.Bt + (size_t)nxt.pn * tstep : cB;
;         for (int t = 0; t < nt; t += 2) {
;             const bool last = (t == nt - 2);
;             const char* a1 = cA + (size_t)(t + 1) * kstep;
;             const char* a2 = last ? nA : cA + (size_t)(t + 2) * kstep; const char* b2 = last ? nB : cB + (size_t)(t + 2) * kstep;
;             const char* a3 = a2 + kstep; const char* b3 = b2 + kstep;
;             if (last && has_next) S.a_ready(nxt);
;             if constexpr (SP2) {
;             PG8_LDB(B0, 0, 0); PG8_LDB(B1, 0, 1); PG8_SCHED; PG8_LDA(At, 0, 0); PG8_STAGE(PG8_SA(1, 1), a1 + hstep, voffA);
;             PG8_WAIT_V(8); PG8_WAIT_L(0); PG8_BAR; PG8_MMA(0, 0, At, B0); PG8_MMA(0, 1, At, B1); PG8_BAR; PG8_SCHED;
;             PG8_LDA(At, 0, 1); PG8_STAGE(PG8_SB(0, 0), b2, voffB); PG8_STAGE(PG8_SB(0, 1), b2 + hstep, voffB); PG8_STAGE(PG8_SA(0, 0), a2, voffA);
;             PG8_WAIT_V(8); PG8_WAIT_L(0); PG8_BAR; PG8_MMA(1, 0, At, B0); PG8_MMA(1, 1, At, B1); PG8_BAR; PG8_SCHED;
.LBB0_229:
	s_ashr_i32 s37, s36, 31
	s_lshl_b64 s[34:35], s[36:37], 21
	s_add_u32 s40, s42, s34
	s_addc_u32 s41, s43, s35
	s_and_b64 s[34:35], s[8:9], exec
	s_cselect_b32 s11, s41, s13
	s_cselect_b32 s34, s40, s12
	s_ashr_i32 s27, s26, 31
	s_lshl_b64 s[50:51], s[26:27], 21
	s_add_u32 s54, s44, s50
	s_addc_u32 s55, s45, s51
	s_and_b64 s[50:51], s[8:9], exec
	s_cselect_b32 s27, s55, s73
	s_cselect_b32 s35, s54, s72
	s_add_u32 s12, s12, 0x100080
	s_addc_u32 s13, s13, 0
	s_add_u32 s37, s72, 0x100
	s_addc_u32 s61, s73, 0
	s_mov_b32 s97, -2
	s_add_u32 s50, s12, 0xfff00080
	s_addc_u32 s51, s13, -1
	s_add_i32 s56, 0, 0x10000
	s_cmp_eq_u32 s97, 60
	s_cselect_b32 s77, s11, s51
	s_cselect_b32 s76, s34, s50
	s_cselect_b32 s73, s27, s61
	s_cselect_b32 s72, s35, s37
	s_add_i32 s57, 0, 0x14000
	v_add_u32_e32 v156, s56, v171
	v_add_u32_e32 v168, s57, v171
	s_waitcnt vmcnt(0)
	ds_read_b128 v[112:115], v156
	ds_read_b128 v[120:123], v156 offset:1024
	ds_read_b128 v[152:155], v156 offset:2048
	ds_read_b128 v[156:159], v156 offset:3072
	ds_read_b128 v[160:163], v168
	ds_read_b128 v[164:167], v168 offset:1024
	s_waitcnt lgkmcnt(0)
	ds_read_b128 v[176:179], v168 offset:2048
	ds_read_b128 v[180:183], v168 offset:3072
	s_add_i32 m0, s47, 0xc000
	ds_read_b128 v[184:187], v173
	ds_read_b128 v[188:191], v173 offset:1024
	ds_read_b128 v[204:207], v173 offset:2048
	ds_read_b128 v[208:211], v173 offset:3072
	ds_read_b128 v[212:215], v173 offset:4096
	ds_read_b128 v[216:219], v173 offset:5120
	ds_read_b128 v[220:223], v173 offset:6144
	ds_read_b128 v[224:227], v173 offset:7168
	global_load_lds_dwordx4 v148, s[12:13]
	s_add_i32 m0, s47, 0xe000
	s_nop 0
	global_load_lds_dwordx4 v150, s[12:13]
	s_waitcnt vmcnt(8) lgkmcnt(0)
	s_barrier
	s_setprio 1
	v_mfma_f32_16x16x32_bf16 v[136:139], v[112:115], v[184:187], 0
	v_mfma_f32_16x16x32_bf16 v[136:139], v[120:123], v[188:191], v[136:139]
	v_mfma_f32_16x16x32_bf16 v[116:119], v[120:123], v[208:211], 0
	v_mfma_f32_16x16x32_bf16 v[116:119], v[112:115], v[204:207], v[116:119]
	v_mfma_f32_16x16x32_bf16 v[96:99], v[112:115], v[212:215], 0
	v_mfma_f32_16x16x32_bf16 v[96:99], v[120:123], v[216:219], v[96:99]
	v_mfma_f32_16x16x32_bf16 v[80:83], v[120:123], v[224:227], 0
	v_mfma_f32_16x16x32_bf16 v[80:83], v[112:115], v[220:223], v[80:83]
	v_mfma_f32_16x16x32_bf16 v[76:79], v[152:155], v[220:223], 0
	v_mfma_f32_16x16x32_bf16 v[76:79], v[156:159], v[224:227], v[76:79]
	v_mfma_f32_16x16x32_bf16 v[92:95], v[156:159], v[216:219], 0
	v_mfma_f32_16x16x32_bf16 v[92:95], v[152:155], v[212:215], v[92:95]
	v_mfma_f32_16x16x32_bf16 v[108:111], v[152:155], v[204:207], 0
	v_mfma_f32_16x16x32_bf16 v[108:111], v[156:159], v[208:211], v[108:111]
	v_mfma_f32_16x16x32_bf16 v[132:135], v[156:159], v[188:191], 0
	v_mfma_f32_16x16x32_bf16 v[132:135], v[152:155], v[184:187], v[132:135]
	v_mfma_f32_16x16x32_bf16 v[128:131], v[160:163], v[184:187], 0
	v_mfma_f32_16x16x32_bf16 v[128:131], v[164:167], v[188:191], v[128:131]
	v_mfma_f32_16x16x32_bf16 v[104:107], v[164:167], v[208:211], 0
	v_mfma_f32_16x16x32_bf16 v[104:107], v[160:163], v[204:207], v[104:107]
	v_mfma_f32_16x16x32_bf16 v[88:91], v[160:163], v[212:215], 0
	v_mfma_f32_16x16x32_bf16 v[88:91], v[164:167], v[216:219], v[88:91]
	v_mfma_f32_16x16x32_bf16 v[72:75], v[164:167], v[224:227], 0
	v_mfma_f32_16x16x32_bf16 v[72:75], v[160:163], v[220:223], v[72:75]
	v_mfma_f32_16x16x32_bf16 v[68:71], v[176:179], v[220:223], 0
	v_mfma_f32_16x16x32_bf16 v[68:71], v[180:183], v[224:227], v[68:71]
	v_mfma_f32_16x16x32_bf16 v[84:87], v[180:183], v[216:219], 0
	v_mfma_f32_16x16x32_bf16 v[84:87], v[176:179], v[212:215], v[84:87]
	v_mfma_f32_16x16x32_bf16 v[100:103], v[176:179], v[204:207], 0
	v_mfma_f32_16x16x32_bf16 v[100:103], v[180:183], v[208:211], v[100:103]
	v_mfma_f32_16x16x32_bf16 v[124:127], v[180:183], v[188:191], 0
	v_mfma_f32_16x16x32_bf16 v[124:127], v[176:179], v[184:187], v[124:127]
	s_setprio 0
	s_barrier
	s_add_i32 s50, s56, s46
	v_lshl_add_u64 v[168:169], s[72:73], 0, v[2:3]
	s_mov_b32 m0, s50
	ds_read_b128 v[184:187], v173 offset:16384
	ds_read_b128 v[188:191], v173 offset:17408
	ds_read_b128 v[204:207], v173 offset:18432
	ds_read_b128 v[208:211], v173 offset:19456
	ds_read_b128 v[212:215], v173 offset:20480
	ds_read_b128 v[216:219], v173 offset:21504
	ds_read_b128 v[220:223], v173 offset:22528
	ds_read_b128 v[224:227], v173 offset:23552
	global_load_lds_dwordx4 v[168:169], off
	s_add_i32 m0, s50, 0x2000
	s_add_u32 s50, s72, 0x100000
	v_lshl_add_u64 v[228:229], s[72:73], 0, v[144:145]
	s_addc_u32 s51, s73, 0
	s_add_i32 s56, s57, s46
	global_load_lds_dwordx4 v[228:229], off
	s_mov_b32 m0, s56
	v_lshl_add_u64 v[242:243], s[76:77], 0, v[142:143]
	global_load_lds_dwordx4 v2, s[50:51]
	s_add_i32 m0, s56, 0x2000
	s_nop 0
	global_load_lds_dwordx4 v144, s[50:51]
	v_lshl_add_u64 v[240:241], s[76:77], 0, v[140:141]
	s_waitcnt vmcnt(6) lgkmcnt(0)
	s_barrier
; #define PG8_STAGE(bufoff, gbase, voff) do { _Pragma("unroll") for (int _i = 0; _i < 2; ++_i) \
;         __builtin_amdgcn_global_load_lds((const unsigned*)((const char*)(gbase) + (voff)[_i]), (PG8_LAS unsigned*)(lds + (bufoff) + ldsw + _i * 8192), 16, 0, 0); } while (0)
; #define PG8_LDA(dst, b, h) do { _Pragma("unroll") for (int m = 0; m < 4; ++m) _Pragma("unroll") for (int k = 0; k < 2; ++k) dst[m][k] = *(const PG8_LAS bf16x8*)(lds + PG8_SA(b, h) + aoff + m * 2048 + k * 1024); } while (0)
; #define PG8_LDB(dst, b, h) do { _Pragma("unroll") for (int n = 0; n < 2; ++n) _Pragma("unroll") for (int k = 0; k < 2; ++k) dst[n][k] = *(const PG8_LAS bf16x8*)(lds + PG8_SB(b, h) + boff + n * 2048 + k * 1024); } while (0)
; #define PG8_WAIT_V(n) asm volatile("s_waitcnt vmcnt(" #n ")" ::: "memory")
; #define PG8_WAIT_L(n) asm volatile("s_waitcnt lgkmcnt(" #n ")" ::: "memory")
; #define PG8_BAR __builtin_amdgcn_s_barrier()
; #define PG8_SCHED __builtin_amdgcn_sched_barrier(0)
; template <class Epi, class Sched, bool ALIGN_EPI = false, bool SP2 = false, bool I8 = false>
; __device__ __forceinline__ void gemm_phase(PG8_LAS unsigned char* lds, const Gemm g, const Sched& S, const Epi& E) {
;     ...
;             PG8_WAIT_V(8); PG8_WAIT_L(0); PG8_BAR; PG8_MMA(0, 0, At, B0); PG8_MMA(0, 1, At, B1); PG8_BAR; PG8_SCHED;
;             PG8_LDA(At, 0, 1); PG8_STAGE(PG8_SB(0, 0), b2, voffB); PG8_STAGE(PG8_SB(0, 1), b2 + hstep, voffB); PG8_STAGE(PG8_SA(0, 0), a2, voffA);
;             PG8_WAIT_V(8); PG8_WAIT_L(0); PG8_BAR; PG8_MMA(1, 0, At, B0); PG8_MMA(1, 1, At, B1); PG8_BAR; PG8_SCHED;
;             PG8_LDB(B0, 1, 0); PG8_LDB(B1, 1, 1); PG8_SCHED; PG8_LDA(At, 1, 0); PG8_STAGE(PG8_SA(0, 1), a2 + hstep, voffA);
;             PG8_WAIT_V(8); PG8_WAIT_L(0); PG8_BAR; PG8_MMA(0, 0, At, B0); PG8_MMA(0, 1, At, B1); PG8_BAR; PG8_SCHED;
;             PG8_LDA(At, 1, 1); PG8_STAGE(PG8_SB(1, 0), b3, voffB); PG8_STAGE(PG8_SB(1, 1), b3 + hstep, voffB); PG8_STAGE(PG8_SA(1, 0), a3, voffA);
	s_setprio 1
	v_mfma_f32_16x16x32_bf16 v[64:67], v[112:115], v[184:187], 0
	v_mfma_f32_16x16x32_bf16 v[64:67], v[120:123], v[188:191], v[64:67]
	v_mfma_f32_16x16x32_bf16 v[48:51], v[120:123], v[208:211], 0
	v_mfma_f32_16x16x32_bf16 v[48:51], v[112:115], v[204:207], v[48:51]
	v_mfma_f32_16x16x32_bf16 v[32:35], v[112:115], v[212:215], 0
	v_mfma_f32_16x16x32_bf16 v[32:35], v[120:123], v[216:219], v[32:35]
	v_mfma_f32_16x16x32_bf16 v[16:19], v[120:123], v[224:227], 0
	v_mfma_f32_16x16x32_bf16 v[16:19], v[112:115], v[220:223], v[16:19]
	v_mfma_f32_16x16x32_bf16 v[12:15], v[152:155], v[220:223], 0
	v_mfma_f32_16x16x32_bf16 v[12:15], v[156:159], v[224:227], v[12:15]
	v_mfma_f32_16x16x32_bf16 v[28:31], v[156:159], v[216:219], 0
	v_mfma_f32_16x16x32_bf16 v[28:31], v[152:155], v[212:215], v[28:31]
	v_mfma_f32_16x16x32_bf16 v[44:47], v[152:155], v[204:207], 0
	v_mfma_f32_16x16x32_bf16 v[44:47], v[156:159], v[208:211], v[44:47]
	v_mfma_f32_16x16x32_bf16 v[60:63], v[156:159], v[188:191], 0
	v_mfma_f32_16x16x32_bf16 v[60:63], v[152:155], v[184:187], v[60:63]
	v_mfma_f32_16x16x32_bf16 v[56:59], v[160:163], v[184:187], 0
	v_mfma_f32_16x16x32_bf16 v[56:59], v[164:167], v[188:191], v[56:59]
	v_mfma_f32_16x16x32_bf16 v[40:43], v[164:167], v[208:211], 0
	v_mfma_f32_16x16x32_bf16 v[40:43], v[160:163], v[204:207], v[40:43]
	v_mfma_f32_16x16x32_bf16 v[24:27], v[160:163], v[212:215], 0
	v_mfma_f32_16x16x32_bf16 v[24:27], v[164:167], v[216:219], v[24:27]
	v_mfma_f32_16x16x32_bf16 v[8:11], v[164:167], v[224:227], 0
	v_mfma_f32_16x16x32_bf16 v[8:11], v[160:163], v[220:223], v[8:11]
	v_mfma_f32_16x16x32_bf16 v[4:7], v[176:179], v[220:223], 0
	v_mfma_f32_16x16x32_bf16 v[4:7], v[180:183], v[224:227], v[4:7]
	v_mfma_f32_16x16x32_bf16 v[20:23], v[180:183], v[216:219], 0
	v_mfma_f32_16x16x32_bf16 v[20:23], v[176:179], v[212:215], v[20:23]
	v_mfma_f32_16x16x32_bf16 v[36:39], v[176:179], v[204:207], 0
	v_mfma_f32_16x16x32_bf16 v[36:39], v[180:183], v[208:211], v[36:39]
	v_mfma_f32_16x16x32_bf16 v[52:55], v[180:183], v[188:191], 0
	v_mfma_f32_16x16x32_bf16 v[52:55], v[176:179], v[184:187], v[52:55]
	s_setprio 0
	s_barrier
	s_mov_b32 m0, s47
	s_nop 0
	global_load_lds_dwordx4 v[240:241], off
	s_mov_b32 m0, s52
	s_nop 0
	global_load_lds_dwordx4 v[242:243], off
	s_add_i32 s56, 0, 0x18000
	s_add_i32 s57, 0, 0x1c000
	v_add_u32_e32 v156, s56, v171
	v_add_u32_e32 v175, s57, v171
	ds_read_b128 v[112:115], v156
	ds_read_b128 v[120:123], v156 offset:1024
	ds_read_b128 v[152:155], v156 offset:2048
	ds_read_b128 v[156:159], v156 offset:3072
	ds_read_b128 v[160:163], v175
	ds_read_b128 v[164:167], v175 offset:1024
	ds_read_b128 v[176:179], v175 offset:2048
	ds_read_b128 v[180:183], v175 offset:3072
	s_add_u32 s50, s76, 0x100000
	s_addc_u32 s51, s77, 0
	s_mov_b32 m0, s53
	ds_read_b128 v[184:187], v173 offset:32768
	ds_read_b128 v[188:191], v173 offset:33792
	ds_read_b128 v[204:207], v173 offset:34816
	ds_read_b128 v[208:211], v173 offset:35840
	ds_read_b128 v[212:215], v173 offset:36864
	ds_read_b128 v[216:219], v173 offset:37888
	ds_read_b128 v[220:223], v173 offset:38912
	ds_read_b128 v[224:227], v173 offset:39936
	global_load_lds_dwordx4 v140, s[50:51]
	s_mov_b32 m0, s64
	s_nop 0
	global_load_lds_dwordx4 v142, s[50:51]
	s_waitcnt vmcnt(8) lgkmcnt(0)
	s_barrier
	s_setprio 1
	v_mfma_f32_16x16x32_bf16 v[136:139], v[112:115], v[184:187], v[136:139]
	v_mfma_f32_16x16x32_bf16 v[136:139], v[120:123], v[188:191], v[136:139]
	v_mfma_f32_16x16x32_bf16 v[116:119], v[120:123], v[208:211], v[116:119]
	v_mfma_f32_16x16x32_bf16 v[116:119], v[112:115], v[204:207], v[116:119]
	v_mfma_f32_16x16x32_bf16 v[96:99], v[112:115], v[212:215], v[96:99]
	v_mfma_f32_16x16x32_bf16 v[96:99], v[120:123], v[216:219], v[96:99]
	v_mfma_f32_16x16x32_bf16 v[80:83], v[120:123], v[224:227], v[80:83]
	v_mfma_f32_16x16x32_bf16 v[80:83], v[112:115], v[220:223], v[80:83]
	v_mfma_f32_16x16x32_bf16 v[76:79], v[152:155], v[220:223], v[76:79]
	v_mfma_f32_16x16x32_bf16 v[76:79], v[156:159], v[224:227], v[76:79]
	v_mfma_f32_16x16x32_bf16 v[92:95], v[156:159], v[216:219], v[92:95]
	v_mfma_f32_16x16x32_bf16 v[92:95], v[152:155], v[212:215], v[92:95]
	v_mfma_f32_16x16x32_bf16 v[108:111], v[152:155], v[204:207], v[108:111]
	v_mfma_f32_16x16x32_bf16 v[108:111], v[156:159], v[208:211], v[108:111]
	v_mfma_f32_16x16x32_bf16 v[132:135], v[156:159], v[188:191], v[132:135]
	v_mfma_f32_16x16x32_bf16 v[132:135], v[152:155], v[184:187], v[132:135]
	v_mfma_f32_16x16x32_bf16 v[128:131], v[160:163], v[184:187], v[128:131]
	v_mfma_f32_16x16x32_bf16 v[128:131], v[164:167], v[188:191], v[128:131]
	v_mfma_f32_16x16x32_bf16 v[104:107], v[164:167], v[208:211], v[104:107]
	v_mfma_f32_16x16x32_bf16 v[104:107], v[160:163], v[204:207], v[104:107]
	v_mfma_f32_16x16x32_bf16 v[88:91], v[160:163], v[212:215], v[88:91]
	v_mfma_f32_16x16x32_bf16 v[88:91], v[164:167], v[216:219], v[88:91]
	v_mfma_f32_16x16x32_bf16 v[72:75], v[164:167], v[224:227], v[72:75]
	v_mfma_f32_16x16x32_bf16 v[72:75], v[160:163], v[220:223], v[72:75]
	v_mfma_f32_16x16x32_bf16 v[68:71], v[176:179], v[220:223], v[68:71]
	v_mfma_f32_16x16x32_bf16 v[68:71], v[180:183], v[224:227], v[68:71]
	v_mfma_f32_16x16x32_bf16 v[84:87], v[180:183], v[216:219], v[84:87]
	v_mfma_f32_16x16x32_bf16 v[84:87], v[176:179], v[212:215], v[84:87]
	v_mfma_f32_16x16x32_bf16 v[100:103], v[176:179], v[204:207], v[100:103]
	v_mfma_f32_16x16x32_bf16 v[100:103], v[180:183], v[208:211], v[100:103]
	v_mfma_f32_16x16x32_bf16 v[124:127], v[180:183], v[188:191], v[124:127]
	v_mfma_f32_16x16x32_bf16 v[124:127], v[176:179], v[184:187], v[124:127]
	s_setprio 0
	s_barrier
	s_add_i32 s50, s56, s46
	v_lshl_add_u64 v[168:169], v[168:169], 0, s[84:85]
	s_mov_b32 m0, s50
	ds_read_b128 v[184:187], v173 offset:49152
	ds_read_b128 v[188:191], v173 offset:50176
	ds_read_b128 v[204:207], v173 offset:51200
	ds_read_b128 v[208:211], v173 offset:52224
	ds_read_b128 v[212:215], v173 offset:53248
	ds_read_b128 v[216:219], v173 offset:54272
	ds_read_b128 v[220:223], v173 offset:55296
	ds_read_b128 v[224:227], v173 offset:56320
	global_load_lds_dwordx4 v[168:169], off
	s_add_i32 m0, s50, 0x2000
	s_add_u32 s50, s72, 0x100080
	v_lshl_add_u64 v[168:169], v[228:229], 0, s[84:85]
	s_addc_u32 s51, s73, 0
	s_add_i32 s56, s57, s46
	global_load_lds_dwordx4 v[168:169], off
	s_mov_b32 m0, s56
	s_nop 0
	global_load_lds_dwordx4 v2, s[50:51]
	s_add_i32 m0, s56, 0x2000
	s_nop 0
	global_load_lds_dwordx4 v144, s[50:51]
	s_cmp_eq_u32 s97, 60
	s_cbranch_scc0 .Ldefer_230_peel
	v_lshl_add_u64 v[168:169], v[240:241], 0, s[84:85]
	s_mov_b32 m0, s28
	s_nop 0
	global_load_lds_dwordx4 v[168:169], off
	v_lshl_add_u64 v[168:169], v[242:243], 0, s[84:85]
	s_mov_b32 m0, s65
	s_nop 0
	global_load_lds_dwordx4 v[168:169], off
; #define PG8_STAGE(bufoff, gbase, voff) do { _Pragma("unroll") for (int _i = 0; _i < 2; ++_i) \
;         __builtin_amdgcn_global_load_lds((const unsigned*)((const char*)(gbase) + (voff)[_i]), (PG8_LAS unsigned*)(lds + (bufoff) + ldsw + _i * 8192), 16, 0, 0); } while (0)
; #define PG8_LDA(dst, b, h) do { _Pragma("unroll") for (int m = 0; m < 4; ++m) _Pragma("unroll") for (int k = 0; k < 2; ++k) dst[m][k] = *(const PG8_LAS bf16x8*)(lds + PG8_SA(b, h) + aoff + m * 2048 + k * 1024); } while (0)
; #define PG8_LDB(dst, b, h) do { _Pragma("unroll") for (int n = 0; n < 2; ++n) _Pragma("unroll") for (int k = 0; k < 2; ++k) dst[n][k] = *(const PG8_LAS bf16x8*)(lds + PG8_SB(b, h) + boff + n * 2048 + k * 1024); } while (0)
; #define PG8_WAIT_V(n) asm volatile("s_waitcnt vmcnt(" #n ")" ::: "memory")
; #define PG8_WAIT_L(n) asm volatile("s_waitcnt lgkmcnt(" #n ")" ::: "memory")
; #define PG8_BAR __builtin_amdgcn_s_barrier()
; #define PG8_SCHED __builtin_amdgcn_sched_barrier(0)
; template <class Epi, class Sched, bool ALIGN_EPI = false, bool SP2 = false, bool I8 = false>
; __device__ __forceinline__ void gemm_phase(PG8_LAS unsigned char* lds, const Gemm g, const Sched& S, const Epi& E) {
;     ...
;         for (int t = 0; t < nt; t += 2) {
;             const bool last = (t == nt - 2);
;             const char* a1 = cA + (size_t)(t + 1) * kstep;
;             const char* a2 = last ? nA : cA + (size_t)(t + 2) * kstep; const char* b2 = last ? nB : cB + (size_t)(t + 2) * kstep;
;             const char* a3 = a2 + kstep; const char* b3 = b2 + kstep;
;             if (last && has_next) S.a_ready(nxt);
;             if constexpr (SP2) {
;             PG8_LDB(B0, 0, 0); PG8_LDB(B1, 0, 1); PG8_SCHED; PG8_LDA(At, 0, 0); PG8_STAGE(PG8_SA(1, 1), a1 + hstep, voffA);
;             PG8_WAIT_V(8); PG8_WAIT_L(0); PG8_BAR; PG8_MMA(0, 0, At, B0); PG8_MMA(0, 1, At, B1); PG8_BAR; PG8_SCHED;
.Ldefer_230_peel:
	s_waitcnt vmcnt(6) lgkmcnt(0)
	s_barrier
	s_setprio 1
	v_mfma_f32_16x16x32_bf16 v[64:67], v[112:115], v[184:187], v[64:67]
	v_mfma_f32_16x16x32_bf16 v[64:67], v[120:123], v[188:191], v[64:67]
	v_mfma_f32_16x16x32_bf16 v[48:51], v[120:123], v[208:211], v[48:51]
	v_mfma_f32_16x16x32_bf16 v[48:51], v[112:115], v[204:207], v[48:51]
	v_mfma_f32_16x16x32_bf16 v[32:35], v[112:115], v[212:215], v[32:35]
	v_mfma_f32_16x16x32_bf16 v[32:35], v[120:123], v[216:219], v[32:35]
	v_mfma_f32_16x16x32_bf16 v[16:19], v[120:123], v[224:227], v[16:19]
	v_mfma_f32_16x16x32_bf16 v[16:19], v[112:115], v[220:223], v[16:19]
	v_mfma_f32_16x16x32_bf16 v[12:15], v[152:155], v[220:223], v[12:15]
	v_mfma_f32_16x16x32_bf16 v[12:15], v[156:159], v[224:227], v[12:15]
	v_mfma_f32_16x16x32_bf16 v[28:31], v[156:159], v[216:219], v[28:31]
	v_mfma_f32_16x16x32_bf16 v[28:31], v[152:155], v[212:215], v[28:31]
	v_mfma_f32_16x16x32_bf16 v[44:47], v[152:155], v[204:207], v[44:47]
	v_mfma_f32_16x16x32_bf16 v[44:47], v[156:159], v[208:211], v[44:47]
	v_mfma_f32_16x16x32_bf16 v[60:63], v[156:159], v[188:191], v[60:63]
	v_mfma_f32_16x16x32_bf16 v[60:63], v[152:155], v[184:187], v[60:63]
	v_mfma_f32_16x16x32_bf16 v[56:59], v[160:163], v[184:187], v[56:59]
	v_mfma_f32_16x16x32_bf16 v[56:59], v[164:167], v[188:191], v[56:59]
	v_mfma_f32_16x16x32_bf16 v[40:43], v[164:167], v[208:211], v[40:43]
	v_mfma_f32_16x16x32_bf16 v[40:43], v[160:163], v[204:207], v[40:43]
	v_mfma_f32_16x16x32_bf16 v[24:27], v[160:163], v[212:215], v[24:27]
	v_mfma_f32_16x16x32_bf16 v[24:27], v[164:167], v[216:219], v[24:27]
	v_mfma_f32_16x16x32_bf16 v[8:11], v[164:167], v[224:227], v[8:11]
	v_mfma_f32_16x16x32_bf16 v[8:11], v[160:163], v[220:223], v[8:11]
	v_mfma_f32_16x16x32_bf16 v[4:7], v[176:179], v[220:223], v[4:7]
	v_mfma_f32_16x16x32_bf16 v[4:7], v[180:183], v[224:227], v[4:7]
	v_mfma_f32_16x16x32_bf16 v[20:23], v[180:183], v[216:219], v[20:23]
	v_mfma_f32_16x16x32_bf16 v[20:23], v[176:179], v[212:215], v[20:23]
	v_mfma_f32_16x16x32_bf16 v[36:39], v[176:179], v[204:207], v[36:39]
	v_mfma_f32_16x16x32_bf16 v[36:39], v[180:183], v[208:211], v[36:39]
	v_mfma_f32_16x16x32_bf16 v[52:55], v[180:183], v[188:191], v[52:55]
	v_mfma_f32_16x16x32_bf16 v[52:55], v[176:179], v[184:187], v[52:55]
	s_setprio 0
	s_barrier
	s_add_i32 s97, s97, 2
	s_add_u32 s12, s12, 0x100
	s_addc_u32 s13, s13, 0
	s_add_u32 s37, s37, 0x100
	s_addc_u32 s61, s61, 0
	s_cmp_gt_u32 s97, 61
	s_cbranch_scc1 .Lkloop_exit_1
.LBB0_230:
	s_add_u32 s50, s12, 0xfff00080
	s_addc_u32 s51, s13, -1
	s_add_i32 s56, 0, 0x10000
	s_cmp_eq_u32 s97, 60
	s_cselect_b32 s77, s11, s51
	s_cselect_b32 s76, s34, s50
	s_cselect_b32 s73, s27, s61
	s_cselect_b32 s72, s35, s37
	s_add_i32 s57, 0, 0x14000
	v_add_u32_e32 v156, s56, v171
	v_add_u32_e32 v168, s57, v171
	ds_read_b128 v[112:115], v156
	ds_read_b128 v[120:123], v156 offset:1024
	ds_read_b128 v[152:155], v156 offset:2048
	ds_read_b128 v[156:159], v156 offset:3072
	ds_read_b128 v[160:163], v168
	ds_read_b128 v[164:167], v168 offset:1024
	ds_read_b128 v[176:179], v168 offset:2048
	ds_read_b128 v[180:183], v168 offset:3072
	v_lshl_add_u64 v[168:169], v[240:241], 0, s[84:85]
	s_mov_b32 m0, s28
	s_nop 0
	global_load_lds_dwordx4 v[168:169], off
	v_lshl_add_u64 v[168:169], v[242:243], 0, s[84:85]
	s_mov_b32 m0, s65
	s_nop 0
	global_load_lds_dwordx4 v[168:169], off
	s_add_i32 m0, s47, 0xc000
	ds_read_b128 v[184:187], v173
	ds_read_b128 v[188:191], v173 offset:1024
	ds_read_b128 v[204:207], v173 offset:2048
	ds_read_b128 v[208:211], v173 offset:3072
	ds_read_b128 v[212:215], v173 offset:4096
	ds_read_b128 v[216:219], v173 offset:5120
	ds_read_b128 v[220:223], v173 offset:6144
	ds_read_b128 v[224:227], v173 offset:7168
	global_load_lds_dwordx4 v148, s[12:13]
	s_add_i32 m0, s47, 0xe000
	s_nop 0
	global_load_lds_dwordx4 v150, s[12:13]
	s_waitcnt vmcnt(8) lgkmcnt(0)
	s_barrier
	s_setprio 1
	v_mfma_f32_16x16x32_bf16 v[136:139], v[112:115], v[184:187], v[136:139]
	v_mfma_f32_16x16x32_bf16 v[136:139], v[120:123], v[188:191], v[136:139]
	v_mfma_f32_16x16x32_bf16 v[116:119], v[120:123], v[208:211], v[116:119]
	v_mfma_f32_16x16x32_bf16 v[116:119], v[112:115], v[204:207], v[116:119]
	v_mfma_f32_16x16x32_bf16 v[96:99], v[112:115], v[212:215], v[96:99]
	v_mfma_f32_16x16x32_bf16 v[96:99], v[120:123], v[216:219], v[96:99]
	v_mfma_f32_16x16x32_bf16 v[80:83], v[120:123], v[224:227], v[80:83]
	v_mfma_f32_16x16x32_bf16 v[80:83], v[112:115], v[220:223], v[80:83]
	v_mfma_f32_16x16x32_bf16 v[76:79], v[152:155], v[220:223], v[76:79]
	v_mfma_f32_16x16x32_bf16 v[76:79], v[156:159], v[224:227], v[76:79]
	v_mfma_f32_16x16x32_bf16 v[92:95], v[156:159], v[216:219], v[92:95]
	v_mfma_f32_16x16x32_bf16 v[92:95], v[152:155], v[212:215], v[92:95]
	v_mfma_f32_16x16x32_bf16 v[108:111], v[152:155], v[204:207], v[108:111]
	v_mfma_f32_16x16x32_bf16 v[108:111], v[156:159], v[208:211], v[108:111]
	v_mfma_f32_16x16x32_bf16 v[132:135], v[156:159], v[188:191], v[132:135]
	v_mfma_f32_16x16x32_bf16 v[132:135], v[152:155], v[184:187], v[132:135]
	v_mfma_f32_16x16x32_bf16 v[128:131], v[160:163], v[184:187], v[128:131]
	v_mfma_f32_16x16x32_bf16 v[128:131], v[164:167], v[188:191], v[128:131]
	v_mfma_f32_16x16x32_bf16 v[104:107], v[164:167], v[208:211], v[104:107]
	v_mfma_f32_16x16x32_bf16 v[104:107], v[160:163], v[204:207], v[104:107]
	v_mfma_f32_16x16x32_bf16 v[88:91], v[160:163], v[212:215], v[88:91]
	v_mfma_f32_16x16x32_bf16 v[88:91], v[164:167], v[216:219], v[88:91]
	v_mfma_f32_16x16x32_bf16 v[72:75], v[164:167], v[224:227], v[72:75]
	v_mfma_f32_16x16x32_bf16 v[72:75], v[160:163], v[220:223], v[72:75]
	v_mfma_f32_16x16x32_bf16 v[68:71], v[176:179], v[220:223], v[68:71]
	v_mfma_f32_16x16x32_bf16 v[68:71], v[180:183], v[224:227], v[68:71]
	v_mfma_f32_16x16x32_bf16 v[84:87], v[180:183], v[216:219], v[84:87]
	v_mfma_f32_16x16x32_bf16 v[84:87], v[176:179], v[212:215], v[84:87]
	v_mfma_f32_16x16x32_bf16 v[100:103], v[176:179], v[204:207], v[100:103]
	v_mfma_f32_16x16x32_bf16 v[100:103], v[180:183], v[208:211], v[100:103]
	v_mfma_f32_16x16x32_bf16 v[124:127], v[180:183], v[188:191], v[124:127]
	v_mfma_f32_16x16x32_bf16 v[124:127], v[176:179], v[184:187], v[124:127]
	s_setprio 0
	s_barrier
; #define PG8_STAGE(bufoff, gbase, voff) do { _Pragma("unroll") for (int _i = 0; _i < 2; ++_i) \
;         __builtin_amdgcn_global_load_lds((const unsigned*)((const char*)(gbase) + (voff)[_i]), (PG8_LAS unsigned*)(lds + (bufoff) + ldsw + _i * 8192), 16, 0, 0); } while (0)
; #define PG8_LDA(dst, b, h) do { _Pragma("unroll") for (int m = 0; m < 4; ++m) _Pragma("unroll") for (int k = 0; k < 2; ++k) dst[m][k] = *(const PG8_LAS bf16x8*)(lds + PG8_SA(b, h) + aoff + m * 2048 + k * 1024); } while (0)
; #define PG8_LDB(dst, b, h) do { _Pragma("unroll") for (int n = 0; n < 2; ++n) _Pragma("unroll") for (int k = 0; k < 2; ++k) dst[n][k] = *(const PG8_LAS bf16x8*)(lds + PG8_SB(b, h) + boff + n * 2048 + k * 1024); } while (0)
; #define PG8_WAIT_V(n) asm volatile("s_waitcnt vmcnt(" #n ")" ::: "memory")
; #define PG8_WAIT_L(n) asm volatile("s_waitcnt lgkmcnt(" #n ")" ::: "memory")
; #define PG8_BAR __builtin_amdgcn_s_barrier()
; #define PG8_SCHED __builtin_amdgcn_sched_barrier(0)
; template <class Epi, class Sched, bool ALIGN_EPI = false, bool SP2 = false, bool I8 = false>
; __device__ __forceinline__ void gemm_phase(PG8_LAS unsigned char* lds, const Gemm g, const Sched& S, const Epi& E) {
;     ...
;             PG8_LDA(At, 0, 1); PG8_STAGE(PG8_SB(0, 0), b2, voffB); PG8_STAGE(PG8_SB(0, 1), b2 + hstep, voffB); PG8_STAGE(PG8_SA(0, 0), a2, voffA);
;             PG8_WAIT_V(8); PG8_WAIT_L(0); PG8_BAR; PG8_MMA(1, 0, At, B0); PG8_MMA(1, 1, At, B1); PG8_BAR; PG8_SCHED;
;             PG8_LDB(B0, 1, 0); PG8_LDB(B1, 1, 1); PG8_SCHED; PG8_LDA(At, 1, 0); PG8_STAGE(PG8_SA(0, 1), a2 + hstep, voffA);
;             PG8_WAIT_V(8); PG8_WAIT_L(0); PG8_BAR; PG8_MMA(0, 0, At, B0); PG8_MMA(0, 1, At, B1); PG8_BAR; PG8_SCHED;
	s_add_i32 s50, s56, s46
	v_lshl_add_u64 v[168:169], s[72:73], 0, v[2:3]
	s_mov_b32 m0, s50
	ds_read_b128 v[184:187], v173 offset:16384
	ds_read_b128 v[188:191], v173 offset:17408
	ds_read_b128 v[204:207], v173 offset:18432
	ds_read_b128 v[208:211], v173 offset:19456
	ds_read_b128 v[212:215], v173 offset:20480
	ds_read_b128 v[216:219], v173 offset:21504
	ds_read_b128 v[220:223], v173 offset:22528
	ds_read_b128 v[224:227], v173 offset:23552
	global_load_lds_dwordx4 v[168:169], off
	s_add_i32 m0, s50, 0x2000
	s_add_u32 s50, s72, 0x100000
	v_lshl_add_u64 v[228:229], s[72:73], 0, v[144:145]
	s_addc_u32 s51, s73, 0
	s_add_i32 s56, s57, s46
	global_load_lds_dwordx4 v[228:229], off
	s_mov_b32 m0, s56
	v_lshl_add_u64 v[242:243], s[76:77], 0, v[142:143]
	global_load_lds_dwordx4 v2, s[50:51]
	s_add_i32 m0, s56, 0x2000
	s_nop 0
	global_load_lds_dwordx4 v144, s[50:51]
	v_lshl_add_u64 v[240:241], s[76:77], 0, v[140:141]
	s_waitcnt vmcnt(6) lgkmcnt(0)
	s_barrier
	s_setprio 1
	v_mfma_f32_16x16x32_bf16 v[64:67], v[112:115], v[184:187], v[64:67]
	v_mfma_f32_16x16x32_bf16 v[64:67], v[120:123], v[188:191], v[64:67]
	v_mfma_f32_16x16x32_bf16 v[48:51], v[120:123], v[208:211], v[48:51]
	v_mfma_f32_16x16x32_bf16 v[48:51], v[112:115], v[204:207], v[48:51]
	v_mfma_f32_16x16x32_bf16 v[32:35], v[112:115], v[212:215], v[32:35]
	v_mfma_f32_16x16x32_bf16 v[32:35], v[120:123], v[216:219], v[32:35]
	v_mfma_f32_16x16x32_bf16 v[16:19], v[120:123], v[224:227], v[16:19]
	v_mfma_f32_16x16x32_bf16 v[16:19], v[112:115], v[220:223], v[16:19]
	v_mfma_f32_16x16x32_bf16 v[12:15], v[152:155], v[220:223], v[12:15]
	v_mfma_f32_16x16x32_bf16 v[12:15], v[156:159], v[224:227], v[12:15]
	v_mfma_f32_16x16x32_bf16 v[28:31], v[156:159], v[216:219], v[28:31]
	v_mfma_f32_16x16x32_bf16 v[28:31], v[152:155], v[212:215], v[28:31]
	v_mfma_f32_16x16x32_bf16 v[44:47], v[152:155], v[204:207], v[44:47]
	v_mfma_f32_16x16x32_bf16 v[44:47], v[156:159], v[208:211], v[44:47]
	v_mfma_f32_16x16x32_bf16 v[60:63], v[156:159], v[188:191], v[60:63]
	v_mfma_f32_16x16x32_bf16 v[60:63], v[152:155], v[184:187], v[60:63]
	v_mfma_f32_16x16x32_bf16 v[56:59], v[160:163], v[184:187], v[56:59]
	v_mfma_f32_16x16x32_bf16 v[56:59], v[164:167], v[188:191], v[56:59]
	v_mfma_f32_16x16x32_bf16 v[40:43], v[164:167], v[208:211], v[40:43]
	v_mfma_f32_16x16x32_bf16 v[40:43], v[160:163], v[204:207], v[40:43]
	v_mfma_f32_16x16x32_bf16 v[24:27], v[160:163], v[212:215], v[24:27]
	v_mfma_f32_16x16x32_bf16 v[24:27], v[164:167], v[216:219], v[24:27]
	v_mfma_f32_16x16x32_bf16 v[8:11], v[164:167], v[224:227], v[8:11]
	v_mfma_f32_16x16x32_bf16 v[8:11], v[160:163], v[220:223], v[8:11]
	v_mfma_f32_16x16x32_bf16 v[4:7], v[176:179], v[220:223], v[4:7]
	v_mfma_f32_16x16x32_bf16 v[4:7], v[180:183], v[224:227], v[4:7]
	v_mfma_f32_16x16x32_bf16 v[20:23], v[180:183], v[216:219], v[20:23]
	v_mfma_f32_16x16x32_bf16 v[20:23], v[176:179], v[212:215], v[20:23]
	v_mfma_f32_16x16x32_bf16 v[36:39], v[176:179], v[204:207], v[36:39]
	v_mfma_f32_16x16x32_bf16 v[36:39], v[180:183], v[208:211], v[36:39]
	v_mfma_f32_16x16x32_bf16 v[52:55], v[180:183], v[188:191], v[52:55]
	v_mfma_f32_16x16x32_bf16 v[52:55], v[176:179], v[184:187], v[52:55]
	s_setprio 0
	s_barrier
	s_mov_b32 m0, s47
	s_nop 0
	global_load_lds_dwordx4 v[240:241], off
	s_mov_b32 m0, s52
	s_nop 0
	global_load_lds_dwordx4 v[242:243], off
	s_add_i32 s56, 0, 0x18000
	s_add_i32 s57, 0, 0x1c000
	v_add_u32_e32 v156, s56, v171
	v_add_u32_e32 v175, s57, v171
	ds_read_b128 v[112:115], v156
	ds_read_b128 v[120:123], v156 offset:1024
	ds_read_b128 v[152:155], v156 offset:2048
	ds_read_b128 v[156:159], v156 offset:3072
	ds_read_b128 v[160:163], v175
	ds_read_b128 v[164:167], v175 offset:1024
	ds_read_b128 v[176:179], v175 offset:2048
	ds_read_b128 v[180:183], v175 offset:3072
	s_add_u32 s50, s76, 0x100000
	s_addc_u32 s51, s77, 0
	s_mov_b32 m0, s53
	ds_read_b128 v[184:187], v173 offset:32768
	ds_read_b128 v[188:191], v173 offset:33792
	ds_read_b128 v[204:207], v173 offset:34816
	ds_read_b128 v[208:211], v173 offset:35840
	ds_read_b128 v[212:215], v173 offset:36864
	ds_read_b128 v[216:219], v173 offset:37888
	ds_read_b128 v[220:223], v173 offset:38912
	ds_read_b128 v[224:227], v173 offset:39936
	global_load_lds_dwordx4 v140, s[50:51]
	s_mov_b32 m0, s64
	s_nop 0
	global_load_lds_dwordx4 v142, s[50:51]
	s_waitcnt vmcnt(8) lgkmcnt(0)
	s_barrier
; #define PG8_STAGE(bufoff, gbase, voff) do { _Pragma("unroll") for (int _i = 0; _i < 2; ++_i) \
;         __builtin_amdgcn_global_load_lds((const unsigned*)((const char*)(gbase) + (voff)[_i]), (PG8_LAS unsigned*)(lds + (bufoff) + ldsw + _i * 8192), 16, 0, 0); } while (0)
; #define PG8_LDA(dst, b, h) do { _Pragma("unroll") for (int m = 0; m < 4; ++m) _Pragma("unroll") for (int k = 0; k < 2; ++k) dst[m][k] = *(const PG8_LAS bf16x8*)(lds + PG8_SA(b, h) + aoff + m * 2048 + k * 1024); } while (0)
; #define PG8_WAIT_V(n) asm volatile("s_waitcnt vmcnt(" #n ")" ::: "memory")
; #define PG8_WAIT_L(n) asm volatile("s_waitcnt lgkmcnt(" #n ")" ::: "memory")
; #define PG8_BAR __builtin_amdgcn_s_barrier()
; #define PG8_SCHED __builtin_amdgcn_sched_barrier(0)
; template <class Epi, class Sched, bool ALIGN_EPI = false, bool SP2 = false, bool I8 = false>
; __device__ __forceinline__ void gemm_phase(PG8_LAS unsigned char* lds, const Gemm g, const Sched& S, const Epi& E) {
;     ...
;             PG8_WAIT_V(8); PG8_WAIT_L(0); PG8_BAR; PG8_MMA(0, 0, At, B0); PG8_MMA(0, 1, At, B1); PG8_BAR; PG8_SCHED;
;             PG8_LDA(At, 1, 1); PG8_STAGE(PG8_SB(1, 0), b3, voffB); PG8_STAGE(PG8_SB(1, 1), b3 + hstep, voffB); PG8_STAGE(PG8_SA(1, 0), a3, voffA);
;             PG8_WAIT_V(8); PG8_WAIT_L(0); PG8_BAR; PG8_MMA(1, 0, At, B0); PG8_MMA(1, 1, At, B1); PG8_BAR; PG8_SCHED;
	s_setprio 1
	v_mfma_f32_16x16x32_bf16 v[136:139], v[112:115], v[184:187], v[136:139]
	v_mfma_f32_16x16x32_bf16 v[136:139], v[120:123], v[188:191], v[136:139]
	v_mfma_f32_16x16x32_bf16 v[116:119], v[120:123], v[208:211], v[116:119]
	v_mfma_f32_16x16x32_bf16 v[116:119], v[112:115], v[204:207], v[116:119]
	v_mfma_f32_16x16x32_bf16 v[96:99], v[112:115], v[212:215], v[96:99]
	v_mfma_f32_16x16x32_bf16 v[96:99], v[120:123], v[216:219], v[96:99]
	v_mfma_f32_16x16x32_bf16 v[80:83], v[120:123], v[224:227], v[80:83]
	v_mfma_f32_16x16x32_bf16 v[80:83], v[112:115], v[220:223], v[80:83]
	v_mfma_f32_16x16x32_bf16 v[76:79], v[152:155], v[220:223], v[76:79]
	v_mfma_f32_16x16x32_bf16 v[76:79], v[156:159], v[224:227], v[76:79]
	v_mfma_f32_16x16x32_bf16 v[92:95], v[156:159], v[216:219], v[92:95]
	v_mfma_f32_16x16x32_bf16 v[92:95], v[152:155], v[212:215], v[92:95]
	v_mfma_f32_16x16x32_bf16 v[108:111], v[152:155], v[204:207], v[108:111]
	v_mfma_f32_16x16x32_bf16 v[108:111], v[156:159], v[208:211], v[108:111]
	v_mfma_f32_16x16x32_bf16 v[132:135], v[156:159], v[188:191], v[132:135]
	v_mfma_f32_16x16x32_bf16 v[132:135], v[152:155], v[184:187], v[132:135]
	v_mfma_f32_16x16x32_bf16 v[128:131], v[160:163], v[184:187], v[128:131]
	v_mfma_f32_16x16x32_bf16 v[128:131], v[164:167], v[188:191], v[128:131]
	v_mfma_f32_16x16x32_bf16 v[104:107], v[164:167], v[208:211], v[104:107]
	v_mfma_f32_16x16x32_bf16 v[104:107], v[160:163], v[204:207], v[104:107]
	v_mfma_f32_16x16x32_bf16 v[88:91], v[160:163], v[212:215], v[88:91]
	v_mfma_f32_16x16x32_bf16 v[88:91], v[164:167], v[216:219], v[88:91]
	v_mfma_f32_16x16x32_bf16 v[72:75], v[164:167], v[224:227], v[72:75]
	v_mfma_f32_16x16x32_bf16 v[72:75], v[160:163], v[220:223], v[72:75]
	v_mfma_f32_16x16x32_bf16 v[68:71], v[176:179], v[220:223], v[68:71]
	v_mfma_f32_16x16x32_bf16 v[68:71], v[180:183], v[224:227], v[68:71]
	v_mfma_f32_16x16x32_bf16 v[84:87], v[180:183], v[216:219], v[84:87]
	v_mfma_f32_16x16x32_bf16 v[84:87], v[176:179], v[212:215], v[84:87]
	v_mfma_f32_16x16x32_bf16 v[100:103], v[176:179], v[204:207], v[100:103]
	v_mfma_f32_16x16x32_bf16 v[100:103], v[180:183], v[208:211], v[100:103]
	v_mfma_f32_16x16x32_bf16 v[124:127], v[180:183], v[188:191], v[124:127]
	v_mfma_f32_16x16x32_bf16 v[124:127], v[176:179], v[184:187], v[124:127]
	s_setprio 0
	s_barrier
	s_add_i32 s50, s56, s46
	v_lshl_add_u64 v[168:169], v[168:169], 0, s[84:85]
	s_mov_b32 m0, s50
	ds_read_b128 v[184:187], v173 offset:49152
	ds_read_b128 v[188:191], v173 offset:50176
	ds_read_b128 v[204:207], v173 offset:51200
	ds_read_b128 v[208:211], v173 offset:52224
	ds_read_b128 v[212:215], v173 offset:53248
	ds_read_b128 v[216:219], v173 offset:54272
	ds_read_b128 v[220:223], v173 offset:55296
	ds_read_b128 v[224:227], v173 offset:56320
	global_load_lds_dwordx4 v[168:169], off
	s_add_i32 m0, s50, 0x2000
	s_add_u32 s50, s72, 0x100080
	v_lshl_add_u64 v[168:169], v[228:229], 0, s[84:85]
	s_addc_u32 s51, s73, 0
	s_add_i32 s56, s57, s46
	global_load_lds_dwordx4 v[168:169], off
	s_mov_b32 m0, s56
	s_nop 0
	global_load_lds_dwordx4 v2, s[50:51]
	s_add_i32 m0, s56, 0x2000
	s_nop 0
	global_load_lds_dwordx4 v144, s[50:51]
	s_cmp_eq_u32 s97, 60
	s_cbranch_scc0 .Ldefer_230_body
	v_lshl_add_u64 v[168:169], v[240:241], 0, s[84:85]
	s_mov_b32 m0, s28
	s_nop 0
	global_load_lds_dwordx4 v[168:169], off
	v_lshl_add_u64 v[168:169], v[242:243], 0, s[84:85]
	s_mov_b32 m0, s65
	s_nop 0
	global_load_lds_dwordx4 v[168:169], off
.Ldefer_230_body:
	s_waitcnt vmcnt(6) lgkmcnt(0)
	s_barrier
	s_setprio 1
	v_mfma_f32_16x16x32_bf16 v[64:67], v[112:115], v[184:187], v[64:67]
	v_mfma_f32_16x16x32_bf16 v[64:67], v[120:123], v[188:191], v[64:67]
	v_mfma_f32_16x16x32_bf16 v[48:51], v[120:123], v[208:211], v[48:51]
	v_mfma_f32_16x16x32_bf16 v[48:51], v[112:115], v[204:207], v[48:51]
	v_mfma_f32_16x16x32_bf16 v[32:35], v[112:115], v[212:215], v[32:35]
	v_mfma_f32_16x16x32_bf16 v[32:35], v[120:123], v[216:219], v[32:35]
	v_mfma_f32_16x16x32_bf16 v[16:19], v[120:123], v[224:227], v[16:19]
	v_mfma_f32_16x16x32_bf16 v[16:19], v[112:115], v[220:223], v[16:19]
	v_mfma_f32_16x16x32_bf16 v[12:15], v[152:155], v[220:223], v[12:15]
	v_mfma_f32_16x16x32_bf16 v[12:15], v[156:159], v[224:227], v[12:15]
	v_mfma_f32_16x16x32_bf16 v[28:31], v[156:159], v[216:219], v[28:31]
	v_mfma_f32_16x16x32_bf16 v[28:31], v[152:155], v[212:215], v[28:31]
	v_mfma_f32_16x16x32_bf16 v[44:47], v[152:155], v[204:207], v[44:47]
	v_mfma_f32_16x16x32_bf16 v[44:47], v[156:159], v[208:211], v[44:47]
	v_mfma_f32_16x16x32_bf16 v[60:63], v[156:159], v[188:191], v[60:63]
	v_mfma_f32_16x16x32_bf16 v[60:63], v[152:155], v[184:187], v[60:63]
	v_mfma_f32_16x16x32_bf16 v[56:59], v[160:163], v[184:187], v[56:59]
	v_mfma_f32_16x16x32_bf16 v[56:59], v[164:167], v[188:191], v[56:59]
	v_mfma_f32_16x16x32_bf16 v[40:43], v[164:167], v[208:211], v[40:43]
	v_mfma_f32_16x16x32_bf16 v[40:43], v[160:163], v[204:207], v[40:43]
	v_mfma_f32_16x16x32_bf16 v[24:27], v[160:163], v[212:215], v[24:27]
	v_mfma_f32_16x16x32_bf16 v[24:27], v[164:167], v[216:219], v[24:27]
	v_mfma_f32_16x16x32_bf16 v[8:11], v[164:167], v[224:227], v[8:11]
	v_mfma_f32_16x16x32_bf16 v[8:11], v[160:163], v[220:223], v[8:11]
	v_mfma_f32_16x16x32_bf16 v[4:7], v[176:179], v[220:223], v[4:7]
	v_mfma_f32_16x16x32_bf16 v[4:7], v[180:183], v[224:227], v[4:7]
	v_mfma_f32_16x16x32_bf16 v[20:23], v[180:183], v[216:219], v[20:23]
	v_mfma_f32_16x16x32_bf16 v[20:23], v[176:179], v[212:215], v[20:23]
	v_mfma_f32_16x16x32_bf16 v[36:39], v[176:179], v[204:207], v[36:39]
	v_mfma_f32_16x16x32_bf16 v[36:39], v[180:183], v[208:211], v[36:39]
	v_mfma_f32_16x16x32_bf16 v[52:55], v[180:183], v[188:191], v[52:55]
	v_mfma_f32_16x16x32_bf16 v[52:55], v[176:179], v[184:187], v[52:55]
	s_setprio 0
	s_barrier
	s_add_i32 s97, s97, 2
	s_add_u32 s12, s12, 0x100
	s_addc_u32 s13, s13, 0
	s_add_u32 s37, s37, 0x100
	s_addc_u32 s61, s61, 0
	s_cmp_gt_u32 s97, 61
	s_cbranch_scc0 .LBB0_230

; #define PG8_STAGE(bufoff, gbase, voff) do { _Pragma("unroll") for (int _i = 0; _i < 2; ++_i) \
;         __builtin_amdgcn_global_load_lds((const unsigned*)((const char*)(gbase) + (voff)[_i]), (PG8_LAS unsigned*)(lds + (bufoff) + ldsw + _i * 8192), 16, 0, 0); } while (0)
; #define PG8_LDA(dst, b, h) do { _Pragma("unroll") for (int m = 0; m < 4; ++m) _Pragma("unroll") for (int k = 0; k < 2; ++k) dst[m][k] = *(const PG8_LAS bf16x8*)(lds + PG8_SA(b, h) + aoff + m * 2048 + k * 1024); } while (0)
; #define PG8_LDB(dst, b, h) do { _Pragma("unroll") for (int n = 0; n < 2; ++n) _Pragma("unroll") for (int k = 0; k < 2; ++k) dst[n][k] = *(const PG8_LAS bf16x8*)(lds + PG8_SB(b, h) + boff + n * 2048 + k * 1024); } while (0)
; #define PG8_WAIT_V(n) asm volatile("s_waitcnt vmcnt(" #n ")" ::: "memory")
; #define PG8_WAIT_L(n) asm volatile("s_waitcnt lgkmcnt(" #n ")" ::: "memory")
; #define PG8_BAR __builtin_amdgcn_s_barrier()
; #define PG8_SCHED __builtin_amdgcn_sched_barrier(0)
; template <class Epi, class Sched, bool ALIGN_EPI = false, bool SP2 = false, bool I8 = false>
; __device__ __forceinline__ void gemm_phase(PG8_LAS unsigned char* lds, const Gemm g, const Sched& S, const Epi& E) {
;     ...
;         const bool has_next = S.next(ui + 1, nxt);
;         const char* nA = has_next ? (const char*)g.A + (size_t)nxt.pm * tstep : cA; const char* nB = has_next ? (const char*)g.Bt + (size_t)nxt.pn * tstep : cB;
;         for (int t = 0; t < nt; t += 2) {
;             const bool last = (t == nt - 2);
;             const char* a1 = cA + (size_t)(t + 1) * kstep;
;             const char* a2 = last ? nA : cA + (size_t)(t + 2) * kstep; const char* b2 = last ? nB : cB + (size_t)(t + 2) * kstep;
;             const char* a3 = a2 + kstep; const char* b3 = b2 + kstep;
;             if (last && has_next) S.a_ready(nxt);
;             if constexpr (SP2) {
;             PG8_LDB(B0, 0, 0); PG8_LDB(B1, 0, 1); PG8_SCHED; PG8_LDA(At, 0, 0); PG8_STAGE(PG8_SA(1, 1), a1 + hstep, voffA);
;             PG8_WAIT_V(8); PG8_WAIT_L(0); PG8_BAR; PG8_MMA(0, 0, At, B0); PG8_MMA(0, 1, At, B1); PG8_BAR; PG8_SCHED;
;             PG8_LDA(At, 0, 1); PG8_STAGE(PG8_SB(0, 0), b2, voffB); PG8_STAGE(PG8_SB(0, 1), b2 + hstep, voffB); PG8_STAGE(PG8_SA(0, 0), a2, voffA);
;             PG8_WAIT_V(8); PG8_WAIT_L(0); PG8_BAR; PG8_MMA(1, 0, At, B0); PG8_MMA(1, 1, At, B1); PG8_BAR; PG8_SCHED;
.LBB0_1455:
	s_ashr_i32 s17, s16, 31
	s_lshl_b64 s[20:21], s[16:17], 21
	s_add_u32 s20, s28, s20
	s_addc_u32 s21, s34, s21
	s_and_b64 s[22:23], s[8:9], exec
	s_cselect_b32 s17, s21, s25
	s_cselect_b32 s51, s20, s24
	s_ashr_i32 s19, s18, 31
	s_lshl_b64 s[22:23], s[18:19], 21
	s_add_u32 s22, s35, s22
	s_addc_u32 s23, s39, s23
	s_and_b64 s[36:37], s[8:9], exec
	s_cselect_b32 s19, s23, s27
	s_cselect_b32 s52, s22, s26
	s_add_u32 s24, s24, 0x100080
	s_addc_u32 s25, s25, 0
	s_add_u32 s53, s26, 0x100
	s_addc_u32 s54, s27, 0
	s_mov_b32 s55, -2
	s_waitcnt vmcnt(0)
	s_add_u32 s26, s24, 0xfff00080
	s_addc_u32 s27, s25, -1
	s_add_i32 s56, 0, 0x10000
	s_cmp_eq_u32 s55, 60
	s_cselect_b32 s37, s17, s27
	s_cselect_b32 s36, s51, s26
	s_cselect_b32 s27, s19, s54
	s_cselect_b32 s26, s52, s53
	s_add_i32 s58, 0, 0x14000
	v_add_u32_e32 v144, s56, v240
	v_add_u32_e32 v160, s58, v240
	ds_read_b128 v[124:127], v144
	ds_read_b128 v[128:131], v144 offset:1024
	ds_read_b128 v[132:135], v144 offset:2048
	ds_read_b128 v[144:147], v144 offset:3072
	ds_read_b128 v[148:151], v160
	ds_read_b128 v[152:155], v160 offset:1024
	ds_read_b128 v[156:159], v160 offset:2048
	ds_read_b128 v[160:163], v160 offset:3072
	s_add_i32 m0, s41, 0xc000
	ds_read_b128 v[164:167], v242
	ds_read_b128 v[168:171], v242 offset:1024
	ds_read_b128 v[172:175], v242 offset:2048
	ds_read_b128 v[176:179], v242 offset:3072
	ds_read_b128 v[180:183], v242 offset:4096
	ds_read_b128 v[184:187], v242 offset:5120
	ds_read_b128 v[188:191], v242 offset:6144
	ds_read_b128 v[214:217], v242 offset:7168
	global_load_lds_dwordx4 v210, s[24:25]
	s_add_i32 m0, s41, 0xe000
	s_nop 0
	global_load_lds_dwordx4 v212, s[24:25]
	s_waitcnt vmcnt(8) lgkmcnt(0)
	s_barrier
	s_setprio 1
	v_mfma_f32_16x16x32_bf16 v[140:143], v[124:127], v[164:167], 0
	v_mfma_f32_16x16x32_bf16 v[140:143], v[128:131], v[168:171], v[140:143]
	v_mfma_f32_16x16x32_bf16 v[112:115], v[128:131], v[176:179], 0
	v_mfma_f32_16x16x32_bf16 v[112:115], v[124:127], v[172:175], v[112:115]
	v_mfma_f32_16x16x32_bf16 v[96:99], v[124:127], v[180:183], 0
	v_mfma_f32_16x16x32_bf16 v[96:99], v[128:131], v[184:187], v[96:99]
	v_mfma_f32_16x16x32_bf16 v[80:83], v[128:131], v[214:217], 0
	v_mfma_f32_16x16x32_bf16 v[80:83], v[124:127], v[188:191], v[80:83]
	v_mfma_f32_16x16x32_bf16 v[76:79], v[132:135], v[188:191], 0
	v_mfma_f32_16x16x32_bf16 v[76:79], v[144:147], v[214:217], v[76:79]
	v_mfma_f32_16x16x32_bf16 v[92:95], v[144:147], v[184:187], 0
	v_mfma_f32_16x16x32_bf16 v[92:95], v[132:135], v[180:183], v[92:95]
	v_mfma_f32_16x16x32_bf16 v[108:111], v[132:135], v[172:175], 0
	v_mfma_f32_16x16x32_bf16 v[108:111], v[144:147], v[176:179], v[108:111]
	v_mfma_f32_16x16x32_bf16 v[136:139], v[144:147], v[168:171], 0
	v_mfma_f32_16x16x32_bf16 v[136:139], v[132:135], v[164:167], v[136:139]
	v_mfma_f32_16x16x32_bf16 v[120:123], v[148:151], v[164:167], 0
	v_mfma_f32_16x16x32_bf16 v[120:123], v[152:155], v[168:171], v[120:123]
	v_mfma_f32_16x16x32_bf16 v[104:107], v[152:155], v[176:179], 0
	v_mfma_f32_16x16x32_bf16 v[104:107], v[148:151], v[172:175], v[104:107]
	v_mfma_f32_16x16x32_bf16 v[88:91], v[148:151], v[180:183], 0
	v_mfma_f32_16x16x32_bf16 v[88:91], v[152:155], v[184:187], v[88:91]
	v_mfma_f32_16x16x32_bf16 v[72:75], v[152:155], v[214:217], 0
	v_mfma_f32_16x16x32_bf16 v[72:75], v[148:151], v[188:191], v[72:75]
	v_mfma_f32_16x16x32_bf16 v[68:71], v[156:159], v[188:191], 0
	v_mfma_f32_16x16x32_bf16 v[68:71], v[160:163], v[214:217], v[68:71]
	v_mfma_f32_16x16x32_bf16 v[84:87], v[160:163], v[184:187], 0
	v_mfma_f32_16x16x32_bf16 v[84:87], v[156:159], v[180:183], v[84:87]
	v_mfma_f32_16x16x32_bf16 v[100:103], v[156:159], v[172:175], 0
	v_mfma_f32_16x16x32_bf16 v[100:103], v[160:163], v[176:179], v[100:103]
	v_mfma_f32_16x16x32_bf16 v[116:119], v[160:163], v[168:171], 0
	v_mfma_f32_16x16x32_bf16 v[116:119], v[156:159], v[164:167], v[116:119]
	s_setprio 0
	s_barrier
	s_add_i32 s56, s56, s40
	v_lshl_add_u64 v[218:219], s[26:27], 0, v[2:3]
	s_mov_b32 m0, s56
	ds_read_b128 v[164:167], v242 offset:16384
	ds_read_b128 v[168:171], v242 offset:17408
	ds_read_b128 v[172:175], v242 offset:18432
	ds_read_b128 v[176:179], v242 offset:19456
	ds_read_b128 v[180:183], v242 offset:20480
	ds_read_b128 v[184:187], v242 offset:21504
	ds_read_b128 v[188:191], v242 offset:22528
	ds_read_b128 v[214:217], v242 offset:23552
	global_load_lds_dwordx4 v[218:219], off
	s_add_i32 m0, s56, 0x2000
	s_add_u32 s56, s26, 0x100000
	v_lshl_add_u64 v[220:221], s[26:27], 0, v[204:205]
	s_addc_u32 s57, s27, 0
	s_add_i32 s58, s58, s40
	global_load_lds_dwordx4 v[220:221], off
	s_mov_b32 m0, s58
	v_lshl_add_u64 v[224:225], s[36:37], 0, v[206:207]
	global_load_lds_dwordx4 v2, s[56:57]
	s_add_i32 m0, s58, 0x2000
	s_nop 0
	global_load_lds_dwordx4 v204, s[56:57]
	v_lshl_add_u64 v[222:223], s[36:37], 0, v[208:209]
	s_waitcnt vmcnt(6) lgkmcnt(0)
	s_barrier
; #define PG8_STAGE(bufoff, gbase, voff) do { _Pragma("unroll") for (int _i = 0; _i < 2; ++_i) \
;         __builtin_amdgcn_global_load_lds((const unsigned*)((const char*)(gbase) + (voff)[_i]), (PG8_LAS unsigned*)(lds + (bufoff) + ldsw + _i * 8192), 16, 0, 0); } while (0)
; #define PG8_LDA(dst, b, h) do { _Pragma("unroll") for (int m = 0; m < 4; ++m) _Pragma("unroll") for (int k = 0; k < 2; ++k) dst[m][k] = *(const PG8_LAS bf16x8*)(lds + PG8_SA(b, h) + aoff + m * 2048 + k * 1024); } while (0)
; #define PG8_LDB(dst, b, h) do { _Pragma("unroll") for (int n = 0; n < 2; ++n) _Pragma("unroll") for (int k = 0; k < 2; ++k) dst[n][k] = *(const PG8_LAS bf16x8*)(lds + PG8_SB(b, h) + boff + n * 2048 + k * 1024); } while (0)
; #define PG8_WAIT_V(n) asm volatile("s_waitcnt vmcnt(" #n ")" ::: "memory")
; #define PG8_WAIT_L(n) asm volatile("s_waitcnt lgkmcnt(" #n ")" ::: "memory")
; #define PG8_BAR __builtin_amdgcn_s_barrier()
; #define PG8_SCHED __builtin_amdgcn_sched_barrier(0)
; template <class Epi, class Sched, bool ALIGN_EPI = false, bool SP2 = false, bool I8 = false>
; __device__ __forceinline__ void gemm_phase(PG8_LAS unsigned char* lds, const Gemm g, const Sched& S, const Epi& E) {
;     ...
;             PG8_WAIT_V(8); PG8_WAIT_L(0); PG8_BAR; PG8_MMA(0, 0, At, B0); PG8_MMA(0, 1, At, B1); PG8_BAR; PG8_SCHED;
;             PG8_LDA(At, 0, 1); PG8_STAGE(PG8_SB(0, 0), b2, voffB); PG8_STAGE(PG8_SB(0, 1), b2 + hstep, voffB); PG8_STAGE(PG8_SA(0, 0), a2, voffA);
;             PG8_WAIT_V(8); PG8_WAIT_L(0); PG8_BAR; PG8_MMA(1, 0, At, B0); PG8_MMA(1, 1, At, B1); PG8_BAR; PG8_SCHED;
;             PG8_LDB(B0, 1, 0); PG8_LDB(B1, 1, 1); PG8_SCHED; PG8_LDA(At, 1, 0); PG8_STAGE(PG8_SA(0, 1), a2 + hstep, voffA);
;             PG8_WAIT_V(8); PG8_WAIT_L(0); PG8_BAR; PG8_MMA(0, 0, At, B0); PG8_MMA(0, 1, At, B1); PG8_BAR; PG8_SCHED;
;             PG8_LDA(At, 1, 1); PG8_STAGE(PG8_SB(1, 0), b3, voffB); PG8_STAGE(PG8_SB(1, 1), b3 + hstep, voffB); PG8_STAGE(PG8_SA(1, 0), a3, voffA);
	s_setprio 1
	v_mfma_f32_16x16x32_bf16 v[64:67], v[124:127], v[164:167], 0
	v_mfma_f32_16x16x32_bf16 v[64:67], v[128:131], v[168:171], v[64:67]
	v_mfma_f32_16x16x32_bf16 v[48:51], v[128:131], v[176:179], 0
	v_mfma_f32_16x16x32_bf16 v[48:51], v[124:127], v[172:175], v[48:51]
	v_mfma_f32_16x16x32_bf16 v[32:35], v[124:127], v[180:183], 0
	v_mfma_f32_16x16x32_bf16 v[32:35], v[128:131], v[184:187], v[32:35]
	v_mfma_f32_16x16x32_bf16 v[16:19], v[128:131], v[214:217], 0
	v_mfma_f32_16x16x32_bf16 v[16:19], v[124:127], v[188:191], v[16:19]
	v_mfma_f32_16x16x32_bf16 v[12:15], v[132:135], v[188:191], 0
	v_mfma_f32_16x16x32_bf16 v[12:15], v[144:147], v[214:217], v[12:15]
	v_mfma_f32_16x16x32_bf16 v[28:31], v[144:147], v[184:187], 0
	v_mfma_f32_16x16x32_bf16 v[28:31], v[132:135], v[180:183], v[28:31]
	v_mfma_f32_16x16x32_bf16 v[44:47], v[132:135], v[172:175], 0
	v_mfma_f32_16x16x32_bf16 v[44:47], v[144:147], v[176:179], v[44:47]
	v_mfma_f32_16x16x32_bf16 v[60:63], v[144:147], v[168:171], 0
	v_mfma_f32_16x16x32_bf16 v[60:63], v[132:135], v[164:167], v[60:63]
	v_mfma_f32_16x16x32_bf16 v[56:59], v[148:151], v[164:167], 0
	v_mfma_f32_16x16x32_bf16 v[56:59], v[152:155], v[168:171], v[56:59]
	v_mfma_f32_16x16x32_bf16 v[40:43], v[152:155], v[176:179], 0
	v_mfma_f32_16x16x32_bf16 v[40:43], v[148:151], v[172:175], v[40:43]
	v_mfma_f32_16x16x32_bf16 v[24:27], v[148:151], v[180:183], 0
	v_mfma_f32_16x16x32_bf16 v[24:27], v[152:155], v[184:187], v[24:27]
	v_mfma_f32_16x16x32_bf16 v[8:11], v[152:155], v[214:217], 0
	v_mfma_f32_16x16x32_bf16 v[8:11], v[148:151], v[188:191], v[8:11]
	v_mfma_f32_16x16x32_bf16 v[4:7], v[156:159], v[188:191], 0
	v_mfma_f32_16x16x32_bf16 v[4:7], v[160:163], v[214:217], v[4:7]
	v_mfma_f32_16x16x32_bf16 v[20:23], v[160:163], v[184:187], 0
	v_mfma_f32_16x16x32_bf16 v[20:23], v[156:159], v[180:183], v[20:23]
	v_mfma_f32_16x16x32_bf16 v[36:39], v[156:159], v[172:175], 0
	v_mfma_f32_16x16x32_bf16 v[36:39], v[160:163], v[176:179], v[36:39]
	v_mfma_f32_16x16x32_bf16 v[52:55], v[160:163], v[168:171], 0
	v_mfma_f32_16x16x32_bf16 v[52:55], v[156:159], v[164:167], v[52:55]
	s_setprio 0
	s_barrier
	s_mov_b32 m0, s41
	s_nop 0
	global_load_lds_dwordx4 v[222:223], off
	s_mov_b32 m0, s42
	s_nop 0
	global_load_lds_dwordx4 v[224:225], off
	s_add_i32 s56, 0, 0x18000
	s_add_i32 s57, 0, 0x1c000
	v_add_u32_e32 v144, s56, v240
	v_add_u32_e32 v160, s57, v240
	ds_read_b128 v[124:127], v144
	ds_read_b128 v[128:131], v144 offset:1024
	ds_read_b128 v[132:135], v144 offset:2048
	ds_read_b128 v[144:147], v144 offset:3072
	ds_read_b128 v[148:151], v160
	ds_read_b128 v[152:155], v160 offset:1024
	ds_read_b128 v[156:159], v160 offset:2048
	ds_read_b128 v[160:163], v160 offset:3072
	s_add_u32 s36, s36, 0x100000
	s_addc_u32 s37, s37, 0
	s_mov_b32 m0, s43
	ds_read_b128 v[164:167], v242 offset:32768
	ds_read_b128 v[168:171], v242 offset:33792
	ds_read_b128 v[172:175], v242 offset:34816
	ds_read_b128 v[176:179], v242 offset:35840
	ds_read_b128 v[180:183], v242 offset:36864
	ds_read_b128 v[184:187], v242 offset:37888
	ds_read_b128 v[188:191], v242 offset:38912
	ds_read_b128 v[214:217], v242 offset:39936
	global_load_lds_dwordx4 v208, s[36:37]
	s_mov_b32 m0, s44
	s_nop 0
	global_load_lds_dwordx4 v206, s[36:37]
	s_waitcnt vmcnt(8) lgkmcnt(0)
	s_barrier
	s_setprio 1
	v_mfma_f32_16x16x32_bf16 v[140:143], v[124:127], v[164:167], v[140:143]
	v_mfma_f32_16x16x32_bf16 v[140:143], v[128:131], v[168:171], v[140:143]
	v_mfma_f32_16x16x32_bf16 v[112:115], v[128:131], v[176:179], v[112:115]
	v_mfma_f32_16x16x32_bf16 v[112:115], v[124:127], v[172:175], v[112:115]
	v_mfma_f32_16x16x32_bf16 v[96:99], v[124:127], v[180:183], v[96:99]
	v_mfma_f32_16x16x32_bf16 v[96:99], v[128:131], v[184:187], v[96:99]
	v_mfma_f32_16x16x32_bf16 v[80:83], v[128:131], v[214:217], v[80:83]
	v_mfma_f32_16x16x32_bf16 v[80:83], v[124:127], v[188:191], v[80:83]
	v_mfma_f32_16x16x32_bf16 v[76:79], v[132:135], v[188:191], v[76:79]
	v_mfma_f32_16x16x32_bf16 v[76:79], v[144:147], v[214:217], v[76:79]
	v_mfma_f32_16x16x32_bf16 v[92:95], v[144:147], v[184:187], v[92:95]
	v_mfma_f32_16x16x32_bf16 v[92:95], v[132:135], v[180:183], v[92:95]
	v_mfma_f32_16x16x32_bf16 v[108:111], v[132:135], v[172:175], v[108:111]
	v_mfma_f32_16x16x32_bf16 v[108:111], v[144:147], v[176:179], v[108:111]
	v_mfma_f32_16x16x32_bf16 v[136:139], v[144:147], v[168:171], v[136:139]
	v_mfma_f32_16x16x32_bf16 v[136:139], v[132:135], v[164:167], v[136:139]
	v_mfma_f32_16x16x32_bf16 v[120:123], v[148:151], v[164:167], v[120:123]
	v_mfma_f32_16x16x32_bf16 v[120:123], v[152:155], v[168:171], v[120:123]
	v_mfma_f32_16x16x32_bf16 v[104:107], v[152:155], v[176:179], v[104:107]
	v_mfma_f32_16x16x32_bf16 v[104:107], v[148:151], v[172:175], v[104:107]
	v_mfma_f32_16x16x32_bf16 v[88:91], v[148:151], v[180:183], v[88:91]
	v_mfma_f32_16x16x32_bf16 v[88:91], v[152:155], v[184:187], v[88:91]
	v_mfma_f32_16x16x32_bf16 v[72:75], v[152:155], v[214:217], v[72:75]
	v_mfma_f32_16x16x32_bf16 v[72:75], v[148:151], v[188:191], v[72:75]
	v_mfma_f32_16x16x32_bf16 v[68:71], v[156:159], v[188:191], v[68:71]
	v_mfma_f32_16x16x32_bf16 v[68:71], v[160:163], v[214:217], v[68:71]
	v_mfma_f32_16x16x32_bf16 v[84:87], v[160:163], v[184:187], v[84:87]
	v_mfma_f32_16x16x32_bf16 v[84:87], v[156:159], v[180:183], v[84:87]
	v_mfma_f32_16x16x32_bf16 v[100:103], v[156:159], v[172:175], v[100:103]
	v_mfma_f32_16x16x32_bf16 v[100:103], v[160:163], v[176:179], v[100:103]
	v_mfma_f32_16x16x32_bf16 v[116:119], v[160:163], v[168:171], v[116:119]
	v_mfma_f32_16x16x32_bf16 v[116:119], v[156:159], v[164:167], v[116:119]
	s_setprio 0
	s_barrier
	s_add_i32 s36, s56, s40
	v_lshl_add_u64 v[218:219], v[218:219], 0, s[84:85]
	s_mov_b32 m0, s36
	ds_read_b128 v[164:167], v242 offset:49152
	ds_read_b128 v[168:171], v242 offset:50176
	ds_read_b128 v[172:175], v242 offset:51200
	ds_read_b128 v[176:179], v242 offset:52224
	ds_read_b128 v[180:183], v242 offset:53248
	ds_read_b128 v[184:187], v242 offset:54272
	ds_read_b128 v[188:191], v242 offset:55296
	ds_read_b128 v[214:217], v242 offset:56320
	global_load_lds_dwordx4 v[218:219], off
	s_add_i32 m0, s36, 0x2000
	s_add_u32 s26, s26, 0x100080
	v_lshl_add_u64 v[218:219], v[220:221], 0, s[84:85]
	s_addc_u32 s27, s27, 0
	s_add_i32 s36, s57, s40
	global_load_lds_dwordx4 v[218:219], off
	s_mov_b32 m0, s36
	s_nop 0
	global_load_lds_dwordx4 v2, s[26:27]
	s_add_i32 m0, s36, 0x2000
	s_nop 0
	global_load_lds_dwordx4 v204, s[26:27]
	s_cmp_eq_u32 s55, 60
	s_cbranch_scc0 .Ldefer_1456_peel
	v_lshl_add_u64 v[218:219], v[222:223], 0, s[84:85]
	s_mov_b32 m0, s45
	s_nop 0
	global_load_lds_dwordx4 v[218:219], off
	v_lshl_add_u64 v[218:219], v[224:225], 0, s[84:85]
	s_mov_b32 m0, s46
	s_nop 0
	global_load_lds_dwordx4 v[218:219], off
; #define PG8_STAGE(bufoff, gbase, voff) do { _Pragma("unroll") for (int _i = 0; _i < 2; ++_i) \
;         __builtin_amdgcn_global_load_lds((const unsigned*)((const char*)(gbase) + (voff)[_i]), (PG8_LAS unsigned*)(lds + (bufoff) + ldsw + _i * 8192), 16, 0, 0); } while (0)
; #define PG8_LDA(dst, b, h) do { _Pragma("unroll") for (int m = 0; m < 4; ++m) _Pragma("unroll") for (int k = 0; k < 2; ++k) dst[m][k] = *(const PG8_LAS bf16x8*)(lds + PG8_SA(b, h) + aoff + m * 2048 + k * 1024); } while (0)
; #define PG8_LDB(dst, b, h) do { _Pragma("unroll") for (int n = 0; n < 2; ++n) _Pragma("unroll") for (int k = 0; k < 2; ++k) dst[n][k] = *(const PG8_LAS bf16x8*)(lds + PG8_SB(b, h) + boff + n * 2048 + k * 1024); } while (0)
; #define PG8_WAIT_V(n) asm volatile("s_waitcnt vmcnt(" #n ")" ::: "memory")
; #define PG8_WAIT_L(n) asm volatile("s_waitcnt lgkmcnt(" #n ")" ::: "memory")
; #define PG8_BAR __builtin_amdgcn_s_barrier()
; #define PG8_SCHED __builtin_amdgcn_sched_barrier(0)
; template <class Epi, class Sched, bool ALIGN_EPI = false, bool SP2 = false, bool I8 = false>
; __device__ __forceinline__ void gemm_phase(PG8_LAS unsigned char* lds, const Gemm g, const Sched& S, const Epi& E) {
;     ...
;         for (int t = 0; t < nt; t += 2) {
;             const bool last = (t == nt - 2);
;             const char* a1 = cA + (size_t)(t + 1) * kstep;
;             const char* a2 = last ? nA : cA + (size_t)(t + 2) * kstep; const char* b2 = last ? nB : cB + (size_t)(t + 2) * kstep;
;             const char* a3 = a2 + kstep; const char* b3 = b2 + kstep;
;             if (last && has_next) S.a_ready(nxt);
;             if constexpr (SP2) {
;             PG8_LDB(B0, 0, 0); PG8_LDB(B1, 0, 1); PG8_SCHED; PG8_LDA(At, 0, 0); PG8_STAGE(PG8_SA(1, 1), a1 + hstep, voffA);
;             PG8_WAIT_V(8); PG8_WAIT_L(0); PG8_BAR; PG8_MMA(0, 0, At, B0); PG8_MMA(0, 1, At, B1); PG8_BAR; PG8_SCHED;
.Ldefer_1456_peel:
	s_waitcnt vmcnt(6) lgkmcnt(0)
	s_barrier
	s_setprio 1
	v_mfma_f32_16x16x32_bf16 v[64:67], v[124:127], v[164:167], v[64:67]
	v_mfma_f32_16x16x32_bf16 v[64:67], v[128:131], v[168:171], v[64:67]
	v_mfma_f32_16x16x32_bf16 v[48:51], v[128:131], v[176:179], v[48:51]
	v_mfma_f32_16x16x32_bf16 v[48:51], v[124:127], v[172:175], v[48:51]
	v_mfma_f32_16x16x32_bf16 v[32:35], v[124:127], v[180:183], v[32:35]
	v_mfma_f32_16x16x32_bf16 v[32:35], v[128:131], v[184:187], v[32:35]
	v_mfma_f32_16x16x32_bf16 v[16:19], v[128:131], v[214:217], v[16:19]
	v_mfma_f32_16x16x32_bf16 v[16:19], v[124:127], v[188:191], v[16:19]
	v_mfma_f32_16x16x32_bf16 v[12:15], v[132:135], v[188:191], v[12:15]
	v_mfma_f32_16x16x32_bf16 v[12:15], v[144:147], v[214:217], v[12:15]
	v_mfma_f32_16x16x32_bf16 v[28:31], v[144:147], v[184:187], v[28:31]
	v_mfma_f32_16x16x32_bf16 v[28:31], v[132:135], v[180:183], v[28:31]
	v_mfma_f32_16x16x32_bf16 v[44:47], v[132:135], v[172:175], v[44:47]
	v_mfma_f32_16x16x32_bf16 v[44:47], v[144:147], v[176:179], v[44:47]
	v_mfma_f32_16x16x32_bf16 v[60:63], v[144:147], v[168:171], v[60:63]
	v_mfma_f32_16x16x32_bf16 v[60:63], v[132:135], v[164:167], v[60:63]
	v_mfma_f32_16x16x32_bf16 v[56:59], v[148:151], v[164:167], v[56:59]
	v_mfma_f32_16x16x32_bf16 v[56:59], v[152:155], v[168:171], v[56:59]
	v_mfma_f32_16x16x32_bf16 v[40:43], v[152:155], v[176:179], v[40:43]
	v_mfma_f32_16x16x32_bf16 v[40:43], v[148:151], v[172:175], v[40:43]
	v_mfma_f32_16x16x32_bf16 v[24:27], v[148:151], v[180:183], v[24:27]
	v_mfma_f32_16x16x32_bf16 v[24:27], v[152:155], v[184:187], v[24:27]
	v_mfma_f32_16x16x32_bf16 v[8:11], v[152:155], v[214:217], v[8:11]
	v_mfma_f32_16x16x32_bf16 v[8:11], v[148:151], v[188:191], v[8:11]
	v_mfma_f32_16x16x32_bf16 v[4:7], v[156:159], v[188:191], v[4:7]
	v_mfma_f32_16x16x32_bf16 v[4:7], v[160:163], v[214:217], v[4:7]
	v_mfma_f32_16x16x32_bf16 v[20:23], v[160:163], v[184:187], v[20:23]
	v_mfma_f32_16x16x32_bf16 v[20:23], v[156:159], v[180:183], v[20:23]
	v_mfma_f32_16x16x32_bf16 v[36:39], v[156:159], v[172:175], v[36:39]
	v_mfma_f32_16x16x32_bf16 v[36:39], v[160:163], v[176:179], v[36:39]
	v_mfma_f32_16x16x32_bf16 v[52:55], v[160:163], v[168:171], v[52:55]
	v_mfma_f32_16x16x32_bf16 v[52:55], v[156:159], v[164:167], v[52:55]
	s_setprio 0
	s_barrier
	s_add_i32 s55, s55, 2
	s_add_u32 s24, s24, 0x100
	s_addc_u32 s25, s25, 0
	s_add_u32 s53, s53, 0x100
	s_addc_u32 s54, s54, 0
	s_cmp_gt_u32 s55, 61
	s_cbranch_scc1 .Lkloop_exit_2
.LBB0_1456:
	s_add_u32 s26, s24, 0xfff00080
	s_addc_u32 s27, s25, -1
	s_add_i32 s56, 0, 0x10000
	s_cmp_eq_u32 s55, 60
	s_cselect_b32 s37, s17, s27
	s_cselect_b32 s36, s51, s26
	s_cselect_b32 s27, s19, s54
	s_cselect_b32 s26, s52, s53
	s_add_i32 s58, 0, 0x14000
	v_add_u32_e32 v144, s56, v240
	v_add_u32_e32 v160, s58, v240
	ds_read_b128 v[124:127], v144
	ds_read_b128 v[128:131], v144 offset:1024
	ds_read_b128 v[132:135], v144 offset:2048
	ds_read_b128 v[144:147], v144 offset:3072
	ds_read_b128 v[148:151], v160
	ds_read_b128 v[152:155], v160 offset:1024
	ds_read_b128 v[156:159], v160 offset:2048
	ds_read_b128 v[160:163], v160 offset:3072
	v_lshl_add_u64 v[218:219], v[222:223], 0, s[84:85]
	s_mov_b32 m0, s45
	s_nop 0
	global_load_lds_dwordx4 v[218:219], off
	v_lshl_add_u64 v[218:219], v[224:225], 0, s[84:85]
	s_mov_b32 m0, s46
	s_nop 0
	global_load_lds_dwordx4 v[218:219], off
	s_add_i32 m0, s41, 0xc000
	ds_read_b128 v[164:167], v242
	ds_read_b128 v[168:171], v242 offset:1024
	ds_read_b128 v[172:175], v242 offset:2048
	ds_read_b128 v[176:179], v242 offset:3072
	ds_read_b128 v[180:183], v242 offset:4096
	ds_read_b128 v[184:187], v242 offset:5120
	ds_read_b128 v[188:191], v242 offset:6144
	ds_read_b128 v[214:217], v242 offset:7168
	global_load_lds_dwordx4 v210, s[24:25]
	s_add_i32 m0, s41, 0xe000
	s_nop 0
	global_load_lds_dwordx4 v212, s[24:25]
	s_waitcnt vmcnt(8) lgkmcnt(0)
	s_barrier
	s_setprio 1
	v_mfma_f32_16x16x32_bf16 v[140:143], v[124:127], v[164:167], v[140:143]
	v_mfma_f32_16x16x32_bf16 v[140:143], v[128:131], v[168:171], v[140:143]
	v_mfma_f32_16x16x32_bf16 v[112:115], v[128:131], v[176:179], v[112:115]
	v_mfma_f32_16x16x32_bf16 v[112:115], v[124:127], v[172:175], v[112:115]
	v_mfma_f32_16x16x32_bf16 v[96:99], v[124:127], v[180:183], v[96:99]
	v_mfma_f32_16x16x32_bf16 v[96:99], v[128:131], v[184:187], v[96:99]
	v_mfma_f32_16x16x32_bf16 v[80:83], v[128:131], v[214:217], v[80:83]
	v_mfma_f32_16x16x32_bf16 v[80:83], v[124:127], v[188:191], v[80:83]
	v_mfma_f32_16x16x32_bf16 v[76:79], v[132:135], v[188:191], v[76:79]
	v_mfma_f32_16x16x32_bf16 v[76:79], v[144:147], v[214:217], v[76:79]
	v_mfma_f32_16x16x32_bf16 v[92:95], v[144:147], v[184:187], v[92:95]
	v_mfma_f32_16x16x32_bf16 v[92:95], v[132:135], v[180:183], v[92:95]
	v_mfma_f32_16x16x32_bf16 v[108:111], v[132:135], v[172:175], v[108:111]
	v_mfma_f32_16x16x32_bf16 v[108:111], v[144:147], v[176:179], v[108:111]
	v_mfma_f32_16x16x32_bf16 v[136:139], v[144:147], v[168:171], v[136:139]
	v_mfma_f32_16x16x32_bf16 v[136:139], v[132:135], v[164:167], v[136:139]
	v_mfma_f32_16x16x32_bf16 v[120:123], v[148:151], v[164:167], v[120:123]
	v_mfma_f32_16x16x32_bf16 v[120:123], v[152:155], v[168:171], v[120:123]
	v_mfma_f32_16x16x32_bf16 v[104:107], v[152:155], v[176:179], v[104:107]
	v_mfma_f32_16x16x32_bf16 v[104:107], v[148:151], v[172:175], v[104:107]
	v_mfma_f32_16x16x32_bf16 v[88:91], v[148:151], v[180:183], v[88:91]
	v_mfma_f32_16x16x32_bf16 v[88:91], v[152:155], v[184:187], v[88:91]
	v_mfma_f32_16x16x32_bf16 v[72:75], v[152:155], v[214:217], v[72:75]
	v_mfma_f32_16x16x32_bf16 v[72:75], v[148:151], v[188:191], v[72:75]
	v_mfma_f32_16x16x32_bf16 v[68:71], v[156:159], v[188:191], v[68:71]
	v_mfma_f32_16x16x32_bf16 v[68:71], v[160:163], v[214:217], v[68:71]
	v_mfma_f32_16x16x32_bf16 v[84:87], v[160:163], v[184:187], v[84:87]
	v_mfma_f32_16x16x32_bf16 v[84:87], v[156:159], v[180:183], v[84:87]
	v_mfma_f32_16x16x32_bf16 v[100:103], v[156:159], v[172:175], v[100:103]
	v_mfma_f32_16x16x32_bf16 v[100:103], v[160:163], v[176:179], v[100:103]
	v_mfma_f32_16x16x32_bf16 v[116:119], v[160:163], v[168:171], v[116:119]
	v_mfma_f32_16x16x32_bf16 v[116:119], v[156:159], v[164:167], v[116:119]
	s_setprio 0
	s_barrier
; #define PG8_STAGE(bufoff, gbase, voff) do { _Pragma("unroll") for (int _i = 0; _i < 2; ++_i) \
;         __builtin_amdgcn_global_load_lds((const unsigned*)((const char*)(gbase) + (voff)[_i]), (PG8_LAS unsigned*)(lds + (bufoff) + ldsw + _i * 8192), 16, 0, 0); } while (0)
; #define PG8_LDA(dst, b, h) do { _Pragma("unroll") for (int m = 0; m < 4; ++m) _Pragma("unroll") for (int k = 0; k < 2; ++k) dst[m][k] = *(const PG8_LAS bf16x8*)(lds + PG8_SA(b, h) + aoff + m * 2048 + k * 1024); } while (0)
; #define PG8_LDB(dst, b, h) do { _Pragma("unroll") for (int n = 0; n < 2; ++n) _Pragma("unroll") for (int k = 0; k < 2; ++k) dst[n][k] = *(const PG8_LAS bf16x8*)(lds + PG8_SB(b, h) + boff + n * 2048 + k * 1024); } while (0)
; #define PG8_WAIT_V(n) asm volatile("s_waitcnt vmcnt(" #n ")" ::: "memory")
; #define PG8_WAIT_L(n) asm volatile("s_waitcnt lgkmcnt(" #n ")" ::: "memory")
; #define PG8_BAR __builtin_amdgcn_s_barrier()
; #define PG8_SCHED __builtin_amdgcn_sched_barrier(0)
; template <class Epi, class Sched, bool ALIGN_EPI = false, bool SP2 = false, bool I8 = false>
; __device__ __forceinline__ void gemm_phase(PG8_LAS unsigned char* lds, const Gemm g, const Sched& S, const Epi& E) {
;     ...
;             PG8_LDA(At, 0, 1); PG8_STAGE(PG8_SB(0, 0), b2, voffB); PG8_STAGE(PG8_SB(0, 1), b2 + hstep, voffB); PG8_STAGE(PG8_SA(0, 0), a2, voffA);
;             PG8_WAIT_V(8); PG8_WAIT_L(0); PG8_BAR; PG8_MMA(1, 0, At, B0); PG8_MMA(1, 1, At, B1); PG8_BAR; PG8_SCHED;
;             PG8_LDB(B0, 1, 0); PG8_LDB(B1, 1, 1); PG8_SCHED; PG8_LDA(At, 1, 0); PG8_STAGE(PG8_SA(0, 1), a2 + hstep, voffA);
;             PG8_WAIT_V(8); PG8_WAIT_L(0); PG8_BAR; PG8_MMA(0, 0, At, B0); PG8_MMA(0, 1, At, B1); PG8_BAR; PG8_SCHED;
	s_add_i32 s56, s56, s40
	v_lshl_add_u64 v[218:219], s[26:27], 0, v[2:3]
	s_mov_b32 m0, s56
	ds_read_b128 v[164:167], v242 offset:16384
	ds_read_b128 v[168:171], v242 offset:17408
	ds_read_b128 v[172:175], v242 offset:18432
	ds_read_b128 v[176:179], v242 offset:19456
	ds_read_b128 v[180:183], v242 offset:20480
	ds_read_b128 v[184:187], v242 offset:21504
	ds_read_b128 v[188:191], v242 offset:22528
	ds_read_b128 v[214:217], v242 offset:23552
	global_load_lds_dwordx4 v[218:219], off
	s_add_i32 m0, s56, 0x2000
	s_add_u32 s56, s26, 0x100000
	v_lshl_add_u64 v[220:221], s[26:27], 0, v[204:205]
	s_addc_u32 s57, s27, 0
	s_add_i32 s58, s58, s40
	global_load_lds_dwordx4 v[220:221], off
	s_mov_b32 m0, s58
	v_lshl_add_u64 v[224:225], s[36:37], 0, v[206:207]
	global_load_lds_dwordx4 v2, s[56:57]
	s_add_i32 m0, s58, 0x2000
	s_nop 0
	global_load_lds_dwordx4 v204, s[56:57]
	v_lshl_add_u64 v[222:223], s[36:37], 0, v[208:209]
	s_waitcnt vmcnt(6) lgkmcnt(0)
	s_barrier
	s_setprio 1
	v_mfma_f32_16x16x32_bf16 v[64:67], v[124:127], v[164:167], v[64:67]
	v_mfma_f32_16x16x32_bf16 v[64:67], v[128:131], v[168:171], v[64:67]
	v_mfma_f32_16x16x32_bf16 v[48:51], v[128:131], v[176:179], v[48:51]
	v_mfma_f32_16x16x32_bf16 v[48:51], v[124:127], v[172:175], v[48:51]
	v_mfma_f32_16x16x32_bf16 v[32:35], v[124:127], v[180:183], v[32:35]
	v_mfma_f32_16x16x32_bf16 v[32:35], v[128:131], v[184:187], v[32:35]
	v_mfma_f32_16x16x32_bf16 v[16:19], v[128:131], v[214:217], v[16:19]
	v_mfma_f32_16x16x32_bf16 v[16:19], v[124:127], v[188:191], v[16:19]
	v_mfma_f32_16x16x32_bf16 v[12:15], v[132:135], v[188:191], v[12:15]
	v_mfma_f32_16x16x32_bf16 v[12:15], v[144:147], v[214:217], v[12:15]
	v_mfma_f32_16x16x32_bf16 v[28:31], v[144:147], v[184:187], v[28:31]
	v_mfma_f32_16x16x32_bf16 v[28:31], v[132:135], v[180:183], v[28:31]
	v_mfma_f32_16x16x32_bf16 v[44:47], v[132:135], v[172:175], v[44:47]
	v_mfma_f32_16x16x32_bf16 v[44:47], v[144:147], v[176:179], v[44:47]
	v_mfma_f32_16x16x32_bf16 v[60:63], v[144:147], v[168:171], v[60:63]
	v_mfma_f32_16x16x32_bf16 v[60:63], v[132:135], v[164:167], v[60:63]
	v_mfma_f32_16x16x32_bf16 v[56:59], v[148:151], v[164:167], v[56:59]
	v_mfma_f32_16x16x32_bf16 v[56:59], v[152:155], v[168:171], v[56:59]
	v_mfma_f32_16x16x32_bf16 v[40:43], v[152:155], v[176:179], v[40:43]
	v_mfma_f32_16x16x32_bf16 v[40:43], v[148:151], v[172:175], v[40:43]
	v_mfma_f32_16x16x32_bf16 v[24:27], v[148:151], v[180:183], v[24:27]
	v_mfma_f32_16x16x32_bf16 v[24:27], v[152:155], v[184:187], v[24:27]
	v_mfma_f32_16x16x32_bf16 v[8:11], v[152:155], v[214:217], v[8:11]
	v_mfma_f32_16x16x32_bf16 v[8:11], v[148:151], v[188:191], v[8:11]
	v_mfma_f32_16x16x32_bf16 v[4:7], v[156:159], v[188:191], v[4:7]
	v_mfma_f32_16x16x32_bf16 v[4:7], v[160:163], v[214:217], v[4:7]
	v_mfma_f32_16x16x32_bf16 v[20:23], v[160:163], v[184:187], v[20:23]
	v_mfma_f32_16x16x32_bf16 v[20:23], v[156:159], v[180:183], v[20:23]
	v_mfma_f32_16x16x32_bf16 v[36:39], v[156:159], v[172:175], v[36:39]
	v_mfma_f32_16x16x32_bf16 v[36:39], v[160:163], v[176:179], v[36:39]
	v_mfma_f32_16x16x32_bf16 v[52:55], v[160:163], v[168:171], v[52:55]
	v_mfma_f32_16x16x32_bf16 v[52:55], v[156:159], v[164:167], v[52:55]
	s_setprio 0
	s_barrier
	s_mov_b32 m0, s41
	s_nop 0
	global_load_lds_dwordx4 v[222:223], off
	s_mov_b32 m0, s42
	s_nop 0
	global_load_lds_dwordx4 v[224:225], off
	s_add_i32 s56, 0, 0x18000
	s_add_i32 s57, 0, 0x1c000
	v_add_u32_e32 v144, s56, v240
	v_add_u32_e32 v160, s57, v240
	ds_read_b128 v[124:127], v144
	ds_read_b128 v[128:131], v144 offset:1024
	ds_read_b128 v[132:135], v144 offset:2048
	ds_read_b128 v[144:147], v144 offset:3072
	ds_read_b128 v[148:151], v160
	ds_read_b128 v[152:155], v160 offset:1024
	ds_read_b128 v[156:159], v160 offset:2048
	ds_read_b128 v[160:163], v160 offset:3072
	s_add_u32 s36, s36, 0x100000
	s_addc_u32 s37, s37, 0
	s_mov_b32 m0, s43
	ds_read_b128 v[164:167], v242 offset:32768
	ds_read_b128 v[168:171], v242 offset:33792
	ds_read_b128 v[172:175], v242 offset:34816
	ds_read_b128 v[176:179], v242 offset:35840
	ds_read_b128 v[180:183], v242 offset:36864
	ds_read_b128 v[184:187], v242 offset:37888
	ds_read_b128 v[188:191], v242 offset:38912
	ds_read_b128 v[214:217], v242 offset:39936
	global_load_lds_dwordx4 v208, s[36:37]
	s_mov_b32 m0, s44
	s_nop 0
	global_load_lds_dwordx4 v206, s[36:37]
	s_waitcnt vmcnt(8) lgkmcnt(0)
	s_barrier
; #define PG8_STAGE(bufoff, gbase, voff) do { _Pragma("unroll") for (int _i = 0; _i < 2; ++_i) \
;         __builtin_amdgcn_global_load_lds((const unsigned*)((const char*)(gbase) + (voff)[_i]), (PG8_LAS unsigned*)(lds + (bufoff) + ldsw + _i * 8192), 16, 0, 0); } while (0)
; #define PG8_LDA(dst, b, h) do { _Pragma("unroll") for (int m = 0; m < 4; ++m) _Pragma("unroll") for (int k = 0; k < 2; ++k) dst[m][k] = *(const PG8_LAS bf16x8*)(lds + PG8_SA(b, h) + aoff + m * 2048 + k * 1024); } while (0)
; #define PG8_WAIT_V(n) asm volatile("s_waitcnt vmcnt(" #n ")" ::: "memory")
; #define PG8_WAIT_L(n) asm volatile("s_waitcnt lgkmcnt(" #n ")" ::: "memory")
; #define PG8_BAR __builtin_amdgcn_s_barrier()
; #define PG8_SCHED __builtin_amdgcn_sched_barrier(0)
; template <class Epi, class Sched, bool ALIGN_EPI = false, bool SP2 = false, bool I8 = false>
; __device__ __forceinline__ void gemm_phase(PG8_LAS unsigned char* lds, const Gemm g, const Sched& S, const Epi& E) {
;     ...
;             PG8_WAIT_V(8); PG8_WAIT_L(0); PG8_BAR; PG8_MMA(0, 0, At, B0); PG8_MMA(0, 1, At, B1); PG8_BAR; PG8_SCHED;
;             PG8_LDA(At, 1, 1); PG8_STAGE(PG8_SB(1, 0), b3, voffB); PG8_STAGE(PG8_SB(1, 1), b3 + hstep, voffB); PG8_STAGE(PG8_SA(1, 0), a3, voffA);
;             PG8_WAIT_V(8); PG8_WAIT_L(0); PG8_BAR; PG8_MMA(1, 0, At, B0); PG8_MMA(1, 1, At, B1); PG8_BAR; PG8_SCHED;
	s_setprio 1
	v_mfma_f32_16x16x32_bf16 v[140:143], v[124:127], v[164:167], v[140:143]
	v_mfma_f32_16x16x32_bf16 v[140:143], v[128:131], v[168:171], v[140:143]
	v_mfma_f32_16x16x32_bf16 v[112:115], v[128:131], v[176:179], v[112:115]
	v_mfma_f32_16x16x32_bf16 v[112:115], v[124:127], v[172:175], v[112:115]
	v_mfma_f32_16x16x32_bf16 v[96:99], v[124:127], v[180:183], v[96:99]
	v_mfma_f32_16x16x32_bf16 v[96:99], v[128:131], v[184:187], v[96:99]
	v_mfma_f32_16x16x32_bf16 v[80:83], v[128:131], v[214:217], v[80:83]
	v_mfma_f32_16x16x32_bf16 v[80:83], v[124:127], v[188:191], v[80:83]
	v_mfma_f32_16x16x32_bf16 v[76:79], v[132:135], v[188:191], v[76:79]
	v_mfma_f32_16x16x32_bf16 v[76:79], v[144:147], v[214:217], v[76:79]
	v_mfma_f32_16x16x32_bf16 v[92:95], v[144:147], v[184:187], v[92:95]
	v_mfma_f32_16x16x32_bf16 v[92:95], v[132:135], v[180:183], v[92:95]
	v_mfma_f32_16x16x32_bf16 v[108:111], v[132:135], v[172:175], v[108:111]
	v_mfma_f32_16x16x32_bf16 v[108:111], v[144:147], v[176:179], v[108:111]
	v_mfma_f32_16x16x32_bf16 v[136:139], v[144:147], v[168:171], v[136:139]
	v_mfma_f32_16x16x32_bf16 v[136:139], v[132:135], v[164:167], v[136:139]
	v_mfma_f32_16x16x32_bf16 v[120:123], v[148:151], v[164:167], v[120:123]
	v_mfma_f32_16x16x32_bf16 v[120:123], v[152:155], v[168:171], v[120:123]
	v_mfma_f32_16x16x32_bf16 v[104:107], v[152:155], v[176:179], v[104:107]
	v_mfma_f32_16x16x32_bf16 v[104:107], v[148:151], v[172:175], v[104:107]
	v_mfma_f32_16x16x32_bf16 v[88:91], v[148:151], v[180:183], v[88:91]
	v_mfma_f32_16x16x32_bf16 v[88:91], v[152:155], v[184:187], v[88:91]
	v_mfma_f32_16x16x32_bf16 v[72:75], v[152:155], v[214:217], v[72:75]
	v_mfma_f32_16x16x32_bf16 v[72:75], v[148:151], v[188:191], v[72:75]
	v_mfma_f32_16x16x32_bf16 v[68:71], v[156:159], v[188:191], v[68:71]
	v_mfma_f32_16x16x32_bf16 v[68:71], v[160:163], v[214:217], v[68:71]
	v_mfma_f32_16x16x32_bf16 v[84:87], v[160:163], v[184:187], v[84:87]
	v_mfma_f32_16x16x32_bf16 v[84:87], v[156:159], v[180:183], v[84:87]
	v_mfma_f32_16x16x32_bf16 v[100:103], v[156:159], v[172:175], v[100:103]
	v_mfma_f32_16x16x32_bf16 v[100:103], v[160:163], v[176:179], v[100:103]
	v_mfma_f32_16x16x32_bf16 v[116:119], v[160:163], v[168:171], v[116:119]
	v_mfma_f32_16x16x32_bf16 v[116:119], v[156:159], v[164:167], v[116:119]
	s_setprio 0
	s_barrier
	s_add_i32 s36, s56, s40
	v_lshl_add_u64 v[218:219], v[218:219], 0, s[84:85]
	s_mov_b32 m0, s36
	ds_read_b128 v[164:167], v242 offset:49152
	ds_read_b128 v[168:171], v242 offset:50176
	ds_read_b128 v[172:175], v242 offset:51200
	ds_read_b128 v[176:179], v242 offset:52224
	ds_read_b128 v[180:183], v242 offset:53248
	ds_read_b128 v[184:187], v242 offset:54272
	ds_read_b128 v[188:191], v242 offset:55296
	ds_read_b128 v[214:217], v242 offset:56320
	global_load_lds_dwordx4 v[218:219], off
	s_add_i32 m0, s36, 0x2000
	s_add_u32 s26, s26, 0x100080
	v_lshl_add_u64 v[218:219], v[220:221], 0, s[84:85]
	s_addc_u32 s27, s27, 0
	s_add_i32 s36, s57, s40
	global_load_lds_dwordx4 v[218:219], off
	s_mov_b32 m0, s36
	s_nop 0
	global_load_lds_dwordx4 v2, s[26:27]
	s_add_i32 m0, s36, 0x2000
	s_nop 0
	global_load_lds_dwordx4 v204, s[26:27]
	s_cmp_eq_u32 s55, 60
	s_cbranch_scc0 .Ldefer_1456_body
	v_lshl_add_u64 v[218:219], v[222:223], 0, s[84:85]
	s_mov_b32 m0, s45
	s_nop 0
	global_load_lds_dwordx4 v[218:219], off
	v_lshl_add_u64 v[218:219], v[224:225], 0, s[84:85]
	s_mov_b32 m0, s46
	s_nop 0
	global_load_lds_dwordx4 v[218:219], off
.Ldefer_1456_body:
	s_waitcnt vmcnt(6) lgkmcnt(0)
	s_barrier
	s_setprio 1
	v_mfma_f32_16x16x32_bf16 v[64:67], v[124:127], v[164:167], v[64:67]
	v_mfma_f32_16x16x32_bf16 v[64:67], v[128:131], v[168:171], v[64:67]
	v_mfma_f32_16x16x32_bf16 v[48:51], v[128:131], v[176:179], v[48:51]
	v_mfma_f32_16x16x32_bf16 v[48:51], v[124:127], v[172:175], v[48:51]
	v_mfma_f32_16x16x32_bf16 v[32:35], v[124:127], v[180:183], v[32:35]
	v_mfma_f32_16x16x32_bf16 v[32:35], v[128:131], v[184:187], v[32:35]
	v_mfma_f32_16x16x32_bf16 v[16:19], v[128:131], v[214:217], v[16:19]
	v_mfma_f32_16x16x32_bf16 v[16:19], v[124:127], v[188:191], v[16:19]
	v_mfma_f32_16x16x32_bf16 v[12:15], v[132:135], v[188:191], v[12:15]
	v_mfma_f32_16x16x32_bf16 v[12:15], v[144:147], v[214:217], v[12:15]
	v_mfma_f32_16x16x32_bf16 v[28:31], v[144:147], v[184:187], v[28:31]
	v_mfma_f32_16x16x32_bf16 v[28:31], v[132:135], v[180:183], v[28:31]
	v_mfma_f32_16x16x32_bf16 v[44:47], v[132:135], v[172:175], v[44:47]
	v_mfma_f32_16x16x32_bf16 v[44:47], v[144:147], v[176:179], v[44:47]
	v_mfma_f32_16x16x32_bf16 v[60:63], v[144:147], v[168:171], v[60:63]
	v_mfma_f32_16x16x32_bf16 v[60:63], v[132:135], v[164:167], v[60:63]
	v_mfma_f32_16x16x32_bf16 v[56:59], v[148:151], v[164:167], v[56:59]
	v_mfma_f32_16x16x32_bf16 v[56:59], v[152:155], v[168:171], v[56:59]
	v_mfma_f32_16x16x32_bf16 v[40:43], v[152:155], v[176:179], v[40:43]
	v_mfma_f32_16x16x32_bf16 v[40:43], v[148:151], v[172:175], v[40:43]
	v_mfma_f32_16x16x32_bf16 v[24:27], v[148:151], v[180:183], v[24:27]
	v_mfma_f32_16x16x32_bf16 v[24:27], v[152:155], v[184:187], v[24:27]
	v_mfma_f32_16x16x32_bf16 v[8:11], v[152:155], v[214:217], v[8:11]
	v_mfma_f32_16x16x32_bf16 v[8:11], v[148:151], v[188:191], v[8:11]
	v_mfma_f32_16x16x32_bf16 v[4:7], v[156:159], v[188:191], v[4:7]
	v_mfma_f32_16x16x32_bf16 v[4:7], v[160:163], v[214:217], v[4:7]
	v_mfma_f32_16x16x32_bf16 v[20:23], v[160:163], v[184:187], v[20:23]
	v_mfma_f32_16x16x32_bf16 v[20:23], v[156:159], v[180:183], v[20:23]
	v_mfma_f32_16x16x32_bf16 v[36:39], v[156:159], v[172:175], v[36:39]
	v_mfma_f32_16x16x32_bf16 v[36:39], v[160:163], v[176:179], v[36:39]
	v_mfma_f32_16x16x32_bf16 v[52:55], v[160:163], v[168:171], v[52:55]
	v_mfma_f32_16x16x32_bf16 v[52:55], v[156:159], v[164:167], v[52:55]
	s_setprio 0
	s_barrier
	s_add_i32 s55, s55, 2
	s_add_u32 s24, s24, 0x100
	s_addc_u32 s25, s25, 0
	s_add_u32 s53, s53, 0x100
	s_addc_u32 s54, s54, 0
	s_cmp_gt_u32 s55, 61
	s_cbranch_scc0 .LBB0_1456

; #define PG8_STAGE(bufoff, gbase, voff) do { _Pragma("unroll") for (int _i = 0; _i < 2; ++_i) \
;         __builtin_amdgcn_global_load_lds((const unsigned*)((const char*)(gbase) + (voff)[_i]), (PG8_LAS unsigned*)(lds + (bufoff) + ldsw + _i * 8192), 16, 0, 0); } while (0)
; #define PG8_LDA(dst, b, h) do { _Pragma("unroll") for (int m = 0; m < 4; ++m) _Pragma("unroll") for (int k = 0; k < 2; ++k) dst[m][k] = *(const PG8_LAS bf16x8*)(lds + PG8_SA(b, h) + aoff + m * 2048 + k * 1024); } while (0)
; #define PG8_LDB(dst, b, h) do { _Pragma("unroll") for (int n = 0; n < 2; ++n) _Pragma("unroll") for (int k = 0; k < 2; ++k) dst[n][k] = *(const PG8_LAS bf16x8*)(lds + PG8_SB(b, h) + boff + n * 2048 + k * 1024); } while (0)
; #define PG8_WAIT_V(n) asm volatile("s_waitcnt vmcnt(" #n ")" ::: "memory")
; #define PG8_WAIT_L(n) asm volatile("s_waitcnt lgkmcnt(" #n ")" ::: "memory")
; #define PG8_BAR __builtin_amdgcn_s_barrier()
; #define PG8_SCHED __builtin_amdgcn_sched_barrier(0)
; template <class Epi, class Sched, bool ALIGN_EPI = false, bool SP2 = false, bool I8 = false>
; __device__ __forceinline__ void gemm_phase(PG8_LAS unsigned char* lds, const Gemm g, const Sched& S, const Epi& E) {
;     ...
;         const bool has_next = S.next(ui + 1, nxt);
;         const char* nA = has_next ? (const char*)g.A + (size_t)nxt.pm * tstep : cA; const char* nB = has_next ? (const char*)g.Bt + (size_t)nxt.pn * tstep : cB;
;         for (int t = 0; t < nt; t += 2) {
;             const bool last = (t == nt - 2);
;             const char* a1 = cA + (size_t)(t + 1) * kstep;
;             const char* a2 = last ? nA : cA + (size_t)(t + 2) * kstep; const char* b2 = last ? nB : cB + (size_t)(t + 2) * kstep;
;             const char* a3 = a2 + kstep; const char* b3 = b2 + kstep;
;             if (last && has_next) S.a_ready(nxt);
;             if constexpr (SP2) {
;             PG8_LDB(B0, 0, 0); PG8_LDB(B1, 0, 1); PG8_SCHED; PG8_LDA(At, 0, 0); PG8_STAGE(PG8_SA(1, 1), a1 + hstep, voffA);
;             PG8_WAIT_V(8); PG8_WAIT_L(0); PG8_BAR; PG8_MMA(0, 0, At, B0); PG8_MMA(0, 1, At, B1); PG8_BAR; PG8_SCHED;
;             PG8_LDA(At, 0, 1); PG8_STAGE(PG8_SB(0, 0), b2, voffB); PG8_STAGE(PG8_SB(0, 1), b2 + hstep, voffB); PG8_STAGE(PG8_SA(0, 0), a2, voffA);
;             PG8_WAIT_V(8); PG8_WAIT_L(0); PG8_BAR; PG8_MMA(1, 0, At, B0); PG8_MMA(1, 1, At, B1); PG8_BAR; PG8_SCHED;
.LBB0_1590:
	s_ashr_i32 s25, s24, 31
	s_lshl_b64 s[26:27], s[24:25], 20
	s_add_u32 s26, s28, s26
	s_addc_u32 s27, s42, s27
	s_and_b64 s[36:37], s[10:11], exec
	s_cselect_b32 s25, s27, s41
	s_cselect_b32 s57, s26, s40
	s_ashr_i32 s23, s22, 31
	s_lshl_b64 s[36:37], s[22:23], 20
	s_add_u32 s36, s43, s36
	s_addc_u32 s37, s46, s37
	s_and_b64 s[48:49], s[10:11], exec
	s_cselect_b32 s23, s37, s45
	s_cselect_b32 s58, s36, s44
	s_add_u32 s40, s40, 0x80080
	s_addc_u32 s41, s41, 0
	s_add_u32 s59, s44, 0x100
	s_addc_u32 s60, s45, 0
	s_mov_b32 s61, -2
	s_add_u32 s44, s40, 0xfff80080
	s_addc_u32 s45, s41, -1
	s_add_i32 s64, 0, 0x10000
	s_cmp_eq_u32 s61, 28
	s_cselect_b32 s49, s25, s45
	s_cselect_b32 s48, s57, s44
	s_cselect_b32 s45, s23, s60
	s_cselect_b32 s44, s58, s59
	s_add_i32 s67, 0, 0x14000
	v_add_u32_e32 v144, s64, v167
	v_add_u32_e32 v158, s67, v167
	ds_read_b128 v[36:39], v144
	ds_read_b128 v[44:47], v144 offset:1024
	ds_read_b128 v[140:143], v144 offset:2048
	ds_read_b128 v[144:147], v144 offset:3072
	ds_read_b128 v[160:163], v158
	ds_read_b128 v[172:175], v158 offset:1024
	ds_read_b128 v[176:179], v158 offset:2048
	ds_read_b128 v[180:183], v158 offset:3072
	s_add_i32 m0, s50, 0xc000
	ds_read_b128 v[184:187], v171
	ds_read_b128 v[188:191], v171 offset:1024
	ds_read_b128 v[204:207], v171 offset:2048
	ds_read_b128 v[208:211], v171 offset:3072
	ds_read_b128 v[212:215], v171 offset:4096
	ds_read_b128 v[216:219], v171 offset:5120
	ds_read_b128 v[220:223], v171 offset:6144
	ds_read_b128 v[224:227], v171 offset:7168
	global_load_lds_dwordx4 v154, s[40:41]
	s_add_i32 m0, s50, 0xe000
	s_nop 0
	global_load_lds_dwordx4 v156, s[40:41]
	s_waitcnt vmcnt(8) lgkmcnt(0)
	s_barrier
	s_setprio 1
	v_mfma_i32_16x16x64_i8 v[136:139], v[36:39], v[184:187], 0
	v_mfma_i32_16x16x64_i8 v[136:139], v[44:47], v[188:191], v[136:139]
	v_mfma_i32_16x16x64_i8 v[120:123], v[44:47], v[208:211], 0
	v_mfma_i32_16x16x64_i8 v[120:123], v[36:39], v[204:207], v[120:123]
	v_mfma_i32_16x16x64_i8 v[104:107], v[36:39], v[212:215], 0
	v_mfma_i32_16x16x64_i8 v[104:107], v[44:47], v[216:219], v[104:107]
	v_mfma_i32_16x16x64_i8 v[88:91], v[44:47], v[224:227], 0
	v_mfma_i32_16x16x64_i8 v[88:91], v[36:39], v[220:223], v[88:91]
	v_mfma_i32_16x16x64_i8 v[80:83], v[140:143], v[220:223], 0
	v_mfma_i32_16x16x64_i8 v[80:83], v[144:147], v[224:227], v[80:83]
	v_mfma_i32_16x16x64_i8 v[96:99], v[144:147], v[216:219], 0
	v_mfma_i32_16x16x64_i8 v[96:99], v[140:143], v[212:215], v[96:99]
	v_mfma_i32_16x16x64_i8 v[112:115], v[140:143], v[204:207], 0
	v_mfma_i32_16x16x64_i8 v[112:115], v[144:147], v[208:211], v[112:115]
	v_mfma_i32_16x16x64_i8 v[128:131], v[144:147], v[188:191], 0
	v_mfma_i32_16x16x64_i8 v[128:131], v[140:143], v[184:187], v[128:131]
	v_mfma_i32_16x16x64_i8 v[132:135], v[160:163], v[184:187], 0
	v_mfma_i32_16x16x64_i8 v[132:135], v[172:175], v[188:191], v[132:135]
	v_mfma_i32_16x16x64_i8 v[116:119], v[172:175], v[208:211], 0
	v_mfma_i32_16x16x64_i8 v[116:119], v[160:163], v[204:207], v[116:119]
	v_mfma_i32_16x16x64_i8 v[100:103], v[160:163], v[212:215], 0
	v_mfma_i32_16x16x64_i8 v[100:103], v[172:175], v[216:219], v[100:103]
	v_mfma_i32_16x16x64_i8 v[84:87], v[172:175], v[224:227], 0
	v_mfma_i32_16x16x64_i8 v[84:87], v[160:163], v[220:223], v[84:87]
	v_mfma_i32_16x16x64_i8 v[76:79], v[176:179], v[220:223], 0
	v_mfma_i32_16x16x64_i8 v[76:79], v[180:183], v[224:227], v[76:79]
	v_mfma_i32_16x16x64_i8 v[92:95], v[180:183], v[216:219], 0
	v_mfma_i32_16x16x64_i8 v[92:95], v[176:179], v[212:215], v[92:95]
	v_mfma_i32_16x16x64_i8 v[108:111], v[176:179], v[204:207], 0
	v_mfma_i32_16x16x64_i8 v[108:111], v[180:183], v[208:211], v[108:111]
	v_mfma_i32_16x16x64_i8 v[124:127], v[180:183], v[188:191], 0
	v_mfma_i32_16x16x64_i8 v[124:127], v[176:179], v[184:187], v[124:127]
	s_setprio 0
	s_barrier
	s_add_i32 s64, s64, s47
	v_lshl_add_u64 v[164:165], s[44:45], 0, v[2:3]
	s_mov_b32 m0, s64
	ds_read_b128 v[184:187], v171 offset:16384
	ds_read_b128 v[188:191], v171 offset:17408
	ds_read_b128 v[204:207], v171 offset:18432
	ds_read_b128 v[208:211], v171 offset:19456
	ds_read_b128 v[212:215], v171 offset:20480
	ds_read_b128 v[216:219], v171 offset:21504
	ds_read_b128 v[220:223], v171 offset:22528
	ds_read_b128 v[224:227], v171 offset:23552
	global_load_lds_dwordx4 v[164:165], off
	s_add_i32 m0, s64, 0x2000
	s_add_u32 s64, s44, 0x80000
	v_lshl_add_u64 v[228:229], s[44:45], 0, v[148:149]
	s_addc_u32 s65, s45, 0
	s_add_i32 s67, s67, s47
	global_load_lds_dwordx4 v[228:229], off
	s_mov_b32 m0, s67
	v_lshl_add_u64 v[242:243], s[48:49], 0, v[150:151]
	global_load_lds_dwordx4 v2, s[64:65]
	s_add_i32 m0, s67, 0x2000
	s_nop 0
	global_load_lds_dwordx4 v148, s[64:65]
	v_lshl_add_u64 v[240:241], s[48:49], 0, v[152:153]
	s_waitcnt vmcnt(6) lgkmcnt(0)
	s_barrier
; #define PG8_STAGE(bufoff, gbase, voff) do { _Pragma("unroll") for (int _i = 0; _i < 2; ++_i) \
;         __builtin_amdgcn_global_load_lds((const unsigned*)((const char*)(gbase) + (voff)[_i]), (PG8_LAS unsigned*)(lds + (bufoff) + ldsw + _i * 8192), 16, 0, 0); } while (0)
; #define PG8_LDA(dst, b, h) do { _Pragma("unroll") for (int m = 0; m < 4; ++m) _Pragma("unroll") for (int k = 0; k < 2; ++k) dst[m][k] = *(const PG8_LAS bf16x8*)(lds + PG8_SA(b, h) + aoff + m * 2048 + k * 1024); } while (0)
; #define PG8_LDB(dst, b, h) do { _Pragma("unroll") for (int n = 0; n < 2; ++n) _Pragma("unroll") for (int k = 0; k < 2; ++k) dst[n][k] = *(const PG8_LAS bf16x8*)(lds + PG8_SB(b, h) + boff + n * 2048 + k * 1024); } while (0)
; #define PG8_WAIT_V(n) asm volatile("s_waitcnt vmcnt(" #n ")" ::: "memory")
; #define PG8_WAIT_L(n) asm volatile("s_waitcnt lgkmcnt(" #n ")" ::: "memory")
; #define PG8_BAR __builtin_amdgcn_s_barrier()
; #define PG8_SCHED __builtin_amdgcn_sched_barrier(0)
; template <class Epi, class Sched, bool ALIGN_EPI = false, bool SP2 = false, bool I8 = false>
; __device__ __forceinline__ void gemm_phase(PG8_LAS unsigned char* lds, const Gemm g, const Sched& S, const Epi& E) {
;     ...
;             PG8_WAIT_V(8); PG8_WAIT_L(0); PG8_BAR; PG8_MMA(0, 0, At, B0); PG8_MMA(0, 1, At, B1); PG8_BAR; PG8_SCHED;
;             PG8_LDA(At, 0, 1); PG8_STAGE(PG8_SB(0, 0), b2, voffB); PG8_STAGE(PG8_SB(0, 1), b2 + hstep, voffB); PG8_STAGE(PG8_SA(0, 0), a2, voffA);
;             PG8_WAIT_V(8); PG8_WAIT_L(0); PG8_BAR; PG8_MMA(1, 0, At, B0); PG8_MMA(1, 1, At, B1); PG8_BAR; PG8_SCHED;
;             PG8_LDB(B0, 1, 0); PG8_LDB(B1, 1, 1); PG8_SCHED; PG8_LDA(At, 1, 0); PG8_STAGE(PG8_SA(0, 1), a2 + hstep, voffA);
;             PG8_WAIT_V(8); PG8_WAIT_L(0); PG8_BAR; PG8_MMA(0, 0, At, B0); PG8_MMA(0, 1, At, B1); PG8_BAR; PG8_SCHED;
;             PG8_LDA(At, 1, 1); PG8_STAGE(PG8_SB(1, 0), b3, voffB); PG8_STAGE(PG8_SB(1, 1), b3 + hstep, voffB); PG8_STAGE(PG8_SA(1, 0), a3, voffA);
	s_setprio 1
	v_mfma_i32_16x16x64_i8 v[72:75], v[36:39], v[184:187], 0
	v_mfma_i32_16x16x64_i8 v[72:75], v[44:47], v[188:191], v[72:75]
	v_mfma_i32_16x16x64_i8 v[56:59], v[44:47], v[208:211], 0
	v_mfma_i32_16x16x64_i8 v[56:59], v[36:39], v[204:207], v[56:59]
	v_mfma_i32_16x16x64_i8 v[32:35], v[36:39], v[212:215], 0
	v_mfma_i32_16x16x64_i8 v[32:35], v[44:47], v[216:219], v[32:35]
	v_mfma_i32_16x16x64_i8 v[16:19], v[44:47], v[224:227], 0
	v_mfma_i32_16x16x64_i8 v[16:19], v[36:39], v[220:223], v[16:19]
	v_mfma_i32_16x16x64_i8 v[8:11], v[140:143], v[220:223], 0
	v_mfma_i32_16x16x64_i8 v[8:11], v[144:147], v[224:227], v[8:11]
	v_mfma_i32_16x16x64_i8 v[24:27], v[144:147], v[216:219], 0
	v_mfma_i32_16x16x64_i8 v[24:27], v[140:143], v[212:215], v[24:27]
	v_mfma_i32_16x16x64_i8 v[48:51], v[140:143], v[204:207], 0
	v_mfma_i32_16x16x64_i8 v[48:51], v[144:147], v[208:211], v[48:51]
	v_mfma_i32_16x16x64_i8 v[64:67], v[144:147], v[188:191], 0
	v_mfma_i32_16x16x64_i8 v[64:67], v[140:143], v[184:187], v[64:67]
	v_mfma_i32_16x16x64_i8 v[36:39], v[160:163], v[184:187], 0
	v_mfma_i32_16x16x64_i8 v[36:39], v[172:175], v[188:191], v[36:39]
	v_mfma_i32_16x16x64_i8 v[52:55], v[172:175], v[208:211], 0
	v_mfma_i32_16x16x64_i8 v[52:55], v[160:163], v[204:207], v[52:55]
	v_mfma_i32_16x16x64_i8 v[28:31], v[160:163], v[212:215], 0
	v_mfma_i32_16x16x64_i8 v[28:31], v[172:175], v[216:219], v[28:31]
	v_mfma_i32_16x16x64_i8 v[12:15], v[172:175], v[224:227], 0
	v_mfma_i32_16x16x64_i8 v[12:15], v[160:163], v[220:223], v[12:15]
	v_mfma_i32_16x16x64_i8 v[4:7], v[176:179], v[220:223], 0
	v_mfma_i32_16x16x64_i8 v[4:7], v[180:183], v[224:227], v[4:7]
	v_mfma_i32_16x16x64_i8 v[20:23], v[180:183], v[216:219], 0
	v_mfma_i32_16x16x64_i8 v[20:23], v[176:179], v[212:215], v[20:23]
	v_mfma_i32_16x16x64_i8 v[40:43], v[176:179], v[204:207], 0
	v_mfma_i32_16x16x64_i8 v[40:43], v[180:183], v[208:211], v[40:43]
	v_mfma_i32_16x16x64_i8 v[44:47], v[180:183], v[188:191], 0
	v_mfma_i32_16x16x64_i8 v[44:47], v[176:179], v[184:187], v[44:47]
	s_setprio 0
	s_barrier
	s_mov_b32 m0, s50
	s_nop 0
	global_load_lds_dwordx4 v[240:241], off
	s_mov_b32 m0, s51
	s_nop 0
	global_load_lds_dwordx4 v[242:243], off
	s_add_i32 s64, 0, 0x18000
	s_add_i32 s65, 0, 0x1c000
	v_add_u32_e32 v144, s64, v167
	v_add_u32_e32 v158, s65, v167
	ds_read_b128 v[60:63], v144
	ds_read_b128 v[68:71], v144 offset:1024
	ds_read_b128 v[140:143], v144 offset:2048
	ds_read_b128 v[144:147], v144 offset:3072
	ds_read_b128 v[160:163], v158
	ds_read_b128 v[172:175], v158 offset:1024
	ds_read_b128 v[176:179], v158 offset:2048
	ds_read_b128 v[180:183], v158 offset:3072
	s_add_u32 s48, s48, 0x80000
	s_addc_u32 s49, s49, 0
	s_mov_b32 m0, s52
	ds_read_b128 v[184:187], v171 offset:32768
	ds_read_b128 v[188:191], v171 offset:33792
	ds_read_b128 v[204:207], v171 offset:34816
	ds_read_b128 v[208:211], v171 offset:35840
	ds_read_b128 v[212:215], v171 offset:36864
	ds_read_b128 v[216:219], v171 offset:37888
	ds_read_b128 v[220:223], v171 offset:38912
	ds_read_b128 v[224:227], v171 offset:39936
	global_load_lds_dwordx4 v152, s[48:49]
	s_mov_b32 m0, s53
	s_nop 0
	global_load_lds_dwordx4 v150, s[48:49]
	s_waitcnt vmcnt(8) lgkmcnt(0)
	s_barrier
	s_setprio 1
	v_mfma_i32_16x16x64_i8 v[136:139], v[60:63], v[184:187], v[136:139]
	v_mfma_i32_16x16x64_i8 v[136:139], v[68:71], v[188:191], v[136:139]
	v_mfma_i32_16x16x64_i8 v[120:123], v[68:71], v[208:211], v[120:123]
	v_mfma_i32_16x16x64_i8 v[120:123], v[60:63], v[204:207], v[120:123]
	v_mfma_i32_16x16x64_i8 v[104:107], v[60:63], v[212:215], v[104:107]
	v_mfma_i32_16x16x64_i8 v[104:107], v[68:71], v[216:219], v[104:107]
	v_mfma_i32_16x16x64_i8 v[88:91], v[68:71], v[224:227], v[88:91]
	v_mfma_i32_16x16x64_i8 v[88:91], v[60:63], v[220:223], v[88:91]
	v_mfma_i32_16x16x64_i8 v[80:83], v[140:143], v[220:223], v[80:83]
	v_mfma_i32_16x16x64_i8 v[80:83], v[144:147], v[224:227], v[80:83]
	v_mfma_i32_16x16x64_i8 v[96:99], v[144:147], v[216:219], v[96:99]
	v_mfma_i32_16x16x64_i8 v[96:99], v[140:143], v[212:215], v[96:99]
	v_mfma_i32_16x16x64_i8 v[112:115], v[140:143], v[204:207], v[112:115]
	v_mfma_i32_16x16x64_i8 v[112:115], v[144:147], v[208:211], v[112:115]
	v_mfma_i32_16x16x64_i8 v[128:131], v[144:147], v[188:191], v[128:131]
	v_mfma_i32_16x16x64_i8 v[128:131], v[140:143], v[184:187], v[128:131]
	v_mfma_i32_16x16x64_i8 v[132:135], v[160:163], v[184:187], v[132:135]
	v_mfma_i32_16x16x64_i8 v[132:135], v[172:175], v[188:191], v[132:135]
	v_mfma_i32_16x16x64_i8 v[116:119], v[172:175], v[208:211], v[116:119]
	v_mfma_i32_16x16x64_i8 v[116:119], v[160:163], v[204:207], v[116:119]
	v_mfma_i32_16x16x64_i8 v[100:103], v[160:163], v[212:215], v[100:103]
	v_mfma_i32_16x16x64_i8 v[100:103], v[172:175], v[216:219], v[100:103]
	v_mfma_i32_16x16x64_i8 v[84:87], v[172:175], v[224:227], v[84:87]
	v_mfma_i32_16x16x64_i8 v[84:87], v[160:163], v[220:223], v[84:87]
	v_mfma_i32_16x16x64_i8 v[76:79], v[176:179], v[220:223], v[76:79]
	v_mfma_i32_16x16x64_i8 v[76:79], v[180:183], v[224:227], v[76:79]
	v_mfma_i32_16x16x64_i8 v[92:95], v[180:183], v[216:219], v[92:95]
	v_mfma_i32_16x16x64_i8 v[92:95], v[176:179], v[212:215], v[92:95]
	v_mfma_i32_16x16x64_i8 v[108:111], v[176:179], v[204:207], v[108:111]
	v_mfma_i32_16x16x64_i8 v[108:111], v[180:183], v[208:211], v[108:111]
	v_mfma_i32_16x16x64_i8 v[124:127], v[180:183], v[188:191], v[124:127]
	v_mfma_i32_16x16x64_i8 v[124:127], v[176:179], v[184:187], v[124:127]
	s_setprio 0
	s_barrier
	s_add_i32 s48, s64, s47
	v_lshl_add_u64 v[164:165], v[164:165], 0, s[84:85]
	s_mov_b32 m0, s48
	ds_read_b128 v[184:187], v171 offset:49152
	ds_read_b128 v[188:191], v171 offset:50176
	ds_read_b128 v[204:207], v171 offset:51200
	ds_read_b128 v[208:211], v171 offset:52224
	ds_read_b128 v[212:215], v171 offset:53248
	ds_read_b128 v[216:219], v171 offset:54272
	ds_read_b128 v[220:223], v171 offset:55296
	ds_read_b128 v[224:227], v171 offset:56320
	global_load_lds_dwordx4 v[164:165], off
	s_add_i32 m0, s48, 0x2000
	s_add_u32 s44, s44, 0x80080
	v_lshl_add_u64 v[164:165], v[228:229], 0, s[84:85]
	s_addc_u32 s45, s45, 0
	s_add_i32 s48, s65, s47
	global_load_lds_dwordx4 v[164:165], off
	s_mov_b32 m0, s48
	s_nop 0
	global_load_lds_dwordx4 v2, s[44:45]
	s_add_i32 m0, s48, 0x2000
	s_nop 0
	global_load_lds_dwordx4 v148, s[44:45]
	s_cmp_eq_u32 s61, 28
	s_cbranch_scc0 .Ldefer_1591_peel
	v_lshl_add_u64 v[164:165], v[240:241], 0, s[84:85]
	s_mov_b32 m0, s54
	s_nop 0
	global_load_lds_dwordx4 v[164:165], off
	v_lshl_add_u64 v[164:165], v[242:243], 0, s[84:85]
	s_mov_b32 m0, s55
	s_nop 0
	global_load_lds_dwordx4 v[164:165], off
; #define PG8_STAGE(bufoff, gbase, voff) do { _Pragma("unroll") for (int _i = 0; _i < 2; ++_i) \
;         __builtin_amdgcn_global_load_lds((const unsigned*)((const char*)(gbase) + (voff)[_i]), (PG8_LAS unsigned*)(lds + (bufoff) + ldsw + _i * 8192), 16, 0, 0); } while (0)
; #define PG8_LDA(dst, b, h) do { _Pragma("unroll") for (int m = 0; m < 4; ++m) _Pragma("unroll") for (int k = 0; k < 2; ++k) dst[m][k] = *(const PG8_LAS bf16x8*)(lds + PG8_SA(b, h) + aoff + m * 2048 + k * 1024); } while (0)
; #define PG8_LDB(dst, b, h) do { _Pragma("unroll") for (int n = 0; n < 2; ++n) _Pragma("unroll") for (int k = 0; k < 2; ++k) dst[n][k] = *(const PG8_LAS bf16x8*)(lds + PG8_SB(b, h) + boff + n * 2048 + k * 1024); } while (0)
; #define PG8_WAIT_V(n) asm volatile("s_waitcnt vmcnt(" #n ")" ::: "memory")
; #define PG8_WAIT_L(n) asm volatile("s_waitcnt lgkmcnt(" #n ")" ::: "memory")
; #define PG8_BAR __builtin_amdgcn_s_barrier()
; #define PG8_SCHED __builtin_amdgcn_sched_barrier(0)
; template <class Epi, class Sched, bool ALIGN_EPI = false, bool SP2 = false, bool I8 = false>
; __device__ __forceinline__ void gemm_phase(PG8_LAS unsigned char* lds, const Gemm g, const Sched& S, const Epi& E) {
;     ...
;         for (int t = 0; t < nt; t += 2) {
;             const bool last = (t == nt - 2);
;             const char* a1 = cA + (size_t)(t + 1) * kstep;
;             const char* a2 = last ? nA : cA + (size_t)(t + 2) * kstep; const char* b2 = last ? nB : cB + (size_t)(t + 2) * kstep;
;             const char* a3 = a2 + kstep; const char* b3 = b2 + kstep;
;             if (last && has_next) S.a_ready(nxt);
;             if constexpr (SP2) {
;             PG8_LDB(B0, 0, 0); PG8_LDB(B1, 0, 1); PG8_SCHED; PG8_LDA(At, 0, 0); PG8_STAGE(PG8_SA(1, 1), a1 + hstep, voffA);
;             PG8_WAIT_V(8); PG8_WAIT_L(0); PG8_BAR; PG8_MMA(0, 0, At, B0); PG8_MMA(0, 1, At, B1); PG8_BAR; PG8_SCHED;
.Ldefer_1591_peel:
	s_waitcnt vmcnt(6) lgkmcnt(0)
	s_barrier
	s_setprio 1
	v_mfma_i32_16x16x64_i8 v[72:75], v[60:63], v[184:187], v[72:75]
	v_mfma_i32_16x16x64_i8 v[72:75], v[68:71], v[188:191], v[72:75]
	v_mfma_i32_16x16x64_i8 v[56:59], v[68:71], v[208:211], v[56:59]
	v_mfma_i32_16x16x64_i8 v[56:59], v[60:63], v[204:207], v[56:59]
	v_mfma_i32_16x16x64_i8 v[32:35], v[60:63], v[212:215], v[32:35]
	v_mfma_i32_16x16x64_i8 v[32:35], v[68:71], v[216:219], v[32:35]
	v_mfma_i32_16x16x64_i8 v[16:19], v[68:71], v[224:227], v[16:19]
	v_mfma_i32_16x16x64_i8 v[16:19], v[60:63], v[220:223], v[16:19]
	v_mfma_i32_16x16x64_i8 v[8:11], v[140:143], v[220:223], v[8:11]
	v_mfma_i32_16x16x64_i8 v[8:11], v[144:147], v[224:227], v[8:11]
	v_mfma_i32_16x16x64_i8 v[24:27], v[144:147], v[216:219], v[24:27]
	v_mfma_i32_16x16x64_i8 v[24:27], v[140:143], v[212:215], v[24:27]
	v_mfma_i32_16x16x64_i8 v[48:51], v[140:143], v[204:207], v[48:51]
	v_mfma_i32_16x16x64_i8 v[48:51], v[144:147], v[208:211], v[48:51]
	v_mfma_i32_16x16x64_i8 v[64:67], v[144:147], v[188:191], v[64:67]
	v_mfma_i32_16x16x64_i8 v[64:67], v[140:143], v[184:187], v[64:67]
	v_mfma_i32_16x16x64_i8 v[36:39], v[160:163], v[184:187], v[36:39]
	v_mfma_i32_16x16x64_i8 v[68:71], v[172:175], v[188:191], v[36:39]
	v_mfma_i32_16x16x64_i8 v[36:39], v[172:175], v[208:211], v[52:55]
	v_mfma_i32_16x16x64_i8 v[52:55], v[160:163], v[204:207], v[36:39]
	v_mfma_i32_16x16x64_i8 v[28:31], v[160:163], v[212:215], v[28:31]
	v_mfma_i32_16x16x64_i8 v[28:31], v[172:175], v[216:219], v[28:31]
	v_mfma_i32_16x16x64_i8 v[12:15], v[172:175], v[224:227], v[12:15]
	v_mfma_i32_16x16x64_i8 v[12:15], v[160:163], v[220:223], v[12:15]
	v_mfma_i32_16x16x64_i8 v[4:7], v[176:179], v[220:223], v[4:7]
	v_mfma_i32_16x16x64_i8 v[4:7], v[180:183], v[224:227], v[4:7]
	v_mfma_i32_16x16x64_i8 v[20:23], v[180:183], v[216:219], v[20:23]
	v_mfma_i32_16x16x64_i8 v[20:23], v[176:179], v[212:215], v[20:23]
	v_mfma_i32_16x16x64_i8 v[36:39], v[176:179], v[204:207], v[40:43]
	v_mfma_i32_16x16x64_i8 v[40:43], v[180:183], v[208:211], v[36:39]
	v_mfma_i32_16x16x64_i8 v[36:39], v[180:183], v[188:191], v[44:47]
	v_mfma_i32_16x16x64_i8 v[60:63], v[176:179], v[184:187], v[36:39]
	s_setprio 0
	s_barrier
	s_add_i32 s61, s61, 2
	s_add_u32 s40, s40, 0x100
	s_addc_u32 s41, s41, 0
	s_add_u32 s59, s59, 0x100
	s_addc_u32 s60, s60, 0
	s_cmp_gt_u32 s61, 29
	s_cbranch_scc1 .Lkloop_exit_3
.LBB0_1591:
	s_add_u32 s44, s40, 0xfff80080
	s_addc_u32 s45, s41, -1
	s_add_i32 s64, 0, 0x10000
	s_cmp_eq_u32 s61, 28
	s_cselect_b32 s49, s25, s45
	s_cselect_b32 s48, s57, s44
	s_cselect_b32 s45, s23, s60
	s_cselect_b32 s44, s58, s59
	s_add_i32 s67, 0, 0x14000
	v_add_u32_e32 v144, s64, v167
	v_add_u32_e32 v158, s67, v167
	ds_read_b128 v[36:39], v144
	ds_read_b128 v[44:47], v144 offset:1024
	ds_read_b128 v[140:143], v144 offset:2048
	ds_read_b128 v[144:147], v144 offset:3072
	ds_read_b128 v[160:163], v158
	ds_read_b128 v[172:175], v158 offset:1024
	ds_read_b128 v[176:179], v158 offset:2048
	ds_read_b128 v[180:183], v158 offset:3072
	v_lshl_add_u64 v[164:165], v[240:241], 0, s[84:85]
	s_mov_b32 m0, s54
	s_nop 0
	global_load_lds_dwordx4 v[164:165], off
	v_lshl_add_u64 v[164:165], v[242:243], 0, s[84:85]
	s_mov_b32 m0, s55
	s_nop 0
	global_load_lds_dwordx4 v[164:165], off
	s_add_i32 m0, s50, 0xc000
	ds_read_b128 v[184:187], v171
	ds_read_b128 v[188:191], v171 offset:1024
	ds_read_b128 v[204:207], v171 offset:2048
	ds_read_b128 v[208:211], v171 offset:3072
	ds_read_b128 v[212:215], v171 offset:4096
	ds_read_b128 v[216:219], v171 offset:5120
	ds_read_b128 v[220:223], v171 offset:6144
	ds_read_b128 v[224:227], v171 offset:7168
	global_load_lds_dwordx4 v154, s[40:41]
	s_add_i32 m0, s50, 0xe000
	s_nop 0
	global_load_lds_dwordx4 v156, s[40:41]
	s_waitcnt vmcnt(8) lgkmcnt(0)
	s_barrier
	s_setprio 1
	v_mfma_i32_16x16x64_i8 v[136:139], v[36:39], v[184:187], v[136:139]
	v_mfma_i32_16x16x64_i8 v[136:139], v[44:47], v[188:191], v[136:139]
	v_mfma_i32_16x16x64_i8 v[120:123], v[44:47], v[208:211], v[120:123]
	v_mfma_i32_16x16x64_i8 v[120:123], v[36:39], v[204:207], v[120:123]
	v_mfma_i32_16x16x64_i8 v[104:107], v[36:39], v[212:215], v[104:107]
	v_mfma_i32_16x16x64_i8 v[104:107], v[44:47], v[216:219], v[104:107]
	v_mfma_i32_16x16x64_i8 v[88:91], v[44:47], v[224:227], v[88:91]
	v_mfma_i32_16x16x64_i8 v[88:91], v[36:39], v[220:223], v[88:91]
	v_mfma_i32_16x16x64_i8 v[80:83], v[140:143], v[220:223], v[80:83]
	v_mfma_i32_16x16x64_i8 v[80:83], v[144:147], v[224:227], v[80:83]
	v_mfma_i32_16x16x64_i8 v[96:99], v[144:147], v[216:219], v[96:99]
	v_mfma_i32_16x16x64_i8 v[96:99], v[140:143], v[212:215], v[96:99]
	v_mfma_i32_16x16x64_i8 v[112:115], v[140:143], v[204:207], v[112:115]
	v_mfma_i32_16x16x64_i8 v[112:115], v[144:147], v[208:211], v[112:115]
	v_mfma_i32_16x16x64_i8 v[128:131], v[144:147], v[188:191], v[128:131]
	v_mfma_i32_16x16x64_i8 v[128:131], v[140:143], v[184:187], v[128:131]
	v_mfma_i32_16x16x64_i8 v[132:135], v[160:163], v[184:187], v[132:135]
	v_mfma_i32_16x16x64_i8 v[132:135], v[172:175], v[188:191], v[132:135]
	v_mfma_i32_16x16x64_i8 v[116:119], v[172:175], v[208:211], v[116:119]
	v_mfma_i32_16x16x64_i8 v[116:119], v[160:163], v[204:207], v[116:119]
	v_mfma_i32_16x16x64_i8 v[100:103], v[160:163], v[212:215], v[100:103]
	v_mfma_i32_16x16x64_i8 v[100:103], v[172:175], v[216:219], v[100:103]
	v_mfma_i32_16x16x64_i8 v[84:87], v[172:175], v[224:227], v[84:87]
	v_mfma_i32_16x16x64_i8 v[84:87], v[160:163], v[220:223], v[84:87]
	v_mfma_i32_16x16x64_i8 v[76:79], v[176:179], v[220:223], v[76:79]
	v_mfma_i32_16x16x64_i8 v[76:79], v[180:183], v[224:227], v[76:79]
	v_mfma_i32_16x16x64_i8 v[92:95], v[180:183], v[216:219], v[92:95]
	v_mfma_i32_16x16x64_i8 v[92:95], v[176:179], v[212:215], v[92:95]
	v_mfma_i32_16x16x64_i8 v[108:111], v[176:179], v[204:207], v[108:111]
	v_mfma_i32_16x16x64_i8 v[108:111], v[180:183], v[208:211], v[108:111]
	v_mfma_i32_16x16x64_i8 v[124:127], v[180:183], v[188:191], v[124:127]
	v_mfma_i32_16x16x64_i8 v[124:127], v[176:179], v[184:187], v[124:127]
	s_setprio 0
	s_barrier
; #define PG8_STAGE(bufoff, gbase, voff) do { _Pragma("unroll") for (int _i = 0; _i < 2; ++_i) \
;         __builtin_amdgcn_global_load_lds((const unsigned*)((const char*)(gbase) + (voff)[_i]), (PG8_LAS unsigned*)(lds + (bufoff) + ldsw + _i * 8192), 16, 0, 0); } while (0)
; #define PG8_LDA(dst, b, h) do { _Pragma("unroll") for (int m = 0; m < 4; ++m) _Pragma("unroll") for (int k = 0; k < 2; ++k) dst[m][k] = *(const PG8_LAS bf16x8*)(lds + PG8_SA(b, h) + aoff + m * 2048 + k * 1024); } while (0)
; #define PG8_LDB(dst, b, h) do { _Pragma("unroll") for (int n = 0; n < 2; ++n) _Pragma("unroll") for (int k = 0; k < 2; ++k) dst[n][k] = *(const PG8_LAS bf16x8*)(lds + PG8_SB(b, h) + boff + n * 2048 + k * 1024); } while (0)
; #define PG8_WAIT_V(n) asm volatile("s_waitcnt vmcnt(" #n ")" ::: "memory")
; #define PG8_WAIT_L(n) asm volatile("s_waitcnt lgkmcnt(" #n ")" ::: "memory")
; #define PG8_BAR __builtin_amdgcn_s_barrier()
; #define PG8_SCHED __builtin_amdgcn_sched_barrier(0)
; template <class Epi, class Sched, bool ALIGN_EPI = false, bool SP2 = false, bool I8 = false>
; __device__ __forceinline__ void gemm_phase(PG8_LAS unsigned char* lds, const Gemm g, const Sched& S, const Epi& E) {
;     ...
;             PG8_LDA(At, 0, 1); PG8_STAGE(PG8_SB(0, 0), b2, voffB); PG8_STAGE(PG8_SB(0, 1), b2 + hstep, voffB); PG8_STAGE(PG8_SA(0, 0), a2, voffA);
;             PG8_WAIT_V(8); PG8_WAIT_L(0); PG8_BAR; PG8_MMA(1, 0, At, B0); PG8_MMA(1, 1, At, B1); PG8_BAR; PG8_SCHED;
;             PG8_LDB(B0, 1, 0); PG8_LDB(B1, 1, 1); PG8_SCHED; PG8_LDA(At, 1, 0); PG8_STAGE(PG8_SA(0, 1), a2 + hstep, voffA);
;             PG8_WAIT_V(8); PG8_WAIT_L(0); PG8_BAR; PG8_MMA(0, 0, At, B0); PG8_MMA(0, 1, At, B1); PG8_BAR; PG8_SCHED;
	s_add_i32 s64, s64, s47
	v_lshl_add_u64 v[164:165], s[44:45], 0, v[2:3]
	s_mov_b32 m0, s64
	ds_read_b128 v[184:187], v171 offset:16384
	ds_read_b128 v[188:191], v171 offset:17408
	ds_read_b128 v[204:207], v171 offset:18432
	ds_read_b128 v[208:211], v171 offset:19456
	ds_read_b128 v[212:215], v171 offset:20480
	ds_read_b128 v[216:219], v171 offset:21504
	ds_read_b128 v[220:223], v171 offset:22528
	ds_read_b128 v[224:227], v171 offset:23552
	global_load_lds_dwordx4 v[164:165], off
	s_add_i32 m0, s64, 0x2000
	s_add_u32 s64, s44, 0x80000
	v_lshl_add_u64 v[228:229], s[44:45], 0, v[148:149]
	s_addc_u32 s65, s45, 0
	s_add_i32 s67, s67, s47
	global_load_lds_dwordx4 v[228:229], off
	s_mov_b32 m0, s67
	v_lshl_add_u64 v[242:243], s[48:49], 0, v[150:151]
	global_load_lds_dwordx4 v2, s[64:65]
	s_add_i32 m0, s67, 0x2000
	s_nop 0
	global_load_lds_dwordx4 v148, s[64:65]
	v_lshl_add_u64 v[240:241], s[48:49], 0, v[152:153]
	s_waitcnt vmcnt(6) lgkmcnt(0)
	s_barrier
	s_setprio 1
	v_mfma_i32_16x16x64_i8 v[72:75], v[36:39], v[184:187], v[72:75]
	v_mfma_i32_16x16x64_i8 v[72:75], v[44:47], v[188:191], v[72:75]
	v_mfma_i32_16x16x64_i8 v[56:59], v[44:47], v[208:211], v[56:59]
	v_mfma_i32_16x16x64_i8 v[56:59], v[36:39], v[204:207], v[56:59]
	v_mfma_i32_16x16x64_i8 v[32:35], v[36:39], v[212:215], v[32:35]
	v_mfma_i32_16x16x64_i8 v[32:35], v[44:47], v[216:219], v[32:35]
	v_mfma_i32_16x16x64_i8 v[16:19], v[44:47], v[224:227], v[16:19]
	v_mfma_i32_16x16x64_i8 v[16:19], v[36:39], v[220:223], v[16:19]
	v_mfma_i32_16x16x64_i8 v[8:11], v[140:143], v[220:223], v[8:11]
	v_mfma_i32_16x16x64_i8 v[8:11], v[144:147], v[224:227], v[8:11]
	v_mfma_i32_16x16x64_i8 v[24:27], v[144:147], v[216:219], v[24:27]
	v_mfma_i32_16x16x64_i8 v[24:27], v[140:143], v[212:215], v[24:27]
	v_mfma_i32_16x16x64_i8 v[48:51], v[140:143], v[204:207], v[48:51]
	v_mfma_i32_16x16x64_i8 v[48:51], v[144:147], v[208:211], v[48:51]
	v_mfma_i32_16x16x64_i8 v[64:67], v[144:147], v[188:191], v[64:67]
	v_mfma_i32_16x16x64_i8 v[64:67], v[140:143], v[184:187], v[64:67]
	v_mfma_i32_16x16x64_i8 v[36:39], v[160:163], v[184:187], v[68:71]
	v_mfma_i32_16x16x64_i8 v[36:39], v[172:175], v[188:191], v[36:39]
	v_mfma_i32_16x16x64_i8 v[52:55], v[172:175], v[208:211], v[52:55]
	v_mfma_i32_16x16x64_i8 v[52:55], v[160:163], v[204:207], v[52:55]
	v_mfma_i32_16x16x64_i8 v[28:31], v[160:163], v[212:215], v[28:31]
	v_mfma_i32_16x16x64_i8 v[28:31], v[172:175], v[216:219], v[28:31]
	v_mfma_i32_16x16x64_i8 v[12:15], v[172:175], v[224:227], v[12:15]
	v_mfma_i32_16x16x64_i8 v[12:15], v[160:163], v[220:223], v[12:15]
	v_mfma_i32_16x16x64_i8 v[4:7], v[176:179], v[220:223], v[4:7]
	v_mfma_i32_16x16x64_i8 v[4:7], v[180:183], v[224:227], v[4:7]
	v_mfma_i32_16x16x64_i8 v[20:23], v[180:183], v[216:219], v[20:23]
	v_mfma_i32_16x16x64_i8 v[20:23], v[176:179], v[212:215], v[20:23]
	v_mfma_i32_16x16x64_i8 v[40:43], v[176:179], v[204:207], v[40:43]
	v_mfma_i32_16x16x64_i8 v[40:43], v[180:183], v[208:211], v[40:43]
	v_mfma_i32_16x16x64_i8 v[44:47], v[180:183], v[188:191], v[60:63]
	v_mfma_i32_16x16x64_i8 v[44:47], v[176:179], v[184:187], v[44:47]
	s_setprio 0
	s_barrier
	s_mov_b32 m0, s50
	s_nop 0
	global_load_lds_dwordx4 v[240:241], off
	s_mov_b32 m0, s51
	s_nop 0
	global_load_lds_dwordx4 v[242:243], off
	s_add_i32 s64, 0, 0x18000
	s_add_i32 s65, 0, 0x1c000
	v_add_u32_e32 v144, s64, v167
	v_add_u32_e32 v158, s65, v167
	ds_read_b128 v[60:63], v144
	ds_read_b128 v[68:71], v144 offset:1024
	ds_read_b128 v[140:143], v144 offset:2048
	ds_read_b128 v[144:147], v144 offset:3072
	ds_read_b128 v[160:163], v158
	ds_read_b128 v[172:175], v158 offset:1024
	ds_read_b128 v[176:179], v158 offset:2048
	ds_read_b128 v[180:183], v158 offset:3072
	s_add_u32 s48, s48, 0x80000
	s_addc_u32 s49, s49, 0
	s_mov_b32 m0, s52
	ds_read_b128 v[184:187], v171 offset:32768
	ds_read_b128 v[188:191], v171 offset:33792
	ds_read_b128 v[204:207], v171 offset:34816
	ds_read_b128 v[208:211], v171 offset:35840
	ds_read_b128 v[212:215], v171 offset:36864
	ds_read_b128 v[216:219], v171 offset:37888
	ds_read_b128 v[220:223], v171 offset:38912
	ds_read_b128 v[224:227], v171 offset:39936
	global_load_lds_dwordx4 v152, s[48:49]
	s_mov_b32 m0, s53
	s_nop 0
	global_load_lds_dwordx4 v150, s[48:49]
	s_waitcnt vmcnt(8) lgkmcnt(0)
	s_barrier
; #define PG8_STAGE(bufoff, gbase, voff) do { _Pragma("unroll") for (int _i = 0; _i < 2; ++_i) \
;         __builtin_amdgcn_global_load_lds((const unsigned*)((const char*)(gbase) + (voff)[_i]), (PG8_LAS unsigned*)(lds + (bufoff) + ldsw + _i * 8192), 16, 0, 0); } while (0)
; #define PG8_LDA(dst, b, h) do { _Pragma("unroll") for (int m = 0; m < 4; ++m) _Pragma("unroll") for (int k = 0; k < 2; ++k) dst[m][k] = *(const PG8_LAS bf16x8*)(lds + PG8_SA(b, h) + aoff + m * 2048 + k * 1024); } while (0)
; #define PG8_WAIT_V(n) asm volatile("s_waitcnt vmcnt(" #n ")" ::: "memory")
; #define PG8_WAIT_L(n) asm volatile("s_waitcnt lgkmcnt(" #n ")" ::: "memory")
; #define PG8_BAR __builtin_amdgcn_s_barrier()
; #define PG8_SCHED __builtin_amdgcn_sched_barrier(0)
; template <class Epi, class Sched, bool ALIGN_EPI = false, bool SP2 = false, bool I8 = false>
; __device__ __forceinline__ void gemm_phase(PG8_LAS unsigned char* lds, const Gemm g, const Sched& S, const Epi& E) {
;     ...
;             PG8_WAIT_V(8); PG8_WAIT_L(0); PG8_BAR; PG8_MMA(0, 0, At, B0); PG8_MMA(0, 1, At, B1); PG8_BAR; PG8_SCHED;
;             PG8_LDA(At, 1, 1); PG8_STAGE(PG8_SB(1, 0), b3, voffB); PG8_STAGE(PG8_SB(1, 1), b3 + hstep, voffB); PG8_STAGE(PG8_SA(1, 0), a3, voffA);
;             PG8_WAIT_V(8); PG8_WAIT_L(0); PG8_BAR; PG8_MMA(1, 0, At, B0); PG8_MMA(1, 1, At, B1); PG8_BAR; PG8_SCHED;
	s_setprio 1
	v_mfma_i32_16x16x64_i8 v[136:139], v[60:63], v[184:187], v[136:139]
	v_mfma_i32_16x16x64_i8 v[136:139], v[68:71], v[188:191], v[136:139]
	v_mfma_i32_16x16x64_i8 v[120:123], v[68:71], v[208:211], v[120:123]
	v_mfma_i32_16x16x64_i8 v[120:123], v[60:63], v[204:207], v[120:123]
	v_mfma_i32_16x16x64_i8 v[104:107], v[60:63], v[212:215], v[104:107]
	v_mfma_i32_16x16x64_i8 v[104:107], v[68:71], v[216:219], v[104:107]
	v_mfma_i32_16x16x64_i8 v[88:91], v[68:71], v[224:227], v[88:91]
	v_mfma_i32_16x16x64_i8 v[88:91], v[60:63], v[220:223], v[88:91]
	v_mfma_i32_16x16x64_i8 v[80:83], v[140:143], v[220:223], v[80:83]
	v_mfma_i32_16x16x64_i8 v[80:83], v[144:147], v[224:227], v[80:83]
	v_mfma_i32_16x16x64_i8 v[96:99], v[144:147], v[216:219], v[96:99]
	v_mfma_i32_16x16x64_i8 v[96:99], v[140:143], v[212:215], v[96:99]
	v_mfma_i32_16x16x64_i8 v[112:115], v[140:143], v[204:207], v[112:115]
	v_mfma_i32_16x16x64_i8 v[112:115], v[144:147], v[208:211], v[112:115]
	v_mfma_i32_16x16x64_i8 v[128:131], v[144:147], v[188:191], v[128:131]
	v_mfma_i32_16x16x64_i8 v[128:131], v[140:143], v[184:187], v[128:131]
	v_mfma_i32_16x16x64_i8 v[132:135], v[160:163], v[184:187], v[132:135]
	v_mfma_i32_16x16x64_i8 v[132:135], v[172:175], v[188:191], v[132:135]
	v_mfma_i32_16x16x64_i8 v[116:119], v[172:175], v[208:211], v[116:119]
	v_mfma_i32_16x16x64_i8 v[116:119], v[160:163], v[204:207], v[116:119]
	v_mfma_i32_16x16x64_i8 v[100:103], v[160:163], v[212:215], v[100:103]
	v_mfma_i32_16x16x64_i8 v[100:103], v[172:175], v[216:219], v[100:103]
	v_mfma_i32_16x16x64_i8 v[84:87], v[172:175], v[224:227], v[84:87]
	v_mfma_i32_16x16x64_i8 v[84:87], v[160:163], v[220:223], v[84:87]
	v_mfma_i32_16x16x64_i8 v[76:79], v[176:179], v[220:223], v[76:79]
	v_mfma_i32_16x16x64_i8 v[76:79], v[180:183], v[224:227], v[76:79]
	v_mfma_i32_16x16x64_i8 v[92:95], v[180:183], v[216:219], v[92:95]
	v_mfma_i32_16x16x64_i8 v[92:95], v[176:179], v[212:215], v[92:95]
	v_mfma_i32_16x16x64_i8 v[108:111], v[176:179], v[204:207], v[108:111]
	v_mfma_i32_16x16x64_i8 v[108:111], v[180:183], v[208:211], v[108:111]
	v_mfma_i32_16x16x64_i8 v[124:127], v[180:183], v[188:191], v[124:127]
	v_mfma_i32_16x16x64_i8 v[124:127], v[176:179], v[184:187], v[124:127]
	s_setprio 0
	s_barrier
	s_add_i32 s48, s64, s47
	v_lshl_add_u64 v[164:165], v[164:165], 0, s[84:85]
	s_mov_b32 m0, s48
	ds_read_b128 v[184:187], v171 offset:49152
	ds_read_b128 v[188:191], v171 offset:50176
	ds_read_b128 v[204:207], v171 offset:51200
	ds_read_b128 v[208:211], v171 offset:52224
	ds_read_b128 v[212:215], v171 offset:53248
	ds_read_b128 v[216:219], v171 offset:54272
	ds_read_b128 v[220:223], v171 offset:55296
	ds_read_b128 v[224:227], v171 offset:56320
	global_load_lds_dwordx4 v[164:165], off
	s_add_i32 m0, s48, 0x2000
	s_add_u32 s44, s44, 0x80080
	v_lshl_add_u64 v[164:165], v[228:229], 0, s[84:85]
	s_addc_u32 s45, s45, 0
	s_add_i32 s48, s65, s47
	global_load_lds_dwordx4 v[164:165], off
	s_mov_b32 m0, s48
	s_nop 0
	global_load_lds_dwordx4 v2, s[44:45]
	s_add_i32 m0, s48, 0x2000
	s_nop 0
	global_load_lds_dwordx4 v148, s[44:45]
	s_cmp_eq_u32 s61, 28
	s_cbranch_scc0 .Ldefer_1591_body
	v_lshl_add_u64 v[164:165], v[240:241], 0, s[84:85]
	s_mov_b32 m0, s54
	s_nop 0
	global_load_lds_dwordx4 v[164:165], off
	v_lshl_add_u64 v[164:165], v[242:243], 0, s[84:85]
	s_mov_b32 m0, s55
	s_nop 0
	global_load_lds_dwordx4 v[164:165], off
.Ldefer_1591_body:
	s_waitcnt vmcnt(6) lgkmcnt(0)
	s_barrier
	s_setprio 1
	v_mfma_i32_16x16x64_i8 v[72:75], v[60:63], v[184:187], v[72:75]
	v_mfma_i32_16x16x64_i8 v[72:75], v[68:71], v[188:191], v[72:75]
	v_mfma_i32_16x16x64_i8 v[56:59], v[68:71], v[208:211], v[56:59]
	v_mfma_i32_16x16x64_i8 v[56:59], v[60:63], v[204:207], v[56:59]
	v_mfma_i32_16x16x64_i8 v[32:35], v[60:63], v[212:215], v[32:35]
	v_mfma_i32_16x16x64_i8 v[32:35], v[68:71], v[216:219], v[32:35]
	v_mfma_i32_16x16x64_i8 v[16:19], v[68:71], v[224:227], v[16:19]
	v_mfma_i32_16x16x64_i8 v[16:19], v[60:63], v[220:223], v[16:19]
	v_mfma_i32_16x16x64_i8 v[8:11], v[140:143], v[220:223], v[8:11]
	v_mfma_i32_16x16x64_i8 v[8:11], v[144:147], v[224:227], v[8:11]
	v_mfma_i32_16x16x64_i8 v[24:27], v[144:147], v[216:219], v[24:27]
	v_mfma_i32_16x16x64_i8 v[24:27], v[140:143], v[212:215], v[24:27]
	v_mfma_i32_16x16x64_i8 v[48:51], v[140:143], v[204:207], v[48:51]
	v_mfma_i32_16x16x64_i8 v[48:51], v[144:147], v[208:211], v[48:51]
	v_mfma_i32_16x16x64_i8 v[64:67], v[144:147], v[188:191], v[64:67]
	v_mfma_i32_16x16x64_i8 v[64:67], v[140:143], v[184:187], v[64:67]
	v_mfma_i32_16x16x64_i8 v[36:39], v[160:163], v[184:187], v[36:39]
	v_mfma_i32_16x16x64_i8 v[68:71], v[172:175], v[188:191], v[36:39]
	v_mfma_i32_16x16x64_i8 v[36:39], v[172:175], v[208:211], v[52:55]
	v_mfma_i32_16x16x64_i8 v[52:55], v[160:163], v[204:207], v[36:39]
	v_mfma_i32_16x16x64_i8 v[28:31], v[160:163], v[212:215], v[28:31]
	v_mfma_i32_16x16x64_i8 v[28:31], v[172:175], v[216:219], v[28:31]
	v_mfma_i32_16x16x64_i8 v[12:15], v[172:175], v[224:227], v[12:15]
	v_mfma_i32_16x16x64_i8 v[12:15], v[160:163], v[220:223], v[12:15]
	v_mfma_i32_16x16x64_i8 v[4:7], v[176:179], v[220:223], v[4:7]
	v_mfma_i32_16x16x64_i8 v[4:7], v[180:183], v[224:227], v[4:7]
	v_mfma_i32_16x16x64_i8 v[20:23], v[180:183], v[216:219], v[20:23]
	v_mfma_i32_16x16x64_i8 v[20:23], v[176:179], v[212:215], v[20:23]
	v_mfma_i32_16x16x64_i8 v[36:39], v[176:179], v[204:207], v[40:43]
	v_mfma_i32_16x16x64_i8 v[40:43], v[180:183], v[208:211], v[36:39]
	v_mfma_i32_16x16x64_i8 v[36:39], v[180:183], v[188:191], v[44:47]
	v_mfma_i32_16x16x64_i8 v[60:63], v[176:179], v[184:187], v[36:39]
	s_setprio 0
	s_barrier
	s_add_i32 s61, s61, 2
	s_add_u32 s40, s40, 0x100
	s_addc_u32 s41, s41, 0
	s_add_u32 s59, s59, 0x100
	s_addc_u32 s60, s60, 0
	s_cmp_gt_u32 s61, 29
	s_cbranch_scc0 .LBB0_1591

; #define PG8_STAGE(bufoff, gbase, voff) do { _Pragma("unroll") for (int _i = 0; _i < 2; ++_i) \
;         __builtin_amdgcn_global_load_lds((const unsigned*)((const char*)(gbase) + (voff)[_i]), (PG8_LAS unsigned*)(lds + (bufoff) + ldsw + _i * 8192), 16, 0, 0); } while (0)
; #define PG8_LDA(dst, b, h) do { _Pragma("unroll") for (int m = 0; m < 4; ++m) _Pragma("unroll") for (int k = 0; k < 2; ++k) dst[m][k] = *(const PG8_LAS bf16x8*)(lds + PG8_SA(b, h) + aoff + m * 2048 + k * 1024); } while (0)
; #define PG8_LDB(dst, b, h) do { _Pragma("unroll") for (int n = 0; n < 2; ++n) _Pragma("unroll") for (int k = 0; k < 2; ++k) dst[n][k] = *(const PG8_LAS bf16x8*)(lds + PG8_SB(b, h) + boff + n * 2048 + k * 1024); } while (0)
; #define PG8_WAIT_V(n) asm volatile("s_waitcnt vmcnt(" #n ")" ::: "memory")
; #define PG8_WAIT_L(n) asm volatile("s_waitcnt lgkmcnt(" #n ")" ::: "memory")
; #define PG8_BAR __builtin_amdgcn_s_barrier()
; #define PG8_SCHED __builtin_amdgcn_sched_barrier(0)
; template <class Epi, class Sched, bool ALIGN_EPI = false, bool SP2 = false, bool I8 = false>
; __device__ __forceinline__ void gemm_phase(PG8_LAS unsigned char* lds, const Gemm g, const Sched& S, const Epi& E) {
;     ...
;         for (int t = 0; t < nt; t += 2) {
;             const bool last = (t == nt - 2);
;             const char* a1 = cA + (size_t)(t + 1) * kstep;
;             const char* a2 = last ? nA : cA + (size_t)(t + 2) * kstep; const char* b2 = last ? nB : cB + (size_t)(t + 2) * kstep;
;             const char* a3 = a2 + kstep; const char* b3 = b2 + kstep;
;             if (last && has_next) S.a_ready(nxt);
;             if constexpr (SP2) {
;             PG8_LDB(B0, 0, 0); PG8_LDB(B1, 0, 1); PG8_SCHED; PG8_LDA(At, 0, 0); PG8_STAGE(PG8_SA(1, 1), a1 + hstep, voffA);
;             PG8_WAIT_V(8); PG8_WAIT_L(0); PG8_BAR; PG8_MMA(0, 0, At, B0); PG8_MMA(0, 1, At, B1); PG8_BAR; PG8_SCHED;
;     ...
;         for (int a = 0; a < 2; ++a)
; #pragma unroll
;             for (int b = 0; b < 2; ++b)
; #pragma unroll
;                 for (int m = 0; m < 4; ++m)
; #pragma unroll
;                     for (int n = 0; n < 2; ++n) acc[a][b][m][n] = (acc_t){0, 0, 0, 0};
.LBB0_1621:
	v_mov_b32_e32 v127, 0
	s_andn2_b64 vcc, exec, s[26:27]
	v_mov_b32_e32 v126, v127
	v_mov_b32_e32 v125, v127
	v_mov_b32_e32 v124, v127
	v_mov_b32_e32 v131, v127
	v_mov_b32_e32 v130, v127
	v_mov_b32_e32 v129, v127
	v_mov_b32_e32 v128, v127
	v_mov_b32_e32 v115, v127
	v_mov_b32_e32 v114, v127
	v_mov_b32_e32 v113, v127
	v_mov_b32_e32 v112, v127
	v_mov_b32_e32 v111, v127
	v_mov_b32_e32 v110, v127
	v_mov_b32_e32 v109, v127
	v_mov_b32_e32 v108, v127
	v_mov_b32_e32 v99, v127
	v_mov_b32_e32 v98, v127
	v_mov_b32_e32 v97, v127
	v_mov_b32_e32 v96, v127
	v_mov_b32_e32 v95, v127
	v_mov_b32_e32 v94, v127
	v_mov_b32_e32 v93, v127
	v_mov_b32_e32 v92, v127
	v_mov_b32_e32 v83, v127
	v_mov_b32_e32 v82, v127
	v_mov_b32_e32 v81, v127
	v_mov_b32_e32 v80, v127
	v_mov_b32_e32 v79, v127
	v_mov_b32_e32 v78, v127
	v_mov_b32_e32 v77, v127
	v_mov_b32_e32 v76, v127
	v_mov_b32_e32 v123, v127
	v_mov_b32_e32 v122, v127
	v_mov_b32_e32 v121, v127
	v_mov_b32_e32 v120, v127
	v_mov_b32_e32 v119, v127
	v_mov_b32_e32 v118, v127
	v_mov_b32_e32 v117, v127
	v_mov_b32_e32 v116, v127
	v_mov_b32_e32 v107, v127
	v_mov_b32_e32 v106, v127
	v_mov_b32_e32 v105, v127
	v_mov_b32_e32 v104, v127
	v_mov_b32_e32 v103, v127
	v_mov_b32_e32 v102, v127
	v_mov_b32_e32 v101, v127
	v_mov_b32_e32 v100, v127
	v_mov_b32_e32 v91, v127
	v_mov_b32_e32 v90, v127
	v_mov_b32_e32 v89, v127
	v_mov_b32_e32 v88, v127
	v_mov_b32_e32 v87, v127
	v_mov_b32_e32 v86, v127
	v_mov_b32_e32 v85, v127
	v_mov_b32_e32 v84, v127
	v_mov_b32_e32 v75, v127
	v_mov_b32_e32 v74, v127
	v_mov_b32_e32 v73, v127
	v_mov_b32_e32 v72, v127
	v_mov_b32_e32 v71, v127
	v_mov_b32_e32 v70, v127
	v_mov_b32_e32 v69, v127
	v_mov_b32_e32 v68, v127
	v_mov_b32_e32 v67, v127
	v_mov_b32_e32 v66, v127
	v_mov_b32_e32 v65, v127
	v_mov_b32_e32 v64, v127
	v_mov_b32_e32 v63, v127
	v_mov_b32_e32 v62, v127
	v_mov_b32_e32 v61, v127
	v_mov_b32_e32 v60, v127
	v_mov_b32_e32 v51, v127
	v_mov_b32_e32 v50, v127
	v_mov_b32_e32 v49, v127
	v_mov_b32_e32 v48, v127
	v_mov_b32_e32 v47, v127
	v_mov_b32_e32 v46, v127
	v_mov_b32_e32 v45, v127
	v_mov_b32_e32 v44, v127
	v_mov_b32_e32 v35, v127
	v_mov_b32_e32 v34, v127
	v_mov_b32_e32 v33, v127
	v_mov_b32_e32 v32, v127
	v_mov_b32_e32 v31, v127
	v_mov_b32_e32 v30, v127
	v_mov_b32_e32 v29, v127
	v_mov_b32_e32 v28, v127
	v_mov_b32_e32 v19, v127
	v_mov_b32_e32 v18, v127
	v_mov_b32_e32 v17, v127
	v_mov_b32_e32 v16, v127
	v_mov_b32_e32 v15, v127
	v_mov_b32_e32 v14, v127
	v_mov_b32_e32 v13, v127
	v_mov_b32_e32 v12, v127
	v_mov_b32_e32 v59, v127
	v_mov_b32_e32 v58, v127
	v_mov_b32_e32 v57, v127
	v_mov_b32_e32 v56, v127
	v_mov_b32_e32 v55, v127
	v_mov_b32_e32 v54, v127
	v_mov_b32_e32 v53, v127
	v_mov_b32_e32 v52, v127
	v_mov_b32_e32 v43, v127
	v_mov_b32_e32 v42, v127
	v_mov_b32_e32 v41, v127
	v_mov_b32_e32 v40, v127
	v_mov_b32_e32 v39, v127
	v_mov_b32_e32 v38, v127
	v_mov_b32_e32 v37, v127
	v_mov_b32_e32 v36, v127
	v_mov_b32_e32 v27, v127
	v_mov_b32_e32 v26, v127
	v_mov_b32_e32 v25, v127
	v_mov_b32_e32 v24, v127
	v_mov_b32_e32 v23, v127
	v_mov_b32_e32 v22, v127
	v_mov_b32_e32 v21, v127
	v_mov_b32_e32 v20, v127
	v_mov_b32_e32 v11, v127
	v_mov_b32_e32 v10, v127
	v_mov_b32_e32 v9, v127
	v_mov_b32_e32 v8, v127
	v_mov_b32_e32 v7, v127
	v_mov_b32_e32 v6, v127
	v_mov_b32_e32 v5, v127
	v_mov_b32_e32 v4, v127
	s_cbranch_vccnz .LBB0_1625
	s_add_u32 s44, s44, 0x80
	s_addc_u32 s45, s45, 0
	s_add_u32 s65, s48, 0x100
	s_addc_u32 s67, s49, 0
	s_mov_b32 s48, 0
	s_add_i32 s72, s48, 2
	s_add_u32 s73, s44, 0x80
	s_addc_u32 s49, s45, 0
	s_add_i32 s86, 0, 0x10000
	s_cmp_eq_u32 s57, s48
	s_cselect_b32 s49, s13, s49
	s_cselect_b32 s48, s12, s73
	s_cselect_b32 s77, s41, s67
	s_cselect_b32 s76, s40, s65
	s_add_i32 s73, 0, 0x14000
	v_add_u32_e32 v158, s86, v143
	v_add_u32_e32 v174, s73, v143
	ds_read_b128 v[146:149], v158
	ds_read_b128 v[150:153], v158 offset:1024
	ds_read_b128 v[154:157], v158 offset:2048
	ds_read_b128 v[158:161], v158 offset:3072
	ds_read_b128 v[162:165], v174
	ds_read_b128 v[166:169], v174 offset:1024
	ds_read_b128 v[170:173], v174 offset:2048
	ds_read_b128 v[174:177], v174 offset:3072
	v_lshl_add_u64 v[190:191], s[44:45], 0, v[138:139]
	s_add_i32 m0, s47, 0xc000
	ds_read_b128 v[178:181], v145
	ds_read_b128 v[182:185], v145 offset:1024
	ds_read_b128 v[186:189], v145 offset:2048
	ds_read_b128 v[204:207], v145 offset:3072
	ds_read_b128 v[208:211], v145 offset:4096
	ds_read_b128 v[212:215], v145 offset:5120
	ds_read_b128 v[216:219], v145 offset:6144
	ds_read_b128 v[220:223], v145 offset:7168
	global_load_lds_dwordx4 v[190:191], off
	v_lshl_add_u64 v[190:191], s[44:45], 0, v[140:141]
	s_add_i32 m0, s47, 0xe000
	s_nop 0
	global_load_lds_dwordx4 v[190:191], off
	s_waitcnt vmcnt(8) lgkmcnt(0)
	s_barrier
; #define PG8_STAGE(bufoff, gbase, voff) do { _Pragma("unroll") for (int _i = 0; _i < 2; ++_i) \
;         __builtin_amdgcn_global_load_lds((const unsigned*)((const char*)(gbase) + (voff)[_i]), (PG8_LAS unsigned*)(lds + (bufoff) + ldsw + _i * 8192), 16, 0, 0); } while (0)
; #define PG8_LDA(dst, b, h) do { _Pragma("unroll") for (int m = 0; m < 4; ++m) _Pragma("unroll") for (int k = 0; k < 2; ++k) dst[m][k] = *(const PG8_LAS bf16x8*)(lds + PG8_SA(b, h) + aoff + m * 2048 + k * 1024); } while (0)
; #define PG8_LDB(dst, b, h) do { _Pragma("unroll") for (int n = 0; n < 2; ++n) _Pragma("unroll") for (int k = 0; k < 2; ++k) dst[n][k] = *(const PG8_LAS bf16x8*)(lds + PG8_SB(b, h) + boff + n * 2048 + k * 1024); } while (0)
; #define PG8_WAIT_V(n) asm volatile("s_waitcnt vmcnt(" #n ")" ::: "memory")
; #define PG8_WAIT_L(n) asm volatile("s_waitcnt lgkmcnt(" #n ")" ::: "memory")
; #define PG8_BAR __builtin_amdgcn_s_barrier()
; #define PG8_SCHED __builtin_amdgcn_sched_barrier(0)
; template <class Epi, class Sched, bool ALIGN_EPI = false, bool SP2 = false, bool I8 = false>
; __device__ __forceinline__ void gemm_phase(PG8_LAS unsigned char* lds, const Gemm g, const Sched& S, const Epi& E) {
;     ...
;             PG8_WAIT_V(8); PG8_WAIT_L(0); PG8_BAR; PG8_MMA(0, 0, At, B0); PG8_MMA(0, 1, At, B1); PG8_BAR; PG8_SCHED;
;             PG8_LDA(At, 0, 1); PG8_STAGE(PG8_SB(0, 0), b2, voffB); PG8_STAGE(PG8_SB(0, 1), b2 + hstep, voffB); PG8_STAGE(PG8_SA(0, 0), a2, voffA);
;             PG8_WAIT_V(8); PG8_WAIT_L(0); PG8_BAR; PG8_MMA(1, 0, At, B0); PG8_MMA(1, 1, At, B1); PG8_BAR; PG8_SCHED;
;             PG8_LDB(B0, 1, 0); PG8_LDB(B1, 1, 1); PG8_SCHED; PG8_LDA(At, 1, 0); PG8_STAGE(PG8_SA(0, 1), a2 + hstep, voffA);
;             PG8_WAIT_V(8); PG8_WAIT_L(0); PG8_BAR; PG8_MMA(0, 0, At, B0); PG8_MMA(0, 1, At, B1); PG8_BAR; PG8_SCHED;
	s_setprio 1
	v_mfma_f32_16x16x32_bf16 v[124:127], v[146:149], v[178:181], 0
	v_mfma_f32_16x16x32_bf16 v[124:127], v[150:153], v[182:185], v[124:127]
	v_mfma_f32_16x16x32_bf16 v[112:115], v[150:153], v[204:207], 0
	v_mfma_f32_16x16x32_bf16 v[112:115], v[146:149], v[186:189], v[112:115]
	v_mfma_f32_16x16x32_bf16 v[96:99], v[146:149], v[208:211], 0
	v_mfma_f32_16x16x32_bf16 v[96:99], v[150:153], v[212:215], v[96:99]
	v_mfma_f32_16x16x32_bf16 v[80:83], v[150:153], v[220:223], 0
	v_mfma_f32_16x16x32_bf16 v[80:83], v[146:149], v[216:219], v[80:83]
	v_mfma_f32_16x16x32_bf16 v[76:79], v[154:157], v[216:219], 0
	v_mfma_f32_16x16x32_bf16 v[76:79], v[158:161], v[220:223], v[76:79]
	v_mfma_f32_16x16x32_bf16 v[92:95], v[158:161], v[212:215], 0
	v_mfma_f32_16x16x32_bf16 v[92:95], v[154:157], v[208:211], v[92:95]
	v_mfma_f32_16x16x32_bf16 v[108:111], v[154:157], v[186:189], 0
	v_mfma_f32_16x16x32_bf16 v[108:111], v[158:161], v[204:207], v[108:111]
	v_mfma_f32_16x16x32_bf16 v[128:131], v[158:161], v[182:185], 0
	v_mfma_f32_16x16x32_bf16 v[128:131], v[154:157], v[178:181], v[128:131]
	v_mfma_f32_16x16x32_bf16 v[120:123], v[162:165], v[178:181], 0
	v_mfma_f32_16x16x32_bf16 v[120:123], v[166:169], v[182:185], v[120:123]
	v_mfma_f32_16x16x32_bf16 v[104:107], v[166:169], v[204:207], 0
	v_mfma_f32_16x16x32_bf16 v[104:107], v[162:165], v[186:189], v[104:107]
	v_mfma_f32_16x16x32_bf16 v[88:91], v[162:165], v[208:211], 0
	v_mfma_f32_16x16x32_bf16 v[88:91], v[166:169], v[212:215], v[88:91]
	v_mfma_f32_16x16x32_bf16 v[72:75], v[166:169], v[220:223], 0
	v_mfma_f32_16x16x32_bf16 v[72:75], v[162:165], v[216:219], v[72:75]
	v_mfma_f32_16x16x32_bf16 v[68:71], v[170:173], v[216:219], 0
	v_mfma_f32_16x16x32_bf16 v[68:71], v[174:177], v[220:223], v[68:71]
	v_mfma_f32_16x16x32_bf16 v[84:87], v[174:177], v[212:215], 0
	v_mfma_f32_16x16x32_bf16 v[84:87], v[170:173], v[208:211], v[84:87]
	v_mfma_f32_16x16x32_bf16 v[100:103], v[170:173], v[186:189], 0
	v_mfma_f32_16x16x32_bf16 v[100:103], v[174:177], v[204:207], v[100:103]
	v_mfma_f32_16x16x32_bf16 v[116:119], v[174:177], v[182:185], 0
	v_mfma_f32_16x16x32_bf16 v[116:119], v[170:173], v[178:181], v[116:119]
	s_setprio 0
	s_barrier
	s_add_i32 s86, s86, s28
	v_lshl_add_u64 v[190:191], s[76:77], 0, v[2:3]
	s_mov_b32 m0, s86
	ds_read_b128 v[178:181], v145 offset:16384
	ds_read_b128 v[182:185], v145 offset:17408
	ds_read_b128 v[186:189], v145 offset:18432
	ds_read_b128 v[204:207], v145 offset:19456
	ds_read_b128 v[208:211], v145 offset:20480
	ds_read_b128 v[212:215], v145 offset:21504
	ds_read_b128 v[216:219], v145 offset:22528
	ds_read_b128 v[220:223], v145 offset:23552
	global_load_lds_dwordx4 v[190:191], off
	s_add_i32 m0, s86, 0x2000
	v_lshl_add_u64 v[224:225], s[76:77], 0, v[136:137]
	s_add_u32 s76, s76, s18
	s_addc_u32 s77, s77, s19
	s_add_i32 s73, s73, s28
	global_load_lds_dwordx4 v[224:225], off
	v_lshl_add_u64 v[226:227], s[76:77], 0, v[2:3]
	s_mov_b32 m0, s73
	v_lshl_add_u64 v[228:229], s[76:77], 0, v[136:137]
	global_load_lds_dwordx4 v[226:227], off
	s_add_i32 m0, s73, 0x2000
	v_lshl_add_u64 v[240:241], s[48:49], 0, v[132:133]
	global_load_lds_dwordx4 v[228:229], off
	v_lshl_add_u64 v[242:243], s[48:49], 0, v[134:135]
	s_waitcnt vmcnt(6) lgkmcnt(0)
	s_barrier
	s_setprio 1
	v_mfma_f32_16x16x32_bf16 v[64:67], v[146:149], v[178:181], 0
	v_mfma_f32_16x16x32_bf16 v[64:67], v[150:153], v[182:185], v[64:67]
	v_mfma_f32_16x16x32_bf16 v[48:51], v[150:153], v[204:207], 0
	v_mfma_f32_16x16x32_bf16 v[48:51], v[146:149], v[186:189], v[48:51]
	v_mfma_f32_16x16x32_bf16 v[32:35], v[146:149], v[208:211], 0
	v_mfma_f32_16x16x32_bf16 v[32:35], v[150:153], v[212:215], v[32:35]
	v_mfma_f32_16x16x32_bf16 v[16:19], v[150:153], v[220:223], 0
	v_mfma_f32_16x16x32_bf16 v[16:19], v[146:149], v[216:219], v[16:19]
	v_mfma_f32_16x16x32_bf16 v[12:15], v[154:157], v[216:219], 0
	v_mfma_f32_16x16x32_bf16 v[12:15], v[158:161], v[220:223], v[12:15]
	v_mfma_f32_16x16x32_bf16 v[28:31], v[158:161], v[212:215], 0
	v_mfma_f32_16x16x32_bf16 v[28:31], v[154:157], v[208:211], v[28:31]
	v_mfma_f32_16x16x32_bf16 v[44:47], v[154:157], v[186:189], 0
	v_mfma_f32_16x16x32_bf16 v[44:47], v[158:161], v[204:207], v[44:47]
	v_mfma_f32_16x16x32_bf16 v[60:63], v[158:161], v[182:185], 0
	v_mfma_f32_16x16x32_bf16 v[60:63], v[154:157], v[178:181], v[60:63]
	v_mfma_f32_16x16x32_bf16 v[56:59], v[162:165], v[178:181], 0
	v_mfma_f32_16x16x32_bf16 v[56:59], v[166:169], v[182:185], v[56:59]
	v_mfma_f32_16x16x32_bf16 v[40:43], v[166:169], v[204:207], 0
	v_mfma_f32_16x16x32_bf16 v[40:43], v[162:165], v[186:189], v[40:43]
	v_mfma_f32_16x16x32_bf16 v[24:27], v[162:165], v[208:211], 0
	v_mfma_f32_16x16x32_bf16 v[24:27], v[166:169], v[212:215], v[24:27]
	v_mfma_f32_16x16x32_bf16 v[8:11], v[166:169], v[220:223], 0
	v_mfma_f32_16x16x32_bf16 v[8:11], v[162:165], v[216:219], v[8:11]
	v_mfma_f32_16x16x32_bf16 v[4:7], v[170:173], v[216:219], 0
	v_mfma_f32_16x16x32_bf16 v[4:7], v[174:177], v[220:223], v[4:7]
	v_mfma_f32_16x16x32_bf16 v[20:23], v[174:177], v[212:215], 0
	v_mfma_f32_16x16x32_bf16 v[20:23], v[170:173], v[208:211], v[20:23]
	v_mfma_f32_16x16x32_bf16 v[36:39], v[170:173], v[186:189], 0
	v_mfma_f32_16x16x32_bf16 v[36:39], v[174:177], v[204:207], v[36:39]
	v_mfma_f32_16x16x32_bf16 v[52:55], v[174:177], v[182:185], 0
	v_mfma_f32_16x16x32_bf16 v[52:55], v[170:173], v[178:181], v[52:55]
	s_setprio 0
	s_barrier
; #define PG8_STAGE(bufoff, gbase, voff) do { _Pragma("unroll") for (int _i = 0; _i < 2; ++_i) \
;         __builtin_amdgcn_global_load_lds((const unsigned*)((const char*)(gbase) + (voff)[_i]), (PG8_LAS unsigned*)(lds + (bufoff) + ldsw + _i * 8192), 16, 0, 0); } while (0)
; #define PG8_LDA(dst, b, h) do { _Pragma("unroll") for (int m = 0; m < 4; ++m) _Pragma("unroll") for (int k = 0; k < 2; ++k) dst[m][k] = *(const PG8_LAS bf16x8*)(lds + PG8_SA(b, h) + aoff + m * 2048 + k * 1024); } while (0)
; #define PG8_LDB(dst, b, h) do { _Pragma("unroll") for (int n = 0; n < 2; ++n) _Pragma("unroll") for (int k = 0; k < 2; ++k) dst[n][k] = *(const PG8_LAS bf16x8*)(lds + PG8_SB(b, h) + boff + n * 2048 + k * 1024); } while (0)
; #define PG8_WAIT_V(n) asm volatile("s_waitcnt vmcnt(" #n ")" ::: "memory")
; #define PG8_WAIT_L(n) asm volatile("s_waitcnt lgkmcnt(" #n ")" ::: "memory")
; #define PG8_BAR __builtin_amdgcn_s_barrier()
; #define PG8_SCHED __builtin_amdgcn_sched_barrier(0)
; template <class Epi, class Sched, bool ALIGN_EPI = false, bool SP2 = false, bool I8 = false>
; __device__ __forceinline__ void gemm_phase(PG8_LAS unsigned char* lds, const Gemm g, const Sched& S, const Epi& E) {
;     ...
;             PG8_LDB(B0, 1, 0); PG8_LDB(B1, 1, 1); PG8_SCHED; PG8_LDA(At, 1, 0); PG8_STAGE(PG8_SA(0, 1), a2 + hstep, voffA);
;             PG8_WAIT_V(8); PG8_WAIT_L(0); PG8_BAR; PG8_MMA(0, 0, At, B0); PG8_MMA(0, 1, At, B1); PG8_BAR; PG8_SCHED;
;             PG8_LDA(At, 1, 1); PG8_STAGE(PG8_SB(1, 0), b3, voffB); PG8_STAGE(PG8_SB(1, 1), b3 + hstep, voffB); PG8_STAGE(PG8_SA(1, 0), a3, voffA);
;             PG8_WAIT_V(8); PG8_WAIT_L(0); PG8_BAR; PG8_MMA(1, 0, At, B0); PG8_MMA(1, 1, At, B1); PG8_BAR; PG8_SCHED;
	s_mov_b32 m0, s47
	s_nop 0
	global_load_lds_dwordx4 v[240:241], off
	s_mov_b32 m0, s50
	s_nop 0
	global_load_lds_dwordx4 v[242:243], off
	s_add_i32 s73, 0, 0x18000
	s_add_i32 s76, 0, 0x1c000
	v_add_u32_e32 v158, s73, v143
	v_add_u32_e32 v174, s76, v143
	ds_read_b128 v[146:149], v158
	ds_read_b128 v[150:153], v158 offset:1024
	ds_read_b128 v[154:157], v158 offset:2048
	ds_read_b128 v[158:161], v158 offset:3072
	ds_read_b128 v[162:165], v174
	ds_read_b128 v[166:169], v174 offset:1024
	ds_read_b128 v[170:173], v174 offset:2048
	ds_read_b128 v[174:177], v174 offset:3072
	s_add_u32 s48, s48, s18
	s_addc_u32 s49, s49, s19
	s_mov_b32 m0, s51
	ds_read_b128 v[178:181], v145 offset:32768
	ds_read_b128 v[182:185], v145 offset:33792
	ds_read_b128 v[186:189], v145 offset:34816
	ds_read_b128 v[204:207], v145 offset:35840
	ds_read_b128 v[208:211], v145 offset:36864
	ds_read_b128 v[212:215], v145 offset:37888
	ds_read_b128 v[216:219], v145 offset:38912
	ds_read_b128 v[220:223], v145 offset:39936
	global_load_lds_dwordx4 v132, s[48:49]
	s_mov_b32 m0, s52
	s_nop 0
	global_load_lds_dwordx4 v134, s[48:49]
	s_waitcnt vmcnt(8) lgkmcnt(0)
	s_barrier
	s_setprio 1
	v_mfma_f32_16x16x32_bf16 v[124:127], v[146:149], v[178:181], v[124:127]
	v_mfma_f32_16x16x32_bf16 v[124:127], v[150:153], v[182:185], v[124:127]
	v_mfma_f32_16x16x32_bf16 v[112:115], v[150:153], v[204:207], v[112:115]
	v_mfma_f32_16x16x32_bf16 v[112:115], v[146:149], v[186:189], v[112:115]
	v_mfma_f32_16x16x32_bf16 v[96:99], v[146:149], v[208:211], v[96:99]
	v_mfma_f32_16x16x32_bf16 v[96:99], v[150:153], v[212:215], v[96:99]
	v_mfma_f32_16x16x32_bf16 v[80:83], v[150:153], v[220:223], v[80:83]
	v_mfma_f32_16x16x32_bf16 v[80:83], v[146:149], v[216:219], v[80:83]
	v_mfma_f32_16x16x32_bf16 v[76:79], v[154:157], v[216:219], v[76:79]
	v_mfma_f32_16x16x32_bf16 v[76:79], v[158:161], v[220:223], v[76:79]
	v_mfma_f32_16x16x32_bf16 v[92:95], v[158:161], v[212:215], v[92:95]
	v_mfma_f32_16x16x32_bf16 v[92:95], v[154:157], v[208:211], v[92:95]
	v_mfma_f32_16x16x32_bf16 v[108:111], v[154:157], v[186:189], v[108:111]
	v_mfma_f32_16x16x32_bf16 v[108:111], v[158:161], v[204:207], v[108:111]
	v_mfma_f32_16x16x32_bf16 v[128:131], v[158:161], v[182:185], v[128:131]
	v_mfma_f32_16x16x32_bf16 v[128:131], v[154:157], v[178:181], v[128:131]
	v_mfma_f32_16x16x32_bf16 v[120:123], v[162:165], v[178:181], v[120:123]
	v_mfma_f32_16x16x32_bf16 v[120:123], v[166:169], v[182:185], v[120:123]
	v_mfma_f32_16x16x32_bf16 v[104:107], v[166:169], v[204:207], v[104:107]
	v_mfma_f32_16x16x32_bf16 v[104:107], v[162:165], v[186:189], v[104:107]
	v_mfma_f32_16x16x32_bf16 v[88:91], v[162:165], v[208:211], v[88:91]
	v_mfma_f32_16x16x32_bf16 v[88:91], v[166:169], v[212:215], v[88:91]
	v_mfma_f32_16x16x32_bf16 v[72:75], v[166:169], v[220:223], v[72:75]
	v_mfma_f32_16x16x32_bf16 v[72:75], v[162:165], v[216:219], v[72:75]
	v_mfma_f32_16x16x32_bf16 v[68:71], v[170:173], v[216:219], v[68:71]
	v_mfma_f32_16x16x32_bf16 v[68:71], v[174:177], v[220:223], v[68:71]
	v_mfma_f32_16x16x32_bf16 v[84:87], v[174:177], v[212:215], v[84:87]
	v_mfma_f32_16x16x32_bf16 v[84:87], v[170:173], v[208:211], v[84:87]
	v_mfma_f32_16x16x32_bf16 v[100:103], v[170:173], v[186:189], v[100:103]
	v_mfma_f32_16x16x32_bf16 v[100:103], v[174:177], v[204:207], v[100:103]
	v_mfma_f32_16x16x32_bf16 v[116:119], v[174:177], v[182:185], v[116:119]
	v_mfma_f32_16x16x32_bf16 v[116:119], v[170:173], v[178:181], v[116:119]
	s_setprio 0
	s_barrier
	s_add_i32 s48, s73, s28
	v_lshl_add_u64 v[190:191], v[190:191], 0, s[84:85]
	s_mov_b32 m0, s48
	ds_read_b128 v[178:181], v145 offset:49152
	ds_read_b128 v[182:185], v145 offset:50176
	ds_read_b128 v[186:189], v145 offset:51200
	ds_read_b128 v[204:207], v145 offset:52224
	ds_read_b128 v[208:211], v145 offset:53248
	ds_read_b128 v[212:215], v145 offset:54272
	ds_read_b128 v[216:219], v145 offset:55296
	ds_read_b128 v[220:223], v145 offset:56320
	global_load_lds_dwordx4 v[190:191], off
	v_lshl_add_u64 v[190:191], v[224:225], 0, s[84:85]
	s_add_i32 m0, s48, 0x2000
	s_add_i32 s48, s76, s28
	global_load_lds_dwordx4 v[190:191], off
	v_lshl_add_u64 v[190:191], v[226:227], 0, s[84:85]
	s_mov_b32 m0, s48
	s_nop 0
	global_load_lds_dwordx4 v[190:191], off
	v_lshl_add_u64 v[190:191], v[228:229], 0, s[84:85]
	s_add_i32 m0, s48, 0x2000
	s_nop 0
	global_load_lds_dwordx4 v[190:191], off
	v_lshl_add_u64 v[190:191], v[240:241], 0, s[84:85]
	s_mov_b32 m0, s55
	s_nop 0
	global_load_lds_dwordx4 v[190:191], off
	v_lshl_add_u64 v[190:191], v[242:243], 0, s[84:85]
	s_mov_b32 m0, s56
	s_nop 0
	global_load_lds_dwordx4 v[190:191], off
	s_waitcnt vmcnt(8) lgkmcnt(0)
	s_barrier
	s_setprio 1
	v_mfma_f32_16x16x32_bf16 v[64:67], v[146:149], v[178:181], v[64:67]
	v_mfma_f32_16x16x32_bf16 v[64:67], v[150:153], v[182:185], v[64:67]
	v_mfma_f32_16x16x32_bf16 v[48:51], v[150:153], v[204:207], v[48:51]
	v_mfma_f32_16x16x32_bf16 v[48:51], v[146:149], v[186:189], v[48:51]
	v_mfma_f32_16x16x32_bf16 v[32:35], v[146:149], v[208:211], v[32:35]
	v_mfma_f32_16x16x32_bf16 v[32:35], v[150:153], v[212:215], v[32:35]
	v_mfma_f32_16x16x32_bf16 v[16:19], v[150:153], v[220:223], v[16:19]
	v_mfma_f32_16x16x32_bf16 v[16:19], v[146:149], v[216:219], v[16:19]
	v_mfma_f32_16x16x32_bf16 v[12:15], v[154:157], v[216:219], v[12:15]
	v_mfma_f32_16x16x32_bf16 v[12:15], v[158:161], v[220:223], v[12:15]
	v_mfma_f32_16x16x32_bf16 v[28:31], v[158:161], v[212:215], v[28:31]
	v_mfma_f32_16x16x32_bf16 v[28:31], v[154:157], v[208:211], v[28:31]
	v_mfma_f32_16x16x32_bf16 v[44:47], v[154:157], v[186:189], v[44:47]
	v_mfma_f32_16x16x32_bf16 v[44:47], v[158:161], v[204:207], v[44:47]
	v_mfma_f32_16x16x32_bf16 v[60:63], v[158:161], v[182:185], v[60:63]
	v_mfma_f32_16x16x32_bf16 v[60:63], v[154:157], v[178:181], v[60:63]
	v_mfma_f32_16x16x32_bf16 v[56:59], v[162:165], v[178:181], v[56:59]
	v_mfma_f32_16x16x32_bf16 v[56:59], v[166:169], v[182:185], v[56:59]
	v_mfma_f32_16x16x32_bf16 v[40:43], v[166:169], v[204:207], v[40:43]
	v_mfma_f32_16x16x32_bf16 v[40:43], v[162:165], v[186:189], v[40:43]
	v_mfma_f32_16x16x32_bf16 v[24:27], v[162:165], v[208:211], v[24:27]
	v_mfma_f32_16x16x32_bf16 v[24:27], v[166:169], v[212:215], v[24:27]
	v_mfma_f32_16x16x32_bf16 v[8:11], v[166:169], v[220:223], v[8:11]
	v_mfma_f32_16x16x32_bf16 v[8:11], v[162:165], v[216:219], v[8:11]
	v_mfma_f32_16x16x32_bf16 v[4:7], v[170:173], v[216:219], v[4:7]
	v_mfma_f32_16x16x32_bf16 v[4:7], v[174:177], v[220:223], v[4:7]
	v_mfma_f32_16x16x32_bf16 v[20:23], v[174:177], v[212:215], v[20:23]
	v_mfma_f32_16x16x32_bf16 v[20:23], v[170:173], v[208:211], v[20:23]
	v_mfma_f32_16x16x32_bf16 v[36:39], v[170:173], v[186:189], v[36:39]
	v_mfma_f32_16x16x32_bf16 v[36:39], v[174:177], v[204:207], v[36:39]
	v_mfma_f32_16x16x32_bf16 v[52:55], v[174:177], v[182:185], v[52:55]
	v_mfma_f32_16x16x32_bf16 v[52:55], v[170:173], v[178:181], v[52:55]
	s_setprio 0
	s_barrier
	s_add_u32 s44, s44, 0x100
	s_addc_u32 s45, s45, 0
	s_add_u32 s65, s65, 0x100
	s_addc_u32 s67, s67, 0
	s_cmp_ge_i32 s72, s53
	s_mov_b32 s48, s72
	s_cbranch_scc1 .Lkloop_exit_4
; #define PG8_STAGE(bufoff, gbase, voff) do { _Pragma("unroll") for (int _i = 0; _i < 2; ++_i) \
;         __builtin_amdgcn_global_load_lds((const unsigned*)((const char*)(gbase) + (voff)[_i]), (PG8_LAS unsigned*)(lds + (bufoff) + ldsw + _i * 8192), 16, 0, 0); } while (0)
; #define PG8_LDA(dst, b, h) do { _Pragma("unroll") for (int m = 0; m < 4; ++m) _Pragma("unroll") for (int k = 0; k < 2; ++k) dst[m][k] = *(const PG8_LAS bf16x8*)(lds + PG8_SA(b, h) + aoff + m * 2048 + k * 1024); } while (0)
; #define PG8_LDB(dst, b, h) do { _Pragma("unroll") for (int n = 0; n < 2; ++n) _Pragma("unroll") for (int k = 0; k < 2; ++k) dst[n][k] = *(const PG8_LAS bf16x8*)(lds + PG8_SB(b, h) + boff + n * 2048 + k * 1024); } while (0)
; #define PG8_WAIT_V(n) asm volatile("s_waitcnt vmcnt(" #n ")" ::: "memory")
; #define PG8_WAIT_L(n) asm volatile("s_waitcnt lgkmcnt(" #n ")" ::: "memory")
; #define PG8_BAR __builtin_amdgcn_s_barrier()
; #define PG8_SCHED __builtin_amdgcn_sched_barrier(0)
; template <class Epi, class Sched, bool ALIGN_EPI = false, bool SP2 = false, bool I8 = false>
; __device__ __forceinline__ void gemm_phase(PG8_LAS unsigned char* lds, const Gemm g, const Sched& S, const Epi& E) {
;     ...
;         for (int t = 0; t < nt; t += 2) {
;             const bool last = (t == nt - 2);
;             const char* a1 = cA + (size_t)(t + 1) * kstep;
;             const char* a2 = last ? nA : cA + (size_t)(t + 2) * kstep; const char* b2 = last ? nB : cB + (size_t)(t + 2) * kstep;
;             const char* a3 = a2 + kstep; const char* b3 = b2 + kstep;
;             if (last && has_next) S.a_ready(nxt);
;             if constexpr (SP2) {
;             PG8_LDB(B0, 0, 0); PG8_LDB(B1, 0, 1); PG8_SCHED; PG8_LDA(At, 0, 0); PG8_STAGE(PG8_SA(1, 1), a1 + hstep, voffA);
;             PG8_WAIT_V(8); PG8_WAIT_L(0); PG8_BAR; PG8_MMA(0, 0, At, B0); PG8_MMA(0, 1, At, B1); PG8_BAR; PG8_SCHED;
;             PG8_LDA(At, 0, 1); PG8_STAGE(PG8_SB(0, 0), b2, voffB); PG8_STAGE(PG8_SB(0, 1), b2 + hstep, voffB); PG8_STAGE(PG8_SA(0, 0), a2, voffA);
;             PG8_WAIT_V(8); PG8_WAIT_L(0); PG8_BAR; PG8_MMA(1, 0, At, B0); PG8_MMA(1, 1, At, B1); PG8_BAR; PG8_SCHED;
.LBB0_1623:
	s_add_i32 s72, s48, 2
	s_add_u32 s73, s44, 0x80
	s_addc_u32 s49, s45, 0
	s_add_i32 s86, 0, 0x10000
	s_cmp_eq_u32 s57, s48
	s_cselect_b32 s49, s13, s49
	s_cselect_b32 s48, s12, s73
	s_cselect_b32 s77, s41, s67
	s_cselect_b32 s76, s40, s65
	s_add_i32 s73, 0, 0x14000
	v_add_u32_e32 v158, s86, v143
	v_add_u32_e32 v174, s73, v143
	ds_read_b128 v[146:149], v158
	ds_read_b128 v[150:153], v158 offset:1024
	ds_read_b128 v[154:157], v158 offset:2048
	ds_read_b128 v[158:161], v158 offset:3072
	ds_read_b128 v[162:165], v174
	ds_read_b128 v[166:169], v174 offset:1024
	ds_read_b128 v[170:173], v174 offset:2048
	ds_read_b128 v[174:177], v174 offset:3072
	v_lshl_add_u64 v[190:191], s[44:45], 0, v[138:139]
	s_add_i32 m0, s47, 0xc000
	ds_read_b128 v[178:181], v145
	ds_read_b128 v[182:185], v145 offset:1024
	ds_read_b128 v[186:189], v145 offset:2048
	ds_read_b128 v[204:207], v145 offset:3072
	ds_read_b128 v[208:211], v145 offset:4096
	ds_read_b128 v[212:215], v145 offset:5120
	ds_read_b128 v[216:219], v145 offset:6144
	ds_read_b128 v[220:223], v145 offset:7168
	global_load_lds_dwordx4 v[190:191], off
	v_lshl_add_u64 v[190:191], s[44:45], 0, v[140:141]
	s_add_i32 m0, s47, 0xe000
	s_nop 0
	global_load_lds_dwordx4 v[190:191], off
	s_waitcnt vmcnt(8) lgkmcnt(0)
	s_barrier
	s_setprio 1
	v_mfma_f32_16x16x32_bf16 v[124:127], v[146:149], v[178:181], v[124:127]
	v_mfma_f32_16x16x32_bf16 v[124:127], v[150:153], v[182:185], v[124:127]
	v_mfma_f32_16x16x32_bf16 v[112:115], v[150:153], v[204:207], v[112:115]
	v_mfma_f32_16x16x32_bf16 v[112:115], v[146:149], v[186:189], v[112:115]
	v_mfma_f32_16x16x32_bf16 v[96:99], v[146:149], v[208:211], v[96:99]
	v_mfma_f32_16x16x32_bf16 v[96:99], v[150:153], v[212:215], v[96:99]
	v_mfma_f32_16x16x32_bf16 v[80:83], v[150:153], v[220:223], v[80:83]
	v_mfma_f32_16x16x32_bf16 v[80:83], v[146:149], v[216:219], v[80:83]
	v_mfma_f32_16x16x32_bf16 v[76:79], v[154:157], v[216:219], v[76:79]
	v_mfma_f32_16x16x32_bf16 v[76:79], v[158:161], v[220:223], v[76:79]
	v_mfma_f32_16x16x32_bf16 v[92:95], v[158:161], v[212:215], v[92:95]
	v_mfma_f32_16x16x32_bf16 v[92:95], v[154:157], v[208:211], v[92:95]
	v_mfma_f32_16x16x32_bf16 v[108:111], v[154:157], v[186:189], v[108:111]
	v_mfma_f32_16x16x32_bf16 v[108:111], v[158:161], v[204:207], v[108:111]
	v_mfma_f32_16x16x32_bf16 v[128:131], v[158:161], v[182:185], v[128:131]
	v_mfma_f32_16x16x32_bf16 v[128:131], v[154:157], v[178:181], v[128:131]
	v_mfma_f32_16x16x32_bf16 v[120:123], v[162:165], v[178:181], v[120:123]
	v_mfma_f32_16x16x32_bf16 v[120:123], v[166:169], v[182:185], v[120:123]
	v_mfma_f32_16x16x32_bf16 v[104:107], v[166:169], v[204:207], v[104:107]
	v_mfma_f32_16x16x32_bf16 v[104:107], v[162:165], v[186:189], v[104:107]
	v_mfma_f32_16x16x32_bf16 v[88:91], v[162:165], v[208:211], v[88:91]
	v_mfma_f32_16x16x32_bf16 v[88:91], v[166:169], v[212:215], v[88:91]
	v_mfma_f32_16x16x32_bf16 v[72:75], v[166:169], v[220:223], v[72:75]
	v_mfma_f32_16x16x32_bf16 v[72:75], v[162:165], v[216:219], v[72:75]
	v_mfma_f32_16x16x32_bf16 v[68:71], v[170:173], v[216:219], v[68:71]
	v_mfma_f32_16x16x32_bf16 v[68:71], v[174:177], v[220:223], v[68:71]
	v_mfma_f32_16x16x32_bf16 v[84:87], v[174:177], v[212:215], v[84:87]
	v_mfma_f32_16x16x32_bf16 v[84:87], v[170:173], v[208:211], v[84:87]
	v_mfma_f32_16x16x32_bf16 v[100:103], v[170:173], v[186:189], v[100:103]
	v_mfma_f32_16x16x32_bf16 v[100:103], v[174:177], v[204:207], v[100:103]
	v_mfma_f32_16x16x32_bf16 v[116:119], v[174:177], v[182:185], v[116:119]
	v_mfma_f32_16x16x32_bf16 v[116:119], v[170:173], v[178:181], v[116:119]
	s_setprio 0
	s_barrier
	s_add_i32 s86, s86, s28
	v_lshl_add_u64 v[190:191], s[76:77], 0, v[2:3]
	s_mov_b32 m0, s86
	ds_read_b128 v[178:181], v145 offset:16384
	ds_read_b128 v[182:185], v145 offset:17408
	ds_read_b128 v[186:189], v145 offset:18432
	ds_read_b128 v[204:207], v145 offset:19456
	ds_read_b128 v[208:211], v145 offset:20480
	ds_read_b128 v[212:215], v145 offset:21504
	ds_read_b128 v[216:219], v145 offset:22528
	ds_read_b128 v[220:223], v145 offset:23552
	global_load_lds_dwordx4 v[190:191], off
	s_add_i32 m0, s86, 0x2000
	v_lshl_add_u64 v[224:225], s[76:77], 0, v[136:137]
	s_add_u32 s76, s76, s18
	s_addc_u32 s77, s77, s19
	s_add_i32 s73, s73, s28
	global_load_lds_dwordx4 v[224:225], off
	v_lshl_add_u64 v[226:227], s[76:77], 0, v[2:3]
	s_mov_b32 m0, s73
	v_lshl_add_u64 v[228:229], s[76:77], 0, v[136:137]
	global_load_lds_dwordx4 v[226:227], off
	s_add_i32 m0, s73, 0x2000
	v_lshl_add_u64 v[240:241], s[48:49], 0, v[132:133]
	global_load_lds_dwordx4 v[228:229], off
	v_lshl_add_u64 v[242:243], s[48:49], 0, v[134:135]
	s_waitcnt vmcnt(6) lgkmcnt(0)
	s_barrier
; #define PG8_STAGE(bufoff, gbase, voff) do { _Pragma("unroll") for (int _i = 0; _i < 2; ++_i) \
;         __builtin_amdgcn_global_load_lds((const unsigned*)((const char*)(gbase) + (voff)[_i]), (PG8_LAS unsigned*)(lds + (bufoff) + ldsw + _i * 8192), 16, 0, 0); } while (0)
; #define PG8_LDA(dst, b, h) do { _Pragma("unroll") for (int m = 0; m < 4; ++m) _Pragma("unroll") for (int k = 0; k < 2; ++k) dst[m][k] = *(const PG8_LAS bf16x8*)(lds + PG8_SA(b, h) + aoff + m * 2048 + k * 1024); } while (0)
; #define PG8_LDB(dst, b, h) do { _Pragma("unroll") for (int n = 0; n < 2; ++n) _Pragma("unroll") for (int k = 0; k < 2; ++k) dst[n][k] = *(const PG8_LAS bf16x8*)(lds + PG8_SB(b, h) + boff + n * 2048 + k * 1024); } while (0)
; #define PG8_WAIT_V(n) asm volatile("s_waitcnt vmcnt(" #n ")" ::: "memory")
; #define PG8_WAIT_L(n) asm volatile("s_waitcnt lgkmcnt(" #n ")" ::: "memory")
; #define PG8_BAR __builtin_amdgcn_s_barrier()
; #define PG8_SCHED __builtin_amdgcn_sched_barrier(0)
; template <class Epi, class Sched, bool ALIGN_EPI = false, bool SP2 = false, bool I8 = false>
; __device__ __forceinline__ void gemm_phase(PG8_LAS unsigned char* lds, const Gemm g, const Sched& S, const Epi& E) {
;     ...
;             PG8_WAIT_V(8); PG8_WAIT_L(0); PG8_BAR; PG8_MMA(1, 0, At, B0); PG8_MMA(1, 1, At, B1); PG8_BAR; PG8_SCHED;
;             PG8_LDB(B0, 1, 0); PG8_LDB(B1, 1, 1); PG8_SCHED; PG8_LDA(At, 1, 0); PG8_STAGE(PG8_SA(0, 1), a2 + hstep, voffA);
;             PG8_WAIT_V(8); PG8_WAIT_L(0); PG8_BAR; PG8_MMA(0, 0, At, B0); PG8_MMA(0, 1, At, B1); PG8_BAR; PG8_SCHED;
;             PG8_LDA(At, 1, 1); PG8_STAGE(PG8_SB(1, 0), b3, voffB); PG8_STAGE(PG8_SB(1, 1), b3 + hstep, voffB); PG8_STAGE(PG8_SA(1, 0), a3, voffA);
	s_setprio 1
	v_mfma_f32_16x16x32_bf16 v[64:67], v[146:149], v[178:181], v[64:67]
	v_mfma_f32_16x16x32_bf16 v[64:67], v[150:153], v[182:185], v[64:67]
	v_mfma_f32_16x16x32_bf16 v[48:51], v[150:153], v[204:207], v[48:51]
	v_mfma_f32_16x16x32_bf16 v[48:51], v[146:149], v[186:189], v[48:51]
	v_mfma_f32_16x16x32_bf16 v[32:35], v[146:149], v[208:211], v[32:35]
	v_mfma_f32_16x16x32_bf16 v[32:35], v[150:153], v[212:215], v[32:35]
	v_mfma_f32_16x16x32_bf16 v[16:19], v[150:153], v[220:223], v[16:19]
	v_mfma_f32_16x16x32_bf16 v[16:19], v[146:149], v[216:219], v[16:19]
	v_mfma_f32_16x16x32_bf16 v[12:15], v[154:157], v[216:219], v[12:15]
	v_mfma_f32_16x16x32_bf16 v[12:15], v[158:161], v[220:223], v[12:15]
	v_mfma_f32_16x16x32_bf16 v[28:31], v[158:161], v[212:215], v[28:31]
	v_mfma_f32_16x16x32_bf16 v[28:31], v[154:157], v[208:211], v[28:31]
	v_mfma_f32_16x16x32_bf16 v[44:47], v[154:157], v[186:189], v[44:47]
	v_mfma_f32_16x16x32_bf16 v[44:47], v[158:161], v[204:207], v[44:47]
	v_mfma_f32_16x16x32_bf16 v[60:63], v[158:161], v[182:185], v[60:63]
	v_mfma_f32_16x16x32_bf16 v[60:63], v[154:157], v[178:181], v[60:63]
	v_mfma_f32_16x16x32_bf16 v[56:59], v[162:165], v[178:181], v[56:59]
	v_mfma_f32_16x16x32_bf16 v[56:59], v[166:169], v[182:185], v[56:59]
	v_mfma_f32_16x16x32_bf16 v[40:43], v[166:169], v[204:207], v[40:43]
	v_mfma_f32_16x16x32_bf16 v[40:43], v[162:165], v[186:189], v[40:43]
	v_mfma_f32_16x16x32_bf16 v[24:27], v[162:165], v[208:211], v[24:27]
	v_mfma_f32_16x16x32_bf16 v[24:27], v[166:169], v[212:215], v[24:27]
	v_mfma_f32_16x16x32_bf16 v[8:11], v[166:169], v[220:223], v[8:11]
	v_mfma_f32_16x16x32_bf16 v[8:11], v[162:165], v[216:219], v[8:11]
	v_mfma_f32_16x16x32_bf16 v[4:7], v[170:173], v[216:219], v[4:7]
	v_mfma_f32_16x16x32_bf16 v[4:7], v[174:177], v[220:223], v[4:7]
	v_mfma_f32_16x16x32_bf16 v[20:23], v[174:177], v[212:215], v[20:23]
	v_mfma_f32_16x16x32_bf16 v[20:23], v[170:173], v[208:211], v[20:23]
	v_mfma_f32_16x16x32_bf16 v[36:39], v[170:173], v[186:189], v[36:39]
	v_mfma_f32_16x16x32_bf16 v[36:39], v[174:177], v[204:207], v[36:39]
	v_mfma_f32_16x16x32_bf16 v[52:55], v[174:177], v[182:185], v[52:55]
	v_mfma_f32_16x16x32_bf16 v[52:55], v[170:173], v[178:181], v[52:55]
	s_setprio 0
	s_barrier
	s_mov_b32 m0, s47
	s_nop 0
	global_load_lds_dwordx4 v[240:241], off
	s_mov_b32 m0, s50
	s_nop 0
	global_load_lds_dwordx4 v[242:243], off
	s_add_i32 s73, 0, 0x18000
	s_add_i32 s76, 0, 0x1c000
	v_add_u32_e32 v158, s73, v143
	v_add_u32_e32 v174, s76, v143
	ds_read_b128 v[146:149], v158
	ds_read_b128 v[150:153], v158 offset:1024
	ds_read_b128 v[154:157], v158 offset:2048
	ds_read_b128 v[158:161], v158 offset:3072
	ds_read_b128 v[162:165], v174
	ds_read_b128 v[166:169], v174 offset:1024
	ds_read_b128 v[170:173], v174 offset:2048
	ds_read_b128 v[174:177], v174 offset:3072
	s_add_u32 s48, s48, s18
	s_addc_u32 s49, s49, s19
	s_mov_b32 m0, s51
	ds_read_b128 v[178:181], v145 offset:32768
	ds_read_b128 v[182:185], v145 offset:33792
	ds_read_b128 v[186:189], v145 offset:34816
	ds_read_b128 v[204:207], v145 offset:35840
	ds_read_b128 v[208:211], v145 offset:36864
	ds_read_b128 v[212:215], v145 offset:37888
	ds_read_b128 v[216:219], v145 offset:38912
	ds_read_b128 v[220:223], v145 offset:39936
	global_load_lds_dwordx4 v132, s[48:49]
	s_mov_b32 m0, s52
	s_nop 0
	global_load_lds_dwordx4 v134, s[48:49]
	s_waitcnt vmcnt(8) lgkmcnt(0)
	s_barrier
	s_setprio 1
	v_mfma_f32_16x16x32_bf16 v[124:127], v[146:149], v[178:181], v[124:127]
	v_mfma_f32_16x16x32_bf16 v[124:127], v[150:153], v[182:185], v[124:127]
	v_mfma_f32_16x16x32_bf16 v[112:115], v[150:153], v[204:207], v[112:115]
	v_mfma_f32_16x16x32_bf16 v[112:115], v[146:149], v[186:189], v[112:115]
	v_mfma_f32_16x16x32_bf16 v[96:99], v[146:149], v[208:211], v[96:99]
	v_mfma_f32_16x16x32_bf16 v[96:99], v[150:153], v[212:215], v[96:99]
	v_mfma_f32_16x16x32_bf16 v[80:83], v[150:153], v[220:223], v[80:83]
	v_mfma_f32_16x16x32_bf16 v[80:83], v[146:149], v[216:219], v[80:83]
	v_mfma_f32_16x16x32_bf16 v[76:79], v[154:157], v[216:219], v[76:79]
	v_mfma_f32_16x16x32_bf16 v[76:79], v[158:161], v[220:223], v[76:79]
	v_mfma_f32_16x16x32_bf16 v[92:95], v[158:161], v[212:215], v[92:95]
	v_mfma_f32_16x16x32_bf16 v[92:95], v[154:157], v[208:211], v[92:95]
	v_mfma_f32_16x16x32_bf16 v[108:111], v[154:157], v[186:189], v[108:111]
	v_mfma_f32_16x16x32_bf16 v[108:111], v[158:161], v[204:207], v[108:111]
	v_mfma_f32_16x16x32_bf16 v[128:131], v[158:161], v[182:185], v[128:131]
	v_mfma_f32_16x16x32_bf16 v[128:131], v[154:157], v[178:181], v[128:131]
	v_mfma_f32_16x16x32_bf16 v[120:123], v[162:165], v[178:181], v[120:123]
	v_mfma_f32_16x16x32_bf16 v[120:123], v[166:169], v[182:185], v[120:123]
	v_mfma_f32_16x16x32_bf16 v[104:107], v[166:169], v[204:207], v[104:107]
	v_mfma_f32_16x16x32_bf16 v[104:107], v[162:165], v[186:189], v[104:107]
	v_mfma_f32_16x16x32_bf16 v[88:91], v[162:165], v[208:211], v[88:91]
	v_mfma_f32_16x16x32_bf16 v[88:91], v[166:169], v[212:215], v[88:91]
	v_mfma_f32_16x16x32_bf16 v[72:75], v[166:169], v[220:223], v[72:75]
	v_mfma_f32_16x16x32_bf16 v[72:75], v[162:165], v[216:219], v[72:75]
	v_mfma_f32_16x16x32_bf16 v[68:71], v[170:173], v[216:219], v[68:71]
	v_mfma_f32_16x16x32_bf16 v[68:71], v[174:177], v[220:223], v[68:71]
	v_mfma_f32_16x16x32_bf16 v[84:87], v[174:177], v[212:215], v[84:87]
	v_mfma_f32_16x16x32_bf16 v[84:87], v[170:173], v[208:211], v[84:87]
	v_mfma_f32_16x16x32_bf16 v[100:103], v[170:173], v[186:189], v[100:103]
	v_mfma_f32_16x16x32_bf16 v[100:103], v[174:177], v[204:207], v[100:103]
	v_mfma_f32_16x16x32_bf16 v[116:119], v[174:177], v[182:185], v[116:119]
	v_mfma_f32_16x16x32_bf16 v[116:119], v[170:173], v[178:181], v[116:119]
	s_setprio 0
	s_barrier
; #define PG8_STAGE(bufoff, gbase, voff) do { _Pragma("unroll") for (int _i = 0; _i < 2; ++_i) \
;         __builtin_amdgcn_global_load_lds((const unsigned*)((const char*)(gbase) + (voff)[_i]), (PG8_LAS unsigned*)(lds + (bufoff) + ldsw + _i * 8192), 16, 0, 0); } while (0)
; #define PG8_LDA(dst, b, h) do { _Pragma("unroll") for (int m = 0; m < 4; ++m) _Pragma("unroll") for (int k = 0; k < 2; ++k) dst[m][k] = *(const PG8_LAS bf16x8*)(lds + PG8_SA(b, h) + aoff + m * 2048 + k * 1024); } while (0)
; #define PG8_WAIT_V(n) asm volatile("s_waitcnt vmcnt(" #n ")" ::: "memory")
; #define PG8_WAIT_L(n) asm volatile("s_waitcnt lgkmcnt(" #n ")" ::: "memory")
; #define PG8_BAR __builtin_amdgcn_s_barrier()
; #define PG8_SCHED __builtin_amdgcn_sched_barrier(0)
; template <class Epi, class Sched, bool ALIGN_EPI = false, bool SP2 = false, bool I8 = false>
; __device__ __forceinline__ void gemm_phase(PG8_LAS unsigned char* lds, const Gemm g, const Sched& S, const Epi& E) {
;     ...
;             PG8_LDA(At, 1, 1); PG8_STAGE(PG8_SB(1, 0), b3, voffB); PG8_STAGE(PG8_SB(1, 1), b3 + hstep, voffB); PG8_STAGE(PG8_SA(1, 0), a3, voffA);
;             PG8_WAIT_V(8); PG8_WAIT_L(0); PG8_BAR; PG8_MMA(1, 0, At, B0); PG8_MMA(1, 1, At, B1); PG8_BAR; PG8_SCHED;
	s_add_i32 s48, s73, s28
	v_lshl_add_u64 v[190:191], v[190:191], 0, s[84:85]
	s_mov_b32 m0, s48
	ds_read_b128 v[178:181], v145 offset:49152
	ds_read_b128 v[182:185], v145 offset:50176
	ds_read_b128 v[186:189], v145 offset:51200
	ds_read_b128 v[204:207], v145 offset:52224
	ds_read_b128 v[208:211], v145 offset:53248
	ds_read_b128 v[212:215], v145 offset:54272
	ds_read_b128 v[216:219], v145 offset:55296
	ds_read_b128 v[220:223], v145 offset:56320
	global_load_lds_dwordx4 v[190:191], off
	v_lshl_add_u64 v[190:191], v[224:225], 0, s[84:85]
	s_add_i32 m0, s48, 0x2000
	s_add_i32 s48, s76, s28
	global_load_lds_dwordx4 v[190:191], off
	v_lshl_add_u64 v[190:191], v[226:227], 0, s[84:85]
	s_mov_b32 m0, s48
	s_nop 0
	global_load_lds_dwordx4 v[190:191], off
	v_lshl_add_u64 v[190:191], v[228:229], 0, s[84:85]
	s_add_i32 m0, s48, 0x2000
	s_nop 0
	global_load_lds_dwordx4 v[190:191], off
	v_lshl_add_u64 v[190:191], v[240:241], 0, s[84:85]
	s_mov_b32 m0, s55
	s_nop 0
	global_load_lds_dwordx4 v[190:191], off
	v_lshl_add_u64 v[190:191], v[242:243], 0, s[84:85]
	s_mov_b32 m0, s56
	s_nop 0
	global_load_lds_dwordx4 v[190:191], off
	s_waitcnt vmcnt(8) lgkmcnt(0)
	s_barrier
	s_setprio 1
	v_mfma_f32_16x16x32_bf16 v[64:67], v[146:149], v[178:181], v[64:67]
	v_mfma_f32_16x16x32_bf16 v[64:67], v[150:153], v[182:185], v[64:67]
	v_mfma_f32_16x16x32_bf16 v[48:51], v[150:153], v[204:207], v[48:51]
	v_mfma_f32_16x16x32_bf16 v[48:51], v[146:149], v[186:189], v[48:51]
	v_mfma_f32_16x16x32_bf16 v[32:35], v[146:149], v[208:211], v[32:35]
	v_mfma_f32_16x16x32_bf16 v[32:35], v[150:153], v[212:215], v[32:35]
	v_mfma_f32_16x16x32_bf16 v[16:19], v[150:153], v[220:223], v[16:19]
	v_mfma_f32_16x16x32_bf16 v[16:19], v[146:149], v[216:219], v[16:19]
	v_mfma_f32_16x16x32_bf16 v[12:15], v[154:157], v[216:219], v[12:15]
	v_mfma_f32_16x16x32_bf16 v[12:15], v[158:161], v[220:223], v[12:15]
	v_mfma_f32_16x16x32_bf16 v[28:31], v[158:161], v[212:215], v[28:31]
	v_mfma_f32_16x16x32_bf16 v[28:31], v[154:157], v[208:211], v[28:31]
	v_mfma_f32_16x16x32_bf16 v[44:47], v[154:157], v[186:189], v[44:47]
	v_mfma_f32_16x16x32_bf16 v[44:47], v[158:161], v[204:207], v[44:47]
	v_mfma_f32_16x16x32_bf16 v[60:63], v[158:161], v[182:185], v[60:63]
	v_mfma_f32_16x16x32_bf16 v[60:63], v[154:157], v[178:181], v[60:63]
	v_mfma_f32_16x16x32_bf16 v[56:59], v[162:165], v[178:181], v[56:59]
	v_mfma_f32_16x16x32_bf16 v[56:59], v[166:169], v[182:185], v[56:59]
	v_mfma_f32_16x16x32_bf16 v[40:43], v[166:169], v[204:207], v[40:43]
	v_mfma_f32_16x16x32_bf16 v[40:43], v[162:165], v[186:189], v[40:43]
	v_mfma_f32_16x16x32_bf16 v[24:27], v[162:165], v[208:211], v[24:27]
	v_mfma_f32_16x16x32_bf16 v[24:27], v[166:169], v[212:215], v[24:27]
	v_mfma_f32_16x16x32_bf16 v[8:11], v[166:169], v[220:223], v[8:11]
	v_mfma_f32_16x16x32_bf16 v[8:11], v[162:165], v[216:219], v[8:11]
	v_mfma_f32_16x16x32_bf16 v[4:7], v[170:173], v[216:219], v[4:7]
	v_mfma_f32_16x16x32_bf16 v[4:7], v[174:177], v[220:223], v[4:7]
	v_mfma_f32_16x16x32_bf16 v[20:23], v[174:177], v[212:215], v[20:23]
	v_mfma_f32_16x16x32_bf16 v[20:23], v[170:173], v[208:211], v[20:23]
	v_mfma_f32_16x16x32_bf16 v[36:39], v[170:173], v[186:189], v[36:39]
	v_mfma_f32_16x16x32_bf16 v[36:39], v[174:177], v[204:207], v[36:39]
	v_mfma_f32_16x16x32_bf16 v[52:55], v[174:177], v[182:185], v[52:55]
	v_mfma_f32_16x16x32_bf16 v[52:55], v[170:173], v[178:181], v[52:55]
	s_setprio 0
	s_barrier
	s_add_u32 s44, s44, 0x100
	s_addc_u32 s45, s45, 0
	s_add_u32 s65, s65, 0x100
	s_addc_u32 s67, s67, 0
	s_cmp_ge_i32 s72, s53
	s_mov_b32 s48, s72
	s_cbranch_scc0 .LBB0_1623

; #define PG8_STAGE(bufoff, gbase, voff) do { _Pragma("unroll") for (int _i = 0; _i < 2; ++_i) \
;         __builtin_amdgcn_global_load_lds((const unsigned*)((const char*)(gbase) + (voff)[_i]), (PG8_LAS unsigned*)(lds + (bufoff) + ldsw + _i * 8192), 16, 0, 0); } while (0)
; #define PG8_LDA(dst, b, h) do { _Pragma("unroll") for (int m = 0; m < 4; ++m) _Pragma("unroll") for (int k = 0; k < 2; ++k) dst[m][k] = *(const PG8_LAS bf16x8*)(lds + PG8_SA(b, h) + aoff + m * 2048 + k * 1024); } while (0)
; #define PG8_LDB(dst, b, h) do { _Pragma("unroll") for (int n = 0; n < 2; ++n) _Pragma("unroll") for (int k = 0; k < 2; ++k) dst[n][k] = *(const PG8_LAS bf16x8*)(lds + PG8_SB(b, h) + boff + n * 2048 + k * 1024); } while (0)
; #define PG8_WAIT_V(n) asm volatile("s_waitcnt vmcnt(" #n ")" ::: "memory")
; #define PG8_WAIT_L(n) asm volatile("s_waitcnt lgkmcnt(" #n ")" ::: "memory")
; #define PG8_BAR __builtin_amdgcn_s_barrier()
; #define PG8_SCHED __builtin_amdgcn_sched_barrier(0)
; template <class Epi, class Sched, bool ALIGN_EPI = false, bool SP2 = false, bool I8 = false>
; __device__ __forceinline__ void gemm_phase(PG8_LAS unsigned char* lds, const Gemm g, const Sched& S, const Epi& E) {
;     ...
;         const bool has_next = S.next(ui + 1, nxt);
;         const char* nA = has_next ? (const char*)g.A + (size_t)nxt.pm * tstep : cA; const char* nB = has_next ? (const char*)g.Bt + (size_t)nxt.pn * tstep : cB;
;         for (int t = 0; t < nt; t += 2) {
;             const bool last = (t == nt - 2);
;             const char* a1 = cA + (size_t)(t + 1) * kstep;
;             const char* a2 = last ? nA : cA + (size_t)(t + 2) * kstep; const char* b2 = last ? nB : cB + (size_t)(t + 2) * kstep;
;             const char* a3 = a2 + kstep; const char* b3 = b2 + kstep;
;             if (last && has_next) S.a_ready(nxt);
;             if constexpr (SP2) {
;             PG8_LDB(B0, 0, 0); PG8_LDB(B1, 0, 1); PG8_SCHED; PG8_LDA(At, 0, 0); PG8_STAGE(PG8_SA(1, 1), a1 + hstep, voffA);
;             PG8_WAIT_V(8); PG8_WAIT_L(0); PG8_BAR; PG8_MMA(0, 0, At, B0); PG8_MMA(0, 1, At, B1); PG8_BAR; PG8_SCHED;
;             PG8_LDA(At, 0, 1); PG8_STAGE(PG8_SB(0, 0), b2, voffB); PG8_STAGE(PG8_SB(0, 1), b2 + hstep, voffB); PG8_STAGE(PG8_SA(0, 0), a2, voffA);
;             PG8_WAIT_V(8); PG8_WAIT_L(0); PG8_BAR; PG8_MMA(1, 0, At, B0); PG8_MMA(1, 1, At, B1); PG8_BAR; PG8_SCHED;
.LBB0_1699:
	s_add_u32 s53, s24, 0x100
	s_addc_u32 s54, s25, 0
	s_mov_b32 s55, -2
	s_add_u32 s24, s22, 0x100
	s_addc_u32 s25, s23, 0
	s_add_i32 s56, 0, 0x10000
	s_cmpk_eq_i32 s55, 0xa8
	s_cselect_b32 s37, s13, s25
	s_cselect_b32 s36, s12, s24
	s_cselect_b32 s27, s21, s54
	s_cselect_b32 s26, s20, s53
	s_add_i32 s57, 0, 0x14000
	v_add_u32_e32 v144, s56, v240
	v_add_u32_e32 v160, s57, v240
	ds_read_b128 v[124:127], v144
	ds_read_b128 v[128:131], v144 offset:1024
	ds_read_b128 v[132:135], v144 offset:2048
	ds_read_b128 v[144:147], v144 offset:3072
	ds_read_b128 v[148:151], v160
	ds_read_b128 v[152:155], v160 offset:1024
	ds_read_b128 v[156:159], v160 offset:2048
	ds_read_b128 v[160:163], v160 offset:3072
	v_lshl_add_u64 v[218:219], s[22:23], 0, v[210:211]
	s_add_i32 m0, s42, 0xc000
	ds_read_b128 v[164:167], v242
	ds_read_b128 v[168:171], v242 offset:1024
	ds_read_b128 v[172:175], v242 offset:2048
	ds_read_b128 v[176:179], v242 offset:3072
	ds_read_b128 v[180:183], v242 offset:4096
	ds_read_b128 v[184:187], v242 offset:5120
	ds_read_b128 v[188:191], v242 offset:6144
	ds_read_b128 v[214:217], v242 offset:7168
	global_load_lds_dwordx4 v[218:219], off
	v_lshl_add_u64 v[218:219], s[22:23], 0, v[212:213]
	s_add_i32 m0, s42, 0xe000
	s_nop 0
	global_load_lds_dwordx4 v[218:219], off
	s_waitcnt vmcnt(8) lgkmcnt(0)
	s_barrier
	s_setprio 1
	v_mfma_f32_16x16x32_bf16 v[140:143], v[124:127], v[164:167], 0
	v_mfma_f32_16x16x32_bf16 v[140:143], v[128:131], v[168:171], v[140:143]
	v_mfma_f32_16x16x32_bf16 v[112:115], v[128:131], v[176:179], 0
	v_mfma_f32_16x16x32_bf16 v[112:115], v[124:127], v[172:175], v[112:115]
	v_mfma_f32_16x16x32_bf16 v[96:99], v[124:127], v[180:183], 0
	v_mfma_f32_16x16x32_bf16 v[96:99], v[128:131], v[184:187], v[96:99]
	v_mfma_f32_16x16x32_bf16 v[80:83], v[128:131], v[214:217], 0
	v_mfma_f32_16x16x32_bf16 v[80:83], v[124:127], v[188:191], v[80:83]
	v_mfma_f32_16x16x32_bf16 v[76:79], v[132:135], v[188:191], 0
	v_mfma_f32_16x16x32_bf16 v[76:79], v[144:147], v[214:217], v[76:79]
	v_mfma_f32_16x16x32_bf16 v[92:95], v[144:147], v[184:187], 0
	v_mfma_f32_16x16x32_bf16 v[92:95], v[132:135], v[180:183], v[92:95]
	v_mfma_f32_16x16x32_bf16 v[108:111], v[132:135], v[172:175], 0
	v_mfma_f32_16x16x32_bf16 v[108:111], v[144:147], v[176:179], v[108:111]
	v_mfma_f32_16x16x32_bf16 v[136:139], v[144:147], v[168:171], 0
	v_mfma_f32_16x16x32_bf16 v[136:139], v[132:135], v[164:167], v[136:139]
	v_mfma_f32_16x16x32_bf16 v[120:123], v[148:151], v[164:167], 0
	v_mfma_f32_16x16x32_bf16 v[120:123], v[152:155], v[168:171], v[120:123]
	v_mfma_f32_16x16x32_bf16 v[104:107], v[152:155], v[176:179], 0
	v_mfma_f32_16x16x32_bf16 v[104:107], v[148:151], v[172:175], v[104:107]
	v_mfma_f32_16x16x32_bf16 v[88:91], v[148:151], v[180:183], 0
	v_mfma_f32_16x16x32_bf16 v[88:91], v[152:155], v[184:187], v[88:91]
	v_mfma_f32_16x16x32_bf16 v[72:75], v[152:155], v[214:217], 0
	v_mfma_f32_16x16x32_bf16 v[72:75], v[148:151], v[188:191], v[72:75]
	v_mfma_f32_16x16x32_bf16 v[68:71], v[156:159], v[188:191], 0
	v_mfma_f32_16x16x32_bf16 v[68:71], v[160:163], v[214:217], v[68:71]
	v_mfma_f32_16x16x32_bf16 v[84:87], v[160:163], v[184:187], 0
	v_mfma_f32_16x16x32_bf16 v[84:87], v[156:159], v[180:183], v[84:87]
	v_mfma_f32_16x16x32_bf16 v[100:103], v[156:159], v[172:175], 0
	v_mfma_f32_16x16x32_bf16 v[100:103], v[160:163], v[176:179], v[100:103]
	v_mfma_f32_16x16x32_bf16 v[116:119], v[160:163], v[168:171], 0
	v_mfma_f32_16x16x32_bf16 v[116:119], v[156:159], v[164:167], v[116:119]
	s_setprio 0
	s_barrier
	s_add_i32 s22, s56, s41
	v_lshl_add_u64 v[218:219], s[26:27], 0, v[2:3]
	s_mov_b32 m0, s22
	ds_read_b128 v[164:167], v242 offset:16384
	ds_read_b128 v[168:171], v242 offset:17408
	ds_read_b128 v[172:175], v242 offset:18432
	ds_read_b128 v[176:179], v242 offset:19456
	ds_read_b128 v[180:183], v242 offset:20480
	ds_read_b128 v[184:187], v242 offset:21504
	ds_read_b128 v[188:191], v242 offset:22528
	ds_read_b128 v[214:217], v242 offset:23552
	global_load_lds_dwordx4 v[218:219], off
	s_add_i32 m0, s22, 0x2000
	s_add_u32 s22, s26, 0x2b0000
	v_lshl_add_u64 v[220:221], s[26:27], 0, v[204:205]
	s_addc_u32 s23, s27, 0
	s_add_i32 s56, s57, s41
	global_load_lds_dwordx4 v[220:221], off
	s_mov_b32 m0, s56
	v_lshl_add_u64 v[224:225], s[36:37], 0, v[206:207]
	global_load_lds_dwordx4 v2, s[22:23]
	s_add_i32 m0, s56, 0x2000
	s_nop 0
	global_load_lds_dwordx4 v204, s[22:23]
	v_lshl_add_u64 v[222:223], s[36:37], 0, v[208:209]
	s_waitcnt vmcnt(6) lgkmcnt(0)
	s_barrier
	s_setprio 1
	v_mfma_f32_16x16x32_bf16 v[64:67], v[124:127], v[164:167], 0
	v_mfma_f32_16x16x32_bf16 v[64:67], v[128:131], v[168:171], v[64:67]
	v_mfma_f32_16x16x32_bf16 v[48:51], v[128:131], v[176:179], 0
	v_mfma_f32_16x16x32_bf16 v[48:51], v[124:127], v[172:175], v[48:51]
	v_mfma_f32_16x16x32_bf16 v[32:35], v[124:127], v[180:183], 0
	v_mfma_f32_16x16x32_bf16 v[32:35], v[128:131], v[184:187], v[32:35]
	v_mfma_f32_16x16x32_bf16 v[16:19], v[128:131], v[214:217], 0
	v_mfma_f32_16x16x32_bf16 v[16:19], v[124:127], v[188:191], v[16:19]
	v_mfma_f32_16x16x32_bf16 v[12:15], v[132:135], v[188:191], 0
	v_mfma_f32_16x16x32_bf16 v[12:15], v[144:147], v[214:217], v[12:15]
	v_mfma_f32_16x16x32_bf16 v[28:31], v[144:147], v[184:187], 0
	v_mfma_f32_16x16x32_bf16 v[28:31], v[132:135], v[180:183], v[28:31]
	v_mfma_f32_16x16x32_bf16 v[44:47], v[132:135], v[172:175], 0
	v_mfma_f32_16x16x32_bf16 v[44:47], v[144:147], v[176:179], v[44:47]
	v_mfma_f32_16x16x32_bf16 v[60:63], v[144:147], v[168:171], 0
	v_mfma_f32_16x16x32_bf16 v[60:63], v[132:135], v[164:167], v[60:63]
	v_mfma_f32_16x16x32_bf16 v[56:59], v[148:151], v[164:167], 0
	v_mfma_f32_16x16x32_bf16 v[56:59], v[152:155], v[168:171], v[56:59]
	v_mfma_f32_16x16x32_bf16 v[40:43], v[152:155], v[176:179], 0
	v_mfma_f32_16x16x32_bf16 v[40:43], v[148:151], v[172:175], v[40:43]
	v_mfma_f32_16x16x32_bf16 v[24:27], v[148:151], v[180:183], 0
	v_mfma_f32_16x16x32_bf16 v[24:27], v[152:155], v[184:187], v[24:27]
	v_mfma_f32_16x16x32_bf16 v[8:11], v[152:155], v[214:217], 0
	v_mfma_f32_16x16x32_bf16 v[8:11], v[148:151], v[188:191], v[8:11]
	v_mfma_f32_16x16x32_bf16 v[4:7], v[156:159], v[188:191], 0
	v_mfma_f32_16x16x32_bf16 v[4:7], v[160:163], v[214:217], v[4:7]
	v_mfma_f32_16x16x32_bf16 v[20:23], v[160:163], v[184:187], 0
	v_mfma_f32_16x16x32_bf16 v[20:23], v[156:159], v[180:183], v[20:23]
	v_mfma_f32_16x16x32_bf16 v[36:39], v[156:159], v[172:175], 0
	v_mfma_f32_16x16x32_bf16 v[36:39], v[160:163], v[176:179], v[36:39]
	v_mfma_f32_16x16x32_bf16 v[52:55], v[160:163], v[168:171], 0
	v_mfma_f32_16x16x32_bf16 v[52:55], v[156:159], v[164:167], v[52:55]
	s_setprio 0
	s_barrier
; #define PG8_STAGE(bufoff, gbase, voff) do { _Pragma("unroll") for (int _i = 0; _i < 2; ++_i) \
;         __builtin_amdgcn_global_load_lds((const unsigned*)((const char*)(gbase) + (voff)[_i]), (PG8_LAS unsigned*)(lds + (bufoff) + ldsw + _i * 8192), 16, 0, 0); } while (0)
; #define PG8_LDA(dst, b, h) do { _Pragma("unroll") for (int m = 0; m < 4; ++m) _Pragma("unroll") for (int k = 0; k < 2; ++k) dst[m][k] = *(const PG8_LAS bf16x8*)(lds + PG8_SA(b, h) + aoff + m * 2048 + k * 1024); } while (0)
; #define PG8_LDB(dst, b, h) do { _Pragma("unroll") for (int n = 0; n < 2; ++n) _Pragma("unroll") for (int k = 0; k < 2; ++k) dst[n][k] = *(const PG8_LAS bf16x8*)(lds + PG8_SB(b, h) + boff + n * 2048 + k * 1024); } while (0)
; #define PG8_WAIT_V(n) asm volatile("s_waitcnt vmcnt(" #n ")" ::: "memory")
; #define PG8_WAIT_L(n) asm volatile("s_waitcnt lgkmcnt(" #n ")" ::: "memory")
; #define PG8_BAR __builtin_amdgcn_s_barrier()
; #define PG8_SCHED __builtin_amdgcn_sched_barrier(0)
; template <class Epi, class Sched, bool ALIGN_EPI = false, bool SP2 = false, bool I8 = false>
; __device__ __forceinline__ void gemm_phase(PG8_LAS unsigned char* lds, const Gemm g, const Sched& S, const Epi& E) {
;     ...
;             PG8_WAIT_V(8); PG8_WAIT_L(0); PG8_BAR; PG8_MMA(0, 0, At, B0); PG8_MMA(0, 1, At, B1); PG8_BAR; PG8_SCHED;
;             PG8_LDA(At, 0, 1); PG8_STAGE(PG8_SB(0, 0), b2, voffB); PG8_STAGE(PG8_SB(0, 1), b2 + hstep, voffB); PG8_STAGE(PG8_SA(0, 0), a2, voffA);
;             PG8_WAIT_V(8); PG8_WAIT_L(0); PG8_BAR; PG8_MMA(1, 0, At, B0); PG8_MMA(1, 1, At, B1); PG8_BAR; PG8_SCHED;
;             PG8_LDB(B0, 1, 0); PG8_LDB(B1, 1, 1); PG8_SCHED; PG8_LDA(At, 1, 0); PG8_STAGE(PG8_SA(0, 1), a2 + hstep, voffA);
;             PG8_WAIT_V(8); PG8_WAIT_L(0); PG8_BAR; PG8_MMA(0, 0, At, B0); PG8_MMA(0, 1, At, B1); PG8_BAR; PG8_SCHED;
;             PG8_LDA(At, 1, 1); PG8_STAGE(PG8_SB(1, 0), b3, voffB); PG8_STAGE(PG8_SB(1, 1), b3 + hstep, voffB); PG8_STAGE(PG8_SA(1, 0), a3, voffA);
;             PG8_WAIT_V(8); PG8_WAIT_L(0); PG8_BAR; PG8_MMA(1, 0, At, B0); PG8_MMA(1, 1, At, B1); PG8_BAR; PG8_SCHED;
	s_mov_b32 m0, s42
	s_nop 0
	global_load_lds_dwordx4 v[222:223], off
	s_mov_b32 m0, s43
	s_nop 0
	global_load_lds_dwordx4 v[224:225], off
	s_add_i32 s56, 0, 0x18000
	s_add_i32 s57, 0, 0x1c000
	v_add_u32_e32 v144, s56, v240
	v_add_u32_e32 v160, s57, v240
	ds_read_b128 v[124:127], v144
	ds_read_b128 v[128:131], v144 offset:1024
	ds_read_b128 v[132:135], v144 offset:2048
	ds_read_b128 v[144:147], v144 offset:3072
	ds_read_b128 v[148:151], v160
	ds_read_b128 v[152:155], v160 offset:1024
	ds_read_b128 v[156:159], v160 offset:2048
	ds_read_b128 v[160:163], v160 offset:3072
	s_add_u32 s22, s36, 0x2b0000
	s_addc_u32 s23, s37, 0
	s_mov_b32 m0, s44
	ds_read_b128 v[164:167], v242 offset:32768
	ds_read_b128 v[168:171], v242 offset:33792
	ds_read_b128 v[172:175], v242 offset:34816
	ds_read_b128 v[176:179], v242 offset:35840
	ds_read_b128 v[180:183], v242 offset:36864
	ds_read_b128 v[184:187], v242 offset:37888
	ds_read_b128 v[188:191], v242 offset:38912
	ds_read_b128 v[214:217], v242 offset:39936
	global_load_lds_dwordx4 v208, s[22:23]
	s_mov_b32 m0, s45
	s_nop 0
	global_load_lds_dwordx4 v206, s[22:23]
	s_waitcnt vmcnt(8) lgkmcnt(0)
	s_barrier
	s_setprio 1
	v_mfma_f32_16x16x32_bf16 v[140:143], v[124:127], v[164:167], v[140:143]
	v_mfma_f32_16x16x32_bf16 v[140:143], v[128:131], v[168:171], v[140:143]
	v_mfma_f32_16x16x32_bf16 v[112:115], v[128:131], v[176:179], v[112:115]
	v_mfma_f32_16x16x32_bf16 v[112:115], v[124:127], v[172:175], v[112:115]
	v_mfma_f32_16x16x32_bf16 v[96:99], v[124:127], v[180:183], v[96:99]
	v_mfma_f32_16x16x32_bf16 v[96:99], v[128:131], v[184:187], v[96:99]
	v_mfma_f32_16x16x32_bf16 v[80:83], v[128:131], v[214:217], v[80:83]
	v_mfma_f32_16x16x32_bf16 v[80:83], v[124:127], v[188:191], v[80:83]
	v_mfma_f32_16x16x32_bf16 v[76:79], v[132:135], v[188:191], v[76:79]
	v_mfma_f32_16x16x32_bf16 v[76:79], v[144:147], v[214:217], v[76:79]
	v_mfma_f32_16x16x32_bf16 v[92:95], v[144:147], v[184:187], v[92:95]
	v_mfma_f32_16x16x32_bf16 v[92:95], v[132:135], v[180:183], v[92:95]
	v_mfma_f32_16x16x32_bf16 v[108:111], v[132:135], v[172:175], v[108:111]
	v_mfma_f32_16x16x32_bf16 v[108:111], v[144:147], v[176:179], v[108:111]
	v_mfma_f32_16x16x32_bf16 v[136:139], v[144:147], v[168:171], v[136:139]
	v_mfma_f32_16x16x32_bf16 v[136:139], v[132:135], v[164:167], v[136:139]
	v_mfma_f32_16x16x32_bf16 v[120:123], v[148:151], v[164:167], v[120:123]
	v_mfma_f32_16x16x32_bf16 v[120:123], v[152:155], v[168:171], v[120:123]
	v_mfma_f32_16x16x32_bf16 v[104:107], v[152:155], v[176:179], v[104:107]
	v_mfma_f32_16x16x32_bf16 v[104:107], v[148:151], v[172:175], v[104:107]
	v_mfma_f32_16x16x32_bf16 v[88:91], v[148:151], v[180:183], v[88:91]
	v_mfma_f32_16x16x32_bf16 v[88:91], v[152:155], v[184:187], v[88:91]
	v_mfma_f32_16x16x32_bf16 v[72:75], v[152:155], v[214:217], v[72:75]
	v_mfma_f32_16x16x32_bf16 v[72:75], v[148:151], v[188:191], v[72:75]
	v_mfma_f32_16x16x32_bf16 v[68:71], v[156:159], v[188:191], v[68:71]
	v_mfma_f32_16x16x32_bf16 v[68:71], v[160:163], v[214:217], v[68:71]
	v_mfma_f32_16x16x32_bf16 v[84:87], v[160:163], v[184:187], v[84:87]
	v_mfma_f32_16x16x32_bf16 v[84:87], v[156:159], v[180:183], v[84:87]
	v_mfma_f32_16x16x32_bf16 v[100:103], v[156:159], v[172:175], v[100:103]
	v_mfma_f32_16x16x32_bf16 v[100:103], v[160:163], v[176:179], v[100:103]
	v_mfma_f32_16x16x32_bf16 v[116:119], v[160:163], v[168:171], v[116:119]
	v_mfma_f32_16x16x32_bf16 v[116:119], v[156:159], v[164:167], v[116:119]
	s_setprio 0
	s_barrier
	s_add_i32 s22, s56, s41
	v_lshl_add_u64 v[218:219], v[218:219], 0, s[84:85]
	s_mov_b32 m0, s22
	ds_read_b128 v[164:167], v242 offset:49152
	ds_read_b128 v[168:171], v242 offset:50176
	ds_read_b128 v[172:175], v242 offset:51200
	ds_read_b128 v[176:179], v242 offset:52224
	ds_read_b128 v[180:183], v242 offset:53248
	ds_read_b128 v[184:187], v242 offset:54272
	ds_read_b128 v[188:191], v242 offset:55296
	ds_read_b128 v[214:217], v242 offset:56320
	global_load_lds_dwordx4 v[218:219], off
	s_add_i32 m0, s22, 0x2000
	s_add_u32 s22, s26, 0x2b0080
	v_lshl_add_u64 v[218:219], v[220:221], 0, s[84:85]
	s_addc_u32 s23, s27, 0
	s_add_i32 s26, s57, s41
	global_load_lds_dwordx4 v[218:219], off
	s_mov_b32 m0, s26
	s_nop 0
	global_load_lds_dwordx4 v2, s[22:23]
	s_add_i32 m0, s26, 0x2000
	s_nop 0
	global_load_lds_dwordx4 v204, s[22:23]
	s_cmpk_eq_i32 s55, 0xa8
	s_cbranch_scc0 .Ldefer_1700_peel
	v_lshl_add_u64 v[218:219], v[222:223], 0, s[84:85]
	s_mov_b32 m0, s46
	s_nop 0
	global_load_lds_dwordx4 v[218:219], off
	v_lshl_add_u64 v[218:219], v[224:225], 0, s[84:85]
	s_mov_b32 m0, s47
	s_nop 0
	global_load_lds_dwordx4 v[218:219], off
; #define PG8_STAGE(bufoff, gbase, voff) do { _Pragma("unroll") for (int _i = 0; _i < 2; ++_i) \
;         __builtin_amdgcn_global_load_lds((const unsigned*)((const char*)(gbase) + (voff)[_i]), (PG8_LAS unsigned*)(lds + (bufoff) + ldsw + _i * 8192), 16, 0, 0); } while (0)
; #define PG8_LDA(dst, b, h) do { _Pragma("unroll") for (int m = 0; m < 4; ++m) _Pragma("unroll") for (int k = 0; k < 2; ++k) dst[m][k] = *(const PG8_LAS bf16x8*)(lds + PG8_SA(b, h) + aoff + m * 2048 + k * 1024); } while (0)
; #define PG8_LDB(dst, b, h) do { _Pragma("unroll") for (int n = 0; n < 2; ++n) _Pragma("unroll") for (int k = 0; k < 2; ++k) dst[n][k] = *(const PG8_LAS bf16x8*)(lds + PG8_SB(b, h) + boff + n * 2048 + k * 1024); } while (0)
; #define PG8_WAIT_V(n) asm volatile("s_waitcnt vmcnt(" #n ")" ::: "memory")
; #define PG8_WAIT_L(n) asm volatile("s_waitcnt lgkmcnt(" #n ")" ::: "memory")
; #define PG8_BAR __builtin_amdgcn_s_barrier()
; #define PG8_SCHED __builtin_amdgcn_sched_barrier(0)
; template <class Epi, class Sched, bool ALIGN_EPI = false, bool SP2 = false, bool I8 = false>
; __device__ __forceinline__ void gemm_phase(PG8_LAS unsigned char* lds, const Gemm g, const Sched& S, const Epi& E) {
;     ...
;         for (int t = 0; t < nt; t += 2) {
;             const bool last = (t == nt - 2);
;             const char* a1 = cA + (size_t)(t + 1) * kstep;
;             const char* a2 = last ? nA : cA + (size_t)(t + 2) * kstep; const char* b2 = last ? nB : cB + (size_t)(t + 2) * kstep;
;             const char* a3 = a2 + kstep; const char* b3 = b2 + kstep;
;             if (last && has_next) S.a_ready(nxt);
;             if constexpr (SP2) {
;             PG8_LDB(B0, 0, 0); PG8_LDB(B1, 0, 1); PG8_SCHED; PG8_LDA(At, 0, 0); PG8_STAGE(PG8_SA(1, 1), a1 + hstep, voffA);
;             PG8_WAIT_V(8); PG8_WAIT_L(0); PG8_BAR; PG8_MMA(0, 0, At, B0); PG8_MMA(0, 1, At, B1); PG8_BAR; PG8_SCHED;
;             PG8_LDA(At, 0, 1); PG8_STAGE(PG8_SB(0, 0), b2, voffB); PG8_STAGE(PG8_SB(0, 1), b2 + hstep, voffB); PG8_STAGE(PG8_SA(0, 0), a2, voffA);
;             PG8_WAIT_V(8); PG8_WAIT_L(0); PG8_BAR; PG8_MMA(1, 0, At, B0); PG8_MMA(1, 1, At, B1); PG8_BAR; PG8_SCHED;
.Ldefer_1700_peel:
	s_waitcnt vmcnt(6) lgkmcnt(0)
	s_barrier
	s_setprio 1
	v_mfma_f32_16x16x32_bf16 v[64:67], v[124:127], v[164:167], v[64:67]
	v_mfma_f32_16x16x32_bf16 v[64:67], v[128:131], v[168:171], v[64:67]
	v_mfma_f32_16x16x32_bf16 v[48:51], v[128:131], v[176:179], v[48:51]
	v_mfma_f32_16x16x32_bf16 v[48:51], v[124:127], v[172:175], v[48:51]
	v_mfma_f32_16x16x32_bf16 v[32:35], v[124:127], v[180:183], v[32:35]
	v_mfma_f32_16x16x32_bf16 v[32:35], v[128:131], v[184:187], v[32:35]
	v_mfma_f32_16x16x32_bf16 v[16:19], v[128:131], v[214:217], v[16:19]
	v_mfma_f32_16x16x32_bf16 v[16:19], v[124:127], v[188:191], v[16:19]
	v_mfma_f32_16x16x32_bf16 v[12:15], v[132:135], v[188:191], v[12:15]
	v_mfma_f32_16x16x32_bf16 v[12:15], v[144:147], v[214:217], v[12:15]
	v_mfma_f32_16x16x32_bf16 v[28:31], v[144:147], v[184:187], v[28:31]
	v_mfma_f32_16x16x32_bf16 v[28:31], v[132:135], v[180:183], v[28:31]
	v_mfma_f32_16x16x32_bf16 v[44:47], v[132:135], v[172:175], v[44:47]
	v_mfma_f32_16x16x32_bf16 v[44:47], v[144:147], v[176:179], v[44:47]
	v_mfma_f32_16x16x32_bf16 v[60:63], v[144:147], v[168:171], v[60:63]
	v_mfma_f32_16x16x32_bf16 v[60:63], v[132:135], v[164:167], v[60:63]
	v_mfma_f32_16x16x32_bf16 v[56:59], v[148:151], v[164:167], v[56:59]
	v_mfma_f32_16x16x32_bf16 v[56:59], v[152:155], v[168:171], v[56:59]
	v_mfma_f32_16x16x32_bf16 v[40:43], v[152:155], v[176:179], v[40:43]
	v_mfma_f32_16x16x32_bf16 v[40:43], v[148:151], v[172:175], v[40:43]
	v_mfma_f32_16x16x32_bf16 v[24:27], v[148:151], v[180:183], v[24:27]
	v_mfma_f32_16x16x32_bf16 v[24:27], v[152:155], v[184:187], v[24:27]
	v_mfma_f32_16x16x32_bf16 v[8:11], v[152:155], v[214:217], v[8:11]
	v_mfma_f32_16x16x32_bf16 v[8:11], v[148:151], v[188:191], v[8:11]
	v_mfma_f32_16x16x32_bf16 v[4:7], v[156:159], v[188:191], v[4:7]
	v_mfma_f32_16x16x32_bf16 v[4:7], v[160:163], v[214:217], v[4:7]
	v_mfma_f32_16x16x32_bf16 v[20:23], v[160:163], v[184:187], v[20:23]
	v_mfma_f32_16x16x32_bf16 v[20:23], v[156:159], v[180:183], v[20:23]
	v_mfma_f32_16x16x32_bf16 v[36:39], v[156:159], v[172:175], v[36:39]
	v_mfma_f32_16x16x32_bf16 v[36:39], v[160:163], v[176:179], v[36:39]
	v_mfma_f32_16x16x32_bf16 v[52:55], v[160:163], v[168:171], v[52:55]
	v_mfma_f32_16x16x32_bf16 v[52:55], v[156:159], v[164:167], v[52:55]
	s_setprio 0
	s_barrier
	s_add_i32 s55, s55, 2
	s_add_u32 s53, s53, 0x100
	s_addc_u32 s54, s54, 0
	s_cmpk_gt_u32 s55, 0xa9
	s_mov_b64 s[22:23], s[24:25]
	s_cbranch_scc1 .Lkloop_exit_5
.LBB0_1700:
	s_add_u32 s24, s22, 0x100
	s_addc_u32 s25, s23, 0
	s_add_i32 s56, 0, 0x10000
	s_cmpk_eq_i32 s55, 0xa8
	s_cselect_b32 s37, s13, s25
	s_cselect_b32 s36, s12, s24
	s_cselect_b32 s27, s21, s54
	s_cselect_b32 s26, s20, s53
	s_add_i32 s57, 0, 0x14000
	v_add_u32_e32 v144, s56, v240
	v_add_u32_e32 v160, s57, v240
	ds_read_b128 v[124:127], v144
	ds_read_b128 v[128:131], v144 offset:1024
	ds_read_b128 v[132:135], v144 offset:2048
	ds_read_b128 v[144:147], v144 offset:3072
	ds_read_b128 v[148:151], v160
	ds_read_b128 v[152:155], v160 offset:1024
	ds_read_b128 v[156:159], v160 offset:2048
	ds_read_b128 v[160:163], v160 offset:3072
	v_lshl_add_u64 v[218:219], v[222:223], 0, s[84:85]
	s_mov_b32 m0, s46
	s_nop 0
	global_load_lds_dwordx4 v[218:219], off
	v_lshl_add_u64 v[218:219], v[224:225], 0, s[84:85]
	s_mov_b32 m0, s47
	s_nop 0
	global_load_lds_dwordx4 v[218:219], off
	v_lshl_add_u64 v[218:219], s[22:23], 0, v[210:211]
	s_add_i32 m0, s42, 0xc000
	ds_read_b128 v[164:167], v242
	ds_read_b128 v[168:171], v242 offset:1024
	ds_read_b128 v[172:175], v242 offset:2048
	ds_read_b128 v[176:179], v242 offset:3072
	ds_read_b128 v[180:183], v242 offset:4096
	ds_read_b128 v[184:187], v242 offset:5120
	ds_read_b128 v[188:191], v242 offset:6144
	ds_read_b128 v[214:217], v242 offset:7168
	global_load_lds_dwordx4 v[218:219], off
	v_lshl_add_u64 v[218:219], s[22:23], 0, v[212:213]
	s_add_i32 m0, s42, 0xe000
	s_nop 0
	global_load_lds_dwordx4 v[218:219], off
	s_waitcnt vmcnt(8) lgkmcnt(0)
	s_barrier
	s_setprio 1
	v_mfma_f32_16x16x32_bf16 v[140:143], v[124:127], v[164:167], v[140:143]
	v_mfma_f32_16x16x32_bf16 v[140:143], v[128:131], v[168:171], v[140:143]
	v_mfma_f32_16x16x32_bf16 v[112:115], v[128:131], v[176:179], v[112:115]
	v_mfma_f32_16x16x32_bf16 v[112:115], v[124:127], v[172:175], v[112:115]
	v_mfma_f32_16x16x32_bf16 v[96:99], v[124:127], v[180:183], v[96:99]
	v_mfma_f32_16x16x32_bf16 v[96:99], v[128:131], v[184:187], v[96:99]
	v_mfma_f32_16x16x32_bf16 v[80:83], v[128:131], v[214:217], v[80:83]
	v_mfma_f32_16x16x32_bf16 v[80:83], v[124:127], v[188:191], v[80:83]
	v_mfma_f32_16x16x32_bf16 v[76:79], v[132:135], v[188:191], v[76:79]
	v_mfma_f32_16x16x32_bf16 v[76:79], v[144:147], v[214:217], v[76:79]
	v_mfma_f32_16x16x32_bf16 v[92:95], v[144:147], v[184:187], v[92:95]
	v_mfma_f32_16x16x32_bf16 v[92:95], v[132:135], v[180:183], v[92:95]
	v_mfma_f32_16x16x32_bf16 v[108:111], v[132:135], v[172:175], v[108:111]
	v_mfma_f32_16x16x32_bf16 v[108:111], v[144:147], v[176:179], v[108:111]
	v_mfma_f32_16x16x32_bf16 v[136:139], v[144:147], v[168:171], v[136:139]
	v_mfma_f32_16x16x32_bf16 v[136:139], v[132:135], v[164:167], v[136:139]
	v_mfma_f32_16x16x32_bf16 v[120:123], v[148:151], v[164:167], v[120:123]
	v_mfma_f32_16x16x32_bf16 v[120:123], v[152:155], v[168:171], v[120:123]
	v_mfma_f32_16x16x32_bf16 v[104:107], v[152:155], v[176:179], v[104:107]
	v_mfma_f32_16x16x32_bf16 v[104:107], v[148:151], v[172:175], v[104:107]
	v_mfma_f32_16x16x32_bf16 v[88:91], v[148:151], v[180:183], v[88:91]
	v_mfma_f32_16x16x32_bf16 v[88:91], v[152:155], v[184:187], v[88:91]
	v_mfma_f32_16x16x32_bf16 v[72:75], v[152:155], v[214:217], v[72:75]
	v_mfma_f32_16x16x32_bf16 v[72:75], v[148:151], v[188:191], v[72:75]
	v_mfma_f32_16x16x32_bf16 v[68:71], v[156:159], v[188:191], v[68:71]
	v_mfma_f32_16x16x32_bf16 v[68:71], v[160:163], v[214:217], v[68:71]
	v_mfma_f32_16x16x32_bf16 v[84:87], v[160:163], v[184:187], v[84:87]
	v_mfma_f32_16x16x32_bf16 v[84:87], v[156:159], v[180:183], v[84:87]
	v_mfma_f32_16x16x32_bf16 v[100:103], v[156:159], v[172:175], v[100:103]
	v_mfma_f32_16x16x32_bf16 v[100:103], v[160:163], v[176:179], v[100:103]
	v_mfma_f32_16x16x32_bf16 v[116:119], v[160:163], v[168:171], v[116:119]
	v_mfma_f32_16x16x32_bf16 v[116:119], v[156:159], v[164:167], v[116:119]
	s_setprio 0
	s_barrier
; #define PG8_STAGE(bufoff, gbase, voff) do { _Pragma("unroll") for (int _i = 0; _i < 2; ++_i) \
;         __builtin_amdgcn_global_load_lds((const unsigned*)((const char*)(gbase) + (voff)[_i]), (PG8_LAS unsigned*)(lds + (bufoff) + ldsw + _i * 8192), 16, 0, 0); } while (0)
; #define PG8_LDA(dst, b, h) do { _Pragma("unroll") for (int m = 0; m < 4; ++m) _Pragma("unroll") for (int k = 0; k < 2; ++k) dst[m][k] = *(const PG8_LAS bf16x8*)(lds + PG8_SA(b, h) + aoff + m * 2048 + k * 1024); } while (0)
; #define PG8_LDB(dst, b, h) do { _Pragma("unroll") for (int n = 0; n < 2; ++n) _Pragma("unroll") for (int k = 0; k < 2; ++k) dst[n][k] = *(const PG8_LAS bf16x8*)(lds + PG8_SB(b, h) + boff + n * 2048 + k * 1024); } while (0)
; #define PG8_WAIT_V(n) asm volatile("s_waitcnt vmcnt(" #n ")" ::: "memory")
; #define PG8_WAIT_L(n) asm volatile("s_waitcnt lgkmcnt(" #n ")" ::: "memory")
; #define PG8_BAR __builtin_amdgcn_s_barrier()
; #define PG8_SCHED __builtin_amdgcn_sched_barrier(0)
; template <class Epi, class Sched, bool ALIGN_EPI = false, bool SP2 = false, bool I8 = false>
; __device__ __forceinline__ void gemm_phase(PG8_LAS unsigned char* lds, const Gemm g, const Sched& S, const Epi& E) {
;     ...
;             PG8_LDA(At, 0, 1); PG8_STAGE(PG8_SB(0, 0), b2, voffB); PG8_STAGE(PG8_SB(0, 1), b2 + hstep, voffB); PG8_STAGE(PG8_SA(0, 0), a2, voffA);
;             PG8_WAIT_V(8); PG8_WAIT_L(0); PG8_BAR; PG8_MMA(1, 0, At, B0); PG8_MMA(1, 1, At, B1); PG8_BAR; PG8_SCHED;
;             PG8_LDB(B0, 1, 0); PG8_LDB(B1, 1, 1); PG8_SCHED; PG8_LDA(At, 1, 0); PG8_STAGE(PG8_SA(0, 1), a2 + hstep, voffA);
;             PG8_WAIT_V(8); PG8_WAIT_L(0); PG8_BAR; PG8_MMA(0, 0, At, B0); PG8_MMA(0, 1, At, B1); PG8_BAR; PG8_SCHED;
	s_add_i32 s22, s56, s41
	v_lshl_add_u64 v[218:219], s[26:27], 0, v[2:3]
	s_mov_b32 m0, s22
	ds_read_b128 v[164:167], v242 offset:16384
	ds_read_b128 v[168:171], v242 offset:17408
	ds_read_b128 v[172:175], v242 offset:18432
	ds_read_b128 v[176:179], v242 offset:19456
	ds_read_b128 v[180:183], v242 offset:20480
	ds_read_b128 v[184:187], v242 offset:21504
	ds_read_b128 v[188:191], v242 offset:22528
	ds_read_b128 v[214:217], v242 offset:23552
	global_load_lds_dwordx4 v[218:219], off
	s_add_i32 m0, s22, 0x2000
	s_add_u32 s22, s26, 0x2b0000
	v_lshl_add_u64 v[220:221], s[26:27], 0, v[204:205]
	s_addc_u32 s23, s27, 0
	s_add_i32 s56, s57, s41
	global_load_lds_dwordx4 v[220:221], off
	s_mov_b32 m0, s56
	v_lshl_add_u64 v[224:225], s[36:37], 0, v[206:207]
	global_load_lds_dwordx4 v2, s[22:23]
	s_add_i32 m0, s56, 0x2000
	s_nop 0
	global_load_lds_dwordx4 v204, s[22:23]
	v_lshl_add_u64 v[222:223], s[36:37], 0, v[208:209]
	s_waitcnt vmcnt(6) lgkmcnt(0)
	s_barrier
	s_setprio 1
	v_mfma_f32_16x16x32_bf16 v[64:67], v[124:127], v[164:167], v[64:67]
	v_mfma_f32_16x16x32_bf16 v[64:67], v[128:131], v[168:171], v[64:67]
	v_mfma_f32_16x16x32_bf16 v[48:51], v[128:131], v[176:179], v[48:51]
	v_mfma_f32_16x16x32_bf16 v[48:51], v[124:127], v[172:175], v[48:51]
	v_mfma_f32_16x16x32_bf16 v[32:35], v[124:127], v[180:183], v[32:35]
	v_mfma_f32_16x16x32_bf16 v[32:35], v[128:131], v[184:187], v[32:35]
	v_mfma_f32_16x16x32_bf16 v[16:19], v[128:131], v[214:217], v[16:19]
	v_mfma_f32_16x16x32_bf16 v[16:19], v[124:127], v[188:191], v[16:19]
	v_mfma_f32_16x16x32_bf16 v[12:15], v[132:135], v[188:191], v[12:15]
	v_mfma_f32_16x16x32_bf16 v[12:15], v[144:147], v[214:217], v[12:15]
	v_mfma_f32_16x16x32_bf16 v[28:31], v[144:147], v[184:187], v[28:31]
	v_mfma_f32_16x16x32_bf16 v[28:31], v[132:135], v[180:183], v[28:31]
	v_mfma_f32_16x16x32_bf16 v[44:47], v[132:135], v[172:175], v[44:47]
	v_mfma_f32_16x16x32_bf16 v[44:47], v[144:147], v[176:179], v[44:47]
	v_mfma_f32_16x16x32_bf16 v[60:63], v[144:147], v[168:171], v[60:63]
	v_mfma_f32_16x16x32_bf16 v[60:63], v[132:135], v[164:167], v[60:63]
	v_mfma_f32_16x16x32_bf16 v[56:59], v[148:151], v[164:167], v[56:59]
	v_mfma_f32_16x16x32_bf16 v[56:59], v[152:155], v[168:171], v[56:59]
	v_mfma_f32_16x16x32_bf16 v[40:43], v[152:155], v[176:179], v[40:43]
	v_mfma_f32_16x16x32_bf16 v[40:43], v[148:151], v[172:175], v[40:43]
	v_mfma_f32_16x16x32_bf16 v[24:27], v[148:151], v[180:183], v[24:27]
	v_mfma_f32_16x16x32_bf16 v[24:27], v[152:155], v[184:187], v[24:27]
	v_mfma_f32_16x16x32_bf16 v[8:11], v[152:155], v[214:217], v[8:11]
	v_mfma_f32_16x16x32_bf16 v[8:11], v[148:151], v[188:191], v[8:11]
	v_mfma_f32_16x16x32_bf16 v[4:7], v[156:159], v[188:191], v[4:7]
	v_mfma_f32_16x16x32_bf16 v[4:7], v[160:163], v[214:217], v[4:7]
	v_mfma_f32_16x16x32_bf16 v[20:23], v[160:163], v[184:187], v[20:23]
	v_mfma_f32_16x16x32_bf16 v[20:23], v[156:159], v[180:183], v[20:23]
	v_mfma_f32_16x16x32_bf16 v[36:39], v[156:159], v[172:175], v[36:39]
	v_mfma_f32_16x16x32_bf16 v[36:39], v[160:163], v[176:179], v[36:39]
	v_mfma_f32_16x16x32_bf16 v[52:55], v[160:163], v[168:171], v[52:55]
	v_mfma_f32_16x16x32_bf16 v[52:55], v[156:159], v[164:167], v[52:55]
	s_setprio 0
	s_barrier
	s_mov_b32 m0, s42
	s_nop 0
	global_load_lds_dwordx4 v[222:223], off
	s_mov_b32 m0, s43
	s_nop 0
	global_load_lds_dwordx4 v[224:225], off
	s_add_i32 s56, 0, 0x18000
	s_add_i32 s57, 0, 0x1c000
	v_add_u32_e32 v144, s56, v240
	v_add_u32_e32 v160, s57, v240
	ds_read_b128 v[124:127], v144
	ds_read_b128 v[128:131], v144 offset:1024
	ds_read_b128 v[132:135], v144 offset:2048
	ds_read_b128 v[144:147], v144 offset:3072
	ds_read_b128 v[148:151], v160
	ds_read_b128 v[152:155], v160 offset:1024
	ds_read_b128 v[156:159], v160 offset:2048
	ds_read_b128 v[160:163], v160 offset:3072
	s_add_u32 s22, s36, 0x2b0000
	s_addc_u32 s23, s37, 0
	s_mov_b32 m0, s44
	ds_read_b128 v[164:167], v242 offset:32768
	ds_read_b128 v[168:171], v242 offset:33792
	ds_read_b128 v[172:175], v242 offset:34816
	ds_read_b128 v[176:179], v242 offset:35840
	ds_read_b128 v[180:183], v242 offset:36864
	ds_read_b128 v[184:187], v242 offset:37888
	ds_read_b128 v[188:191], v242 offset:38912
	ds_read_b128 v[214:217], v242 offset:39936
	global_load_lds_dwordx4 v208, s[22:23]
	s_mov_b32 m0, s45
	s_nop 0
	global_load_lds_dwordx4 v206, s[22:23]
	s_waitcnt vmcnt(8) lgkmcnt(0)
	s_barrier
; #define PG8_STAGE(bufoff, gbase, voff) do { _Pragma("unroll") for (int _i = 0; _i < 2; ++_i) \
;         __builtin_amdgcn_global_load_lds((const unsigned*)((const char*)(gbase) + (voff)[_i]), (PG8_LAS unsigned*)(lds + (bufoff) + ldsw + _i * 8192), 16, 0, 0); } while (0)
; #define PG8_LDA(dst, b, h) do { _Pragma("unroll") for (int m = 0; m < 4; ++m) _Pragma("unroll") for (int k = 0; k < 2; ++k) dst[m][k] = *(const PG8_LAS bf16x8*)(lds + PG8_SA(b, h) + aoff + m * 2048 + k * 1024); } while (0)
; #define PG8_LDB(dst, b, h) do { _Pragma("unroll") for (int n = 0; n < 2; ++n) _Pragma("unroll") for (int k = 0; k < 2; ++k) dst[n][k] = *(const PG8_LAS bf16x8*)(lds + PG8_SB(b, h) + boff + n * 2048 + k * 1024); } while (0)
; #define PG8_WAIT_V(n) asm volatile("s_waitcnt vmcnt(" #n ")" ::: "memory")
; #define PG8_WAIT_L(n) asm volatile("s_waitcnt lgkmcnt(" #n ")" ::: "memory")
; #define PG8_BAR __builtin_amdgcn_s_barrier()
; #define PG8_SCHED __builtin_amdgcn_sched_barrier(0)
; template <class Epi, class Sched, bool ALIGN_EPI = false, bool SP2 = false, bool I8 = false>
; __device__ __forceinline__ void gemm_phase(PG8_LAS unsigned char* lds, const Gemm g, const Sched& S, const Epi& E) {
;     ...
;             PG8_LDB(B0, 0, 0); PG8_LDB(B1, 0, 1); PG8_SCHED; PG8_LDA(At, 0, 0); PG8_STAGE(PG8_SA(1, 1), a1 + hstep, voffA);
;             PG8_WAIT_V(8); PG8_WAIT_L(0); PG8_BAR; PG8_MMA(0, 0, At, B0); PG8_MMA(0, 1, At, B1); PG8_BAR; PG8_SCHED;
;             PG8_LDA(At, 0, 1); PG8_STAGE(PG8_SB(0, 0), b2, voffB); PG8_STAGE(PG8_SB(0, 1), b2 + hstep, voffB); PG8_STAGE(PG8_SA(0, 0), a2, voffA);
;             PG8_WAIT_V(8); PG8_WAIT_L(0); PG8_BAR; PG8_MMA(1, 0, At, B0); PG8_MMA(1, 1, At, B1); PG8_BAR; PG8_SCHED;
;             PG8_LDB(B0, 1, 0); PG8_LDB(B1, 1, 1); PG8_SCHED; PG8_LDA(At, 1, 0); PG8_STAGE(PG8_SA(0, 1), a2 + hstep, voffA);
;             PG8_WAIT_V(8); PG8_WAIT_L(0); PG8_BAR; PG8_MMA(0, 0, At, B0); PG8_MMA(0, 1, At, B1); PG8_BAR; PG8_SCHED;
;             PG8_LDA(At, 1, 1); PG8_STAGE(PG8_SB(1, 0), b3, voffB); PG8_STAGE(PG8_SB(1, 1), b3 + hstep, voffB); PG8_STAGE(PG8_SA(1, 0), a3, voffA);
;             PG8_WAIT_V(8); PG8_WAIT_L(0); PG8_BAR; PG8_MMA(1, 0, At, B0); PG8_MMA(1, 1, At, B1); PG8_BAR; PG8_SCHED;
	s_setprio 1
	v_mfma_f32_16x16x32_bf16 v[140:143], v[124:127], v[164:167], v[140:143]
	v_mfma_f32_16x16x32_bf16 v[140:143], v[128:131], v[168:171], v[140:143]
	v_mfma_f32_16x16x32_bf16 v[112:115], v[128:131], v[176:179], v[112:115]
	v_mfma_f32_16x16x32_bf16 v[112:115], v[124:127], v[172:175], v[112:115]
	v_mfma_f32_16x16x32_bf16 v[96:99], v[124:127], v[180:183], v[96:99]
	v_mfma_f32_16x16x32_bf16 v[96:99], v[128:131], v[184:187], v[96:99]
	v_mfma_f32_16x16x32_bf16 v[80:83], v[128:131], v[214:217], v[80:83]
	v_mfma_f32_16x16x32_bf16 v[80:83], v[124:127], v[188:191], v[80:83]
	v_mfma_f32_16x16x32_bf16 v[76:79], v[132:135], v[188:191], v[76:79]
	v_mfma_f32_16x16x32_bf16 v[76:79], v[144:147], v[214:217], v[76:79]
	v_mfma_f32_16x16x32_bf16 v[92:95], v[144:147], v[184:187], v[92:95]
	v_mfma_f32_16x16x32_bf16 v[92:95], v[132:135], v[180:183], v[92:95]
	v_mfma_f32_16x16x32_bf16 v[108:111], v[132:135], v[172:175], v[108:111]
	v_mfma_f32_16x16x32_bf16 v[108:111], v[144:147], v[176:179], v[108:111]
	v_mfma_f32_16x16x32_bf16 v[136:139], v[144:147], v[168:171], v[136:139]
	v_mfma_f32_16x16x32_bf16 v[136:139], v[132:135], v[164:167], v[136:139]
	v_mfma_f32_16x16x32_bf16 v[120:123], v[148:151], v[164:167], v[120:123]
	v_mfma_f32_16x16x32_bf16 v[120:123], v[152:155], v[168:171], v[120:123]
	v_mfma_f32_16x16x32_bf16 v[104:107], v[152:155], v[176:179], v[104:107]
	v_mfma_f32_16x16x32_bf16 v[104:107], v[148:151], v[172:175], v[104:107]
	v_mfma_f32_16x16x32_bf16 v[88:91], v[148:151], v[180:183], v[88:91]
	v_mfma_f32_16x16x32_bf16 v[88:91], v[152:155], v[184:187], v[88:91]
	v_mfma_f32_16x16x32_bf16 v[72:75], v[152:155], v[214:217], v[72:75]
	v_mfma_f32_16x16x32_bf16 v[72:75], v[148:151], v[188:191], v[72:75]
	v_mfma_f32_16x16x32_bf16 v[68:71], v[156:159], v[188:191], v[68:71]
	v_mfma_f32_16x16x32_bf16 v[68:71], v[160:163], v[214:217], v[68:71]
	v_mfma_f32_16x16x32_bf16 v[84:87], v[160:163], v[184:187], v[84:87]
	v_mfma_f32_16x16x32_bf16 v[84:87], v[156:159], v[180:183], v[84:87]
	v_mfma_f32_16x16x32_bf16 v[100:103], v[156:159], v[172:175], v[100:103]
	v_mfma_f32_16x16x32_bf16 v[100:103], v[160:163], v[176:179], v[100:103]
	v_mfma_f32_16x16x32_bf16 v[116:119], v[160:163], v[168:171], v[116:119]
	v_mfma_f32_16x16x32_bf16 v[116:119], v[156:159], v[164:167], v[116:119]
	s_setprio 0
	s_barrier
	s_add_i32 s22, s56, s41
	v_lshl_add_u64 v[218:219], v[218:219], 0, s[84:85]
	s_mov_b32 m0, s22
	ds_read_b128 v[164:167], v242 offset:49152
	ds_read_b128 v[168:171], v242 offset:50176
	ds_read_b128 v[172:175], v242 offset:51200
	ds_read_b128 v[176:179], v242 offset:52224
	ds_read_b128 v[180:183], v242 offset:53248
	ds_read_b128 v[184:187], v242 offset:54272
	ds_read_b128 v[188:191], v242 offset:55296
	ds_read_b128 v[214:217], v242 offset:56320
	global_load_lds_dwordx4 v[218:219], off
	s_add_i32 m0, s22, 0x2000
	s_add_u32 s22, s26, 0x2b0080
	v_lshl_add_u64 v[218:219], v[220:221], 0, s[84:85]
	s_addc_u32 s23, s27, 0
	s_add_i32 s26, s57, s41
	global_load_lds_dwordx4 v[218:219], off
	s_mov_b32 m0, s26
	s_nop 0
	global_load_lds_dwordx4 v2, s[22:23]
	s_add_i32 m0, s26, 0x2000
	s_nop 0
	global_load_lds_dwordx4 v204, s[22:23]
	s_cmpk_eq_i32 s55, 0xa8
	s_cbranch_scc0 .Ldefer_1700_body
	v_lshl_add_u64 v[218:219], v[222:223], 0, s[84:85]
	s_mov_b32 m0, s46
	s_nop 0
	global_load_lds_dwordx4 v[218:219], off
	v_lshl_add_u64 v[218:219], v[224:225], 0, s[84:85]
	s_mov_b32 m0, s47
	s_nop 0
	global_load_lds_dwordx4 v[218:219], off
.Ldefer_1700_body:
	s_waitcnt vmcnt(6) lgkmcnt(0)
	s_barrier
	s_setprio 1
	v_mfma_f32_16x16x32_bf16 v[64:67], v[124:127], v[164:167], v[64:67]
	v_mfma_f32_16x16x32_bf16 v[64:67], v[128:131], v[168:171], v[64:67]
	v_mfma_f32_16x16x32_bf16 v[48:51], v[128:131], v[176:179], v[48:51]
	v_mfma_f32_16x16x32_bf16 v[48:51], v[124:127], v[172:175], v[48:51]
	v_mfma_f32_16x16x32_bf16 v[32:35], v[124:127], v[180:183], v[32:35]
	v_mfma_f32_16x16x32_bf16 v[32:35], v[128:131], v[184:187], v[32:35]
	v_mfma_f32_16x16x32_bf16 v[16:19], v[128:131], v[214:217], v[16:19]
	v_mfma_f32_16x16x32_bf16 v[16:19], v[124:127], v[188:191], v[16:19]
	v_mfma_f32_16x16x32_bf16 v[12:15], v[132:135], v[188:191], v[12:15]
	v_mfma_f32_16x16x32_bf16 v[12:15], v[144:147], v[214:217], v[12:15]
	v_mfma_f32_16x16x32_bf16 v[28:31], v[144:147], v[184:187], v[28:31]
	v_mfma_f32_16x16x32_bf16 v[28:31], v[132:135], v[180:183], v[28:31]
	v_mfma_f32_16x16x32_bf16 v[44:47], v[132:135], v[172:175], v[44:47]
	v_mfma_f32_16x16x32_bf16 v[44:47], v[144:147], v[176:179], v[44:47]
	v_mfma_f32_16x16x32_bf16 v[60:63], v[144:147], v[168:171], v[60:63]
	v_mfma_f32_16x16x32_bf16 v[60:63], v[132:135], v[164:167], v[60:63]
	v_mfma_f32_16x16x32_bf16 v[56:59], v[148:151], v[164:167], v[56:59]
	v_mfma_f32_16x16x32_bf16 v[56:59], v[152:155], v[168:171], v[56:59]
	v_mfma_f32_16x16x32_bf16 v[40:43], v[152:155], v[176:179], v[40:43]
	v_mfma_f32_16x16x32_bf16 v[40:43], v[148:151], v[172:175], v[40:43]
	v_mfma_f32_16x16x32_bf16 v[24:27], v[148:151], v[180:183], v[24:27]
	v_mfma_f32_16x16x32_bf16 v[24:27], v[152:155], v[184:187], v[24:27]
	v_mfma_f32_16x16x32_bf16 v[8:11], v[152:155], v[214:217], v[8:11]
	v_mfma_f32_16x16x32_bf16 v[8:11], v[148:151], v[188:191], v[8:11]
	v_mfma_f32_16x16x32_bf16 v[4:7], v[156:159], v[188:191], v[4:7]
	v_mfma_f32_16x16x32_bf16 v[4:7], v[160:163], v[214:217], v[4:7]
	v_mfma_f32_16x16x32_bf16 v[20:23], v[160:163], v[184:187], v[20:23]
	v_mfma_f32_16x16x32_bf16 v[20:23], v[156:159], v[180:183], v[20:23]
	v_mfma_f32_16x16x32_bf16 v[36:39], v[156:159], v[172:175], v[36:39]
	v_mfma_f32_16x16x32_bf16 v[36:39], v[160:163], v[176:179], v[36:39]
	v_mfma_f32_16x16x32_bf16 v[52:55], v[160:163], v[168:171], v[52:55]
	v_mfma_f32_16x16x32_bf16 v[52:55], v[156:159], v[164:167], v[52:55]
	s_setprio 0
	s_barrier
	s_add_i32 s55, s55, 2
	s_add_u32 s53, s53, 0x100
	s_addc_u32 s54, s54, 0
	s_cmpk_gt_u32 s55, 0xa9
	s_mov_b64 s[22:23], s[24:25]
	s_cbranch_scc0 .LBB0_1700

; #define PG8_STAGE(bufoff, gbase, voff) do { _Pragma("unroll") for (int _i = 0; _i < 2; ++_i) \
;         __builtin_amdgcn_global_load_lds((const unsigned*)((const char*)(gbase) + (voff)[_i]), (PG8_LAS unsigned*)(lds + (bufoff) + ldsw + _i * 8192), 16, 0, 0); } while (0)
; #define PG8_LDA(dst, b, h) do { _Pragma("unroll") for (int m = 0; m < 4; ++m) _Pragma("unroll") for (int k = 0; k < 2; ++k) dst[m][k] = *(const PG8_LAS bf16x8*)(lds + PG8_SA(b, h) + aoff + m * 2048 + k * 1024); } while (0)
; #define PG8_LDB(dst, b, h) do { _Pragma("unroll") for (int n = 0; n < 2; ++n) _Pragma("unroll") for (int k = 0; k < 2; ++k) dst[n][k] = *(const PG8_LAS bf16x8*)(lds + PG8_SB(b, h) + boff + n * 2048 + k * 1024); } while (0)
; #define PG8_WAIT_V(n) asm volatile("s_waitcnt vmcnt(" #n ")" ::: "memory")
; #define PG8_WAIT_L(n) asm volatile("s_waitcnt lgkmcnt(" #n ")" ::: "memory")
; #define PG8_BAR __builtin_amdgcn_s_barrier()
; #define PG8_SCHED __builtin_amdgcn_sched_barrier(0)
; template <class Epi, class Sched, bool ALIGN_EPI = false, bool SP2 = false, bool I8 = false>
; __device__ __forceinline__ void gemm_phase(PG8_LAS unsigned char* lds, const Gemm g, const Sched& S, const Epi& E) {
;     ...
;         const bool has_next = S.next(ui + 1, nxt);
;         const char* nA = has_next ? (const char*)g.A + (size_t)nxt.pm * tstep : cA; const char* nB = has_next ? (const char*)g.Bt + (size_t)nxt.pn * tstep : cB;
;         for (int t = 0; t < nt; t += 2) {
;             const bool last = (t == nt - 2);
;             const char* a1 = cA + (size_t)(t + 1) * kstep;
;             const char* a2 = last ? nA : cA + (size_t)(t + 2) * kstep; const char* b2 = last ? nB : cB + (size_t)(t + 2) * kstep;
;             const char* a3 = a2 + kstep; const char* b3 = b2 + kstep;
;             if (last && has_next) S.a_ready(nxt);
;             if constexpr (SP2) {
;             PG8_LDB(B0, 0, 0); PG8_LDB(B1, 0, 1); PG8_SCHED; PG8_LDA(At, 0, 0); PG8_STAGE(PG8_SA(1, 1), a1 + hstep, voffA);
;             PG8_WAIT_V(8); PG8_WAIT_L(0); PG8_BAR; PG8_MMA(0, 0, At, B0); PG8_MMA(0, 1, At, B1); PG8_BAR; PG8_SCHED;
;             PG8_LDA(At, 0, 1); PG8_STAGE(PG8_SB(0, 0), b2, voffB); PG8_STAGE(PG8_SB(0, 1), b2 + hstep, voffB); PG8_STAGE(PG8_SA(0, 0), a2, voffA);
;             PG8_WAIT_V(8); PG8_WAIT_L(0); PG8_BAR; PG8_MMA(1, 0, At, B0); PG8_MMA(1, 1, At, B1); PG8_BAR; PG8_SCHED;
.LBB0_1842:
	s_ashr_i32 s45, s44, 31
	s_lshl_b64 s[34:35], s[44:45], 20
	s_add_u32 s50, s47, s34
	s_addc_u32 s51, s52, s35
	s_and_b64 s[34:35], s[8:9], exec
	s_cselect_b32 s11, s51, s55
	s_cselect_b32 s13, s50, s54
	s_ashr_i32 s49, s48, 31
	s_lshl_b64 s[34:35], s[48:49], 20
	s_add_u32 s56, s53, s34
	s_addc_u32 s57, s64, s35
	s_and_b64 s[34:35], s[8:9], exec
	s_cselect_b32 s34, s57, s59
	s_cselect_b32 s35, s56, s58
	s_add_u32 s54, s54, 0x80080
	s_addc_u32 s55, s55, 0
	s_add_u32 s45, s58, 0x100
	s_addc_u32 s49, s59, 0
	s_mov_b32 s86, -2
	s_waitcnt lgkmcnt(0)
	s_add_u32 s58, s54, 0xfff80080
	s_addc_u32 s59, s55, -1
	s_add_i32 s87, 0, 0x10000
	s_cmp_eq_u32 s86, 28
	s_cselect_b32 s61, s11, s59
	s_cselect_b32 s60, s13, s58
	s_cselect_b32 s59, s34, s49
	s_cselect_b32 s58, s35, s45
	s_add_i32 vcc_lo, 0, 0x14000
	v_add_u32_e32 v40, s87, v217
	v_add_u32_e32 v160, vcc_lo, v217
	ds_read_b128 v[28:31], v40
	ds_read_b128 v[32:35], v40 offset:1024
	ds_read_b128 v[36:39], v40 offset:2048
	ds_read_b128 v[40:43], v40 offset:3072
	ds_read_b128 v[140:143], v160
	ds_read_b128 v[144:147], v160 offset:1024
	ds_read_b128 v[156:159], v160 offset:2048
	ds_read_b128 v[160:163], v160 offset:3072
	s_add_i32 m0, s65, 0xc000
	ds_read_b128 v[164:167], v219
	ds_read_b128 v[168:171], v219 offset:1024
	ds_read_b128 v[172:175], v219 offset:2048
	ds_read_b128 v[176:179], v219 offset:3072
	ds_read_b128 v[204:207], v219 offset:4096
	ds_read_b128 v[208:211], v219 offset:5120
	ds_read_b128 v[212:215], v219 offset:6144
	ds_read_b128 v[220:223], v219 offset:7168
	global_load_lds_dwordx4 v186, s[54:55]
	s_add_i32 m0, s65, 0xe000
	s_nop 0
	global_load_lds_dwordx4 v188, s[54:55]
	s_waitcnt vmcnt(8) lgkmcnt(0)
	s_barrier
	s_setprio 1
	v_mfma_i32_16x16x64_i8 v[152:155], v[28:31], v[164:167], 0
	v_mfma_i32_16x16x64_i8 v[152:155], v[32:35], v[168:171], v[152:155]
	v_mfma_i32_16x16x64_i8 v[128:131], v[32:35], v[176:179], 0
	v_mfma_i32_16x16x64_i8 v[128:131], v[28:31], v[172:175], v[128:131]
	v_mfma_i32_16x16x64_i8 v[112:115], v[28:31], v[204:207], 0
	v_mfma_i32_16x16x64_i8 v[112:115], v[32:35], v[208:211], v[112:115]
	v_mfma_i32_16x16x64_i8 v[96:99], v[32:35], v[220:223], 0
	v_mfma_i32_16x16x64_i8 v[96:99], v[28:31], v[212:215], v[96:99]
	v_mfma_i32_16x16x64_i8 v[92:95], v[36:39], v[212:215], 0
	v_mfma_i32_16x16x64_i8 v[92:95], v[40:43], v[220:223], v[92:95]
	v_mfma_i32_16x16x64_i8 v[108:111], v[40:43], v[208:211], 0
	v_mfma_i32_16x16x64_i8 v[108:111], v[36:39], v[204:207], v[108:111]
	v_mfma_i32_16x16x64_i8 v[124:127], v[36:39], v[172:175], 0
	v_mfma_i32_16x16x64_i8 v[124:127], v[40:43], v[176:179], v[124:127]
	v_mfma_i32_16x16x64_i8 v[148:151], v[40:43], v[168:171], 0
	v_mfma_i32_16x16x64_i8 v[148:151], v[36:39], v[164:167], v[148:151]
	v_mfma_i32_16x16x64_i8 v[136:139], v[140:143], v[164:167], 0
	v_mfma_i32_16x16x64_i8 v[136:139], v[144:147], v[168:171], v[136:139]
	v_mfma_i32_16x16x64_i8 v[120:123], v[144:147], v[176:179], 0
	v_mfma_i32_16x16x64_i8 v[120:123], v[140:143], v[172:175], v[120:123]
	v_mfma_i32_16x16x64_i8 v[104:107], v[140:143], v[204:207], 0
	v_mfma_i32_16x16x64_i8 v[104:107], v[144:147], v[208:211], v[104:107]
	v_mfma_i32_16x16x64_i8 v[88:91], v[144:147], v[220:223], 0
	v_mfma_i32_16x16x64_i8 v[88:91], v[140:143], v[212:215], v[88:91]
	v_mfma_i32_16x16x64_i8 v[84:87], v[156:159], v[212:215], 0
	v_mfma_i32_16x16x64_i8 v[84:87], v[160:163], v[220:223], v[84:87]
	v_mfma_i32_16x16x64_i8 v[100:103], v[160:163], v[208:211], 0
	v_mfma_i32_16x16x64_i8 v[100:103], v[156:159], v[204:207], v[100:103]
	v_mfma_i32_16x16x64_i8 v[116:119], v[156:159], v[172:175], 0
	v_mfma_i32_16x16x64_i8 v[116:119], v[160:163], v[176:179], v[116:119]
	v_mfma_i32_16x16x64_i8 v[132:135], v[160:163], v[168:171], 0
	v_mfma_i32_16x16x64_i8 v[132:135], v[156:159], v[164:167], v[132:135]
	s_setprio 0
	s_barrier
	s_add_i32 s87, s87, s46
	v_lshl_add_u64 v[190:191], s[58:59], 0, v[2:3]
	s_mov_b32 m0, s87
	ds_read_b128 v[164:167], v219 offset:16384
	ds_read_b128 v[168:171], v219 offset:17408
	ds_read_b128 v[172:175], v219 offset:18432
	ds_read_b128 v[176:179], v219 offset:19456
	ds_read_b128 v[204:207], v219 offset:20480
	ds_read_b128 v[208:211], v219 offset:21504
	ds_read_b128 v[212:215], v219 offset:22528
	ds_read_b128 v[220:223], v219 offset:23552
	global_load_lds_dwordx4 v[190:191], off
	s_add_i32 m0, s87, 0x2000
	s_add_u32 s96, s58, 0x80000
	v_lshl_add_u64 v[224:225], s[58:59], 0, v[184:185]
	s_addc_u32 s97, s59, 0
	s_add_i32 s87, vcc_lo, s46
	global_load_lds_dwordx4 v[224:225], off
	s_mov_b32 m0, s87
	v_lshl_add_u64 v[228:229], s[60:61], 0, v[182:183]
	global_load_lds_dwordx4 v2, s[96:97]
	s_add_i32 m0, s87, 0x2000
	s_nop 0
	global_load_lds_dwordx4 v184, s[96:97]
	v_lshl_add_u64 v[226:227], s[60:61], 0, v[180:181]
	s_waitcnt vmcnt(6) lgkmcnt(0)
	s_barrier
; #define PG8_STAGE(bufoff, gbase, voff) do { _Pragma("unroll") for (int _i = 0; _i < 2; ++_i) \
;         __builtin_amdgcn_global_load_lds((const unsigned*)((const char*)(gbase) + (voff)[_i]), (PG8_LAS unsigned*)(lds + (bufoff) + ldsw + _i * 8192), 16, 0, 0); } while (0)
; #define PG8_LDA(dst, b, h) do { _Pragma("unroll") for (int m = 0; m < 4; ++m) _Pragma("unroll") for (int k = 0; k < 2; ++k) dst[m][k] = *(const PG8_LAS bf16x8*)(lds + PG8_SA(b, h) + aoff + m * 2048 + k * 1024); } while (0)
; #define PG8_LDB(dst, b, h) do { _Pragma("unroll") for (int n = 0; n < 2; ++n) _Pragma("unroll") for (int k = 0; k < 2; ++k) dst[n][k] = *(const PG8_LAS bf16x8*)(lds + PG8_SB(b, h) + boff + n * 2048 + k * 1024); } while (0)
; #define PG8_WAIT_V(n) asm volatile("s_waitcnt vmcnt(" #n ")" ::: "memory")
; #define PG8_WAIT_L(n) asm volatile("s_waitcnt lgkmcnt(" #n ")" ::: "memory")
; #define PG8_BAR __builtin_amdgcn_s_barrier()
; #define PG8_SCHED __builtin_amdgcn_sched_barrier(0)
; template <class Epi, class Sched, bool ALIGN_EPI = false, bool SP2 = false, bool I8 = false>
; __device__ __forceinline__ void gemm_phase(PG8_LAS unsigned char* lds, const Gemm g, const Sched& S, const Epi& E) {
;     ...
;             PG8_WAIT_V(8); PG8_WAIT_L(0); PG8_BAR; PG8_MMA(0, 0, At, B0); PG8_MMA(0, 1, At, B1); PG8_BAR; PG8_SCHED;
;             PG8_LDA(At, 0, 1); PG8_STAGE(PG8_SB(0, 0), b2, voffB); PG8_STAGE(PG8_SB(0, 1), b2 + hstep, voffB); PG8_STAGE(PG8_SA(0, 0), a2, voffA);
;             PG8_WAIT_V(8); PG8_WAIT_L(0); PG8_BAR; PG8_MMA(1, 0, At, B0); PG8_MMA(1, 1, At, B1); PG8_BAR; PG8_SCHED;
;             PG8_LDB(B0, 1, 0); PG8_LDB(B1, 1, 1); PG8_SCHED; PG8_LDA(At, 1, 0); PG8_STAGE(PG8_SA(0, 1), a2 + hstep, voffA);
;             PG8_WAIT_V(8); PG8_WAIT_L(0); PG8_BAR; PG8_MMA(0, 0, At, B0); PG8_MMA(0, 1, At, B1); PG8_BAR; PG8_SCHED;
;             PG8_LDA(At, 1, 1); PG8_STAGE(PG8_SB(1, 0), b3, voffB); PG8_STAGE(PG8_SB(1, 1), b3 + hstep, voffB); PG8_STAGE(PG8_SA(1, 0), a3, voffA);
;             PG8_WAIT_V(8); PG8_WAIT_L(0); PG8_BAR; PG8_MMA(1, 0, At, B0); PG8_MMA(1, 1, At, B1); PG8_BAR; PG8_SCHED;
	s_setprio 1
	v_mfma_i32_16x16x64_i8 v[80:83], v[28:31], v[164:167], 0
	v_mfma_i32_16x16x64_i8 v[80:83], v[32:35], v[168:171], v[80:83]
	v_mfma_i32_16x16x64_i8 v[64:67], v[32:35], v[176:179], 0
	v_mfma_i32_16x16x64_i8 v[64:67], v[28:31], v[172:175], v[64:67]
	v_mfma_i32_16x16x64_i8 v[48:51], v[28:31], v[204:207], 0
	v_mfma_i32_16x16x64_i8 v[48:51], v[32:35], v[208:211], v[48:51]
	v_mfma_i32_16x16x64_i8 v[16:19], v[32:35], v[220:223], 0
	v_mfma_i32_16x16x64_i8 v[16:19], v[28:31], v[212:215], v[16:19]
	v_mfma_i32_16x16x64_i8 v[12:15], v[36:39], v[212:215], 0
	v_mfma_i32_16x16x64_i8 v[12:15], v[40:43], v[220:223], v[12:15]
	v_mfma_i32_16x16x64_i8 v[44:47], v[40:43], v[208:211], 0
	v_mfma_i32_16x16x64_i8 v[44:47], v[36:39], v[204:207], v[44:47]
	v_mfma_i32_16x16x64_i8 v[60:63], v[36:39], v[172:175], 0
	v_mfma_i32_16x16x64_i8 v[60:63], v[40:43], v[176:179], v[60:63]
	v_mfma_i32_16x16x64_i8 v[76:79], v[40:43], v[168:171], 0
	v_mfma_i32_16x16x64_i8 v[76:79], v[36:39], v[164:167], v[76:79]
	v_mfma_i32_16x16x64_i8 v[28:31], v[140:143], v[164:167], 0
	v_mfma_i32_16x16x64_i8 v[28:31], v[144:147], v[168:171], v[28:31]
	v_mfma_i32_16x16x64_i8 v[36:39], v[144:147], v[176:179], 0
	v_mfma_i32_16x16x64_i8 v[36:39], v[140:143], v[172:175], v[36:39]
	v_mfma_i32_16x16x64_i8 v[24:27], v[140:143], v[204:207], 0
	v_mfma_i32_16x16x64_i8 v[24:27], v[144:147], v[208:211], v[24:27]
	v_mfma_i32_16x16x64_i8 v[8:11], v[144:147], v[220:223], 0
	v_mfma_i32_16x16x64_i8 v[8:11], v[140:143], v[212:215], v[8:11]
	v_mfma_i32_16x16x64_i8 v[4:7], v[156:159], v[212:215], 0
	v_mfma_i32_16x16x64_i8 v[4:7], v[160:163], v[220:223], v[4:7]
	v_mfma_i32_16x16x64_i8 v[20:23], v[160:163], v[208:211], 0
	v_mfma_i32_16x16x64_i8 v[20:23], v[156:159], v[204:207], v[20:23]
	v_mfma_i32_16x16x64_i8 v[40:43], v[156:159], v[172:175], 0
	v_mfma_i32_16x16x64_i8 v[40:43], v[160:163], v[176:179], v[40:43]
	v_mfma_i32_16x16x64_i8 v[32:35], v[160:163], v[168:171], 0
	v_mfma_i32_16x16x64_i8 v[32:35], v[156:159], v[164:167], v[32:35]
	s_setprio 0
	s_barrier
	s_mov_b32 m0, s65
	s_nop 0
	global_load_lds_dwordx4 v[226:227], off
	s_mov_b32 m0, s67
	s_nop 0
	global_load_lds_dwordx4 v[228:229], off
	s_add_i32 s87, 0, 0x18000
	s_add_i32 s96, 0, 0x1c000
	v_add_u32_e32 v72, s87, v217
	v_add_u32_e32 v160, s96, v217
	ds_read_b128 v[52:55], v72
	ds_read_b128 v[56:59], v72 offset:1024
	ds_read_b128 v[68:71], v72 offset:2048
	ds_read_b128 v[72:75], v72 offset:3072
	ds_read_b128 v[140:143], v160
	ds_read_b128 v[144:147], v160 offset:1024
	ds_read_b128 v[156:159], v160 offset:2048
	ds_read_b128 v[160:163], v160 offset:3072
	s_add_u32 s60, s60, 0x80000
	s_addc_u32 s61, s61, 0
	s_mov_b32 m0, s72
	ds_read_b128 v[164:167], v219 offset:32768
	ds_read_b128 v[168:171], v219 offset:33792
	ds_read_b128 v[172:175], v219 offset:34816
	ds_read_b128 v[176:179], v219 offset:35840
	ds_read_b128 v[204:207], v219 offset:36864
	ds_read_b128 v[208:211], v219 offset:37888
	ds_read_b128 v[212:215], v219 offset:38912
	ds_read_b128 v[220:223], v219 offset:39936
	global_load_lds_dwordx4 v180, s[60:61]
	s_mov_b32 m0, s73
	s_nop 0
	global_load_lds_dwordx4 v182, s[60:61]
	s_waitcnt vmcnt(8) lgkmcnt(0)
	s_barrier
	s_setprio 1
	v_mfma_i32_16x16x64_i8 v[152:155], v[52:55], v[164:167], v[152:155]
	v_mfma_i32_16x16x64_i8 v[152:155], v[56:59], v[168:171], v[152:155]
	v_mfma_i32_16x16x64_i8 v[128:131], v[56:59], v[176:179], v[128:131]
	v_mfma_i32_16x16x64_i8 v[128:131], v[52:55], v[172:175], v[128:131]
	v_mfma_i32_16x16x64_i8 v[112:115], v[52:55], v[204:207], v[112:115]
	v_mfma_i32_16x16x64_i8 v[112:115], v[56:59], v[208:211], v[112:115]
	v_mfma_i32_16x16x64_i8 v[96:99], v[56:59], v[220:223], v[96:99]
	v_mfma_i32_16x16x64_i8 v[96:99], v[52:55], v[212:215], v[96:99]
	v_mfma_i32_16x16x64_i8 v[92:95], v[68:71], v[212:215], v[92:95]
	v_mfma_i32_16x16x64_i8 v[92:95], v[72:75], v[220:223], v[92:95]
	v_mfma_i32_16x16x64_i8 v[108:111], v[72:75], v[208:211], v[108:111]
	v_mfma_i32_16x16x64_i8 v[108:111], v[68:71], v[204:207], v[108:111]
	v_mfma_i32_16x16x64_i8 v[124:127], v[68:71], v[172:175], v[124:127]
	v_mfma_i32_16x16x64_i8 v[124:127], v[72:75], v[176:179], v[124:127]
	v_mfma_i32_16x16x64_i8 v[148:151], v[72:75], v[168:171], v[148:151]
	v_mfma_i32_16x16x64_i8 v[148:151], v[68:71], v[164:167], v[148:151]
	v_mfma_i32_16x16x64_i8 v[136:139], v[140:143], v[164:167], v[136:139]
	v_mfma_i32_16x16x64_i8 v[136:139], v[144:147], v[168:171], v[136:139]
	v_mfma_i32_16x16x64_i8 v[120:123], v[144:147], v[176:179], v[120:123]
	v_mfma_i32_16x16x64_i8 v[120:123], v[140:143], v[172:175], v[120:123]
	v_mfma_i32_16x16x64_i8 v[104:107], v[140:143], v[204:207], v[104:107]
	v_mfma_i32_16x16x64_i8 v[104:107], v[144:147], v[208:211], v[104:107]
	v_mfma_i32_16x16x64_i8 v[88:91], v[144:147], v[220:223], v[88:91]
	v_mfma_i32_16x16x64_i8 v[88:91], v[140:143], v[212:215], v[88:91]
	v_mfma_i32_16x16x64_i8 v[84:87], v[156:159], v[212:215], v[84:87]
	v_mfma_i32_16x16x64_i8 v[84:87], v[160:163], v[220:223], v[84:87]
	v_mfma_i32_16x16x64_i8 v[100:103], v[160:163], v[208:211], v[100:103]
	v_mfma_i32_16x16x64_i8 v[100:103], v[156:159], v[204:207], v[100:103]
	v_mfma_i32_16x16x64_i8 v[116:119], v[156:159], v[172:175], v[116:119]
	v_mfma_i32_16x16x64_i8 v[116:119], v[160:163], v[176:179], v[116:119]
	v_mfma_i32_16x16x64_i8 v[132:135], v[160:163], v[168:171], v[132:135]
	v_mfma_i32_16x16x64_i8 v[132:135], v[156:159], v[164:167], v[132:135]
	s_setprio 0
	s_barrier
	s_add_i32 s60, s87, s46
	v_lshl_add_u64 v[190:191], v[190:191], 0, s[84:85]
	s_mov_b32 m0, s60
	ds_read_b128 v[164:167], v219 offset:49152
	ds_read_b128 v[168:171], v219 offset:50176
	ds_read_b128 v[172:175], v219 offset:51200
	ds_read_b128 v[176:179], v219 offset:52224
	ds_read_b128 v[204:207], v219 offset:53248
	ds_read_b128 v[208:211], v219 offset:54272
	ds_read_b128 v[212:215], v219 offset:55296
	ds_read_b128 v[220:223], v219 offset:56320
	global_load_lds_dwordx4 v[190:191], off
	s_add_i32 m0, s60, 0x2000
	s_add_u32 s58, s58, 0x80080
	v_lshl_add_u64 v[190:191], v[224:225], 0, s[84:85]
	s_addc_u32 s59, s59, 0
	s_add_i32 s60, s96, s46
	global_load_lds_dwordx4 v[190:191], off
	s_mov_b32 m0, s60
	s_nop 0
	global_load_lds_dwordx4 v2, s[58:59]
	s_add_i32 m0, s60, 0x2000
	s_nop 0
	global_load_lds_dwordx4 v184, s[58:59]
	s_cmp_eq_u32 s86, 28
	s_cbranch_scc0 .Ldefer_1843_peel
	v_lshl_add_u64 v[190:191], v[226:227], 0, s[84:85]
	s_mov_b32 m0, s28
	s_nop 0
	global_load_lds_dwordx4 v[190:191], off
	v_lshl_add_u64 v[190:191], v[228:229], 0, s[84:85]
	s_mov_b32 m0, s77
	s_nop 0
	global_load_lds_dwordx4 v[190:191], off
; #define PG8_STAGE(bufoff, gbase, voff) do { _Pragma("unroll") for (int _i = 0; _i < 2; ++_i) \
;         __builtin_amdgcn_global_load_lds((const unsigned*)((const char*)(gbase) + (voff)[_i]), (PG8_LAS unsigned*)(lds + (bufoff) + ldsw + _i * 8192), 16, 0, 0); } while (0)
; #define PG8_LDA(dst, b, h) do { _Pragma("unroll") for (int m = 0; m < 4; ++m) _Pragma("unroll") for (int k = 0; k < 2; ++k) dst[m][k] = *(const PG8_LAS bf16x8*)(lds + PG8_SA(b, h) + aoff + m * 2048 + k * 1024); } while (0)
; #define PG8_LDB(dst, b, h) do { _Pragma("unroll") for (int n = 0; n < 2; ++n) _Pragma("unroll") for (int k = 0; k < 2; ++k) dst[n][k] = *(const PG8_LAS bf16x8*)(lds + PG8_SB(b, h) + boff + n * 2048 + k * 1024); } while (0)
; #define PG8_WAIT_V(n) asm volatile("s_waitcnt vmcnt(" #n ")" ::: "memory")
; #define PG8_WAIT_L(n) asm volatile("s_waitcnt lgkmcnt(" #n ")" ::: "memory")
; #define PG8_BAR __builtin_amdgcn_s_barrier()
; #define PG8_SCHED __builtin_amdgcn_sched_barrier(0)
; template <class Epi, class Sched, bool ALIGN_EPI = false, bool SP2 = false, bool I8 = false>
; __device__ __forceinline__ void gemm_phase(PG8_LAS unsigned char* lds, const Gemm g, const Sched& S, const Epi& E) {
;     ...
;         for (int t = 0; t < nt; t += 2) {
;             const bool last = (t == nt - 2);
;             const char* a1 = cA + (size_t)(t + 1) * kstep;
;             const char* a2 = last ? nA : cA + (size_t)(t + 2) * kstep; const char* b2 = last ? nB : cB + (size_t)(t + 2) * kstep;
;             const char* a3 = a2 + kstep; const char* b3 = b2 + kstep;
;             if (last && has_next) S.a_ready(nxt);
;             if constexpr (SP2) {
;             PG8_LDB(B0, 0, 0); PG8_LDB(B1, 0, 1); PG8_SCHED; PG8_LDA(At, 0, 0); PG8_STAGE(PG8_SA(1, 1), a1 + hstep, voffA);
;             PG8_WAIT_V(8); PG8_WAIT_L(0); PG8_BAR; PG8_MMA(0, 0, At, B0); PG8_MMA(0, 1, At, B1); PG8_BAR; PG8_SCHED;
.Ldefer_1843_peel:
	s_waitcnt vmcnt(6) lgkmcnt(0)
	s_barrier
	s_setprio 1
	v_mfma_i32_16x16x64_i8 v[80:83], v[52:55], v[164:167], v[80:83]
	v_mfma_i32_16x16x64_i8 v[80:83], v[56:59], v[168:171], v[80:83]
	v_mfma_i32_16x16x64_i8 v[64:67], v[56:59], v[176:179], v[64:67]
	v_mfma_i32_16x16x64_i8 v[64:67], v[52:55], v[172:175], v[64:67]
	v_mfma_i32_16x16x64_i8 v[48:51], v[52:55], v[204:207], v[48:51]
	v_mfma_i32_16x16x64_i8 v[48:51], v[56:59], v[208:211], v[48:51]
	v_mfma_i32_16x16x64_i8 v[16:19], v[56:59], v[220:223], v[16:19]
	v_mfma_i32_16x16x64_i8 v[16:19], v[52:55], v[212:215], v[16:19]
	v_mfma_i32_16x16x64_i8 v[12:15], v[68:71], v[212:215], v[12:15]
	v_mfma_i32_16x16x64_i8 v[12:15], v[72:75], v[220:223], v[12:15]
	v_mfma_i32_16x16x64_i8 v[44:47], v[72:75], v[208:211], v[44:47]
	v_mfma_i32_16x16x64_i8 v[44:47], v[68:71], v[204:207], v[44:47]
	v_mfma_i32_16x16x64_i8 v[60:63], v[68:71], v[172:175], v[60:63]
	v_mfma_i32_16x16x64_i8 v[60:63], v[72:75], v[176:179], v[60:63]
	v_mfma_i32_16x16x64_i8 v[76:79], v[72:75], v[168:171], v[76:79]
	v_mfma_i32_16x16x64_i8 v[76:79], v[68:71], v[164:167], v[76:79]
	v_mfma_i32_16x16x64_i8 v[28:31], v[140:143], v[164:167], v[28:31]
	v_mfma_i32_16x16x64_i8 v[72:75], v[144:147], v[168:171], v[28:31]
	v_mfma_i32_16x16x64_i8 v[28:31], v[144:147], v[176:179], v[36:39]
	v_mfma_i32_16x16x64_i8 v[56:59], v[140:143], v[172:175], v[28:31]
	v_mfma_i32_16x16x64_i8 v[24:27], v[140:143], v[204:207], v[24:27]
	v_mfma_i32_16x16x64_i8 v[24:27], v[144:147], v[208:211], v[24:27]
	v_mfma_i32_16x16x64_i8 v[8:11], v[144:147], v[220:223], v[8:11]
	v_mfma_i32_16x16x64_i8 v[8:11], v[140:143], v[212:215], v[8:11]
	v_mfma_i32_16x16x64_i8 v[4:7], v[156:159], v[212:215], v[4:7]
	v_mfma_i32_16x16x64_i8 v[4:7], v[160:163], v[220:223], v[4:7]
	v_mfma_i32_16x16x64_i8 v[20:23], v[160:163], v[208:211], v[20:23]
	v_mfma_i32_16x16x64_i8 v[20:23], v[156:159], v[204:207], v[20:23]
	v_mfma_i32_16x16x64_i8 v[28:31], v[156:159], v[172:175], v[40:43]
	v_mfma_i32_16x16x64_i8 v[52:55], v[160:163], v[176:179], v[28:31]
	v_mfma_i32_16x16x64_i8 v[28:31], v[160:163], v[168:171], v[32:35]
	v_mfma_i32_16x16x64_i8 v[68:71], v[156:159], v[164:167], v[28:31]
	s_setprio 0
	s_barrier
	s_add_i32 s86, s86, 2
	s_add_u32 s54, s54, 0x100
	s_addc_u32 s55, s55, 0
	s_add_u32 s45, s45, 0x100
	s_addc_u32 s49, s49, 0
	s_cmp_gt_u32 s86, 29
	s_cbranch_scc1 .Lkloop_exit_6
.LBB0_1843:
	s_add_u32 s58, s54, 0xfff80080
	s_addc_u32 s59, s55, -1
	s_add_i32 s87, 0, 0x10000
	s_cmp_eq_u32 s86, 28
	s_cselect_b32 s61, s11, s59
	s_cselect_b32 s60, s13, s58
	s_cselect_b32 s59, s34, s49
	s_cselect_b32 s58, s35, s45
	s_add_i32 vcc_lo, 0, 0x14000
	v_add_u32_e32 v40, s87, v217
	v_add_u32_e32 v160, vcc_lo, v217
	ds_read_b128 v[28:31], v40
	ds_read_b128 v[32:35], v40 offset:1024
	ds_read_b128 v[36:39], v40 offset:2048
	ds_read_b128 v[40:43], v40 offset:3072
	ds_read_b128 v[140:143], v160
	ds_read_b128 v[144:147], v160 offset:1024
	ds_read_b128 v[156:159], v160 offset:2048
	ds_read_b128 v[160:163], v160 offset:3072
	v_lshl_add_u64 v[190:191], v[226:227], 0, s[84:85]
	s_mov_b32 m0, s28
	s_nop 0
	global_load_lds_dwordx4 v[190:191], off
	v_lshl_add_u64 v[190:191], v[228:229], 0, s[84:85]
	s_mov_b32 m0, s77
	s_nop 0
	global_load_lds_dwordx4 v[190:191], off
	s_add_i32 m0, s65, 0xc000
	ds_read_b128 v[164:167], v219
	ds_read_b128 v[168:171], v219 offset:1024
	ds_read_b128 v[172:175], v219 offset:2048
	ds_read_b128 v[176:179], v219 offset:3072
	ds_read_b128 v[204:207], v219 offset:4096
	ds_read_b128 v[208:211], v219 offset:5120
	ds_read_b128 v[212:215], v219 offset:6144
	ds_read_b128 v[220:223], v219 offset:7168
	global_load_lds_dwordx4 v186, s[54:55]
	s_add_i32 m0, s65, 0xe000
	s_nop 0
	global_load_lds_dwordx4 v188, s[54:55]
	s_waitcnt vmcnt(8) lgkmcnt(0)
	s_barrier
	s_setprio 1
	v_mfma_i32_16x16x64_i8 v[152:155], v[28:31], v[164:167], v[152:155]
	v_mfma_i32_16x16x64_i8 v[152:155], v[32:35], v[168:171], v[152:155]
	v_mfma_i32_16x16x64_i8 v[128:131], v[32:35], v[176:179], v[128:131]
	v_mfma_i32_16x16x64_i8 v[128:131], v[28:31], v[172:175], v[128:131]
	v_mfma_i32_16x16x64_i8 v[112:115], v[28:31], v[204:207], v[112:115]
	v_mfma_i32_16x16x64_i8 v[112:115], v[32:35], v[208:211], v[112:115]
	v_mfma_i32_16x16x64_i8 v[96:99], v[32:35], v[220:223], v[96:99]
	v_mfma_i32_16x16x64_i8 v[96:99], v[28:31], v[212:215], v[96:99]
	v_mfma_i32_16x16x64_i8 v[92:95], v[36:39], v[212:215], v[92:95]
	v_mfma_i32_16x16x64_i8 v[92:95], v[40:43], v[220:223], v[92:95]
	v_mfma_i32_16x16x64_i8 v[108:111], v[40:43], v[208:211], v[108:111]
	v_mfma_i32_16x16x64_i8 v[108:111], v[36:39], v[204:207], v[108:111]
	v_mfma_i32_16x16x64_i8 v[124:127], v[36:39], v[172:175], v[124:127]
	v_mfma_i32_16x16x64_i8 v[124:127], v[40:43], v[176:179], v[124:127]
	v_mfma_i32_16x16x64_i8 v[148:151], v[40:43], v[168:171], v[148:151]
	v_mfma_i32_16x16x64_i8 v[148:151], v[36:39], v[164:167], v[148:151]
	v_mfma_i32_16x16x64_i8 v[136:139], v[140:143], v[164:167], v[136:139]
	v_mfma_i32_16x16x64_i8 v[136:139], v[144:147], v[168:171], v[136:139]
	v_mfma_i32_16x16x64_i8 v[120:123], v[144:147], v[176:179], v[120:123]
	v_mfma_i32_16x16x64_i8 v[120:123], v[140:143], v[172:175], v[120:123]
	v_mfma_i32_16x16x64_i8 v[104:107], v[140:143], v[204:207], v[104:107]
	v_mfma_i32_16x16x64_i8 v[104:107], v[144:147], v[208:211], v[104:107]
	v_mfma_i32_16x16x64_i8 v[88:91], v[144:147], v[220:223], v[88:91]
	v_mfma_i32_16x16x64_i8 v[88:91], v[140:143], v[212:215], v[88:91]
	v_mfma_i32_16x16x64_i8 v[84:87], v[156:159], v[212:215], v[84:87]
	v_mfma_i32_16x16x64_i8 v[84:87], v[160:163], v[220:223], v[84:87]
	v_mfma_i32_16x16x64_i8 v[100:103], v[160:163], v[208:211], v[100:103]
	v_mfma_i32_16x16x64_i8 v[100:103], v[156:159], v[204:207], v[100:103]
	v_mfma_i32_16x16x64_i8 v[116:119], v[156:159], v[172:175], v[116:119]
	v_mfma_i32_16x16x64_i8 v[116:119], v[160:163], v[176:179], v[116:119]
	v_mfma_i32_16x16x64_i8 v[132:135], v[160:163], v[168:171], v[132:135]
	v_mfma_i32_16x16x64_i8 v[132:135], v[156:159], v[164:167], v[132:135]
	s_setprio 0
	s_barrier
; #define PG8_STAGE(bufoff, gbase, voff) do { _Pragma("unroll") for (int _i = 0; _i < 2; ++_i) \
;         __builtin_amdgcn_global_load_lds((const unsigned*)((const char*)(gbase) + (voff)[_i]), (PG8_LAS unsigned*)(lds + (bufoff) + ldsw + _i * 8192), 16, 0, 0); } while (0)
; #define PG8_LDA(dst, b, h) do { _Pragma("unroll") for (int m = 0; m < 4; ++m) _Pragma("unroll") for (int k = 0; k < 2; ++k) dst[m][k] = *(const PG8_LAS bf16x8*)(lds + PG8_SA(b, h) + aoff + m * 2048 + k * 1024); } while (0)
; #define PG8_LDB(dst, b, h) do { _Pragma("unroll") for (int n = 0; n < 2; ++n) _Pragma("unroll") for (int k = 0; k < 2; ++k) dst[n][k] = *(const PG8_LAS bf16x8*)(lds + PG8_SB(b, h) + boff + n * 2048 + k * 1024); } while (0)
; #define PG8_WAIT_V(n) asm volatile("s_waitcnt vmcnt(" #n ")" ::: "memory")
; #define PG8_WAIT_L(n) asm volatile("s_waitcnt lgkmcnt(" #n ")" ::: "memory")
; #define PG8_BAR __builtin_amdgcn_s_barrier()
; #define PG8_SCHED __builtin_amdgcn_sched_barrier(0)
; template <class Epi, class Sched, bool ALIGN_EPI = false, bool SP2 = false, bool I8 = false>
; __device__ __forceinline__ void gemm_phase(PG8_LAS unsigned char* lds, const Gemm g, const Sched& S, const Epi& E) {
;     ...
;             PG8_LDA(At, 0, 1); PG8_STAGE(PG8_SB(0, 0), b2, voffB); PG8_STAGE(PG8_SB(0, 1), b2 + hstep, voffB); PG8_STAGE(PG8_SA(0, 0), a2, voffA);
;             PG8_WAIT_V(8); PG8_WAIT_L(0); PG8_BAR; PG8_MMA(1, 0, At, B0); PG8_MMA(1, 1, At, B1); PG8_BAR; PG8_SCHED;
;             PG8_LDB(B0, 1, 0); PG8_LDB(B1, 1, 1); PG8_SCHED; PG8_LDA(At, 1, 0); PG8_STAGE(PG8_SA(0, 1), a2 + hstep, voffA);
;             PG8_WAIT_V(8); PG8_WAIT_L(0); PG8_BAR; PG8_MMA(0, 0, At, B0); PG8_MMA(0, 1, At, B1); PG8_BAR; PG8_SCHED;
	s_add_i32 s87, s87, s46
	v_lshl_add_u64 v[190:191], s[58:59], 0, v[2:3]
	s_mov_b32 m0, s87
	ds_read_b128 v[164:167], v219 offset:16384
	ds_read_b128 v[168:171], v219 offset:17408
	ds_read_b128 v[172:175], v219 offset:18432
	ds_read_b128 v[176:179], v219 offset:19456
	ds_read_b128 v[204:207], v219 offset:20480
	ds_read_b128 v[208:211], v219 offset:21504
	ds_read_b128 v[212:215], v219 offset:22528
	ds_read_b128 v[220:223], v219 offset:23552
	global_load_lds_dwordx4 v[190:191], off
	s_add_i32 m0, s87, 0x2000
	s_add_u32 s96, s58, 0x80000
	v_lshl_add_u64 v[224:225], s[58:59], 0, v[184:185]
	s_addc_u32 s97, s59, 0
	s_add_i32 s87, vcc_lo, s46
	global_load_lds_dwordx4 v[224:225], off
	s_mov_b32 m0, s87
	v_lshl_add_u64 v[228:229], s[60:61], 0, v[182:183]
	global_load_lds_dwordx4 v2, s[96:97]
	s_add_i32 m0, s87, 0x2000
	s_nop 0
	global_load_lds_dwordx4 v184, s[96:97]
	v_lshl_add_u64 v[226:227], s[60:61], 0, v[180:181]
	s_waitcnt vmcnt(6) lgkmcnt(0)
	s_barrier
	s_setprio 1
	v_mfma_i32_16x16x64_i8 v[80:83], v[28:31], v[164:167], v[80:83]
	v_mfma_i32_16x16x64_i8 v[80:83], v[32:35], v[168:171], v[80:83]
	v_mfma_i32_16x16x64_i8 v[64:67], v[32:35], v[176:179], v[64:67]
	v_mfma_i32_16x16x64_i8 v[64:67], v[28:31], v[172:175], v[64:67]
	v_mfma_i32_16x16x64_i8 v[48:51], v[28:31], v[204:207], v[48:51]
	v_mfma_i32_16x16x64_i8 v[48:51], v[32:35], v[208:211], v[48:51]
	v_mfma_i32_16x16x64_i8 v[16:19], v[32:35], v[220:223], v[16:19]
	v_mfma_i32_16x16x64_i8 v[16:19], v[28:31], v[212:215], v[16:19]
	v_mfma_i32_16x16x64_i8 v[12:15], v[36:39], v[212:215], v[12:15]
	v_mfma_i32_16x16x64_i8 v[12:15], v[40:43], v[220:223], v[12:15]
	v_mfma_i32_16x16x64_i8 v[44:47], v[40:43], v[208:211], v[44:47]
	v_mfma_i32_16x16x64_i8 v[44:47], v[36:39], v[204:207], v[44:47]
	v_mfma_i32_16x16x64_i8 v[60:63], v[36:39], v[172:175], v[60:63]
	v_mfma_i32_16x16x64_i8 v[60:63], v[40:43], v[176:179], v[60:63]
	v_mfma_i32_16x16x64_i8 v[76:79], v[40:43], v[168:171], v[76:79]
	v_mfma_i32_16x16x64_i8 v[76:79], v[36:39], v[164:167], v[76:79]
	v_mfma_i32_16x16x64_i8 v[28:31], v[140:143], v[164:167], v[72:75]
	v_mfma_i32_16x16x64_i8 v[28:31], v[144:147], v[168:171], v[28:31]
	v_mfma_i32_16x16x64_i8 v[36:39], v[144:147], v[176:179], v[56:59]
	v_mfma_i32_16x16x64_i8 v[36:39], v[140:143], v[172:175], v[36:39]
	v_mfma_i32_16x16x64_i8 v[24:27], v[140:143], v[204:207], v[24:27]
	v_mfma_i32_16x16x64_i8 v[24:27], v[144:147], v[208:211], v[24:27]
	v_mfma_i32_16x16x64_i8 v[8:11], v[144:147], v[220:223], v[8:11]
	v_mfma_i32_16x16x64_i8 v[8:11], v[140:143], v[212:215], v[8:11]
	v_mfma_i32_16x16x64_i8 v[4:7], v[156:159], v[212:215], v[4:7]
	v_mfma_i32_16x16x64_i8 v[4:7], v[160:163], v[220:223], v[4:7]
	v_mfma_i32_16x16x64_i8 v[20:23], v[160:163], v[208:211], v[20:23]
	v_mfma_i32_16x16x64_i8 v[20:23], v[156:159], v[204:207], v[20:23]
	v_mfma_i32_16x16x64_i8 v[40:43], v[156:159], v[172:175], v[52:55]
	v_mfma_i32_16x16x64_i8 v[40:43], v[160:163], v[176:179], v[40:43]
	v_mfma_i32_16x16x64_i8 v[32:35], v[160:163], v[168:171], v[68:71]
	v_mfma_i32_16x16x64_i8 v[32:35], v[156:159], v[164:167], v[32:35]
	s_setprio 0
	s_barrier
	s_mov_b32 m0, s65
	s_nop 0
	global_load_lds_dwordx4 v[226:227], off
	s_mov_b32 m0, s67
	s_nop 0
	global_load_lds_dwordx4 v[228:229], off
	s_add_i32 s87, 0, 0x18000
	s_add_i32 s96, 0, 0x1c000
	v_add_u32_e32 v72, s87, v217
	v_add_u32_e32 v160, s96, v217
	ds_read_b128 v[52:55], v72
	ds_read_b128 v[56:59], v72 offset:1024
	ds_read_b128 v[68:71], v72 offset:2048
	ds_read_b128 v[72:75], v72 offset:3072
	ds_read_b128 v[140:143], v160
	ds_read_b128 v[144:147], v160 offset:1024
	ds_read_b128 v[156:159], v160 offset:2048
	ds_read_b128 v[160:163], v160 offset:3072
	s_add_u32 s60, s60, 0x80000
	s_addc_u32 s61, s61, 0
	s_mov_b32 m0, s72
	ds_read_b128 v[164:167], v219 offset:32768
	ds_read_b128 v[168:171], v219 offset:33792
	ds_read_b128 v[172:175], v219 offset:34816
	ds_read_b128 v[176:179], v219 offset:35840
	ds_read_b128 v[204:207], v219 offset:36864
	ds_read_b128 v[208:211], v219 offset:37888
	ds_read_b128 v[212:215], v219 offset:38912
	ds_read_b128 v[220:223], v219 offset:39936
	global_load_lds_dwordx4 v180, s[60:61]
	s_mov_b32 m0, s73
	s_nop 0
	global_load_lds_dwordx4 v182, s[60:61]
	s_waitcnt vmcnt(8) lgkmcnt(0)
	s_barrier
; #define PG8_STAGE(bufoff, gbase, voff) do { _Pragma("unroll") for (int _i = 0; _i < 2; ++_i) \
;         __builtin_amdgcn_global_load_lds((const unsigned*)((const char*)(gbase) + (voff)[_i]), (PG8_LAS unsigned*)(lds + (bufoff) + ldsw + _i * 8192), 16, 0, 0); } while (0)
; #define PG8_LDA(dst, b, h) do { _Pragma("unroll") for (int m = 0; m < 4; ++m) _Pragma("unroll") for (int k = 0; k < 2; ++k) dst[m][k] = *(const PG8_LAS bf16x8*)(lds + PG8_SA(b, h) + aoff + m * 2048 + k * 1024); } while (0)
; #define PG8_LDB(dst, b, h) do { _Pragma("unroll") for (int n = 0; n < 2; ++n) _Pragma("unroll") for (int k = 0; k < 2; ++k) dst[n][k] = *(const PG8_LAS bf16x8*)(lds + PG8_SB(b, h) + boff + n * 2048 + k * 1024); } while (0)
; #define PG8_WAIT_V(n) asm volatile("s_waitcnt vmcnt(" #n ")" ::: "memory")
; #define PG8_WAIT_L(n) asm volatile("s_waitcnt lgkmcnt(" #n ")" ::: "memory")
; #define PG8_BAR __builtin_amdgcn_s_barrier()
; #define PG8_SCHED __builtin_amdgcn_sched_barrier(0)
; template <class Epi, class Sched, bool ALIGN_EPI = false, bool SP2 = false, bool I8 = false>
; __device__ __forceinline__ void gemm_phase(PG8_LAS unsigned char* lds, const Gemm g, const Sched& S, const Epi& E) {
;     ...
;             PG8_LDB(B0, 0, 0); PG8_LDB(B1, 0, 1); PG8_SCHED; PG8_LDA(At, 0, 0); PG8_STAGE(PG8_SA(1, 1), a1 + hstep, voffA);
;             PG8_WAIT_V(8); PG8_WAIT_L(0); PG8_BAR; PG8_MMA(0, 0, At, B0); PG8_MMA(0, 1, At, B1); PG8_BAR; PG8_SCHED;
;             PG8_LDA(At, 0, 1); PG8_STAGE(PG8_SB(0, 0), b2, voffB); PG8_STAGE(PG8_SB(0, 1), b2 + hstep, voffB); PG8_STAGE(PG8_SA(0, 0), a2, voffA);
;             PG8_WAIT_V(8); PG8_WAIT_L(0); PG8_BAR; PG8_MMA(1, 0, At, B0); PG8_MMA(1, 1, At, B1); PG8_BAR; PG8_SCHED;
;             PG8_LDB(B0, 1, 0); PG8_LDB(B1, 1, 1); PG8_SCHED; PG8_LDA(At, 1, 0); PG8_STAGE(PG8_SA(0, 1), a2 + hstep, voffA);
;             PG8_WAIT_V(8); PG8_WAIT_L(0); PG8_BAR; PG8_MMA(0, 0, At, B0); PG8_MMA(0, 1, At, B1); PG8_BAR; PG8_SCHED;
;             PG8_LDA(At, 1, 1); PG8_STAGE(PG8_SB(1, 0), b3, voffB); PG8_STAGE(PG8_SB(1, 1), b3 + hstep, voffB); PG8_STAGE(PG8_SA(1, 0), a3, voffA);
;             PG8_WAIT_V(8); PG8_WAIT_L(0); PG8_BAR; PG8_MMA(1, 0, At, B0); PG8_MMA(1, 1, At, B1); PG8_BAR; PG8_SCHED;
	s_setprio 1
	v_mfma_i32_16x16x64_i8 v[152:155], v[52:55], v[164:167], v[152:155]
	v_mfma_i32_16x16x64_i8 v[152:155], v[56:59], v[168:171], v[152:155]
	v_mfma_i32_16x16x64_i8 v[128:131], v[56:59], v[176:179], v[128:131]
	v_mfma_i32_16x16x64_i8 v[128:131], v[52:55], v[172:175], v[128:131]
	v_mfma_i32_16x16x64_i8 v[112:115], v[52:55], v[204:207], v[112:115]
	v_mfma_i32_16x16x64_i8 v[112:115], v[56:59], v[208:211], v[112:115]
	v_mfma_i32_16x16x64_i8 v[96:99], v[56:59], v[220:223], v[96:99]
	v_mfma_i32_16x16x64_i8 v[96:99], v[52:55], v[212:215], v[96:99]
	v_mfma_i32_16x16x64_i8 v[92:95], v[68:71], v[212:215], v[92:95]
	v_mfma_i32_16x16x64_i8 v[92:95], v[72:75], v[220:223], v[92:95]
	v_mfma_i32_16x16x64_i8 v[108:111], v[72:75], v[208:211], v[108:111]
	v_mfma_i32_16x16x64_i8 v[108:111], v[68:71], v[204:207], v[108:111]
	v_mfma_i32_16x16x64_i8 v[124:127], v[68:71], v[172:175], v[124:127]
	v_mfma_i32_16x16x64_i8 v[124:127], v[72:75], v[176:179], v[124:127]
	v_mfma_i32_16x16x64_i8 v[148:151], v[72:75], v[168:171], v[148:151]
	v_mfma_i32_16x16x64_i8 v[148:151], v[68:71], v[164:167], v[148:151]
	v_mfma_i32_16x16x64_i8 v[136:139], v[140:143], v[164:167], v[136:139]
	v_mfma_i32_16x16x64_i8 v[136:139], v[144:147], v[168:171], v[136:139]
	v_mfma_i32_16x16x64_i8 v[120:123], v[144:147], v[176:179], v[120:123]
	v_mfma_i32_16x16x64_i8 v[120:123], v[140:143], v[172:175], v[120:123]
	v_mfma_i32_16x16x64_i8 v[104:107], v[140:143], v[204:207], v[104:107]
	v_mfma_i32_16x16x64_i8 v[104:107], v[144:147], v[208:211], v[104:107]
	v_mfma_i32_16x16x64_i8 v[88:91], v[144:147], v[220:223], v[88:91]
	v_mfma_i32_16x16x64_i8 v[88:91], v[140:143], v[212:215], v[88:91]
	v_mfma_i32_16x16x64_i8 v[84:87], v[156:159], v[212:215], v[84:87]
	v_mfma_i32_16x16x64_i8 v[84:87], v[160:163], v[220:223], v[84:87]
	v_mfma_i32_16x16x64_i8 v[100:103], v[160:163], v[208:211], v[100:103]
	v_mfma_i32_16x16x64_i8 v[100:103], v[156:159], v[204:207], v[100:103]
	v_mfma_i32_16x16x64_i8 v[116:119], v[156:159], v[172:175], v[116:119]
	v_mfma_i32_16x16x64_i8 v[116:119], v[160:163], v[176:179], v[116:119]
	v_mfma_i32_16x16x64_i8 v[132:135], v[160:163], v[168:171], v[132:135]
	v_mfma_i32_16x16x64_i8 v[132:135], v[156:159], v[164:167], v[132:135]
	s_setprio 0
	s_barrier
	s_add_i32 s60, s87, s46
	v_lshl_add_u64 v[190:191], v[190:191], 0, s[84:85]
	s_mov_b32 m0, s60
	ds_read_b128 v[164:167], v219 offset:49152
	ds_read_b128 v[168:171], v219 offset:50176
	ds_read_b128 v[172:175], v219 offset:51200
	ds_read_b128 v[176:179], v219 offset:52224
	ds_read_b128 v[204:207], v219 offset:53248
	ds_read_b128 v[208:211], v219 offset:54272
	ds_read_b128 v[212:215], v219 offset:55296
	ds_read_b128 v[220:223], v219 offset:56320
	global_load_lds_dwordx4 v[190:191], off
	s_add_i32 m0, s60, 0x2000
	s_add_u32 s58, s58, 0x80080
	v_lshl_add_u64 v[190:191], v[224:225], 0, s[84:85]
	s_addc_u32 s59, s59, 0
	s_add_i32 s60, s96, s46
	global_load_lds_dwordx4 v[190:191], off
	s_mov_b32 m0, s60
	s_nop 0
	global_load_lds_dwordx4 v2, s[58:59]
	s_add_i32 m0, s60, 0x2000
	s_nop 0
	global_load_lds_dwordx4 v184, s[58:59]
	s_cmp_eq_u32 s86, 28
	s_cbranch_scc0 .Ldefer_1843_body
	v_lshl_add_u64 v[190:191], v[226:227], 0, s[84:85]
	s_mov_b32 m0, s28
	s_nop 0
	global_load_lds_dwordx4 v[190:191], off
	v_lshl_add_u64 v[190:191], v[228:229], 0, s[84:85]
	s_mov_b32 m0, s77
	s_nop 0
	global_load_lds_dwordx4 v[190:191], off
.Ldefer_1843_body:
	s_waitcnt vmcnt(6) lgkmcnt(0)
	s_barrier
	s_setprio 1
	v_mfma_i32_16x16x64_i8 v[80:83], v[52:55], v[164:167], v[80:83]
	v_mfma_i32_16x16x64_i8 v[80:83], v[56:59], v[168:171], v[80:83]
	v_mfma_i32_16x16x64_i8 v[64:67], v[56:59], v[176:179], v[64:67]
	v_mfma_i32_16x16x64_i8 v[64:67], v[52:55], v[172:175], v[64:67]
	v_mfma_i32_16x16x64_i8 v[48:51], v[52:55], v[204:207], v[48:51]
	v_mfma_i32_16x16x64_i8 v[48:51], v[56:59], v[208:211], v[48:51]
	v_mfma_i32_16x16x64_i8 v[16:19], v[56:59], v[220:223], v[16:19]
	v_mfma_i32_16x16x64_i8 v[16:19], v[52:55], v[212:215], v[16:19]
	v_mfma_i32_16x16x64_i8 v[12:15], v[68:71], v[212:215], v[12:15]
	v_mfma_i32_16x16x64_i8 v[12:15], v[72:75], v[220:223], v[12:15]
	v_mfma_i32_16x16x64_i8 v[44:47], v[72:75], v[208:211], v[44:47]
	v_mfma_i32_16x16x64_i8 v[44:47], v[68:71], v[204:207], v[44:47]
	v_mfma_i32_16x16x64_i8 v[60:63], v[68:71], v[172:175], v[60:63]
	v_mfma_i32_16x16x64_i8 v[60:63], v[72:75], v[176:179], v[60:63]
	v_mfma_i32_16x16x64_i8 v[76:79], v[72:75], v[168:171], v[76:79]
	v_mfma_i32_16x16x64_i8 v[76:79], v[68:71], v[164:167], v[76:79]
	v_mfma_i32_16x16x64_i8 v[28:31], v[140:143], v[164:167], v[28:31]
	v_mfma_i32_16x16x64_i8 v[72:75], v[144:147], v[168:171], v[28:31]
	v_mfma_i32_16x16x64_i8 v[28:31], v[144:147], v[176:179], v[36:39]
	v_mfma_i32_16x16x64_i8 v[56:59], v[140:143], v[172:175], v[28:31]
	v_mfma_i32_16x16x64_i8 v[24:27], v[140:143], v[204:207], v[24:27]
	v_mfma_i32_16x16x64_i8 v[24:27], v[144:147], v[208:211], v[24:27]
	v_mfma_i32_16x16x64_i8 v[8:11], v[144:147], v[220:223], v[8:11]
	v_mfma_i32_16x16x64_i8 v[8:11], v[140:143], v[212:215], v[8:11]
	v_mfma_i32_16x16x64_i8 v[4:7], v[156:159], v[212:215], v[4:7]
	v_mfma_i32_16x16x64_i8 v[4:7], v[160:163], v[220:223], v[4:7]
	v_mfma_i32_16x16x64_i8 v[20:23], v[160:163], v[208:211], v[20:23]
	v_mfma_i32_16x16x64_i8 v[20:23], v[156:159], v[204:207], v[20:23]
	v_mfma_i32_16x16x64_i8 v[28:31], v[156:159], v[172:175], v[40:43]
	v_mfma_i32_16x16x64_i8 v[52:55], v[160:163], v[176:179], v[28:31]
	v_mfma_i32_16x16x64_i8 v[28:31], v[160:163], v[168:171], v[32:35]
	v_mfma_i32_16x16x64_i8 v[68:71], v[156:159], v[164:167], v[28:31]
	s_setprio 0
	s_barrier
	s_add_i32 s86, s86, 2
	s_add_u32 s54, s54, 0x100
	s_addc_u32 s55, s55, 0
	s_add_u32 s45, s45, 0x100
	s_addc_u32 s49, s49, 0
	s_cmp_gt_u32 s86, 29
	s_cbranch_scc0 .LBB0_1843
